# P15 hand-written: no prefetch beyond the chunk in the last pass (removes 16 tokens of dummy loads per wave)
# speedup vs baseline: 1.0368x; 1.0027x over previous
; DEV u16 f2bf(float f) { return (u16)(pack2(f, f) & 0xffffu); }
; DEV float bf2f(u16 h) { return __uint_as_float(((unsigned)h) << 16); }
; DEV float sigmoid_f(float x) { return __builtin_amdgcn_rcpf(1.f + __expf(-x)); }
; DEV void phase_p15(const Params& p, int g) {
;     ...
;         for (int e = 0; e < 8; ++e) {
;           const int jj = j8 * 8 + e;
;           const int j = dir ? 63 - jj : jj;
;           const size_t tok = (size_t)cidx * 64 + j;
;           const float f = lb[cc] + (1.f - lb[cc]) * sigmoid_f(bf2f(xr[st][cc][e]));
;           G[cc] += __logf(f);
;           const float eg = __expf(G[cc]), ig = __expf(-G[cc]);
;           Qp[tok * 512 + c] = f2bf(bf2f(qr[st][cc][e]) * eg);
;           const u16 kk = f2bf((1.f - f) * ig);
;           Kp[tok * 512 + c] = kk;
;           kb[e] = kk;
;         }
.Lp15_d0_loop:
	s_waitcnt vmcnt(32)
	v_lshlrev_b32_e32 v92, 16, v0
	v_and_b32_e32 v93, 0xffff0000, v0
	v_lshlrev_b32_e32 v94, 16, v1
	v_and_b32_e32 v95, 0xffff0000, v1
	v_mul_f32_e32 v92, 0xbfb8aa3b, v92
	v_mul_f32_e32 v93, 0xbfb8aa3b, v93
	v_mul_f32_e32 v94, 0xbfb8aa3b, v94
	v_mul_f32_e32 v95, 0xbfb8aa3b, v95
	v_exp_f32_e32 v92, v92
	v_exp_f32_e32 v93, v93
	v_exp_f32_e32 v94, v94
	v_exp_f32_e32 v95, v95
	v_add_f32_e32 v92, 1.0, v92
	v_add_f32_e32 v93, 1.0, v93
	v_add_f32_e32 v94, 1.0, v94
	v_add_f32_e32 v95, 1.0, v95
	v_rcp_f32_e32 v92, v92
	v_rcp_f32_e32 v93, v93
	v_rcp_f32_e32 v94, v94
	v_rcp_f32_e32 v95, v95
	v_fma_f32 v96, v72, v92, v68
	v_fma_f32 v97, v73, v93, v69
	v_fma_f32 v98, v74, v94, v70
	v_fma_f32 v99, v75, v95, v71
	v_cmp_gt_f32_e64 s[22:23], s30, v96
	v_cmp_gt_f32_e64 s[24:25], s30, v97
	v_cmp_gt_f32_e64 s[26:27], s30, v98
	v_cmp_gt_f32_e64 s[28:29], s30, v99
	v_cndmask_b32_e64 v92, 0, 32, s[22:23]
	v_cndmask_b32_e64 v93, 0, 32, s[24:25]
	v_cndmask_b32_e64 v94, 0, 32, s[26:27]
	v_cndmask_b32_e64 v95, 0, 32, s[28:29]
	v_ldexp_f32 v92, v96, v92
	v_ldexp_f32 v93, v97, v93
	v_ldexp_f32 v94, v98, v94
	v_ldexp_f32 v95, v99, v95
	v_log_f32_e32 v92, v92
	v_log_f32_e32 v93, v93
	v_log_f32_e32 v94, v94
	v_log_f32_e32 v95, v95
	v_mul_f32_e32 v100, 0x3f317217, v92
	v_mul_f32_e32 v101, 0x3f317217, v93
	v_mul_f32_e32 v102, 0x3f317217, v94
	v_mul_f32_e32 v103, 0x3f317217, v95
	v_fma_f32 v100, v92, s31, -v100
	v_fma_f32 v101, v93, s31, -v101
	v_fma_f32 v102, v94, s31, -v102
	v_fma_f32 v103, v95, s31, -v103
	v_fmac_f32_e32 v100, 0x3377d1cf, v92
	v_fmac_f32_e32 v101, 0x3377d1cf, v93
	v_fmac_f32_e32 v102, 0x3377d1cf, v94
	v_fmac_f32_e32 v103, 0x3377d1cf, v95
	v_fmac_f32_e32 v100, 0x3f317217, v92
	v_fmac_f32_e32 v101, 0x3f317217, v93
	v_fmac_f32_e32 v102, 0x3f317217, v94
	v_fmac_f32_e32 v103, 0x3f317217, v95
	v_cmp_lt_f32_e64 vcc, |v92|, s34
	v_cndmask_b32_e32 v92, v92, v100, vcc
	v_cmp_lt_f32_e64 vcc, |v93|, s34
	v_cndmask_b32_e32 v93, v93, v101, vcc
	v_cmp_lt_f32_e64 vcc, |v94|, s34
	v_cndmask_b32_e32 v94, v94, v102, vcc
	v_cmp_lt_f32_e64 vcc, |v95|, s34
	v_cndmask_b32_e32 v95, v95, v103, vcc
	v_cndmask_b32_e64 v100, 0, v213, s[22:23]
	v_cndmask_b32_e64 v101, 0, v213, s[24:25]
	v_cndmask_b32_e64 v102, 0, v213, s[26:27]
	v_cndmask_b32_e64 v103, 0, v213, s[28:29]
	v_sub_f32_e32 v92, v92, v100
	v_sub_f32_e32 v93, v93, v101
	v_sub_f32_e32 v94, v94, v102
	v_sub_f32_e32 v95, v95, v103
	v_add_f32_e32 v64, v64, v92
	v_add_f32_e32 v65, v65, v93
	v_add_f32_e32 v66, v66, v94
	v_add_f32_e32 v67, v67, v95
	v_mul_f32_e32 v92, 0xbfb8aa3b, v64
	v_mul_f32_e32 v93, 0xbfb8aa3b, v65
	v_mul_f32_e32 v94, 0xbfb8aa3b, v66
	v_mul_f32_e32 v95, 0xbfb8aa3b, v67
	v_mul_f32_e32 v100, 0x3fb8aa3b, v64
	v_mul_f32_e32 v101, 0x3fb8aa3b, v65
	v_mul_f32_e32 v102, 0x3fb8aa3b, v66
	v_mul_f32_e32 v103, 0x3fb8aa3b, v67
	v_exp_f32_e32 v92, v92
	v_exp_f32_e32 v93, v93
	v_exp_f32_e32 v94, v94
	v_exp_f32_e32 v95, v95
	v_exp_f32_e32 v100, v100
	v_exp_f32_e32 v101, v101
	v_exp_f32_e32 v102, v102
	v_exp_f32_e32 v103, v103
	v_sub_f32_e32 v96, 1.0, v96
	v_sub_f32_e32 v97, 1.0, v97
	v_sub_f32_e32 v98, 1.0, v98
	v_sub_f32_e32 v99, 1.0, v99
	v_mul_f32_e32 v96, v96, v92
	v_mul_f32_e32 v97, v97, v93
	v_mul_f32_e32 v98, v98, v94
	v_mul_f32_e32 v99, v99, v95
	v_lshlrev_b32_e32 v92, 16, v2
	v_and_b32_e32 v93, 0xffff0000, v2
	v_lshlrev_b32_e32 v94, 16, v3
	v_and_b32_e32 v95, 0xffff0000, v3
	v_mul_f32_e32 v92, v92, v100
	v_mul_f32_e32 v93, v93, v101
	v_mul_f32_e32 v94, v94, v102
	v_mul_f32_e32 v95, v95, v103
	v_mov_b32_e32 v116, v96
	v_mov_b32_e32 v132, v97
	v_mov_b32_e32 v166, v98
	v_mov_b32_e32 v182, v99
	v_cvt_pk_bf16_f32 v92, v92, v93
	v_cvt_pk_bf16_f32 v93, v94, v95
	v_cvt_pk_bf16_f32 v96, v96, v97
	v_cvt_pk_bf16_f32 v97, v98, v99
	global_store_dwordx2 v112, v[92:93], s[2:3]
	global_store_dwordx2 v114, v[96:97], s[2:3]
	s_add_u32 s2, s2, 0x400
	s_addc_u32 s3, s3, 0
	v_lshlrev_b32_e32 v92, 16, v4
	v_and_b32_e32 v93, 0xffff0000, v4
	v_lshlrev_b32_e32 v94, 16, v5
	v_and_b32_e32 v95, 0xffff0000, v5
	v_mul_f32_e32 v92, 0xbfb8aa3b, v92
	v_mul_f32_e32 v93, 0xbfb8aa3b, v93
	v_mul_f32_e32 v94, 0xbfb8aa3b, v94
	v_mul_f32_e32 v95, 0xbfb8aa3b, v95
	v_exp_f32_e32 v92, v92
	v_exp_f32_e32 v93, v93
	v_exp_f32_e32 v94, v94
	v_exp_f32_e32 v95, v95
	v_add_f32_e32 v92, 1.0, v92
	v_add_f32_e32 v93, 1.0, v93
	v_add_f32_e32 v94, 1.0, v94
	v_add_f32_e32 v95, 1.0, v95
	v_rcp_f32_e32 v92, v92
	v_rcp_f32_e32 v93, v93
	v_rcp_f32_e32 v94, v94
	v_rcp_f32_e32 v95, v95
	v_fma_f32 v96, v72, v92, v68
	v_fma_f32 v97, v73, v93, v69
	v_fma_f32 v98, v74, v94, v70
	v_fma_f32 v99, v75, v95, v71
	v_cmp_gt_f32_e64 s[22:23], s30, v96
	v_cmp_gt_f32_e64 s[24:25], s30, v97
	v_cmp_gt_f32_e64 s[26:27], s30, v98
	v_cmp_gt_f32_e64 s[28:29], s30, v99
	v_cndmask_b32_e64 v92, 0, 32, s[22:23]
	v_cndmask_b32_e64 v93, 0, 32, s[24:25]
	v_cndmask_b32_e64 v94, 0, 32, s[26:27]
	v_cndmask_b32_e64 v95, 0, 32, s[28:29]
	v_ldexp_f32 v92, v96, v92
	v_ldexp_f32 v93, v97, v93
	v_ldexp_f32 v94, v98, v94
	v_ldexp_f32 v95, v99, v95
	v_log_f32_e32 v92, v92
	v_log_f32_e32 v93, v93
	v_log_f32_e32 v94, v94
	v_log_f32_e32 v95, v95
	v_mul_f32_e32 v100, 0x3f317217, v92
	v_mul_f32_e32 v101, 0x3f317217, v93
	v_mul_f32_e32 v102, 0x3f317217, v94
	v_mul_f32_e32 v103, 0x3f317217, v95
	v_fma_f32 v100, v92, s31, -v100
	v_fma_f32 v101, v93, s31, -v101
	v_fma_f32 v102, v94, s31, -v102
	v_fma_f32 v103, v95, s31, -v103
	v_fmac_f32_e32 v100, 0x3377d1cf, v92
	v_fmac_f32_e32 v101, 0x3377d1cf, v93
	v_fmac_f32_e32 v102, 0x3377d1cf, v94
	v_fmac_f32_e32 v103, 0x3377d1cf, v95
	v_fmac_f32_e32 v100, 0x3f317217, v92
	v_fmac_f32_e32 v101, 0x3f317217, v93
	v_fmac_f32_e32 v102, 0x3f317217, v94
; DEV u16 f2bf(float f) { return (u16)(pack2(f, f) & 0xffffu); }
; DEV float bf2f(u16 h) { return __uint_as_float(((unsigned)h) << 16); }
; DEV float sigmoid_f(float x) { return __builtin_amdgcn_rcpf(1.f + __expf(-x)); }
; DEV void phase_p15(const Params& p, int g) {
;     ...
;         for (int e = 0; e < 8; ++e) {
;           const int jj = j8 * 8 + e;
;           const int j = dir ? 63 - jj : jj;
;           const size_t tok = (size_t)cidx * 64 + j;
;           const float f = lb[cc] + (1.f - lb[cc]) * sigmoid_f(bf2f(xr[st][cc][e]));
;           G[cc] += __logf(f);
;           const float eg = __expf(G[cc]), ig = __expf(-G[cc]);
;           Qp[tok * 512 + c] = f2bf(bf2f(qr[st][cc][e]) * eg);
;           const u16 kk = f2bf((1.f - f) * ig);
;           Kp[tok * 512 + c] = kk;
;           kb[e] = kk;
;         }
	v_fmac_f32_e32 v103, 0x3f317217, v95
	v_cmp_lt_f32_e64 vcc, |v92|, s34
	v_cndmask_b32_e32 v92, v92, v100, vcc
	v_cmp_lt_f32_e64 vcc, |v93|, s34
	v_cndmask_b32_e32 v93, v93, v101, vcc
	v_cmp_lt_f32_e64 vcc, |v94|, s34
	v_cndmask_b32_e32 v94, v94, v102, vcc
	v_cmp_lt_f32_e64 vcc, |v95|, s34
	v_cndmask_b32_e32 v95, v95, v103, vcc
	v_cndmask_b32_e64 v100, 0, v213, s[22:23]
	v_cndmask_b32_e64 v101, 0, v213, s[24:25]
	v_cndmask_b32_e64 v102, 0, v213, s[26:27]
	v_cndmask_b32_e64 v103, 0, v213, s[28:29]
	v_sub_f32_e32 v92, v92, v100
	v_sub_f32_e32 v93, v93, v101
	v_sub_f32_e32 v94, v94, v102
	v_sub_f32_e32 v95, v95, v103
	v_add_f32_e32 v64, v64, v92
	v_add_f32_e32 v65, v65, v93
	v_add_f32_e32 v66, v66, v94
	v_add_f32_e32 v67, v67, v95
	v_mul_f32_e32 v92, 0xbfb8aa3b, v64
	v_mul_f32_e32 v93, 0xbfb8aa3b, v65
	v_mul_f32_e32 v94, 0xbfb8aa3b, v66
	v_mul_f32_e32 v95, 0xbfb8aa3b, v67
	v_mul_f32_e32 v100, 0x3fb8aa3b, v64
	v_mul_f32_e32 v101, 0x3fb8aa3b, v65
	v_mul_f32_e32 v102, 0x3fb8aa3b, v66
	v_mul_f32_e32 v103, 0x3fb8aa3b, v67
	v_exp_f32_e32 v92, v92
	v_exp_f32_e32 v93, v93
	v_exp_f32_e32 v94, v94
	v_exp_f32_e32 v95, v95
	v_exp_f32_e32 v100, v100
	v_exp_f32_e32 v101, v101
	v_exp_f32_e32 v102, v102
	v_exp_f32_e32 v103, v103
	v_sub_f32_e32 v96, 1.0, v96
	v_sub_f32_e32 v97, 1.0, v97
	v_sub_f32_e32 v98, 1.0, v98
	v_sub_f32_e32 v99, 1.0, v99
	v_mul_f32_e32 v96, v96, v92
	v_mul_f32_e32 v97, v97, v93
	v_mul_f32_e32 v98, v98, v94
	v_mul_f32_e32 v99, v99, v95
	v_lshlrev_b32_e32 v92, 16, v6
	v_and_b32_e32 v93, 0xffff0000, v6
	v_lshlrev_b32_e32 v94, 16, v7
	v_and_b32_e32 v95, 0xffff0000, v7
	v_mul_f32_e32 v92, v92, v100
	v_mul_f32_e32 v93, v93, v101
	v_mul_f32_e32 v94, v94, v102
	v_mul_f32_e32 v95, v95, v103
	v_cvt_pk_bf16_f32 v116, v116, v96
	v_cvt_pk_bf16_f32 v132, v132, v97
	v_cvt_pk_bf16_f32 v166, v166, v98
	v_cvt_pk_bf16_f32 v182, v182, v99
	v_cvt_pk_bf16_f32 v92, v92, v93
	v_cvt_pk_bf16_f32 v93, v94, v95
	v_cvt_pk_bf16_f32 v96, v96, v97
	v_cvt_pk_bf16_f32 v97, v98, v99
	global_store_dwordx2 v112, v[92:93], s[2:3]
	global_store_dwordx2 v114, v[96:97], s[2:3]
	s_add_u32 s2, s2, 0x400
	s_addc_u32 s3, s3, 0
	v_lshlrev_b32_e32 v92, 16, v8
	v_and_b32_e32 v93, 0xffff0000, v8
	v_lshlrev_b32_e32 v94, 16, v9
	v_and_b32_e32 v95, 0xffff0000, v9
	v_mul_f32_e32 v92, 0xbfb8aa3b, v92
	v_mul_f32_e32 v93, 0xbfb8aa3b, v93
	v_mul_f32_e32 v94, 0xbfb8aa3b, v94
	v_mul_f32_e32 v95, 0xbfb8aa3b, v95
	v_exp_f32_e32 v92, v92
	v_exp_f32_e32 v93, v93
	v_exp_f32_e32 v94, v94
	v_exp_f32_e32 v95, v95
	v_add_f32_e32 v92, 1.0, v92
	v_add_f32_e32 v93, 1.0, v93
	v_add_f32_e32 v94, 1.0, v94
	v_add_f32_e32 v95, 1.0, v95
	v_rcp_f32_e32 v92, v92
	v_rcp_f32_e32 v93, v93
	v_rcp_f32_e32 v94, v94
	v_rcp_f32_e32 v95, v95
	v_fma_f32 v96, v72, v92, v68
	v_fma_f32 v97, v73, v93, v69
	v_fma_f32 v98, v74, v94, v70
	v_fma_f32 v99, v75, v95, v71
	v_cmp_gt_f32_e64 s[22:23], s30, v96
	v_cmp_gt_f32_e64 s[24:25], s30, v97
	v_cmp_gt_f32_e64 s[26:27], s30, v98
	v_cmp_gt_f32_e64 s[28:29], s30, v99
	v_cndmask_b32_e64 v92, 0, 32, s[22:23]
	v_cndmask_b32_e64 v93, 0, 32, s[24:25]
	v_cndmask_b32_e64 v94, 0, 32, s[26:27]
	v_cndmask_b32_e64 v95, 0, 32, s[28:29]
	v_ldexp_f32 v92, v96, v92
	v_ldexp_f32 v93, v97, v93
	v_ldexp_f32 v94, v98, v94
	v_ldexp_f32 v95, v99, v95
	v_log_f32_e32 v92, v92
	v_log_f32_e32 v93, v93
	v_log_f32_e32 v94, v94
	v_log_f32_e32 v95, v95
	v_mul_f32_e32 v100, 0x3f317217, v92
	v_mul_f32_e32 v101, 0x3f317217, v93
	v_mul_f32_e32 v102, 0x3f317217, v94
	v_mul_f32_e32 v103, 0x3f317217, v95
	v_fma_f32 v100, v92, s31, -v100
	v_fma_f32 v101, v93, s31, -v101
	v_fma_f32 v102, v94, s31, -v102
	v_fma_f32 v103, v95, s31, -v103
	v_fmac_f32_e32 v100, 0x3377d1cf, v92
	v_fmac_f32_e32 v101, 0x3377d1cf, v93
	v_fmac_f32_e32 v102, 0x3377d1cf, v94
	v_fmac_f32_e32 v103, 0x3377d1cf, v95
	v_fmac_f32_e32 v100, 0x3f317217, v92
	v_fmac_f32_e32 v101, 0x3f317217, v93
	v_fmac_f32_e32 v102, 0x3f317217, v94
	v_fmac_f32_e32 v103, 0x3f317217, v95
	v_cmp_lt_f32_e64 vcc, |v92|, s34
	v_cndmask_b32_e32 v92, v92, v100, vcc
	v_cmp_lt_f32_e64 vcc, |v93|, s34
	v_cndmask_b32_e32 v93, v93, v101, vcc
	v_cmp_lt_f32_e64 vcc, |v94|, s34
	v_cndmask_b32_e32 v94, v94, v102, vcc
	v_cmp_lt_f32_e64 vcc, |v95|, s34
	v_cndmask_b32_e32 v95, v95, v103, vcc
	v_cndmask_b32_e64 v100, 0, v213, s[22:23]
	v_cndmask_b32_e64 v101, 0, v213, s[24:25]
	v_cndmask_b32_e64 v102, 0, v213, s[26:27]
	v_cndmask_b32_e64 v103, 0, v213, s[28:29]
	v_sub_f32_e32 v92, v92, v100
	v_sub_f32_e32 v93, v93, v101
	v_sub_f32_e32 v94, v94, v102
	v_sub_f32_e32 v95, v95, v103
	v_add_f32_e32 v64, v64, v92
	v_add_f32_e32 v65, v65, v93
	v_add_f32_e32 v66, v66, v94
	v_add_f32_e32 v67, v67, v95
	v_mul_f32_e32 v92, 0xbfb8aa3b, v64
	v_mul_f32_e32 v93, 0xbfb8aa3b, v65
	v_mul_f32_e32 v94, 0xbfb8aa3b, v66
	v_mul_f32_e32 v95, 0xbfb8aa3b, v67
	v_mul_f32_e32 v100, 0x3fb8aa3b, v64
	v_mul_f32_e32 v101, 0x3fb8aa3b, v65
	v_mul_f32_e32 v102, 0x3fb8aa3b, v66
	v_mul_f32_e32 v103, 0x3fb8aa3b, v67
	v_exp_f32_e32 v92, v92
	v_exp_f32_e32 v93, v93
	v_exp_f32_e32 v94, v94
	v_exp_f32_e32 v95, v95
	v_exp_f32_e32 v100, v100
	v_exp_f32_e32 v101, v101
	v_exp_f32_e32 v102, v102
	v_exp_f32_e32 v103, v103
	v_sub_f32_e32 v96, 1.0, v96
	v_sub_f32_e32 v97, 1.0, v97
	v_sub_f32_e32 v98, 1.0, v98
	v_sub_f32_e32 v99, 1.0, v99
	v_mul_f32_e32 v96, v96, v92
	v_mul_f32_e32 v97, v97, v93
	v_mul_f32_e32 v98, v98, v94
	v_mul_f32_e32 v99, v99, v95
	v_lshlrev_b32_e32 v92, 16, v10
	v_and_b32_e32 v93, 0xffff0000, v10
	v_lshlrev_b32_e32 v94, 16, v11
	v_and_b32_e32 v95, 0xffff0000, v11
	v_mul_f32_e32 v92, v92, v100
	v_mul_f32_e32 v93, v93, v101
	v_mul_f32_e32 v94, v94, v102
	v_mul_f32_e32 v95, v95, v103
	v_mov_b32_e32 v117, v96
; DEV u16 f2bf(float f) { return (u16)(pack2(f, f) & 0xffffu); }
; DEV float bf2f(u16 h) { return __uint_as_float(((unsigned)h) << 16); }
; DEV float sigmoid_f(float x) { return __builtin_amdgcn_rcpf(1.f + __expf(-x)); }
; DEV void phase_p15(const Params& p, int g) {
;     ...
;         for (int e = 0; e < 8; ++e) {
;           const int jj = j8 * 8 + e;
;           const int j = dir ? 63 - jj : jj;
;           const size_t tok = (size_t)cidx * 64 + j;
;           const float f = lb[cc] + (1.f - lb[cc]) * sigmoid_f(bf2f(xr[st][cc][e]));
;           G[cc] += __logf(f);
;           const float eg = __expf(G[cc]), ig = __expf(-G[cc]);
;           Qp[tok * 512 + c] = f2bf(bf2f(qr[st][cc][e]) * eg);
;           const u16 kk = f2bf((1.f - f) * ig);
;           Kp[tok * 512 + c] = kk;
;           kb[e] = kk;
;         }
	v_mov_b32_e32 v133, v97
	v_mov_b32_e32 v167, v98
	v_mov_b32_e32 v183, v99
	v_cvt_pk_bf16_f32 v92, v92, v93
	v_cvt_pk_bf16_f32 v93, v94, v95
	v_cvt_pk_bf16_f32 v96, v96, v97
	v_cvt_pk_bf16_f32 v97, v98, v99
	global_store_dwordx2 v112, v[92:93], s[2:3]
	global_store_dwordx2 v114, v[96:97], s[2:3]
	s_add_u32 s2, s2, 0x400
	s_addc_u32 s3, s3, 0
	v_lshlrev_b32_e32 v92, 16, v12
	v_and_b32_e32 v93, 0xffff0000, v12
	v_lshlrev_b32_e32 v94, 16, v13
	v_and_b32_e32 v95, 0xffff0000, v13
	v_mul_f32_e32 v92, 0xbfb8aa3b, v92
	v_mul_f32_e32 v93, 0xbfb8aa3b, v93
	v_mul_f32_e32 v94, 0xbfb8aa3b, v94
	v_mul_f32_e32 v95, 0xbfb8aa3b, v95
	v_exp_f32_e32 v92, v92
	v_exp_f32_e32 v93, v93
	v_exp_f32_e32 v94, v94
	v_exp_f32_e32 v95, v95
	v_add_f32_e32 v92, 1.0, v92
	v_add_f32_e32 v93, 1.0, v93
	v_add_f32_e32 v94, 1.0, v94
	v_add_f32_e32 v95, 1.0, v95
	v_rcp_f32_e32 v92, v92
	v_rcp_f32_e32 v93, v93
	v_rcp_f32_e32 v94, v94
	v_rcp_f32_e32 v95, v95
	v_fma_f32 v96, v72, v92, v68
	v_fma_f32 v97, v73, v93, v69
	v_fma_f32 v98, v74, v94, v70
	v_fma_f32 v99, v75, v95, v71
	v_cmp_gt_f32_e64 s[22:23], s30, v96
	v_cmp_gt_f32_e64 s[24:25], s30, v97
	v_cmp_gt_f32_e64 s[26:27], s30, v98
	v_cmp_gt_f32_e64 s[28:29], s30, v99
	v_cndmask_b32_e64 v92, 0, 32, s[22:23]
	v_cndmask_b32_e64 v93, 0, 32, s[24:25]
	v_cndmask_b32_e64 v94, 0, 32, s[26:27]
	v_cndmask_b32_e64 v95, 0, 32, s[28:29]
	v_ldexp_f32 v92, v96, v92
	v_ldexp_f32 v93, v97, v93
	v_ldexp_f32 v94, v98, v94
	v_ldexp_f32 v95, v99, v95
	v_log_f32_e32 v92, v92
	v_log_f32_e32 v93, v93
	v_log_f32_e32 v94, v94
	v_log_f32_e32 v95, v95
	v_mul_f32_e32 v100, 0x3f317217, v92
	v_mul_f32_e32 v101, 0x3f317217, v93
	v_mul_f32_e32 v102, 0x3f317217, v94
	v_mul_f32_e32 v103, 0x3f317217, v95
	v_fma_f32 v100, v92, s31, -v100
	v_fma_f32 v101, v93, s31, -v101
	v_fma_f32 v102, v94, s31, -v102
	v_fma_f32 v103, v95, s31, -v103
	v_fmac_f32_e32 v100, 0x3377d1cf, v92
	v_fmac_f32_e32 v101, 0x3377d1cf, v93
	v_fmac_f32_e32 v102, 0x3377d1cf, v94
	v_fmac_f32_e32 v103, 0x3377d1cf, v95
	v_fmac_f32_e32 v100, 0x3f317217, v92
	v_fmac_f32_e32 v101, 0x3f317217, v93
	v_fmac_f32_e32 v102, 0x3f317217, v94
	v_fmac_f32_e32 v103, 0x3f317217, v95
	v_cmp_lt_f32_e64 vcc, |v92|, s34
	v_cndmask_b32_e32 v92, v92, v100, vcc
	v_cmp_lt_f32_e64 vcc, |v93|, s34
	v_cndmask_b32_e32 v93, v93, v101, vcc
	v_cmp_lt_f32_e64 vcc, |v94|, s34
	v_cndmask_b32_e32 v94, v94, v102, vcc
	v_cmp_lt_f32_e64 vcc, |v95|, s34
	v_cndmask_b32_e32 v95, v95, v103, vcc
	v_cndmask_b32_e64 v100, 0, v213, s[22:23]
	v_cndmask_b32_e64 v101, 0, v213, s[24:25]
	v_cndmask_b32_e64 v102, 0, v213, s[26:27]
	v_cndmask_b32_e64 v103, 0, v213, s[28:29]
	v_sub_f32_e32 v92, v92, v100
	v_sub_f32_e32 v93, v93, v101
	v_sub_f32_e32 v94, v94, v102
	v_sub_f32_e32 v95, v95, v103
	v_add_f32_e32 v64, v64, v92
	v_add_f32_e32 v65, v65, v93
	v_add_f32_e32 v66, v66, v94
	v_add_f32_e32 v67, v67, v95
	v_mul_f32_e32 v92, 0xbfb8aa3b, v64
	v_mul_f32_e32 v93, 0xbfb8aa3b, v65
	v_mul_f32_e32 v94, 0xbfb8aa3b, v66
	v_mul_f32_e32 v95, 0xbfb8aa3b, v67
	v_mul_f32_e32 v100, 0x3fb8aa3b, v64
	v_mul_f32_e32 v101, 0x3fb8aa3b, v65
	v_mul_f32_e32 v102, 0x3fb8aa3b, v66
	v_mul_f32_e32 v103, 0x3fb8aa3b, v67
	v_exp_f32_e32 v92, v92
	v_exp_f32_e32 v93, v93
	v_exp_f32_e32 v94, v94
	v_exp_f32_e32 v95, v95
	v_exp_f32_e32 v100, v100
	v_exp_f32_e32 v101, v101
	v_exp_f32_e32 v102, v102
	v_exp_f32_e32 v103, v103
	v_sub_f32_e32 v96, 1.0, v96
	v_sub_f32_e32 v97, 1.0, v97
	v_sub_f32_e32 v98, 1.0, v98
	v_sub_f32_e32 v99, 1.0, v99
	v_mul_f32_e32 v96, v96, v92
	v_mul_f32_e32 v97, v97, v93
	v_mul_f32_e32 v98, v98, v94
	v_mul_f32_e32 v99, v99, v95
	v_lshlrev_b32_e32 v92, 16, v14
	v_and_b32_e32 v93, 0xffff0000, v14
	v_lshlrev_b32_e32 v94, 16, v15
	v_and_b32_e32 v95, 0xffff0000, v15
	v_mul_f32_e32 v92, v92, v100
	v_mul_f32_e32 v93, v93, v101
	v_mul_f32_e32 v94, v94, v102
	v_mul_f32_e32 v95, v95, v103
	v_cvt_pk_bf16_f32 v117, v117, v96
	v_cvt_pk_bf16_f32 v133, v133, v97
	v_cvt_pk_bf16_f32 v167, v167, v98
	v_cvt_pk_bf16_f32 v183, v183, v99
	v_cvt_pk_bf16_f32 v92, v92, v93
	v_cvt_pk_bf16_f32 v93, v94, v95
	v_cvt_pk_bf16_f32 v96, v96, v97
	v_cvt_pk_bf16_f32 v97, v98, v99
	global_store_dwordx2 v112, v[92:93], s[2:3]
	global_store_dwordx2 v114, v[96:97], s[2:3]
	s_add_u32 s2, s2, 0x400
	s_addc_u32 s3, s3, 0
	v_lshlrev_b32_e32 v92, 16, v16
	v_and_b32_e32 v93, 0xffff0000, v16
	v_lshlrev_b32_e32 v94, 16, v17
	v_and_b32_e32 v95, 0xffff0000, v17
	v_mul_f32_e32 v92, 0xbfb8aa3b, v92
	v_mul_f32_e32 v93, 0xbfb8aa3b, v93
	v_mul_f32_e32 v94, 0xbfb8aa3b, v94
	v_mul_f32_e32 v95, 0xbfb8aa3b, v95
	v_exp_f32_e32 v92, v92
	v_exp_f32_e32 v93, v93
	v_exp_f32_e32 v94, v94
	v_exp_f32_e32 v95, v95
	v_add_f32_e32 v92, 1.0, v92
	v_add_f32_e32 v93, 1.0, v93
	v_add_f32_e32 v94, 1.0, v94
	v_add_f32_e32 v95, 1.0, v95
	v_rcp_f32_e32 v92, v92
	v_rcp_f32_e32 v93, v93
	v_rcp_f32_e32 v94, v94
	v_rcp_f32_e32 v95, v95
	v_fma_f32 v96, v72, v92, v68
	v_fma_f32 v97, v73, v93, v69
	v_fma_f32 v98, v74, v94, v70
	v_fma_f32 v99, v75, v95, v71
	v_cmp_gt_f32_e64 s[22:23], s30, v96
	v_cmp_gt_f32_e64 s[24:25], s30, v97
	v_cmp_gt_f32_e64 s[26:27], s30, v98
	v_cmp_gt_f32_e64 s[28:29], s30, v99
	v_cndmask_b32_e64 v92, 0, 32, s[22:23]
	v_cndmask_b32_e64 v93, 0, 32, s[24:25]
	v_cndmask_b32_e64 v94, 0, 32, s[26:27]
	v_cndmask_b32_e64 v95, 0, 32, s[28:29]
	v_ldexp_f32 v92, v96, v92
	v_ldexp_f32 v93, v97, v93
	v_ldexp_f32 v94, v98, v94
	v_ldexp_f32 v95, v99, v95
	v_log_f32_e32 v92, v92
	v_log_f32_e32 v93, v93
	v_log_f32_e32 v94, v94
	v_log_f32_e32 v95, v95
	v_mul_f32_e32 v100, 0x3f317217, v92
	v_mul_f32_e32 v101, 0x3f317217, v93
	v_mul_f32_e32 v102, 0x3f317217, v94
	v_mul_f32_e32 v103, 0x3f317217, v95
	v_fma_f32 v100, v92, s31, -v100
; DEV u16 f2bf(float f) { return (u16)(pack2(f, f) & 0xffffu); }
; DEV float bf2f(u16 h) { return __uint_as_float(((unsigned)h) << 16); }
; DEV float sigmoid_f(float x) { return __builtin_amdgcn_rcpf(1.f + __expf(-x)); }
; DEV void phase_p15(const Params& p, int g) {
;     ...
;         for (int e = 0; e < 8; ++e) {
;           const int jj = j8 * 8 + e;
;           const int j = dir ? 63 - jj : jj;
;           const size_t tok = (size_t)cidx * 64 + j;
;           const float f = lb[cc] + (1.f - lb[cc]) * sigmoid_f(bf2f(xr[st][cc][e]));
;           G[cc] += __logf(f);
;           const float eg = __expf(G[cc]), ig = __expf(-G[cc]);
;           Qp[tok * 512 + c] = f2bf(bf2f(qr[st][cc][e]) * eg);
;           const u16 kk = f2bf((1.f - f) * ig);
;           Kp[tok * 512 + c] = kk;
;           kb[e] = kk;
;         }
	v_fma_f32 v101, v93, s31, -v101
	v_fma_f32 v102, v94, s31, -v102
	v_fma_f32 v103, v95, s31, -v103
	v_fmac_f32_e32 v100, 0x3377d1cf, v92
	v_fmac_f32_e32 v101, 0x3377d1cf, v93
	v_fmac_f32_e32 v102, 0x3377d1cf, v94
	v_fmac_f32_e32 v103, 0x3377d1cf, v95
	v_fmac_f32_e32 v100, 0x3f317217, v92
	v_fmac_f32_e32 v101, 0x3f317217, v93
	v_fmac_f32_e32 v102, 0x3f317217, v94
	v_fmac_f32_e32 v103, 0x3f317217, v95
	v_cmp_lt_f32_e64 vcc, |v92|, s34
	v_cndmask_b32_e32 v92, v92, v100, vcc
	v_cmp_lt_f32_e64 vcc, |v93|, s34
	v_cndmask_b32_e32 v93, v93, v101, vcc
	v_cmp_lt_f32_e64 vcc, |v94|, s34
	v_cndmask_b32_e32 v94, v94, v102, vcc
	v_cmp_lt_f32_e64 vcc, |v95|, s34
	v_cndmask_b32_e32 v95, v95, v103, vcc
	v_cndmask_b32_e64 v100, 0, v213, s[22:23]
	v_cndmask_b32_e64 v101, 0, v213, s[24:25]
	v_cndmask_b32_e64 v102, 0, v213, s[26:27]
	v_cndmask_b32_e64 v103, 0, v213, s[28:29]
	v_sub_f32_e32 v92, v92, v100
	v_sub_f32_e32 v93, v93, v101
	v_sub_f32_e32 v94, v94, v102
	v_sub_f32_e32 v95, v95, v103
	v_add_f32_e32 v64, v64, v92
	v_add_f32_e32 v65, v65, v93
	v_add_f32_e32 v66, v66, v94
	v_add_f32_e32 v67, v67, v95
	v_mul_f32_e32 v92, 0xbfb8aa3b, v64
	v_mul_f32_e32 v93, 0xbfb8aa3b, v65
	v_mul_f32_e32 v94, 0xbfb8aa3b, v66
	v_mul_f32_e32 v95, 0xbfb8aa3b, v67
	v_mul_f32_e32 v100, 0x3fb8aa3b, v64
	v_mul_f32_e32 v101, 0x3fb8aa3b, v65
	v_mul_f32_e32 v102, 0x3fb8aa3b, v66
	v_mul_f32_e32 v103, 0x3fb8aa3b, v67
	v_exp_f32_e32 v92, v92
	v_exp_f32_e32 v93, v93
	v_exp_f32_e32 v94, v94
	v_exp_f32_e32 v95, v95
	v_exp_f32_e32 v100, v100
	v_exp_f32_e32 v101, v101
	v_exp_f32_e32 v102, v102
	v_exp_f32_e32 v103, v103
	v_sub_f32_e32 v96, 1.0, v96
	v_sub_f32_e32 v97, 1.0, v97
	v_sub_f32_e32 v98, 1.0, v98
	v_sub_f32_e32 v99, 1.0, v99
	v_mul_f32_e32 v96, v96, v92
	v_mul_f32_e32 v97, v97, v93
	v_mul_f32_e32 v98, v98, v94
	v_mul_f32_e32 v99, v99, v95
	v_lshlrev_b32_e32 v92, 16, v18
	v_and_b32_e32 v93, 0xffff0000, v18
	v_lshlrev_b32_e32 v94, 16, v19
	v_and_b32_e32 v95, 0xffff0000, v19
	v_mul_f32_e32 v92, v92, v100
	v_mul_f32_e32 v93, v93, v101
	v_mul_f32_e32 v94, v94, v102
	v_mul_f32_e32 v95, v95, v103
	v_mov_b32_e32 v118, v96
	v_mov_b32_e32 v134, v97
	v_mov_b32_e32 v168, v98
	v_mov_b32_e32 v184, v99
	v_cvt_pk_bf16_f32 v92, v92, v93
	v_cvt_pk_bf16_f32 v93, v94, v95
	v_cvt_pk_bf16_f32 v96, v96, v97
	v_cvt_pk_bf16_f32 v97, v98, v99
	global_store_dwordx2 v112, v[92:93], s[2:3]
	global_store_dwordx2 v114, v[96:97], s[2:3]
	s_add_u32 s2, s2, 0x400
	s_addc_u32 s3, s3, 0
	v_lshlrev_b32_e32 v92, 16, v20
	v_and_b32_e32 v93, 0xffff0000, v20
	v_lshlrev_b32_e32 v94, 16, v21
	v_and_b32_e32 v95, 0xffff0000, v21
	v_mul_f32_e32 v92, 0xbfb8aa3b, v92
	v_mul_f32_e32 v93, 0xbfb8aa3b, v93
	v_mul_f32_e32 v94, 0xbfb8aa3b, v94
	v_mul_f32_e32 v95, 0xbfb8aa3b, v95
	v_exp_f32_e32 v92, v92
	v_exp_f32_e32 v93, v93
	v_exp_f32_e32 v94, v94
	v_exp_f32_e32 v95, v95
	v_add_f32_e32 v92, 1.0, v92
	v_add_f32_e32 v93, 1.0, v93
	v_add_f32_e32 v94, 1.0, v94
	v_add_f32_e32 v95, 1.0, v95
	v_rcp_f32_e32 v92, v92
	v_rcp_f32_e32 v93, v93
	v_rcp_f32_e32 v94, v94
	v_rcp_f32_e32 v95, v95
	v_fma_f32 v96, v72, v92, v68
	v_fma_f32 v97, v73, v93, v69
	v_fma_f32 v98, v74, v94, v70
	v_fma_f32 v99, v75, v95, v71
	v_cmp_gt_f32_e64 s[22:23], s30, v96
	v_cmp_gt_f32_e64 s[24:25], s30, v97
	v_cmp_gt_f32_e64 s[26:27], s30, v98
	v_cmp_gt_f32_e64 s[28:29], s30, v99
	v_cndmask_b32_e64 v92, 0, 32, s[22:23]
	v_cndmask_b32_e64 v93, 0, 32, s[24:25]
	v_cndmask_b32_e64 v94, 0, 32, s[26:27]
	v_cndmask_b32_e64 v95, 0, 32, s[28:29]
	v_ldexp_f32 v92, v96, v92
	v_ldexp_f32 v93, v97, v93
	v_ldexp_f32 v94, v98, v94
	v_ldexp_f32 v95, v99, v95
	v_log_f32_e32 v92, v92
	v_log_f32_e32 v93, v93
	v_log_f32_e32 v94, v94
	v_log_f32_e32 v95, v95
	v_mul_f32_e32 v100, 0x3f317217, v92
	v_mul_f32_e32 v101, 0x3f317217, v93
	v_mul_f32_e32 v102, 0x3f317217, v94
	v_mul_f32_e32 v103, 0x3f317217, v95
	v_fma_f32 v100, v92, s31, -v100
	v_fma_f32 v101, v93, s31, -v101
	v_fma_f32 v102, v94, s31, -v102
	v_fma_f32 v103, v95, s31, -v103
	v_fmac_f32_e32 v100, 0x3377d1cf, v92
	v_fmac_f32_e32 v101, 0x3377d1cf, v93
	v_fmac_f32_e32 v102, 0x3377d1cf, v94
	v_fmac_f32_e32 v103, 0x3377d1cf, v95
	v_fmac_f32_e32 v100, 0x3f317217, v92
	v_fmac_f32_e32 v101, 0x3f317217, v93
	v_fmac_f32_e32 v102, 0x3f317217, v94
	v_fmac_f32_e32 v103, 0x3f317217, v95
	v_cmp_lt_f32_e64 vcc, |v92|, s34
	v_cndmask_b32_e32 v92, v92, v100, vcc
	v_cmp_lt_f32_e64 vcc, |v93|, s34
	v_cndmask_b32_e32 v93, v93, v101, vcc
	v_cmp_lt_f32_e64 vcc, |v94|, s34
	v_cndmask_b32_e32 v94, v94, v102, vcc
	v_cmp_lt_f32_e64 vcc, |v95|, s34
	v_cndmask_b32_e32 v95, v95, v103, vcc
	v_cndmask_b32_e64 v100, 0, v213, s[22:23]
	v_cndmask_b32_e64 v101, 0, v213, s[24:25]
	v_cndmask_b32_e64 v102, 0, v213, s[26:27]
	v_cndmask_b32_e64 v103, 0, v213, s[28:29]
	v_sub_f32_e32 v92, v92, v100
	v_sub_f32_e32 v93, v93, v101
	v_sub_f32_e32 v94, v94, v102
	v_sub_f32_e32 v95, v95, v103
	v_add_f32_e32 v64, v64, v92
	v_add_f32_e32 v65, v65, v93
	v_add_f32_e32 v66, v66, v94
	v_add_f32_e32 v67, v67, v95
	v_mul_f32_e32 v92, 0xbfb8aa3b, v64
	v_mul_f32_e32 v93, 0xbfb8aa3b, v65
	v_mul_f32_e32 v94, 0xbfb8aa3b, v66
	v_mul_f32_e32 v95, 0xbfb8aa3b, v67
	v_mul_f32_e32 v100, 0x3fb8aa3b, v64
	v_mul_f32_e32 v101, 0x3fb8aa3b, v65
	v_mul_f32_e32 v102, 0x3fb8aa3b, v66
	v_mul_f32_e32 v103, 0x3fb8aa3b, v67
	v_exp_f32_e32 v92, v92
	v_exp_f32_e32 v93, v93
	v_exp_f32_e32 v94, v94
	v_exp_f32_e32 v95, v95
	v_exp_f32_e32 v100, v100
	v_exp_f32_e32 v101, v101
	v_exp_f32_e32 v102, v102
	v_exp_f32_e32 v103, v103
	v_sub_f32_e32 v96, 1.0, v96
	v_sub_f32_e32 v97, 1.0, v97
	v_sub_f32_e32 v98, 1.0, v98
	v_sub_f32_e32 v99, 1.0, v99
	v_mul_f32_e32 v96, v96, v92
	v_mul_f32_e32 v97, v97, v93
	v_mul_f32_e32 v98, v98, v94
; DEV u16 f2bf(float f) { return (u16)(pack2(f, f) & 0xffffu); }
; DEV float bf2f(u16 h) { return __uint_as_float(((unsigned)h) << 16); }
; DEV float sigmoid_f(float x) { return __builtin_amdgcn_rcpf(1.f + __expf(-x)); }
; DEV void phase_p15(const Params& p, int g) {
;     ...
;         for (int e = 0; e < 8; ++e) {
;           const int jj = j8 * 8 + e;
;           const int j = dir ? 63 - jj : jj;
;           const size_t tok = (size_t)cidx * 64 + j;
;           const float f = lb[cc] + (1.f - lb[cc]) * sigmoid_f(bf2f(xr[st][cc][e]));
;           G[cc] += __logf(f);
;           const float eg = __expf(G[cc]), ig = __expf(-G[cc]);
;           Qp[tok * 512 + c] = f2bf(bf2f(qr[st][cc][e]) * eg);
;           const u16 kk = f2bf((1.f - f) * ig);
;           Kp[tok * 512 + c] = kk;
;           kb[e] = kk;
;         }
	v_mul_f32_e32 v99, v99, v95
	v_lshlrev_b32_e32 v92, 16, v22
	v_and_b32_e32 v93, 0xffff0000, v22
	v_lshlrev_b32_e32 v94, 16, v23
	v_and_b32_e32 v95, 0xffff0000, v23
	v_mul_f32_e32 v92, v92, v100
	v_mul_f32_e32 v93, v93, v101
	v_mul_f32_e32 v94, v94, v102
	v_mul_f32_e32 v95, v95, v103
	v_cvt_pk_bf16_f32 v118, v118, v96
	v_cvt_pk_bf16_f32 v134, v134, v97
	v_cvt_pk_bf16_f32 v168, v168, v98
	v_cvt_pk_bf16_f32 v184, v184, v99
	v_cvt_pk_bf16_f32 v92, v92, v93
	v_cvt_pk_bf16_f32 v93, v94, v95
	v_cvt_pk_bf16_f32 v96, v96, v97
	v_cvt_pk_bf16_f32 v97, v98, v99
	global_store_dwordx2 v112, v[92:93], s[2:3]
	global_store_dwordx2 v114, v[96:97], s[2:3]
	s_add_u32 s2, s2, 0x400
	s_addc_u32 s3, s3, 0
	v_lshlrev_b32_e32 v92, 16, v24
	v_and_b32_e32 v93, 0xffff0000, v24
	v_lshlrev_b32_e32 v94, 16, v25
	v_and_b32_e32 v95, 0xffff0000, v25
	v_mul_f32_e32 v92, 0xbfb8aa3b, v92
	v_mul_f32_e32 v93, 0xbfb8aa3b, v93
	v_mul_f32_e32 v94, 0xbfb8aa3b, v94
	v_mul_f32_e32 v95, 0xbfb8aa3b, v95
	v_exp_f32_e32 v92, v92
	v_exp_f32_e32 v93, v93
	v_exp_f32_e32 v94, v94
	v_exp_f32_e32 v95, v95
	v_add_f32_e32 v92, 1.0, v92
	v_add_f32_e32 v93, 1.0, v93
	v_add_f32_e32 v94, 1.0, v94
	v_add_f32_e32 v95, 1.0, v95
	v_rcp_f32_e32 v92, v92
	v_rcp_f32_e32 v93, v93
	v_rcp_f32_e32 v94, v94
	v_rcp_f32_e32 v95, v95
	v_fma_f32 v96, v72, v92, v68
	v_fma_f32 v97, v73, v93, v69
	v_fma_f32 v98, v74, v94, v70
	v_fma_f32 v99, v75, v95, v71
	v_cmp_gt_f32_e64 s[22:23], s30, v96
	v_cmp_gt_f32_e64 s[24:25], s30, v97
	v_cmp_gt_f32_e64 s[26:27], s30, v98
	v_cmp_gt_f32_e64 s[28:29], s30, v99
	v_cndmask_b32_e64 v92, 0, 32, s[22:23]
	v_cndmask_b32_e64 v93, 0, 32, s[24:25]
	v_cndmask_b32_e64 v94, 0, 32, s[26:27]
	v_cndmask_b32_e64 v95, 0, 32, s[28:29]
	v_ldexp_f32 v92, v96, v92
	v_ldexp_f32 v93, v97, v93
	v_ldexp_f32 v94, v98, v94
	v_ldexp_f32 v95, v99, v95
	v_log_f32_e32 v92, v92
	v_log_f32_e32 v93, v93
	v_log_f32_e32 v94, v94
	v_log_f32_e32 v95, v95
	v_mul_f32_e32 v100, 0x3f317217, v92
	v_mul_f32_e32 v101, 0x3f317217, v93
	v_mul_f32_e32 v102, 0x3f317217, v94
	v_mul_f32_e32 v103, 0x3f317217, v95
	v_fma_f32 v100, v92, s31, -v100
	v_fma_f32 v101, v93, s31, -v101
	v_fma_f32 v102, v94, s31, -v102
	v_fma_f32 v103, v95, s31, -v103
	v_fmac_f32_e32 v100, 0x3377d1cf, v92
	v_fmac_f32_e32 v101, 0x3377d1cf, v93
	v_fmac_f32_e32 v102, 0x3377d1cf, v94
	v_fmac_f32_e32 v103, 0x3377d1cf, v95
	v_fmac_f32_e32 v100, 0x3f317217, v92
	v_fmac_f32_e32 v101, 0x3f317217, v93
	v_fmac_f32_e32 v102, 0x3f317217, v94
	v_fmac_f32_e32 v103, 0x3f317217, v95
	v_cmp_lt_f32_e64 vcc, |v92|, s34
	v_cndmask_b32_e32 v92, v92, v100, vcc
	v_cmp_lt_f32_e64 vcc, |v93|, s34
	v_cndmask_b32_e32 v93, v93, v101, vcc
	v_cmp_lt_f32_e64 vcc, |v94|, s34
	v_cndmask_b32_e32 v94, v94, v102, vcc
	v_cmp_lt_f32_e64 vcc, |v95|, s34
	v_cndmask_b32_e32 v95, v95, v103, vcc
	v_cndmask_b32_e64 v100, 0, v213, s[22:23]
	v_cndmask_b32_e64 v101, 0, v213, s[24:25]
	v_cndmask_b32_e64 v102, 0, v213, s[26:27]
	v_cndmask_b32_e64 v103, 0, v213, s[28:29]
	v_sub_f32_e32 v92, v92, v100
	v_sub_f32_e32 v93, v93, v101
	v_sub_f32_e32 v94, v94, v102
	v_sub_f32_e32 v95, v95, v103
	v_add_f32_e32 v64, v64, v92
	v_add_f32_e32 v65, v65, v93
	v_add_f32_e32 v66, v66, v94
	v_add_f32_e32 v67, v67, v95
	v_mul_f32_e32 v92, 0xbfb8aa3b, v64
	v_mul_f32_e32 v93, 0xbfb8aa3b, v65
	v_mul_f32_e32 v94, 0xbfb8aa3b, v66
	v_mul_f32_e32 v95, 0xbfb8aa3b, v67
	v_mul_f32_e32 v100, 0x3fb8aa3b, v64
	v_mul_f32_e32 v101, 0x3fb8aa3b, v65
	v_mul_f32_e32 v102, 0x3fb8aa3b, v66
	v_mul_f32_e32 v103, 0x3fb8aa3b, v67
	v_exp_f32_e32 v92, v92
	v_exp_f32_e32 v93, v93
	v_exp_f32_e32 v94, v94
	v_exp_f32_e32 v95, v95
	v_exp_f32_e32 v100, v100
	v_exp_f32_e32 v101, v101
	v_exp_f32_e32 v102, v102
	v_exp_f32_e32 v103, v103
	v_sub_f32_e32 v96, 1.0, v96
	v_sub_f32_e32 v97, 1.0, v97
	v_sub_f32_e32 v98, 1.0, v98
	v_sub_f32_e32 v99, 1.0, v99
	v_mul_f32_e32 v96, v96, v92
	v_mul_f32_e32 v97, v97, v93
	v_mul_f32_e32 v98, v98, v94
	v_mul_f32_e32 v99, v99, v95
	v_lshlrev_b32_e32 v92, 16, v26
	v_and_b32_e32 v93, 0xffff0000, v26
	v_lshlrev_b32_e32 v94, 16, v27
	v_and_b32_e32 v95, 0xffff0000, v27
	v_mul_f32_e32 v92, v92, v100
	v_mul_f32_e32 v93, v93, v101
	v_mul_f32_e32 v94, v94, v102
	v_mul_f32_e32 v95, v95, v103
	v_mov_b32_e32 v119, v96
	v_mov_b32_e32 v135, v97
	v_mov_b32_e32 v169, v98
	v_mov_b32_e32 v185, v99
	v_cvt_pk_bf16_f32 v92, v92, v93
	v_cvt_pk_bf16_f32 v93, v94, v95
	v_cvt_pk_bf16_f32 v96, v96, v97
	v_cvt_pk_bf16_f32 v97, v98, v99
	global_store_dwordx2 v112, v[92:93], s[2:3]
	global_store_dwordx2 v114, v[96:97], s[2:3]
	s_add_u32 s2, s2, 0x400
	s_addc_u32 s3, s3, 0
	v_lshlrev_b32_e32 v92, 16, v28
	v_and_b32_e32 v93, 0xffff0000, v28
	v_lshlrev_b32_e32 v94, 16, v29
	v_and_b32_e32 v95, 0xffff0000, v29
	v_mul_f32_e32 v92, 0xbfb8aa3b, v92
	v_mul_f32_e32 v93, 0xbfb8aa3b, v93
	v_mul_f32_e32 v94, 0xbfb8aa3b, v94
	v_mul_f32_e32 v95, 0xbfb8aa3b, v95
	v_exp_f32_e32 v92, v92
	v_exp_f32_e32 v93, v93
	v_exp_f32_e32 v94, v94
	v_exp_f32_e32 v95, v95
	v_add_f32_e32 v92, 1.0, v92
	v_add_f32_e32 v93, 1.0, v93
	v_add_f32_e32 v94, 1.0, v94
	v_add_f32_e32 v95, 1.0, v95
	v_rcp_f32_e32 v92, v92
	v_rcp_f32_e32 v93, v93
	v_rcp_f32_e32 v94, v94
	v_rcp_f32_e32 v95, v95
	v_fma_f32 v96, v72, v92, v68
	v_fma_f32 v97, v73, v93, v69
	v_fma_f32 v98, v74, v94, v70
	v_fma_f32 v99, v75, v95, v71
	v_cmp_gt_f32_e64 s[22:23], s30, v96
	v_cmp_gt_f32_e64 s[24:25], s30, v97
	v_cmp_gt_f32_e64 s[26:27], s30, v98
	v_cmp_gt_f32_e64 s[28:29], s30, v99
	v_cndmask_b32_e64 v92, 0, 32, s[22:23]
	v_cndmask_b32_e64 v93, 0, 32, s[24:25]
	v_cndmask_b32_e64 v94, 0, 32, s[26:27]
	v_cndmask_b32_e64 v95, 0, 32, s[28:29]
	v_ldexp_f32 v92, v96, v92
	v_ldexp_f32 v93, v97, v93
	v_ldexp_f32 v94, v98, v94
; DEV u16 f2bf(float f) { return (u16)(pack2(f, f) & 0xffffu); }
; DEV float bf2f(u16 h) { return __uint_as_float(((unsigned)h) << 16); }
; DEV float sigmoid_f(float x) { return __builtin_amdgcn_rcpf(1.f + __expf(-x)); }
; DEV void phase_p15(const Params& p, int g) {
;     ...
;     P15_LOAD(0, 0);
;     P15_LOAD(1, 1);
; #pragma unroll
;     for (int j8 = 0; j8 < 8; ++j8) {
;       const int st = j8 % 3;
;       if (j8 < 6) { P15_LOAD((j8 + 2) % 3, j8 + 2); }
;     ...
;         for (int e = 0; e < 8; ++e) {
;           const int jj = j8 * 8 + e;
;           const int j = dir ? 63 - jj : jj;
;           const size_t tok = (size_t)cidx * 64 + j;
;           const float f = lb[cc] + (1.f - lb[cc]) * sigmoid_f(bf2f(xr[st][cc][e]));
;           G[cc] += __logf(f);
;           const float eg = __expf(G[cc]), ig = __expf(-G[cc]);
;           Qp[tok * 512 + c] = f2bf(bf2f(qr[st][cc][e]) * eg);
;           const u16 kk = f2bf((1.f - f) * ig);
;           Kp[tok * 512 + c] = kk;
;           kb[e] = kk;
;         }
	v_ldexp_f32 v95, v99, v95
	v_log_f32_e32 v92, v92
	v_log_f32_e32 v93, v93
	v_log_f32_e32 v94, v94
	v_log_f32_e32 v95, v95
	v_mul_f32_e32 v100, 0x3f317217, v92
	v_mul_f32_e32 v101, 0x3f317217, v93
	v_mul_f32_e32 v102, 0x3f317217, v94
	v_mul_f32_e32 v103, 0x3f317217, v95
	v_fma_f32 v100, v92, s31, -v100
	v_fma_f32 v101, v93, s31, -v101
	v_fma_f32 v102, v94, s31, -v102
	v_fma_f32 v103, v95, s31, -v103
	v_fmac_f32_e32 v100, 0x3377d1cf, v92
	v_fmac_f32_e32 v101, 0x3377d1cf, v93
	v_fmac_f32_e32 v102, 0x3377d1cf, v94
	v_fmac_f32_e32 v103, 0x3377d1cf, v95
	v_fmac_f32_e32 v100, 0x3f317217, v92
	v_fmac_f32_e32 v101, 0x3f317217, v93
	v_fmac_f32_e32 v102, 0x3f317217, v94
	v_fmac_f32_e32 v103, 0x3f317217, v95
	v_cmp_lt_f32_e64 vcc, |v92|, s34
	v_cndmask_b32_e32 v92, v92, v100, vcc
	v_cmp_lt_f32_e64 vcc, |v93|, s34
	v_cndmask_b32_e32 v93, v93, v101, vcc
	v_cmp_lt_f32_e64 vcc, |v94|, s34
	v_cndmask_b32_e32 v94, v94, v102, vcc
	v_cmp_lt_f32_e64 vcc, |v95|, s34
	v_cndmask_b32_e32 v95, v95, v103, vcc
	v_cndmask_b32_e64 v100, 0, v213, s[22:23]
	v_cndmask_b32_e64 v101, 0, v213, s[24:25]
	v_cndmask_b32_e64 v102, 0, v213, s[26:27]
	v_cndmask_b32_e64 v103, 0, v213, s[28:29]
	v_sub_f32_e32 v92, v92, v100
	v_sub_f32_e32 v93, v93, v101
	v_sub_f32_e32 v94, v94, v102
	v_sub_f32_e32 v95, v95, v103
	v_add_f32_e32 v64, v64, v92
	v_add_f32_e32 v65, v65, v93
	v_add_f32_e32 v66, v66, v94
	v_add_f32_e32 v67, v67, v95
	v_mul_f32_e32 v92, 0xbfb8aa3b, v64
	v_mul_f32_e32 v93, 0xbfb8aa3b, v65
	v_mul_f32_e32 v94, 0xbfb8aa3b, v66
	v_mul_f32_e32 v95, 0xbfb8aa3b, v67
	v_mul_f32_e32 v100, 0x3fb8aa3b, v64
	v_mul_f32_e32 v101, 0x3fb8aa3b, v65
	v_mul_f32_e32 v102, 0x3fb8aa3b, v66
	v_mul_f32_e32 v103, 0x3fb8aa3b, v67
	v_exp_f32_e32 v92, v92
	v_exp_f32_e32 v93, v93
	v_exp_f32_e32 v94, v94
	v_exp_f32_e32 v95, v95
	v_exp_f32_e32 v100, v100
	v_exp_f32_e32 v101, v101
	v_exp_f32_e32 v102, v102
	v_exp_f32_e32 v103, v103
	v_sub_f32_e32 v96, 1.0, v96
	v_sub_f32_e32 v97, 1.0, v97
	v_sub_f32_e32 v98, 1.0, v98
	v_sub_f32_e32 v99, 1.0, v99
	v_mul_f32_e32 v96, v96, v92
	v_mul_f32_e32 v97, v97, v93
	v_mul_f32_e32 v98, v98, v94
	v_mul_f32_e32 v99, v99, v95
	v_lshlrev_b32_e32 v92, 16, v30
	v_and_b32_e32 v93, 0xffff0000, v30
	v_lshlrev_b32_e32 v94, 16, v31
	v_and_b32_e32 v95, 0xffff0000, v31
	v_mul_f32_e32 v92, v92, v100
	v_mul_f32_e32 v93, v93, v101
	v_mul_f32_e32 v94, v94, v102
	v_mul_f32_e32 v95, v95, v103
	v_cvt_pk_bf16_f32 v119, v119, v96
	v_cvt_pk_bf16_f32 v135, v135, v97
	v_cvt_pk_bf16_f32 v169, v169, v98
	v_cvt_pk_bf16_f32 v185, v185, v99
	v_cvt_pk_bf16_f32 v92, v92, v93
	v_cvt_pk_bf16_f32 v93, v94, v95
	v_cvt_pk_bf16_f32 v96, v96, v97
	v_cvt_pk_bf16_f32 v97, v98, v99
	global_store_dwordx2 v112, v[92:93], s[2:3]
	global_store_dwordx2 v114, v[96:97], s[2:3]
	s_add_u32 s2, s2, 0x400
	s_addc_u32 s3, s3, 0
	global_load_dwordx2 v[0:1], v113, s[0:1]
	global_load_dwordx2 v[2:3], v112, s[0:1]
	s_add_u32 s0, s0, 0x1400
	s_addc_u32 s1, s1, 0
	global_load_dwordx2 v[4:5], v113, s[0:1]
	global_load_dwordx2 v[6:7], v112, s[0:1]
	s_add_u32 s0, s0, 0x1400
	s_addc_u32 s1, s1, 0
	global_load_dwordx2 v[8:9], v113, s[0:1]
	global_load_dwordx2 v[10:11], v112, s[0:1]
	s_add_u32 s0, s0, 0x1400
	s_addc_u32 s1, s1, 0
	global_load_dwordx2 v[12:13], v113, s[0:1]
	global_load_dwordx2 v[14:15], v112, s[0:1]
	s_add_u32 s0, s0, 0x1400
	s_addc_u32 s1, s1, 0
	global_load_dwordx2 v[16:17], v113, s[0:1]
	global_load_dwordx2 v[18:19], v112, s[0:1]
	s_add_u32 s0, s0, 0x1400
	s_addc_u32 s1, s1, 0
	global_load_dwordx2 v[20:21], v113, s[0:1]
	global_load_dwordx2 v[22:23], v112, s[0:1]
	s_add_u32 s0, s0, 0x1400
	s_addc_u32 s1, s1, 0
	global_load_dwordx2 v[24:25], v113, s[0:1]
	global_load_dwordx2 v[26:27], v112, s[0:1]
	s_add_u32 s0, s0, 0x1400
	s_addc_u32 s1, s1, 0
	global_load_dwordx2 v[28:29], v113, s[0:1]
	global_load_dwordx2 v[30:31], v112, s[0:1]
	s_add_u32 s0, s0, 0x1400
	s_addc_u32 s1, s1, 0
	s_waitcnt vmcnt(32)
	v_lshlrev_b32_e32 v92, 16, v32
	v_and_b32_e32 v93, 0xffff0000, v32
	v_lshlrev_b32_e32 v94, 16, v33
	v_and_b32_e32 v95, 0xffff0000, v33
	v_mul_f32_e32 v92, 0xbfb8aa3b, v92
	v_mul_f32_e32 v93, 0xbfb8aa3b, v93
	v_mul_f32_e32 v94, 0xbfb8aa3b, v94
	v_mul_f32_e32 v95, 0xbfb8aa3b, v95
	v_exp_f32_e32 v92, v92
	v_exp_f32_e32 v93, v93
	v_exp_f32_e32 v94, v94
	v_exp_f32_e32 v95, v95
	v_add_f32_e32 v92, 1.0, v92
	v_add_f32_e32 v93, 1.0, v93
	v_add_f32_e32 v94, 1.0, v94
	v_add_f32_e32 v95, 1.0, v95
	v_rcp_f32_e32 v92, v92
	v_rcp_f32_e32 v93, v93
	v_rcp_f32_e32 v94, v94
	v_rcp_f32_e32 v95, v95
	v_fma_f32 v96, v72, v92, v68
	v_fma_f32 v97, v73, v93, v69
	v_fma_f32 v98, v74, v94, v70
	v_fma_f32 v99, v75, v95, v71
	v_cmp_gt_f32_e64 s[22:23], s30, v96
	v_cmp_gt_f32_e64 s[24:25], s30, v97
	v_cmp_gt_f32_e64 s[26:27], s30, v98
	v_cmp_gt_f32_e64 s[28:29], s30, v99
	v_cndmask_b32_e64 v92, 0, 32, s[22:23]
	v_cndmask_b32_e64 v93, 0, 32, s[24:25]
	v_cndmask_b32_e64 v94, 0, 32, s[26:27]
	v_cndmask_b32_e64 v95, 0, 32, s[28:29]
	v_ldexp_f32 v92, v96, v92
	v_ldexp_f32 v93, v97, v93
	v_ldexp_f32 v94, v98, v94
	v_ldexp_f32 v95, v99, v95
	v_log_f32_e32 v92, v92
	v_log_f32_e32 v93, v93
	v_log_f32_e32 v94, v94
	v_log_f32_e32 v95, v95
	v_mul_f32_e32 v100, 0x3f317217, v92
	v_mul_f32_e32 v101, 0x3f317217, v93
	v_mul_f32_e32 v102, 0x3f317217, v94
	v_mul_f32_e32 v103, 0x3f317217, v95
	v_fma_f32 v100, v92, s31, -v100
	v_fma_f32 v101, v93, s31, -v101
	v_fma_f32 v102, v94, s31, -v102
	v_fma_f32 v103, v95, s31, -v103
	v_fmac_f32_e32 v100, 0x3377d1cf, v92
	v_fmac_f32_e32 v101, 0x3377d1cf, v93
	v_fmac_f32_e32 v102, 0x3377d1cf, v94
	v_fmac_f32_e32 v103, 0x3377d1cf, v95
	v_fmac_f32_e32 v100, 0x3f317217, v92
	v_fmac_f32_e32 v101, 0x3f317217, v93
; DEV u16 f2bf(float f) { return (u16)(pack2(f, f) & 0xffffu); }
; DEV float bf2f(u16 h) { return __uint_as_float(((unsigned)h) << 16); }
; DEV float sigmoid_f(float x) { return __builtin_amdgcn_rcpf(1.f + __expf(-x)); }
; DEV void phase_p15(const Params& p, int g) {
;     ...
;         for (int e = 0; e < 8; ++e) {
;           const int jj = j8 * 8 + e;
;           const int j = dir ? 63 - jj : jj;
;           const size_t tok = (size_t)cidx * 64 + j;
;           const float f = lb[cc] + (1.f - lb[cc]) * sigmoid_f(bf2f(xr[st][cc][e]));
;           G[cc] += __logf(f);
;           const float eg = __expf(G[cc]), ig = __expf(-G[cc]);
;           Qp[tok * 512 + c] = f2bf(bf2f(qr[st][cc][e]) * eg);
;           const u16 kk = f2bf((1.f - f) * ig);
;           Kp[tok * 512 + c] = kk;
;           kb[e] = kk;
;         }
	v_fmac_f32_e32 v102, 0x3f317217, v94
	v_fmac_f32_e32 v103, 0x3f317217, v95
	v_cmp_lt_f32_e64 vcc, |v92|, s34
	v_cndmask_b32_e32 v92, v92, v100, vcc
	v_cmp_lt_f32_e64 vcc, |v93|, s34
	v_cndmask_b32_e32 v93, v93, v101, vcc
	v_cmp_lt_f32_e64 vcc, |v94|, s34
	v_cndmask_b32_e32 v94, v94, v102, vcc
	v_cmp_lt_f32_e64 vcc, |v95|, s34
	v_cndmask_b32_e32 v95, v95, v103, vcc
	v_cndmask_b32_e64 v100, 0, v213, s[22:23]
	v_cndmask_b32_e64 v101, 0, v213, s[24:25]
	v_cndmask_b32_e64 v102, 0, v213, s[26:27]
	v_cndmask_b32_e64 v103, 0, v213, s[28:29]
	v_sub_f32_e32 v92, v92, v100
	v_sub_f32_e32 v93, v93, v101
	v_sub_f32_e32 v94, v94, v102
	v_sub_f32_e32 v95, v95, v103
	v_add_f32_e32 v64, v64, v92
	v_add_f32_e32 v65, v65, v93
	v_add_f32_e32 v66, v66, v94
	v_add_f32_e32 v67, v67, v95
	v_mul_f32_e32 v92, 0xbfb8aa3b, v64
	v_mul_f32_e32 v93, 0xbfb8aa3b, v65
	v_mul_f32_e32 v94, 0xbfb8aa3b, v66
	v_mul_f32_e32 v95, 0xbfb8aa3b, v67
	v_mul_f32_e32 v100, 0x3fb8aa3b, v64
	v_mul_f32_e32 v101, 0x3fb8aa3b, v65
	v_mul_f32_e32 v102, 0x3fb8aa3b, v66
	v_mul_f32_e32 v103, 0x3fb8aa3b, v67
	v_exp_f32_e32 v92, v92
	v_exp_f32_e32 v93, v93
	v_exp_f32_e32 v94, v94
	v_exp_f32_e32 v95, v95
	v_exp_f32_e32 v100, v100
	v_exp_f32_e32 v101, v101
	v_exp_f32_e32 v102, v102
	v_exp_f32_e32 v103, v103
	v_sub_f32_e32 v96, 1.0, v96
	v_sub_f32_e32 v97, 1.0, v97
	v_sub_f32_e32 v98, 1.0, v98
	v_sub_f32_e32 v99, 1.0, v99
	v_mul_f32_e32 v96, v96, v92
	v_mul_f32_e32 v97, v97, v93
	v_mul_f32_e32 v98, v98, v94
	v_mul_f32_e32 v99, v99, v95
	v_lshlrev_b32_e32 v92, 16, v34
	v_and_b32_e32 v93, 0xffff0000, v34
	v_lshlrev_b32_e32 v94, 16, v35
	v_and_b32_e32 v95, 0xffff0000, v35
	v_mul_f32_e32 v92, v92, v100
	v_mul_f32_e32 v93, v93, v101
	v_mul_f32_e32 v94, v94, v102
	v_mul_f32_e32 v95, v95, v103
	v_mov_b32_e32 v120, v96
	v_mov_b32_e32 v136, v97
	v_mov_b32_e32 v170, v98
	v_mov_b32_e32 v186, v99
	v_cvt_pk_bf16_f32 v92, v92, v93
	v_cvt_pk_bf16_f32 v93, v94, v95
	v_cvt_pk_bf16_f32 v96, v96, v97
	v_cvt_pk_bf16_f32 v97, v98, v99
	global_store_dwordx2 v112, v[92:93], s[2:3]
	global_store_dwordx2 v114, v[96:97], s[2:3]
	s_add_u32 s2, s2, 0x400
	s_addc_u32 s3, s3, 0
	v_lshlrev_b32_e32 v92, 16, v36
	v_and_b32_e32 v93, 0xffff0000, v36
	v_lshlrev_b32_e32 v94, 16, v37
	v_and_b32_e32 v95, 0xffff0000, v37
	v_mul_f32_e32 v92, 0xbfb8aa3b, v92
	v_mul_f32_e32 v93, 0xbfb8aa3b, v93
	v_mul_f32_e32 v94, 0xbfb8aa3b, v94
	v_mul_f32_e32 v95, 0xbfb8aa3b, v95
	v_exp_f32_e32 v92, v92
	v_exp_f32_e32 v93, v93
	v_exp_f32_e32 v94, v94
	v_exp_f32_e32 v95, v95
	v_add_f32_e32 v92, 1.0, v92
	v_add_f32_e32 v93, 1.0, v93
	v_add_f32_e32 v94, 1.0, v94
	v_add_f32_e32 v95, 1.0, v95
	v_rcp_f32_e32 v92, v92
	v_rcp_f32_e32 v93, v93
	v_rcp_f32_e32 v94, v94
	v_rcp_f32_e32 v95, v95
	v_fma_f32 v96, v72, v92, v68
	v_fma_f32 v97, v73, v93, v69
	v_fma_f32 v98, v74, v94, v70
	v_fma_f32 v99, v75, v95, v71
	v_cmp_gt_f32_e64 s[22:23], s30, v96
	v_cmp_gt_f32_e64 s[24:25], s30, v97
	v_cmp_gt_f32_e64 s[26:27], s30, v98
	v_cmp_gt_f32_e64 s[28:29], s30, v99
	v_cndmask_b32_e64 v92, 0, 32, s[22:23]
	v_cndmask_b32_e64 v93, 0, 32, s[24:25]
	v_cndmask_b32_e64 v94, 0, 32, s[26:27]
	v_cndmask_b32_e64 v95, 0, 32, s[28:29]
	v_ldexp_f32 v92, v96, v92
	v_ldexp_f32 v93, v97, v93
	v_ldexp_f32 v94, v98, v94
	v_ldexp_f32 v95, v99, v95
	v_log_f32_e32 v92, v92
	v_log_f32_e32 v93, v93
	v_log_f32_e32 v94, v94
	v_log_f32_e32 v95, v95
	v_mul_f32_e32 v100, 0x3f317217, v92
	v_mul_f32_e32 v101, 0x3f317217, v93
	v_mul_f32_e32 v102, 0x3f317217, v94
	v_mul_f32_e32 v103, 0x3f317217, v95
	v_fma_f32 v100, v92, s31, -v100
	v_fma_f32 v101, v93, s31, -v101
	v_fma_f32 v102, v94, s31, -v102
	v_fma_f32 v103, v95, s31, -v103
	v_fmac_f32_e32 v100, 0x3377d1cf, v92
	v_fmac_f32_e32 v101, 0x3377d1cf, v93
	v_fmac_f32_e32 v102, 0x3377d1cf, v94
	v_fmac_f32_e32 v103, 0x3377d1cf, v95
	v_fmac_f32_e32 v100, 0x3f317217, v92
	v_fmac_f32_e32 v101, 0x3f317217, v93
	v_fmac_f32_e32 v102, 0x3f317217, v94
	v_fmac_f32_e32 v103, 0x3f317217, v95
	v_cmp_lt_f32_e64 vcc, |v92|, s34
	v_cndmask_b32_e32 v92, v92, v100, vcc
	v_cmp_lt_f32_e64 vcc, |v93|, s34
	v_cndmask_b32_e32 v93, v93, v101, vcc
	v_cmp_lt_f32_e64 vcc, |v94|, s34
	v_cndmask_b32_e32 v94, v94, v102, vcc
	v_cmp_lt_f32_e64 vcc, |v95|, s34
	v_cndmask_b32_e32 v95, v95, v103, vcc
	v_cndmask_b32_e64 v100, 0, v213, s[22:23]
	v_cndmask_b32_e64 v101, 0, v213, s[24:25]
	v_cndmask_b32_e64 v102, 0, v213, s[26:27]
	v_cndmask_b32_e64 v103, 0, v213, s[28:29]
	v_sub_f32_e32 v92, v92, v100
	v_sub_f32_e32 v93, v93, v101
	v_sub_f32_e32 v94, v94, v102
	v_sub_f32_e32 v95, v95, v103
	v_add_f32_e32 v64, v64, v92
	v_add_f32_e32 v65, v65, v93
	v_add_f32_e32 v66, v66, v94
	v_add_f32_e32 v67, v67, v95
	v_mul_f32_e32 v92, 0xbfb8aa3b, v64
	v_mul_f32_e32 v93, 0xbfb8aa3b, v65
	v_mul_f32_e32 v94, 0xbfb8aa3b, v66
	v_mul_f32_e32 v95, 0xbfb8aa3b, v67
	v_mul_f32_e32 v100, 0x3fb8aa3b, v64
	v_mul_f32_e32 v101, 0x3fb8aa3b, v65
	v_mul_f32_e32 v102, 0x3fb8aa3b, v66
	v_mul_f32_e32 v103, 0x3fb8aa3b, v67
	v_exp_f32_e32 v92, v92
	v_exp_f32_e32 v93, v93
	v_exp_f32_e32 v94, v94
	v_exp_f32_e32 v95, v95
	v_exp_f32_e32 v100, v100
	v_exp_f32_e32 v101, v101
	v_exp_f32_e32 v102, v102
	v_exp_f32_e32 v103, v103
	v_sub_f32_e32 v96, 1.0, v96
	v_sub_f32_e32 v97, 1.0, v97
	v_sub_f32_e32 v98, 1.0, v98
	v_sub_f32_e32 v99, 1.0, v99
	v_mul_f32_e32 v96, v96, v92
	v_mul_f32_e32 v97, v97, v93
	v_mul_f32_e32 v98, v98, v94
	v_mul_f32_e32 v99, v99, v95
	v_lshlrev_b32_e32 v92, 16, v38
	v_and_b32_e32 v93, 0xffff0000, v38
	v_lshlrev_b32_e32 v94, 16, v39
	v_and_b32_e32 v95, 0xffff0000, v39
	v_mul_f32_e32 v92, v92, v100
	v_mul_f32_e32 v93, v93, v101
	v_mul_f32_e32 v94, v94, v102
	v_mul_f32_e32 v95, v95, v103
	v_cvt_pk_bf16_f32 v120, v120, v96
; DEV u16 f2bf(float f) { return (u16)(pack2(f, f) & 0xffffu); }
; DEV float bf2f(u16 h) { return __uint_as_float(((unsigned)h) << 16); }
; DEV float sigmoid_f(float x) { return __builtin_amdgcn_rcpf(1.f + __expf(-x)); }
; DEV void phase_p15(const Params& p, int g) {
;     ...
;         for (int e = 0; e < 8; ++e) {
;           const int jj = j8 * 8 + e;
;           const int j = dir ? 63 - jj : jj;
;           const size_t tok = (size_t)cidx * 64 + j;
;           const float f = lb[cc] + (1.f - lb[cc]) * sigmoid_f(bf2f(xr[st][cc][e]));
;           G[cc] += __logf(f);
;           const float eg = __expf(G[cc]), ig = __expf(-G[cc]);
;           Qp[tok * 512 + c] = f2bf(bf2f(qr[st][cc][e]) * eg);
;           const u16 kk = f2bf((1.f - f) * ig);
;           Kp[tok * 512 + c] = kk;
;           kb[e] = kk;
;         }
	v_cvt_pk_bf16_f32 v136, v136, v97
	v_cvt_pk_bf16_f32 v170, v170, v98
	v_cvt_pk_bf16_f32 v186, v186, v99
	v_cvt_pk_bf16_f32 v92, v92, v93
	v_cvt_pk_bf16_f32 v93, v94, v95
	v_cvt_pk_bf16_f32 v96, v96, v97
	v_cvt_pk_bf16_f32 v97, v98, v99
	global_store_dwordx2 v112, v[92:93], s[2:3]
	global_store_dwordx2 v114, v[96:97], s[2:3]
	s_add_u32 s2, s2, 0x400
	s_addc_u32 s3, s3, 0
	v_lshlrev_b32_e32 v92, 16, v40
	v_and_b32_e32 v93, 0xffff0000, v40
	v_lshlrev_b32_e32 v94, 16, v41
	v_and_b32_e32 v95, 0xffff0000, v41
	v_mul_f32_e32 v92, 0xbfb8aa3b, v92
	v_mul_f32_e32 v93, 0xbfb8aa3b, v93
	v_mul_f32_e32 v94, 0xbfb8aa3b, v94
	v_mul_f32_e32 v95, 0xbfb8aa3b, v95
	v_exp_f32_e32 v92, v92
	v_exp_f32_e32 v93, v93
	v_exp_f32_e32 v94, v94
	v_exp_f32_e32 v95, v95
	v_add_f32_e32 v92, 1.0, v92
	v_add_f32_e32 v93, 1.0, v93
	v_add_f32_e32 v94, 1.0, v94
	v_add_f32_e32 v95, 1.0, v95
	v_rcp_f32_e32 v92, v92
	v_rcp_f32_e32 v93, v93
	v_rcp_f32_e32 v94, v94
	v_rcp_f32_e32 v95, v95
	v_fma_f32 v96, v72, v92, v68
	v_fma_f32 v97, v73, v93, v69
	v_fma_f32 v98, v74, v94, v70
	v_fma_f32 v99, v75, v95, v71
	v_cmp_gt_f32_e64 s[22:23], s30, v96
	v_cmp_gt_f32_e64 s[24:25], s30, v97
	v_cmp_gt_f32_e64 s[26:27], s30, v98
	v_cmp_gt_f32_e64 s[28:29], s30, v99
	v_cndmask_b32_e64 v92, 0, 32, s[22:23]
	v_cndmask_b32_e64 v93, 0, 32, s[24:25]
	v_cndmask_b32_e64 v94, 0, 32, s[26:27]
	v_cndmask_b32_e64 v95, 0, 32, s[28:29]
	v_ldexp_f32 v92, v96, v92
	v_ldexp_f32 v93, v97, v93
	v_ldexp_f32 v94, v98, v94
	v_ldexp_f32 v95, v99, v95
	v_log_f32_e32 v92, v92
	v_log_f32_e32 v93, v93
	v_log_f32_e32 v94, v94
	v_log_f32_e32 v95, v95
	v_mul_f32_e32 v100, 0x3f317217, v92
	v_mul_f32_e32 v101, 0x3f317217, v93
	v_mul_f32_e32 v102, 0x3f317217, v94
	v_mul_f32_e32 v103, 0x3f317217, v95
	v_fma_f32 v100, v92, s31, -v100
	v_fma_f32 v101, v93, s31, -v101
	v_fma_f32 v102, v94, s31, -v102
	v_fma_f32 v103, v95, s31, -v103
	v_fmac_f32_e32 v100, 0x3377d1cf, v92
	v_fmac_f32_e32 v101, 0x3377d1cf, v93
	v_fmac_f32_e32 v102, 0x3377d1cf, v94
	v_fmac_f32_e32 v103, 0x3377d1cf, v95
	v_fmac_f32_e32 v100, 0x3f317217, v92
	v_fmac_f32_e32 v101, 0x3f317217, v93
	v_fmac_f32_e32 v102, 0x3f317217, v94
	v_fmac_f32_e32 v103, 0x3f317217, v95
	v_cmp_lt_f32_e64 vcc, |v92|, s34
	v_cndmask_b32_e32 v92, v92, v100, vcc
	v_cmp_lt_f32_e64 vcc, |v93|, s34
	v_cndmask_b32_e32 v93, v93, v101, vcc
	v_cmp_lt_f32_e64 vcc, |v94|, s34
	v_cndmask_b32_e32 v94, v94, v102, vcc
	v_cmp_lt_f32_e64 vcc, |v95|, s34
	v_cndmask_b32_e32 v95, v95, v103, vcc
	v_cndmask_b32_e64 v100, 0, v213, s[22:23]
	v_cndmask_b32_e64 v101, 0, v213, s[24:25]
	v_cndmask_b32_e64 v102, 0, v213, s[26:27]
	v_cndmask_b32_e64 v103, 0, v213, s[28:29]
	v_sub_f32_e32 v92, v92, v100
	v_sub_f32_e32 v93, v93, v101
	v_sub_f32_e32 v94, v94, v102
	v_sub_f32_e32 v95, v95, v103
	v_add_f32_e32 v64, v64, v92
	v_add_f32_e32 v65, v65, v93
	v_add_f32_e32 v66, v66, v94
	v_add_f32_e32 v67, v67, v95
	v_mul_f32_e32 v92, 0xbfb8aa3b, v64
	v_mul_f32_e32 v93, 0xbfb8aa3b, v65
	v_mul_f32_e32 v94, 0xbfb8aa3b, v66
	v_mul_f32_e32 v95, 0xbfb8aa3b, v67
	v_mul_f32_e32 v100, 0x3fb8aa3b, v64
	v_mul_f32_e32 v101, 0x3fb8aa3b, v65
	v_mul_f32_e32 v102, 0x3fb8aa3b, v66
	v_mul_f32_e32 v103, 0x3fb8aa3b, v67
	v_exp_f32_e32 v92, v92
	v_exp_f32_e32 v93, v93
	v_exp_f32_e32 v94, v94
	v_exp_f32_e32 v95, v95
	v_exp_f32_e32 v100, v100
	v_exp_f32_e32 v101, v101
	v_exp_f32_e32 v102, v102
	v_exp_f32_e32 v103, v103
	v_sub_f32_e32 v96, 1.0, v96
	v_sub_f32_e32 v97, 1.0, v97
	v_sub_f32_e32 v98, 1.0, v98
	v_sub_f32_e32 v99, 1.0, v99
	v_mul_f32_e32 v96, v96, v92
	v_mul_f32_e32 v97, v97, v93
	v_mul_f32_e32 v98, v98, v94
	v_mul_f32_e32 v99, v99, v95
	v_lshlrev_b32_e32 v92, 16, v42
	v_and_b32_e32 v93, 0xffff0000, v42
	v_lshlrev_b32_e32 v94, 16, v43
	v_and_b32_e32 v95, 0xffff0000, v43
	v_mul_f32_e32 v92, v92, v100
	v_mul_f32_e32 v93, v93, v101
	v_mul_f32_e32 v94, v94, v102
	v_mul_f32_e32 v95, v95, v103
	v_mov_b32_e32 v121, v96
	v_mov_b32_e32 v137, v97
	v_mov_b32_e32 v171, v98
	v_mov_b32_e32 v187, v99
	v_cvt_pk_bf16_f32 v92, v92, v93
	v_cvt_pk_bf16_f32 v93, v94, v95
	v_cvt_pk_bf16_f32 v96, v96, v97
	v_cvt_pk_bf16_f32 v97, v98, v99
	global_store_dwordx2 v112, v[92:93], s[2:3]
	global_store_dwordx2 v114, v[96:97], s[2:3]
	s_add_u32 s2, s2, 0x400
	s_addc_u32 s3, s3, 0
	v_lshlrev_b32_e32 v92, 16, v44
	v_and_b32_e32 v93, 0xffff0000, v44
	v_lshlrev_b32_e32 v94, 16, v45
	v_and_b32_e32 v95, 0xffff0000, v45
	v_mul_f32_e32 v92, 0xbfb8aa3b, v92
	v_mul_f32_e32 v93, 0xbfb8aa3b, v93
	v_mul_f32_e32 v94, 0xbfb8aa3b, v94
	v_mul_f32_e32 v95, 0xbfb8aa3b, v95
	v_exp_f32_e32 v92, v92
	v_exp_f32_e32 v93, v93
	v_exp_f32_e32 v94, v94
	v_exp_f32_e32 v95, v95
	v_add_f32_e32 v92, 1.0, v92
	v_add_f32_e32 v93, 1.0, v93
	v_add_f32_e32 v94, 1.0, v94
	v_add_f32_e32 v95, 1.0, v95
	v_rcp_f32_e32 v92, v92
	v_rcp_f32_e32 v93, v93
	v_rcp_f32_e32 v94, v94
	v_rcp_f32_e32 v95, v95
	v_fma_f32 v96, v72, v92, v68
	v_fma_f32 v97, v73, v93, v69
	v_fma_f32 v98, v74, v94, v70
	v_fma_f32 v99, v75, v95, v71
	v_cmp_gt_f32_e64 s[22:23], s30, v96
	v_cmp_gt_f32_e64 s[24:25], s30, v97
	v_cmp_gt_f32_e64 s[26:27], s30, v98
	v_cmp_gt_f32_e64 s[28:29], s30, v99
	v_cndmask_b32_e64 v92, 0, 32, s[22:23]
	v_cndmask_b32_e64 v93, 0, 32, s[24:25]
	v_cndmask_b32_e64 v94, 0, 32, s[26:27]
	v_cndmask_b32_e64 v95, 0, 32, s[28:29]
	v_ldexp_f32 v92, v96, v92
	v_ldexp_f32 v93, v97, v93
	v_ldexp_f32 v94, v98, v94
	v_ldexp_f32 v95, v99, v95
	v_log_f32_e32 v92, v92
	v_log_f32_e32 v93, v93
	v_log_f32_e32 v94, v94
	v_log_f32_e32 v95, v95
	v_mul_f32_e32 v100, 0x3f317217, v92
	v_mul_f32_e32 v101, 0x3f317217, v93
	v_mul_f32_e32 v102, 0x3f317217, v94
	v_mul_f32_e32 v103, 0x3f317217, v95
	v_fma_f32 v100, v92, s31, -v100
; DEV u16 f2bf(float f) { return (u16)(pack2(f, f) & 0xffffu); }
; DEV float bf2f(u16 h) { return __uint_as_float(((unsigned)h) << 16); }
; DEV float sigmoid_f(float x) { return __builtin_amdgcn_rcpf(1.f + __expf(-x)); }
; DEV void phase_p15(const Params& p, int g) {
;     ...
;         for (int e = 0; e < 8; ++e) {
;           const int jj = j8 * 8 + e;
;           const int j = dir ? 63 - jj : jj;
;           const size_t tok = (size_t)cidx * 64 + j;
;           const float f = lb[cc] + (1.f - lb[cc]) * sigmoid_f(bf2f(xr[st][cc][e]));
;           G[cc] += __logf(f);
;           const float eg = __expf(G[cc]), ig = __expf(-G[cc]);
;           Qp[tok * 512 + c] = f2bf(bf2f(qr[st][cc][e]) * eg);
;           const u16 kk = f2bf((1.f - f) * ig);
;           Kp[tok * 512 + c] = kk;
;           kb[e] = kk;
;         }
	v_fma_f32 v101, v93, s31, -v101
	v_fma_f32 v102, v94, s31, -v102
	v_fma_f32 v103, v95, s31, -v103
	v_fmac_f32_e32 v100, 0x3377d1cf, v92
	v_fmac_f32_e32 v101, 0x3377d1cf, v93
	v_fmac_f32_e32 v102, 0x3377d1cf, v94
	v_fmac_f32_e32 v103, 0x3377d1cf, v95
	v_fmac_f32_e32 v100, 0x3f317217, v92
	v_fmac_f32_e32 v101, 0x3f317217, v93
	v_fmac_f32_e32 v102, 0x3f317217, v94
	v_fmac_f32_e32 v103, 0x3f317217, v95
	v_cmp_lt_f32_e64 vcc, |v92|, s34
	v_cndmask_b32_e32 v92, v92, v100, vcc
	v_cmp_lt_f32_e64 vcc, |v93|, s34
	v_cndmask_b32_e32 v93, v93, v101, vcc
	v_cmp_lt_f32_e64 vcc, |v94|, s34
	v_cndmask_b32_e32 v94, v94, v102, vcc
	v_cmp_lt_f32_e64 vcc, |v95|, s34
	v_cndmask_b32_e32 v95, v95, v103, vcc
	v_cndmask_b32_e64 v100, 0, v213, s[22:23]
	v_cndmask_b32_e64 v101, 0, v213, s[24:25]
	v_cndmask_b32_e64 v102, 0, v213, s[26:27]
	v_cndmask_b32_e64 v103, 0, v213, s[28:29]
	v_sub_f32_e32 v92, v92, v100
	v_sub_f32_e32 v93, v93, v101
	v_sub_f32_e32 v94, v94, v102
	v_sub_f32_e32 v95, v95, v103
	v_add_f32_e32 v64, v64, v92
	v_add_f32_e32 v65, v65, v93
	v_add_f32_e32 v66, v66, v94
	v_add_f32_e32 v67, v67, v95
	v_mul_f32_e32 v92, 0xbfb8aa3b, v64
	v_mul_f32_e32 v93, 0xbfb8aa3b, v65
	v_mul_f32_e32 v94, 0xbfb8aa3b, v66
	v_mul_f32_e32 v95, 0xbfb8aa3b, v67
	v_mul_f32_e32 v100, 0x3fb8aa3b, v64
	v_mul_f32_e32 v101, 0x3fb8aa3b, v65
	v_mul_f32_e32 v102, 0x3fb8aa3b, v66
	v_mul_f32_e32 v103, 0x3fb8aa3b, v67
	v_exp_f32_e32 v92, v92
	v_exp_f32_e32 v93, v93
	v_exp_f32_e32 v94, v94
	v_exp_f32_e32 v95, v95
	v_exp_f32_e32 v100, v100
	v_exp_f32_e32 v101, v101
	v_exp_f32_e32 v102, v102
	v_exp_f32_e32 v103, v103
	v_sub_f32_e32 v96, 1.0, v96
	v_sub_f32_e32 v97, 1.0, v97
	v_sub_f32_e32 v98, 1.0, v98
	v_sub_f32_e32 v99, 1.0, v99
	v_mul_f32_e32 v96, v96, v92
	v_mul_f32_e32 v97, v97, v93
	v_mul_f32_e32 v98, v98, v94
	v_mul_f32_e32 v99, v99, v95
	v_lshlrev_b32_e32 v92, 16, v46
	v_and_b32_e32 v93, 0xffff0000, v46
	v_lshlrev_b32_e32 v94, 16, v47
	v_and_b32_e32 v95, 0xffff0000, v47
	v_mul_f32_e32 v92, v92, v100
	v_mul_f32_e32 v93, v93, v101
	v_mul_f32_e32 v94, v94, v102
	v_mul_f32_e32 v95, v95, v103
	v_cvt_pk_bf16_f32 v121, v121, v96
	v_cvt_pk_bf16_f32 v137, v137, v97
	v_cvt_pk_bf16_f32 v171, v171, v98
	v_cvt_pk_bf16_f32 v187, v187, v99
	v_cvt_pk_bf16_f32 v92, v92, v93
	v_cvt_pk_bf16_f32 v93, v94, v95
	v_cvt_pk_bf16_f32 v96, v96, v97
	v_cvt_pk_bf16_f32 v97, v98, v99
	global_store_dwordx2 v112, v[92:93], s[2:3]
	global_store_dwordx2 v114, v[96:97], s[2:3]
	s_add_u32 s2, s2, 0x400
	s_addc_u32 s3, s3, 0
	v_lshlrev_b32_e32 v92, 16, v48
	v_and_b32_e32 v93, 0xffff0000, v48
	v_lshlrev_b32_e32 v94, 16, v49
	v_and_b32_e32 v95, 0xffff0000, v49
	v_mul_f32_e32 v92, 0xbfb8aa3b, v92
	v_mul_f32_e32 v93, 0xbfb8aa3b, v93
	v_mul_f32_e32 v94, 0xbfb8aa3b, v94
	v_mul_f32_e32 v95, 0xbfb8aa3b, v95
	v_exp_f32_e32 v92, v92
	v_exp_f32_e32 v93, v93
	v_exp_f32_e32 v94, v94
	v_exp_f32_e32 v95, v95
	v_add_f32_e32 v92, 1.0, v92
	v_add_f32_e32 v93, 1.0, v93
	v_add_f32_e32 v94, 1.0, v94
	v_add_f32_e32 v95, 1.0, v95
	v_rcp_f32_e32 v92, v92
	v_rcp_f32_e32 v93, v93
	v_rcp_f32_e32 v94, v94
	v_rcp_f32_e32 v95, v95
	v_fma_f32 v96, v72, v92, v68
	v_fma_f32 v97, v73, v93, v69
	v_fma_f32 v98, v74, v94, v70
	v_fma_f32 v99, v75, v95, v71
	v_cmp_gt_f32_e64 s[22:23], s30, v96
	v_cmp_gt_f32_e64 s[24:25], s30, v97
	v_cmp_gt_f32_e64 s[26:27], s30, v98
	v_cmp_gt_f32_e64 s[28:29], s30, v99
	v_cndmask_b32_e64 v92, 0, 32, s[22:23]
	v_cndmask_b32_e64 v93, 0, 32, s[24:25]
	v_cndmask_b32_e64 v94, 0, 32, s[26:27]
	v_cndmask_b32_e64 v95, 0, 32, s[28:29]
	v_ldexp_f32 v92, v96, v92
	v_ldexp_f32 v93, v97, v93
	v_ldexp_f32 v94, v98, v94
	v_ldexp_f32 v95, v99, v95
	v_log_f32_e32 v92, v92
	v_log_f32_e32 v93, v93
	v_log_f32_e32 v94, v94
	v_log_f32_e32 v95, v95
	v_mul_f32_e32 v100, 0x3f317217, v92
	v_mul_f32_e32 v101, 0x3f317217, v93
	v_mul_f32_e32 v102, 0x3f317217, v94
	v_mul_f32_e32 v103, 0x3f317217, v95
	v_fma_f32 v100, v92, s31, -v100
	v_fma_f32 v101, v93, s31, -v101
	v_fma_f32 v102, v94, s31, -v102
	v_fma_f32 v103, v95, s31, -v103
	v_fmac_f32_e32 v100, 0x3377d1cf, v92
	v_fmac_f32_e32 v101, 0x3377d1cf, v93
	v_fmac_f32_e32 v102, 0x3377d1cf, v94
	v_fmac_f32_e32 v103, 0x3377d1cf, v95
	v_fmac_f32_e32 v100, 0x3f317217, v92
	v_fmac_f32_e32 v101, 0x3f317217, v93
	v_fmac_f32_e32 v102, 0x3f317217, v94
	v_fmac_f32_e32 v103, 0x3f317217, v95
	v_cmp_lt_f32_e64 vcc, |v92|, s34
	v_cndmask_b32_e32 v92, v92, v100, vcc
	v_cmp_lt_f32_e64 vcc, |v93|, s34
	v_cndmask_b32_e32 v93, v93, v101, vcc
	v_cmp_lt_f32_e64 vcc, |v94|, s34
	v_cndmask_b32_e32 v94, v94, v102, vcc
	v_cmp_lt_f32_e64 vcc, |v95|, s34
	v_cndmask_b32_e32 v95, v95, v103, vcc
	v_cndmask_b32_e64 v100, 0, v213, s[22:23]
	v_cndmask_b32_e64 v101, 0, v213, s[24:25]
	v_cndmask_b32_e64 v102, 0, v213, s[26:27]
	v_cndmask_b32_e64 v103, 0, v213, s[28:29]
	v_sub_f32_e32 v92, v92, v100
	v_sub_f32_e32 v93, v93, v101
	v_sub_f32_e32 v94, v94, v102
	v_sub_f32_e32 v95, v95, v103
	v_add_f32_e32 v64, v64, v92
	v_add_f32_e32 v65, v65, v93
	v_add_f32_e32 v66, v66, v94
	v_add_f32_e32 v67, v67, v95
	v_mul_f32_e32 v92, 0xbfb8aa3b, v64
	v_mul_f32_e32 v93, 0xbfb8aa3b, v65
	v_mul_f32_e32 v94, 0xbfb8aa3b, v66
	v_mul_f32_e32 v95, 0xbfb8aa3b, v67
	v_mul_f32_e32 v100, 0x3fb8aa3b, v64
	v_mul_f32_e32 v101, 0x3fb8aa3b, v65
	v_mul_f32_e32 v102, 0x3fb8aa3b, v66
	v_mul_f32_e32 v103, 0x3fb8aa3b, v67
	v_exp_f32_e32 v92, v92
	v_exp_f32_e32 v93, v93
	v_exp_f32_e32 v94, v94
	v_exp_f32_e32 v95, v95
	v_exp_f32_e32 v100, v100
	v_exp_f32_e32 v101, v101
	v_exp_f32_e32 v102, v102
	v_exp_f32_e32 v103, v103
	v_sub_f32_e32 v96, 1.0, v96
	v_sub_f32_e32 v97, 1.0, v97
	v_sub_f32_e32 v98, 1.0, v98
	v_sub_f32_e32 v99, 1.0, v99
	v_mul_f32_e32 v96, v96, v92
; DEV u16 f2bf(float f) { return (u16)(pack2(f, f) & 0xffffu); }
; DEV float bf2f(u16 h) { return __uint_as_float(((unsigned)h) << 16); }
; DEV float sigmoid_f(float x) { return __builtin_amdgcn_rcpf(1.f + __expf(-x)); }
; DEV void phase_p15(const Params& p, int g) {
;     ...
;         for (int e = 0; e < 8; ++e) {
;           const int jj = j8 * 8 + e;
;           const int j = dir ? 63 - jj : jj;
;           const size_t tok = (size_t)cidx * 64 + j;
;           const float f = lb[cc] + (1.f - lb[cc]) * sigmoid_f(bf2f(xr[st][cc][e]));
;           G[cc] += __logf(f);
;           const float eg = __expf(G[cc]), ig = __expf(-G[cc]);
;           Qp[tok * 512 + c] = f2bf(bf2f(qr[st][cc][e]) * eg);
;           const u16 kk = f2bf((1.f - f) * ig);
;           Kp[tok * 512 + c] = kk;
;           kb[e] = kk;
;         }
	v_mul_f32_e32 v97, v97, v93
	v_mul_f32_e32 v98, v98, v94
	v_mul_f32_e32 v99, v99, v95
	v_lshlrev_b32_e32 v92, 16, v50
	v_and_b32_e32 v93, 0xffff0000, v50
	v_lshlrev_b32_e32 v94, 16, v51
	v_and_b32_e32 v95, 0xffff0000, v51
	v_mul_f32_e32 v92, v92, v100
	v_mul_f32_e32 v93, v93, v101
	v_mul_f32_e32 v94, v94, v102
	v_mul_f32_e32 v95, v95, v103
	v_mov_b32_e32 v122, v96
	v_mov_b32_e32 v138, v97
	v_mov_b32_e32 v172, v98
	v_mov_b32_e32 v188, v99
	v_cvt_pk_bf16_f32 v92, v92, v93
	v_cvt_pk_bf16_f32 v93, v94, v95
	v_cvt_pk_bf16_f32 v96, v96, v97
	v_cvt_pk_bf16_f32 v97, v98, v99
	global_store_dwordx2 v112, v[92:93], s[2:3]
	global_store_dwordx2 v114, v[96:97], s[2:3]
	s_add_u32 s2, s2, 0x400
	s_addc_u32 s3, s3, 0
	v_lshlrev_b32_e32 v92, 16, v52
	v_and_b32_e32 v93, 0xffff0000, v52
	v_lshlrev_b32_e32 v94, 16, v53
	v_and_b32_e32 v95, 0xffff0000, v53
	v_mul_f32_e32 v92, 0xbfb8aa3b, v92
	v_mul_f32_e32 v93, 0xbfb8aa3b, v93
	v_mul_f32_e32 v94, 0xbfb8aa3b, v94
	v_mul_f32_e32 v95, 0xbfb8aa3b, v95
	v_exp_f32_e32 v92, v92
	v_exp_f32_e32 v93, v93
	v_exp_f32_e32 v94, v94
	v_exp_f32_e32 v95, v95
	v_add_f32_e32 v92, 1.0, v92
	v_add_f32_e32 v93, 1.0, v93
	v_add_f32_e32 v94, 1.0, v94
	v_add_f32_e32 v95, 1.0, v95
	v_rcp_f32_e32 v92, v92
	v_rcp_f32_e32 v93, v93
	v_rcp_f32_e32 v94, v94
	v_rcp_f32_e32 v95, v95
	v_fma_f32 v96, v72, v92, v68
	v_fma_f32 v97, v73, v93, v69
	v_fma_f32 v98, v74, v94, v70
	v_fma_f32 v99, v75, v95, v71
	v_cmp_gt_f32_e64 s[22:23], s30, v96
	v_cmp_gt_f32_e64 s[24:25], s30, v97
	v_cmp_gt_f32_e64 s[26:27], s30, v98
	v_cmp_gt_f32_e64 s[28:29], s30, v99
	v_cndmask_b32_e64 v92, 0, 32, s[22:23]
	v_cndmask_b32_e64 v93, 0, 32, s[24:25]
	v_cndmask_b32_e64 v94, 0, 32, s[26:27]
	v_cndmask_b32_e64 v95, 0, 32, s[28:29]
	v_ldexp_f32 v92, v96, v92
	v_ldexp_f32 v93, v97, v93
	v_ldexp_f32 v94, v98, v94
	v_ldexp_f32 v95, v99, v95
	v_log_f32_e32 v92, v92
	v_log_f32_e32 v93, v93
	v_log_f32_e32 v94, v94
	v_log_f32_e32 v95, v95
	v_mul_f32_e32 v100, 0x3f317217, v92
	v_mul_f32_e32 v101, 0x3f317217, v93
	v_mul_f32_e32 v102, 0x3f317217, v94
	v_mul_f32_e32 v103, 0x3f317217, v95
	v_fma_f32 v100, v92, s31, -v100
	v_fma_f32 v101, v93, s31, -v101
	v_fma_f32 v102, v94, s31, -v102
	v_fma_f32 v103, v95, s31, -v103
	v_fmac_f32_e32 v100, 0x3377d1cf, v92
	v_fmac_f32_e32 v101, 0x3377d1cf, v93
	v_fmac_f32_e32 v102, 0x3377d1cf, v94
	v_fmac_f32_e32 v103, 0x3377d1cf, v95
	v_fmac_f32_e32 v100, 0x3f317217, v92
	v_fmac_f32_e32 v101, 0x3f317217, v93
	v_fmac_f32_e32 v102, 0x3f317217, v94
	v_fmac_f32_e32 v103, 0x3f317217, v95
	v_cmp_lt_f32_e64 vcc, |v92|, s34
	v_cndmask_b32_e32 v92, v92, v100, vcc
	v_cmp_lt_f32_e64 vcc, |v93|, s34
	v_cndmask_b32_e32 v93, v93, v101, vcc
	v_cmp_lt_f32_e64 vcc, |v94|, s34
	v_cndmask_b32_e32 v94, v94, v102, vcc
	v_cmp_lt_f32_e64 vcc, |v95|, s34
	v_cndmask_b32_e32 v95, v95, v103, vcc
	v_cndmask_b32_e64 v100, 0, v213, s[22:23]
	v_cndmask_b32_e64 v101, 0, v213, s[24:25]
	v_cndmask_b32_e64 v102, 0, v213, s[26:27]
	v_cndmask_b32_e64 v103, 0, v213, s[28:29]
	v_sub_f32_e32 v92, v92, v100
	v_sub_f32_e32 v93, v93, v101
	v_sub_f32_e32 v94, v94, v102
	v_sub_f32_e32 v95, v95, v103
	v_add_f32_e32 v64, v64, v92
	v_add_f32_e32 v65, v65, v93
	v_add_f32_e32 v66, v66, v94
	v_add_f32_e32 v67, v67, v95
	v_mul_f32_e32 v92, 0xbfb8aa3b, v64
	v_mul_f32_e32 v93, 0xbfb8aa3b, v65
	v_mul_f32_e32 v94, 0xbfb8aa3b, v66
	v_mul_f32_e32 v95, 0xbfb8aa3b, v67
	v_mul_f32_e32 v100, 0x3fb8aa3b, v64
	v_mul_f32_e32 v101, 0x3fb8aa3b, v65
	v_mul_f32_e32 v102, 0x3fb8aa3b, v66
	v_mul_f32_e32 v103, 0x3fb8aa3b, v67
	v_exp_f32_e32 v92, v92
	v_exp_f32_e32 v93, v93
	v_exp_f32_e32 v94, v94
	v_exp_f32_e32 v95, v95
	v_exp_f32_e32 v100, v100
	v_exp_f32_e32 v101, v101
	v_exp_f32_e32 v102, v102
	v_exp_f32_e32 v103, v103
	v_sub_f32_e32 v96, 1.0, v96
	v_sub_f32_e32 v97, 1.0, v97
	v_sub_f32_e32 v98, 1.0, v98
	v_sub_f32_e32 v99, 1.0, v99
	v_mul_f32_e32 v96, v96, v92
	v_mul_f32_e32 v97, v97, v93
	v_mul_f32_e32 v98, v98, v94
	v_mul_f32_e32 v99, v99, v95
	v_lshlrev_b32_e32 v92, 16, v54
	v_and_b32_e32 v93, 0xffff0000, v54
	v_lshlrev_b32_e32 v94, 16, v55
	v_and_b32_e32 v95, 0xffff0000, v55
	v_mul_f32_e32 v92, v92, v100
	v_mul_f32_e32 v93, v93, v101
	v_mul_f32_e32 v94, v94, v102
	v_mul_f32_e32 v95, v95, v103
	v_cvt_pk_bf16_f32 v122, v122, v96
	v_cvt_pk_bf16_f32 v138, v138, v97
	v_cvt_pk_bf16_f32 v172, v172, v98
	v_cvt_pk_bf16_f32 v188, v188, v99
	v_cvt_pk_bf16_f32 v92, v92, v93
	v_cvt_pk_bf16_f32 v93, v94, v95
	v_cvt_pk_bf16_f32 v96, v96, v97
	v_cvt_pk_bf16_f32 v97, v98, v99
	global_store_dwordx2 v112, v[92:93], s[2:3]
	global_store_dwordx2 v114, v[96:97], s[2:3]
	s_add_u32 s2, s2, 0x400
	s_addc_u32 s3, s3, 0
	v_lshlrev_b32_e32 v92, 16, v56
	v_and_b32_e32 v93, 0xffff0000, v56
	v_lshlrev_b32_e32 v94, 16, v57
	v_and_b32_e32 v95, 0xffff0000, v57
	v_mul_f32_e32 v92, 0xbfb8aa3b, v92
	v_mul_f32_e32 v93, 0xbfb8aa3b, v93
	v_mul_f32_e32 v94, 0xbfb8aa3b, v94
	v_mul_f32_e32 v95, 0xbfb8aa3b, v95
	v_exp_f32_e32 v92, v92
	v_exp_f32_e32 v93, v93
	v_exp_f32_e32 v94, v94
	v_exp_f32_e32 v95, v95
	v_add_f32_e32 v92, 1.0, v92
	v_add_f32_e32 v93, 1.0, v93
	v_add_f32_e32 v94, 1.0, v94
	v_add_f32_e32 v95, 1.0, v95
	v_rcp_f32_e32 v92, v92
	v_rcp_f32_e32 v93, v93
	v_rcp_f32_e32 v94, v94
	v_rcp_f32_e32 v95, v95
	v_fma_f32 v96, v72, v92, v68
	v_fma_f32 v97, v73, v93, v69
	v_fma_f32 v98, v74, v94, v70
	v_fma_f32 v99, v75, v95, v71
	v_cmp_gt_f32_e64 s[22:23], s30, v96
	v_cmp_gt_f32_e64 s[24:25], s30, v97
	v_cmp_gt_f32_e64 s[26:27], s30, v98
	v_cmp_gt_f32_e64 s[28:29], s30, v99
	v_cndmask_b32_e64 v92, 0, 32, s[22:23]
	v_cndmask_b32_e64 v93, 0, 32, s[24:25]
	v_cndmask_b32_e64 v94, 0, 32, s[26:27]
	v_cndmask_b32_e64 v95, 0, 32, s[28:29]
	v_ldexp_f32 v92, v96, v92
; DEV u16 f2bf(float f) { return (u16)(pack2(f, f) & 0xffffu); }
; DEV float bf2f(u16 h) { return __uint_as_float(((unsigned)h) << 16); }
; DEV float sigmoid_f(float x) { return __builtin_amdgcn_rcpf(1.f + __expf(-x)); }
; DEV void phase_p15(const Params& p, int g) {
;     ...
;         for (int e = 0; e < 8; ++e) {
;           const int jj = j8 * 8 + e;
;           const int j = dir ? 63 - jj : jj;
;           const size_t tok = (size_t)cidx * 64 + j;
;           const float f = lb[cc] + (1.f - lb[cc]) * sigmoid_f(bf2f(xr[st][cc][e]));
;           G[cc] += __logf(f);
;           const float eg = __expf(G[cc]), ig = __expf(-G[cc]);
;           Qp[tok * 512 + c] = f2bf(bf2f(qr[st][cc][e]) * eg);
;           const u16 kk = f2bf((1.f - f) * ig);
;           Kp[tok * 512 + c] = kk;
;           kb[e] = kk;
;         }
	v_ldexp_f32 v93, v97, v93
	v_ldexp_f32 v94, v98, v94
	v_ldexp_f32 v95, v99, v95
	v_log_f32_e32 v92, v92
	v_log_f32_e32 v93, v93
	v_log_f32_e32 v94, v94
	v_log_f32_e32 v95, v95
	v_mul_f32_e32 v100, 0x3f317217, v92
	v_mul_f32_e32 v101, 0x3f317217, v93
	v_mul_f32_e32 v102, 0x3f317217, v94
	v_mul_f32_e32 v103, 0x3f317217, v95
	v_fma_f32 v100, v92, s31, -v100
	v_fma_f32 v101, v93, s31, -v101
	v_fma_f32 v102, v94, s31, -v102
	v_fma_f32 v103, v95, s31, -v103
	v_fmac_f32_e32 v100, 0x3377d1cf, v92
	v_fmac_f32_e32 v101, 0x3377d1cf, v93
	v_fmac_f32_e32 v102, 0x3377d1cf, v94
	v_fmac_f32_e32 v103, 0x3377d1cf, v95
	v_fmac_f32_e32 v100, 0x3f317217, v92
	v_fmac_f32_e32 v101, 0x3f317217, v93
	v_fmac_f32_e32 v102, 0x3f317217, v94
	v_fmac_f32_e32 v103, 0x3f317217, v95
	v_cmp_lt_f32_e64 vcc, |v92|, s34
	v_cndmask_b32_e32 v92, v92, v100, vcc
	v_cmp_lt_f32_e64 vcc, |v93|, s34
	v_cndmask_b32_e32 v93, v93, v101, vcc
	v_cmp_lt_f32_e64 vcc, |v94|, s34
	v_cndmask_b32_e32 v94, v94, v102, vcc
	v_cmp_lt_f32_e64 vcc, |v95|, s34
	v_cndmask_b32_e32 v95, v95, v103, vcc
	v_cndmask_b32_e64 v100, 0, v213, s[22:23]
	v_cndmask_b32_e64 v101, 0, v213, s[24:25]
	v_cndmask_b32_e64 v102, 0, v213, s[26:27]
	v_cndmask_b32_e64 v103, 0, v213, s[28:29]
	v_sub_f32_e32 v92, v92, v100
	v_sub_f32_e32 v93, v93, v101
	v_sub_f32_e32 v94, v94, v102
	v_sub_f32_e32 v95, v95, v103
	v_add_f32_e32 v64, v64, v92
	v_add_f32_e32 v65, v65, v93
	v_add_f32_e32 v66, v66, v94
	v_add_f32_e32 v67, v67, v95
	v_mul_f32_e32 v92, 0xbfb8aa3b, v64
	v_mul_f32_e32 v93, 0xbfb8aa3b, v65
	v_mul_f32_e32 v94, 0xbfb8aa3b, v66
	v_mul_f32_e32 v95, 0xbfb8aa3b, v67
	v_mul_f32_e32 v100, 0x3fb8aa3b, v64
	v_mul_f32_e32 v101, 0x3fb8aa3b, v65
	v_mul_f32_e32 v102, 0x3fb8aa3b, v66
	v_mul_f32_e32 v103, 0x3fb8aa3b, v67
	v_exp_f32_e32 v92, v92
	v_exp_f32_e32 v93, v93
	v_exp_f32_e32 v94, v94
	v_exp_f32_e32 v95, v95
	v_exp_f32_e32 v100, v100
	v_exp_f32_e32 v101, v101
	v_exp_f32_e32 v102, v102
	v_exp_f32_e32 v103, v103
	v_sub_f32_e32 v96, 1.0, v96
	v_sub_f32_e32 v97, 1.0, v97
	v_sub_f32_e32 v98, 1.0, v98
	v_sub_f32_e32 v99, 1.0, v99
	v_mul_f32_e32 v96, v96, v92
	v_mul_f32_e32 v97, v97, v93
	v_mul_f32_e32 v98, v98, v94
	v_mul_f32_e32 v99, v99, v95
	v_lshlrev_b32_e32 v92, 16, v58
	v_and_b32_e32 v93, 0xffff0000, v58
	v_lshlrev_b32_e32 v94, 16, v59
	v_and_b32_e32 v95, 0xffff0000, v59
	v_mul_f32_e32 v92, v92, v100
	v_mul_f32_e32 v93, v93, v101
	v_mul_f32_e32 v94, v94, v102
	v_mul_f32_e32 v95, v95, v103
	v_mov_b32_e32 v123, v96
	v_mov_b32_e32 v139, v97
	v_mov_b32_e32 v173, v98
	v_mov_b32_e32 v189, v99
	v_cvt_pk_bf16_f32 v92, v92, v93
	v_cvt_pk_bf16_f32 v93, v94, v95
	v_cvt_pk_bf16_f32 v96, v96, v97
	v_cvt_pk_bf16_f32 v97, v98, v99
	global_store_dwordx2 v112, v[92:93], s[2:3]
	global_store_dwordx2 v114, v[96:97], s[2:3]
	s_add_u32 s2, s2, 0x400
	s_addc_u32 s3, s3, 0
	v_lshlrev_b32_e32 v92, 16, v60
	v_and_b32_e32 v93, 0xffff0000, v60
	v_lshlrev_b32_e32 v94, 16, v61
	v_and_b32_e32 v95, 0xffff0000, v61
	v_mul_f32_e32 v92, 0xbfb8aa3b, v92
	v_mul_f32_e32 v93, 0xbfb8aa3b, v93
	v_mul_f32_e32 v94, 0xbfb8aa3b, v94
	v_mul_f32_e32 v95, 0xbfb8aa3b, v95
	v_exp_f32_e32 v92, v92
	v_exp_f32_e32 v93, v93
	v_exp_f32_e32 v94, v94
	v_exp_f32_e32 v95, v95
	v_add_f32_e32 v92, 1.0, v92
	v_add_f32_e32 v93, 1.0, v93
	v_add_f32_e32 v94, 1.0, v94
	v_add_f32_e32 v95, 1.0, v95
	v_rcp_f32_e32 v92, v92
	v_rcp_f32_e32 v93, v93
	v_rcp_f32_e32 v94, v94
	v_rcp_f32_e32 v95, v95
	v_fma_f32 v96, v72, v92, v68
	v_fma_f32 v97, v73, v93, v69
	v_fma_f32 v98, v74, v94, v70
	v_fma_f32 v99, v75, v95, v71
	v_cmp_gt_f32_e64 s[22:23], s30, v96
	v_cmp_gt_f32_e64 s[24:25], s30, v97
	v_cmp_gt_f32_e64 s[26:27], s30, v98
	v_cmp_gt_f32_e64 s[28:29], s30, v99
	v_cndmask_b32_e64 v92, 0, 32, s[22:23]
	v_cndmask_b32_e64 v93, 0, 32, s[24:25]
	v_cndmask_b32_e64 v94, 0, 32, s[26:27]
	v_cndmask_b32_e64 v95, 0, 32, s[28:29]
	v_ldexp_f32 v92, v96, v92
	v_ldexp_f32 v93, v97, v93
	v_ldexp_f32 v94, v98, v94
	v_ldexp_f32 v95, v99, v95
	v_log_f32_e32 v92, v92
	v_log_f32_e32 v93, v93
	v_log_f32_e32 v94, v94
	v_log_f32_e32 v95, v95
	v_mul_f32_e32 v100, 0x3f317217, v92
	v_mul_f32_e32 v101, 0x3f317217, v93
	v_mul_f32_e32 v102, 0x3f317217, v94
	v_mul_f32_e32 v103, 0x3f317217, v95
	v_fma_f32 v100, v92, s31, -v100
	v_fma_f32 v101, v93, s31, -v101
	v_fma_f32 v102, v94, s31, -v102
	v_fma_f32 v103, v95, s31, -v103
	v_fmac_f32_e32 v100, 0x3377d1cf, v92
	v_fmac_f32_e32 v101, 0x3377d1cf, v93
	v_fmac_f32_e32 v102, 0x3377d1cf, v94
	v_fmac_f32_e32 v103, 0x3377d1cf, v95
	v_fmac_f32_e32 v100, 0x3f317217, v92
	v_fmac_f32_e32 v101, 0x3f317217, v93
	v_fmac_f32_e32 v102, 0x3f317217, v94
	v_fmac_f32_e32 v103, 0x3f317217, v95
	v_cmp_lt_f32_e64 vcc, |v92|, s34
	v_cndmask_b32_e32 v92, v92, v100, vcc
	v_cmp_lt_f32_e64 vcc, |v93|, s34
	v_cndmask_b32_e32 v93, v93, v101, vcc
	v_cmp_lt_f32_e64 vcc, |v94|, s34
	v_cndmask_b32_e32 v94, v94, v102, vcc
	v_cmp_lt_f32_e64 vcc, |v95|, s34
	v_cndmask_b32_e32 v95, v95, v103, vcc
	v_cndmask_b32_e64 v100, 0, v213, s[22:23]
	v_cndmask_b32_e64 v101, 0, v213, s[24:25]
	v_cndmask_b32_e64 v102, 0, v213, s[26:27]
	v_cndmask_b32_e64 v103, 0, v213, s[28:29]
	v_sub_f32_e32 v92, v92, v100
	v_sub_f32_e32 v93, v93, v101
	v_sub_f32_e32 v94, v94, v102
	v_sub_f32_e32 v95, v95, v103
	v_add_f32_e32 v64, v64, v92
	v_add_f32_e32 v65, v65, v93
	v_add_f32_e32 v66, v66, v94
	v_add_f32_e32 v67, v67, v95
	v_mul_f32_e32 v92, 0xbfb8aa3b, v64
	v_mul_f32_e32 v93, 0xbfb8aa3b, v65
	v_mul_f32_e32 v94, 0xbfb8aa3b, v66
	v_mul_f32_e32 v95, 0xbfb8aa3b, v67
	v_mul_f32_e32 v100, 0x3fb8aa3b, v64
	v_mul_f32_e32 v101, 0x3fb8aa3b, v65
	v_mul_f32_e32 v102, 0x3fb8aa3b, v66
	v_mul_f32_e32 v103, 0x3fb8aa3b, v67
	v_exp_f32_e32 v92, v92
; DEV u16 f2bf(float f) { return (u16)(pack2(f, f) & 0xffffu); }
; DEV float bf2f(u16 h) { return __uint_as_float(((unsigned)h) << 16); }
; DEV float sigmoid_f(float x) { return __builtin_amdgcn_rcpf(1.f + __expf(-x)); }
; DEV void phase_p15(const Params& p, int g) {
;     ...
;     P15_LOAD(0, 0);
;     P15_LOAD(1, 1);
; #pragma unroll
;     for (int j8 = 0; j8 < 8; ++j8) {
;       const int st = j8 % 3;
;       if (j8 < 6) { P15_LOAD((j8 + 2) % 3, j8 + 2); }
;     ...
;         for (int e = 0; e < 8; ++e) {
;           const int jj = j8 * 8 + e;
;           const int j = dir ? 63 - jj : jj;
;           const size_t tok = (size_t)cidx * 64 + j;
;           const float f = lb[cc] + (1.f - lb[cc]) * sigmoid_f(bf2f(xr[st][cc][e]));
;           G[cc] += __logf(f);
;           const float eg = __expf(G[cc]), ig = __expf(-G[cc]);
;           Qp[tok * 512 + c] = f2bf(bf2f(qr[st][cc][e]) * eg);
;           const u16 kk = f2bf((1.f - f) * ig);
;           Kp[tok * 512 + c] = kk;
;           kb[e] = kk;
;         }
	v_exp_f32_e32 v93, v93
	v_exp_f32_e32 v94, v94
	v_exp_f32_e32 v95, v95
	v_exp_f32_e32 v100, v100
	v_exp_f32_e32 v101, v101
	v_exp_f32_e32 v102, v102
	v_exp_f32_e32 v103, v103
	v_sub_f32_e32 v96, 1.0, v96
	v_sub_f32_e32 v97, 1.0, v97
	v_sub_f32_e32 v98, 1.0, v98
	v_sub_f32_e32 v99, 1.0, v99
	v_mul_f32_e32 v96, v96, v92
	v_mul_f32_e32 v97, v97, v93
	v_mul_f32_e32 v98, v98, v94
	v_mul_f32_e32 v99, v99, v95
	v_lshlrev_b32_e32 v92, 16, v62
	v_and_b32_e32 v93, 0xffff0000, v62
	v_lshlrev_b32_e32 v94, 16, v63
	v_and_b32_e32 v95, 0xffff0000, v63
	v_mul_f32_e32 v92, v92, v100
	v_mul_f32_e32 v93, v93, v101
	v_mul_f32_e32 v94, v94, v102
	v_mul_f32_e32 v95, v95, v103
	v_cvt_pk_bf16_f32 v123, v123, v96
	v_cvt_pk_bf16_f32 v139, v139, v97
	v_cvt_pk_bf16_f32 v173, v173, v98
	v_cvt_pk_bf16_f32 v189, v189, v99
	v_cvt_pk_bf16_f32 v92, v92, v93
	v_cvt_pk_bf16_f32 v93, v94, v95
	v_cvt_pk_bf16_f32 v96, v96, v97
	v_cvt_pk_bf16_f32 v97, v98, v99
	global_store_dwordx2 v112, v[92:93], s[2:3]
	global_store_dwordx2 v114, v[96:97], s[2:3]
	s_add_u32 s2, s2, 0x400
	s_addc_u32 s3, s3, 0
	global_load_dwordx2 v[32:33], v113, s[0:1]
	global_load_dwordx2 v[34:35], v112, s[0:1]
	s_add_u32 s0, s0, 0x1400
	s_addc_u32 s1, s1, 0
	global_load_dwordx2 v[36:37], v113, s[0:1]
	global_load_dwordx2 v[38:39], v112, s[0:1]
	s_add_u32 s0, s0, 0x1400
	s_addc_u32 s1, s1, 0
	global_load_dwordx2 v[40:41], v113, s[0:1]
	global_load_dwordx2 v[42:43], v112, s[0:1]
	s_add_u32 s0, s0, 0x1400
	s_addc_u32 s1, s1, 0
	global_load_dwordx2 v[44:45], v113, s[0:1]
	global_load_dwordx2 v[46:47], v112, s[0:1]
	s_add_u32 s0, s0, 0x1400
	s_addc_u32 s1, s1, 0
	global_load_dwordx2 v[48:49], v113, s[0:1]
	global_load_dwordx2 v[50:51], v112, s[0:1]
	s_add_u32 s0, s0, 0x1400
	s_addc_u32 s1, s1, 0
	global_load_dwordx2 v[52:53], v113, s[0:1]
	global_load_dwordx2 v[54:55], v112, s[0:1]
	s_add_u32 s0, s0, 0x1400
	s_addc_u32 s1, s1, 0
	global_load_dwordx2 v[56:57], v113, s[0:1]
	global_load_dwordx2 v[58:59], v112, s[0:1]
	s_add_u32 s0, s0, 0x1400
	s_addc_u32 s1, s1, 0
	global_load_dwordx2 v[60:61], v113, s[0:1]
	global_load_dwordx2 v[62:63], v112, s[0:1]
	s_add_u32 s0, s0, 0x1400
	s_addc_u32 s1, s1, 0
	s_waitcnt vmcnt(32)
	v_lshlrev_b32_e32 v92, 16, v0
	v_and_b32_e32 v93, 0xffff0000, v0
	v_lshlrev_b32_e32 v94, 16, v1
	v_and_b32_e32 v95, 0xffff0000, v1
	v_mul_f32_e32 v92, 0xbfb8aa3b, v92
	v_mul_f32_e32 v93, 0xbfb8aa3b, v93
	v_mul_f32_e32 v94, 0xbfb8aa3b, v94
	v_mul_f32_e32 v95, 0xbfb8aa3b, v95
	v_exp_f32_e32 v92, v92
	v_exp_f32_e32 v93, v93
	v_exp_f32_e32 v94, v94
	v_exp_f32_e32 v95, v95
	v_add_f32_e32 v92, 1.0, v92
	v_add_f32_e32 v93, 1.0, v93
	v_add_f32_e32 v94, 1.0, v94
	v_add_f32_e32 v95, 1.0, v95
	v_rcp_f32_e32 v92, v92
	v_rcp_f32_e32 v93, v93
	v_rcp_f32_e32 v94, v94
	v_rcp_f32_e32 v95, v95
	v_fma_f32 v96, v72, v92, v68
	v_fma_f32 v97, v73, v93, v69
	v_fma_f32 v98, v74, v94, v70
	v_fma_f32 v99, v75, v95, v71
	v_cmp_gt_f32_e64 s[22:23], s30, v96
	v_cmp_gt_f32_e64 s[24:25], s30, v97
	v_cmp_gt_f32_e64 s[26:27], s30, v98
	v_cmp_gt_f32_e64 s[28:29], s30, v99
	v_cndmask_b32_e64 v92, 0, 32, s[22:23]
	v_cndmask_b32_e64 v93, 0, 32, s[24:25]
	v_cndmask_b32_e64 v94, 0, 32, s[26:27]
	v_cndmask_b32_e64 v95, 0, 32, s[28:29]
	v_ldexp_f32 v92, v96, v92
	v_ldexp_f32 v93, v97, v93
	v_ldexp_f32 v94, v98, v94
	v_ldexp_f32 v95, v99, v95
	v_log_f32_e32 v92, v92
	v_log_f32_e32 v93, v93
	v_log_f32_e32 v94, v94
	v_log_f32_e32 v95, v95
	v_mul_f32_e32 v100, 0x3f317217, v92
	v_mul_f32_e32 v101, 0x3f317217, v93
	v_mul_f32_e32 v102, 0x3f317217, v94
	v_mul_f32_e32 v103, 0x3f317217, v95
	v_fma_f32 v100, v92, s31, -v100
	v_fma_f32 v101, v93, s31, -v101
	v_fma_f32 v102, v94, s31, -v102
	v_fma_f32 v103, v95, s31, -v103
	v_fmac_f32_e32 v100, 0x3377d1cf, v92
	v_fmac_f32_e32 v101, 0x3377d1cf, v93
	v_fmac_f32_e32 v102, 0x3377d1cf, v94
	v_fmac_f32_e32 v103, 0x3377d1cf, v95
	v_fmac_f32_e32 v100, 0x3f317217, v92
	v_fmac_f32_e32 v101, 0x3f317217, v93
	v_fmac_f32_e32 v102, 0x3f317217, v94
	v_fmac_f32_e32 v103, 0x3f317217, v95
	v_cmp_lt_f32_e64 vcc, |v92|, s34
	v_cndmask_b32_e32 v92, v92, v100, vcc
	v_cmp_lt_f32_e64 vcc, |v93|, s34
	v_cndmask_b32_e32 v93, v93, v101, vcc
	v_cmp_lt_f32_e64 vcc, |v94|, s34
	v_cndmask_b32_e32 v94, v94, v102, vcc
	v_cmp_lt_f32_e64 vcc, |v95|, s34
	v_cndmask_b32_e32 v95, v95, v103, vcc
	v_cndmask_b32_e64 v100, 0, v213, s[22:23]
	v_cndmask_b32_e64 v101, 0, v213, s[24:25]
	v_cndmask_b32_e64 v102, 0, v213, s[26:27]
	v_cndmask_b32_e64 v103, 0, v213, s[28:29]
	v_sub_f32_e32 v92, v92, v100
	v_sub_f32_e32 v93, v93, v101
	v_sub_f32_e32 v94, v94, v102
	v_sub_f32_e32 v95, v95, v103
	v_add_f32_e32 v64, v64, v92
	v_add_f32_e32 v65, v65, v93
	v_add_f32_e32 v66, v66, v94
	v_add_f32_e32 v67, v67, v95
	v_mul_f32_e32 v92, 0xbfb8aa3b, v64
	v_mul_f32_e32 v93, 0xbfb8aa3b, v65
	v_mul_f32_e32 v94, 0xbfb8aa3b, v66
	v_mul_f32_e32 v95, 0xbfb8aa3b, v67
	v_mul_f32_e32 v100, 0x3fb8aa3b, v64
	v_mul_f32_e32 v101, 0x3fb8aa3b, v65
	v_mul_f32_e32 v102, 0x3fb8aa3b, v66
	v_mul_f32_e32 v103, 0x3fb8aa3b, v67
	v_exp_f32_e32 v92, v92
	v_exp_f32_e32 v93, v93
	v_exp_f32_e32 v94, v94
	v_exp_f32_e32 v95, v95
	v_exp_f32_e32 v100, v100
	v_exp_f32_e32 v101, v101
	v_exp_f32_e32 v102, v102
	v_exp_f32_e32 v103, v103
	v_sub_f32_e32 v96, 1.0, v96
	v_sub_f32_e32 v97, 1.0, v97
	v_sub_f32_e32 v98, 1.0, v98
	v_sub_f32_e32 v99, 1.0, v99
	v_mul_f32_e32 v96, v96, v92
	v_mul_f32_e32 v97, v97, v93
	v_mul_f32_e32 v98, v98, v94
	v_mul_f32_e32 v99, v99, v95
	v_lshlrev_b32_e32 v92, 16, v2
	v_and_b32_e32 v93, 0xffff0000, v2
	v_lshlrev_b32_e32 v94, 16, v3
	v_and_b32_e32 v95, 0xffff0000, v3
	v_mul_f32_e32 v92, v92, v100
	v_mul_f32_e32 v93, v93, v101
	v_mul_f32_e32 v94, v94, v102
; DEV u16 f2bf(float f) { return (u16)(pack2(f, f) & 0xffffu); }
; DEV float bf2f(u16 h) { return __uint_as_float(((unsigned)h) << 16); }
; DEV float sigmoid_f(float x) { return __builtin_amdgcn_rcpf(1.f + __expf(-x)); }
; DEV void phase_p15(const Params& p, int g) {
;     ...
;         for (int e = 0; e < 8; ++e) {
;           const int jj = j8 * 8 + e;
;           const int j = dir ? 63 - jj : jj;
;           const size_t tok = (size_t)cidx * 64 + j;
;           const float f = lb[cc] + (1.f - lb[cc]) * sigmoid_f(bf2f(xr[st][cc][e]));
;           G[cc] += __logf(f);
;           const float eg = __expf(G[cc]), ig = __expf(-G[cc]);
;           Qp[tok * 512 + c] = f2bf(bf2f(qr[st][cc][e]) * eg);
;           const u16 kk = f2bf((1.f - f) * ig);
;           Kp[tok * 512 + c] = kk;
;           kb[e] = kk;
;         }
	v_mul_f32_e32 v95, v95, v103
	v_mov_b32_e32 v124, v96
	v_mov_b32_e32 v140, v97
	v_mov_b32_e32 v174, v98
	v_mov_b32_e32 v190, v99
	v_cvt_pk_bf16_f32 v92, v92, v93
	v_cvt_pk_bf16_f32 v93, v94, v95
	v_cvt_pk_bf16_f32 v96, v96, v97
	v_cvt_pk_bf16_f32 v97, v98, v99
	global_store_dwordx2 v112, v[92:93], s[2:3]
	global_store_dwordx2 v114, v[96:97], s[2:3]
	s_add_u32 s2, s2, 0x400
	s_addc_u32 s3, s3, 0
	v_lshlrev_b32_e32 v92, 16, v4
	v_and_b32_e32 v93, 0xffff0000, v4
	v_lshlrev_b32_e32 v94, 16, v5
	v_and_b32_e32 v95, 0xffff0000, v5
	v_mul_f32_e32 v92, 0xbfb8aa3b, v92
	v_mul_f32_e32 v93, 0xbfb8aa3b, v93
	v_mul_f32_e32 v94, 0xbfb8aa3b, v94
	v_mul_f32_e32 v95, 0xbfb8aa3b, v95
	v_exp_f32_e32 v92, v92
	v_exp_f32_e32 v93, v93
	v_exp_f32_e32 v94, v94
	v_exp_f32_e32 v95, v95
	v_add_f32_e32 v92, 1.0, v92
	v_add_f32_e32 v93, 1.0, v93
	v_add_f32_e32 v94, 1.0, v94
	v_add_f32_e32 v95, 1.0, v95
	v_rcp_f32_e32 v92, v92
	v_rcp_f32_e32 v93, v93
	v_rcp_f32_e32 v94, v94
	v_rcp_f32_e32 v95, v95
	v_fma_f32 v96, v72, v92, v68
	v_fma_f32 v97, v73, v93, v69
	v_fma_f32 v98, v74, v94, v70
	v_fma_f32 v99, v75, v95, v71
	v_cmp_gt_f32_e64 s[22:23], s30, v96
	v_cmp_gt_f32_e64 s[24:25], s30, v97
	v_cmp_gt_f32_e64 s[26:27], s30, v98
	v_cmp_gt_f32_e64 s[28:29], s30, v99
	v_cndmask_b32_e64 v92, 0, 32, s[22:23]
	v_cndmask_b32_e64 v93, 0, 32, s[24:25]
	v_cndmask_b32_e64 v94, 0, 32, s[26:27]
	v_cndmask_b32_e64 v95, 0, 32, s[28:29]
	v_ldexp_f32 v92, v96, v92
	v_ldexp_f32 v93, v97, v93
	v_ldexp_f32 v94, v98, v94
	v_ldexp_f32 v95, v99, v95
	v_log_f32_e32 v92, v92
	v_log_f32_e32 v93, v93
	v_log_f32_e32 v94, v94
	v_log_f32_e32 v95, v95
	v_mul_f32_e32 v100, 0x3f317217, v92
	v_mul_f32_e32 v101, 0x3f317217, v93
	v_mul_f32_e32 v102, 0x3f317217, v94
	v_mul_f32_e32 v103, 0x3f317217, v95
	v_fma_f32 v100, v92, s31, -v100
	v_fma_f32 v101, v93, s31, -v101
	v_fma_f32 v102, v94, s31, -v102
	v_fma_f32 v103, v95, s31, -v103
	v_fmac_f32_e32 v100, 0x3377d1cf, v92
	v_fmac_f32_e32 v101, 0x3377d1cf, v93
	v_fmac_f32_e32 v102, 0x3377d1cf, v94
	v_fmac_f32_e32 v103, 0x3377d1cf, v95
	v_fmac_f32_e32 v100, 0x3f317217, v92
	v_fmac_f32_e32 v101, 0x3f317217, v93
	v_fmac_f32_e32 v102, 0x3f317217, v94
	v_fmac_f32_e32 v103, 0x3f317217, v95
	v_cmp_lt_f32_e64 vcc, |v92|, s34
	v_cndmask_b32_e32 v92, v92, v100, vcc
	v_cmp_lt_f32_e64 vcc, |v93|, s34
	v_cndmask_b32_e32 v93, v93, v101, vcc
	v_cmp_lt_f32_e64 vcc, |v94|, s34
	v_cndmask_b32_e32 v94, v94, v102, vcc
	v_cmp_lt_f32_e64 vcc, |v95|, s34
	v_cndmask_b32_e32 v95, v95, v103, vcc
	v_cndmask_b32_e64 v100, 0, v213, s[22:23]
	v_cndmask_b32_e64 v101, 0, v213, s[24:25]
	v_cndmask_b32_e64 v102, 0, v213, s[26:27]
	v_cndmask_b32_e64 v103, 0, v213, s[28:29]
	v_sub_f32_e32 v92, v92, v100
	v_sub_f32_e32 v93, v93, v101
	v_sub_f32_e32 v94, v94, v102
	v_sub_f32_e32 v95, v95, v103
	v_add_f32_e32 v64, v64, v92
	v_add_f32_e32 v65, v65, v93
	v_add_f32_e32 v66, v66, v94
	v_add_f32_e32 v67, v67, v95
	v_mul_f32_e32 v92, 0xbfb8aa3b, v64
	v_mul_f32_e32 v93, 0xbfb8aa3b, v65
	v_mul_f32_e32 v94, 0xbfb8aa3b, v66
	v_mul_f32_e32 v95, 0xbfb8aa3b, v67
	v_mul_f32_e32 v100, 0x3fb8aa3b, v64
	v_mul_f32_e32 v101, 0x3fb8aa3b, v65
	v_mul_f32_e32 v102, 0x3fb8aa3b, v66
	v_mul_f32_e32 v103, 0x3fb8aa3b, v67
	v_exp_f32_e32 v92, v92
	v_exp_f32_e32 v93, v93
	v_exp_f32_e32 v94, v94
	v_exp_f32_e32 v95, v95
	v_exp_f32_e32 v100, v100
	v_exp_f32_e32 v101, v101
	v_exp_f32_e32 v102, v102
	v_exp_f32_e32 v103, v103
	v_sub_f32_e32 v96, 1.0, v96
	v_sub_f32_e32 v97, 1.0, v97
	v_sub_f32_e32 v98, 1.0, v98
	v_sub_f32_e32 v99, 1.0, v99
	v_mul_f32_e32 v96, v96, v92
	v_mul_f32_e32 v97, v97, v93
	v_mul_f32_e32 v98, v98, v94
	v_mul_f32_e32 v99, v99, v95
	v_lshlrev_b32_e32 v92, 16, v6
	v_and_b32_e32 v93, 0xffff0000, v6
	v_lshlrev_b32_e32 v94, 16, v7
	v_and_b32_e32 v95, 0xffff0000, v7
	v_mul_f32_e32 v92, v92, v100
	v_mul_f32_e32 v93, v93, v101
	v_mul_f32_e32 v94, v94, v102
	v_mul_f32_e32 v95, v95, v103
	v_cvt_pk_bf16_f32 v124, v124, v96
	v_cvt_pk_bf16_f32 v140, v140, v97
	v_cvt_pk_bf16_f32 v174, v174, v98
	v_cvt_pk_bf16_f32 v190, v190, v99
	v_cvt_pk_bf16_f32 v92, v92, v93
	v_cvt_pk_bf16_f32 v93, v94, v95
	v_cvt_pk_bf16_f32 v96, v96, v97
	v_cvt_pk_bf16_f32 v97, v98, v99
	global_store_dwordx2 v112, v[92:93], s[2:3]
	global_store_dwordx2 v114, v[96:97], s[2:3]
	s_add_u32 s2, s2, 0x400
	s_addc_u32 s3, s3, 0
	v_lshlrev_b32_e32 v92, 16, v8
	v_and_b32_e32 v93, 0xffff0000, v8
	v_lshlrev_b32_e32 v94, 16, v9
	v_and_b32_e32 v95, 0xffff0000, v9
	v_mul_f32_e32 v92, 0xbfb8aa3b, v92
	v_mul_f32_e32 v93, 0xbfb8aa3b, v93
	v_mul_f32_e32 v94, 0xbfb8aa3b, v94
	v_mul_f32_e32 v95, 0xbfb8aa3b, v95
	v_exp_f32_e32 v92, v92
	v_exp_f32_e32 v93, v93
	v_exp_f32_e32 v94, v94
	v_exp_f32_e32 v95, v95
	v_add_f32_e32 v92, 1.0, v92
	v_add_f32_e32 v93, 1.0, v93
	v_add_f32_e32 v94, 1.0, v94
	v_add_f32_e32 v95, 1.0, v95
	v_rcp_f32_e32 v92, v92
	v_rcp_f32_e32 v93, v93
	v_rcp_f32_e32 v94, v94
	v_rcp_f32_e32 v95, v95
	v_fma_f32 v96, v72, v92, v68
	v_fma_f32 v97, v73, v93, v69
	v_fma_f32 v98, v74, v94, v70
	v_fma_f32 v99, v75, v95, v71
	v_cmp_gt_f32_e64 s[22:23], s30, v96
	v_cmp_gt_f32_e64 s[24:25], s30, v97
	v_cmp_gt_f32_e64 s[26:27], s30, v98
	v_cmp_gt_f32_e64 s[28:29], s30, v99
	v_cndmask_b32_e64 v92, 0, 32, s[22:23]
	v_cndmask_b32_e64 v93, 0, 32, s[24:25]
	v_cndmask_b32_e64 v94, 0, 32, s[26:27]
	v_cndmask_b32_e64 v95, 0, 32, s[28:29]
	v_ldexp_f32 v92, v96, v92
	v_ldexp_f32 v93, v97, v93
	v_ldexp_f32 v94, v98, v94
	v_ldexp_f32 v95, v99, v95
	v_log_f32_e32 v92, v92
	v_log_f32_e32 v93, v93
	v_log_f32_e32 v94, v94
	v_log_f32_e32 v95, v95
	v_mul_f32_e32 v100, 0x3f317217, v92
	v_mul_f32_e32 v101, 0x3f317217, v93
	v_mul_f32_e32 v102, 0x3f317217, v94
	v_mul_f32_e32 v103, 0x3f317217, v95
; DEV u16 f2bf(float f) { return (u16)(pack2(f, f) & 0xffffu); }
; DEV float bf2f(u16 h) { return __uint_as_float(((unsigned)h) << 16); }
; DEV float sigmoid_f(float x) { return __builtin_amdgcn_rcpf(1.f + __expf(-x)); }
; DEV void phase_p15(const Params& p, int g) {
;     ...
;         for (int e = 0; e < 8; ++e) {
;           const int jj = j8 * 8 + e;
;           const int j = dir ? 63 - jj : jj;
;           const size_t tok = (size_t)cidx * 64 + j;
;           const float f = lb[cc] + (1.f - lb[cc]) * sigmoid_f(bf2f(xr[st][cc][e]));
;           G[cc] += __logf(f);
;           const float eg = __expf(G[cc]), ig = __expf(-G[cc]);
;           Qp[tok * 512 + c] = f2bf(bf2f(qr[st][cc][e]) * eg);
;           const u16 kk = f2bf((1.f - f) * ig);
;           Kp[tok * 512 + c] = kk;
;           kb[e] = kk;
;         }
	v_fma_f32 v100, v92, s31, -v100
	v_fma_f32 v101, v93, s31, -v101
	v_fma_f32 v102, v94, s31, -v102
	v_fma_f32 v103, v95, s31, -v103
	v_fmac_f32_e32 v100, 0x3377d1cf, v92
	v_fmac_f32_e32 v101, 0x3377d1cf, v93
	v_fmac_f32_e32 v102, 0x3377d1cf, v94
	v_fmac_f32_e32 v103, 0x3377d1cf, v95
	v_fmac_f32_e32 v100, 0x3f317217, v92
	v_fmac_f32_e32 v101, 0x3f317217, v93
	v_fmac_f32_e32 v102, 0x3f317217, v94
	v_fmac_f32_e32 v103, 0x3f317217, v95
	v_cmp_lt_f32_e64 vcc, |v92|, s34
	v_cndmask_b32_e32 v92, v92, v100, vcc
	v_cmp_lt_f32_e64 vcc, |v93|, s34
	v_cndmask_b32_e32 v93, v93, v101, vcc
	v_cmp_lt_f32_e64 vcc, |v94|, s34
	v_cndmask_b32_e32 v94, v94, v102, vcc
	v_cmp_lt_f32_e64 vcc, |v95|, s34
	v_cndmask_b32_e32 v95, v95, v103, vcc
	v_cndmask_b32_e64 v100, 0, v213, s[22:23]
	v_cndmask_b32_e64 v101, 0, v213, s[24:25]
	v_cndmask_b32_e64 v102, 0, v213, s[26:27]
	v_cndmask_b32_e64 v103, 0, v213, s[28:29]
	v_sub_f32_e32 v92, v92, v100
	v_sub_f32_e32 v93, v93, v101
	v_sub_f32_e32 v94, v94, v102
	v_sub_f32_e32 v95, v95, v103
	v_add_f32_e32 v64, v64, v92
	v_add_f32_e32 v65, v65, v93
	v_add_f32_e32 v66, v66, v94
	v_add_f32_e32 v67, v67, v95
	v_mul_f32_e32 v92, 0xbfb8aa3b, v64
	v_mul_f32_e32 v93, 0xbfb8aa3b, v65
	v_mul_f32_e32 v94, 0xbfb8aa3b, v66
	v_mul_f32_e32 v95, 0xbfb8aa3b, v67
	v_mul_f32_e32 v100, 0x3fb8aa3b, v64
	v_mul_f32_e32 v101, 0x3fb8aa3b, v65
	v_mul_f32_e32 v102, 0x3fb8aa3b, v66
	v_mul_f32_e32 v103, 0x3fb8aa3b, v67
	v_exp_f32_e32 v92, v92
	v_exp_f32_e32 v93, v93
	v_exp_f32_e32 v94, v94
	v_exp_f32_e32 v95, v95
	v_exp_f32_e32 v100, v100
	v_exp_f32_e32 v101, v101
	v_exp_f32_e32 v102, v102
	v_exp_f32_e32 v103, v103
	v_sub_f32_e32 v96, 1.0, v96
	v_sub_f32_e32 v97, 1.0, v97
	v_sub_f32_e32 v98, 1.0, v98
	v_sub_f32_e32 v99, 1.0, v99
	v_mul_f32_e32 v96, v96, v92
	v_mul_f32_e32 v97, v97, v93
	v_mul_f32_e32 v98, v98, v94
	v_mul_f32_e32 v99, v99, v95
	v_lshlrev_b32_e32 v92, 16, v10
	v_and_b32_e32 v93, 0xffff0000, v10
	v_lshlrev_b32_e32 v94, 16, v11
	v_and_b32_e32 v95, 0xffff0000, v11
	v_mul_f32_e32 v92, v92, v100
	v_mul_f32_e32 v93, v93, v101
	v_mul_f32_e32 v94, v94, v102
	v_mul_f32_e32 v95, v95, v103
	v_mov_b32_e32 v125, v96
	v_mov_b32_e32 v141, v97
	v_mov_b32_e32 v175, v98
	v_mov_b32_e32 v191, v99
	v_cvt_pk_bf16_f32 v92, v92, v93
	v_cvt_pk_bf16_f32 v93, v94, v95
	v_cvt_pk_bf16_f32 v96, v96, v97
	v_cvt_pk_bf16_f32 v97, v98, v99
	global_store_dwordx2 v112, v[92:93], s[2:3]
	global_store_dwordx2 v114, v[96:97], s[2:3]
	s_add_u32 s2, s2, 0x400
	s_addc_u32 s3, s3, 0
	v_lshlrev_b32_e32 v92, 16, v12
	v_and_b32_e32 v93, 0xffff0000, v12
	v_lshlrev_b32_e32 v94, 16, v13
	v_and_b32_e32 v95, 0xffff0000, v13
	v_mul_f32_e32 v92, 0xbfb8aa3b, v92
	v_mul_f32_e32 v93, 0xbfb8aa3b, v93
	v_mul_f32_e32 v94, 0xbfb8aa3b, v94
	v_mul_f32_e32 v95, 0xbfb8aa3b, v95
	v_exp_f32_e32 v92, v92
	v_exp_f32_e32 v93, v93
	v_exp_f32_e32 v94, v94
	v_exp_f32_e32 v95, v95
	v_add_f32_e32 v92, 1.0, v92
	v_add_f32_e32 v93, 1.0, v93
	v_add_f32_e32 v94, 1.0, v94
	v_add_f32_e32 v95, 1.0, v95
	v_rcp_f32_e32 v92, v92
	v_rcp_f32_e32 v93, v93
	v_rcp_f32_e32 v94, v94
	v_rcp_f32_e32 v95, v95
	v_fma_f32 v96, v72, v92, v68
	v_fma_f32 v97, v73, v93, v69
	v_fma_f32 v98, v74, v94, v70
	v_fma_f32 v99, v75, v95, v71
	v_cmp_gt_f32_e64 s[22:23], s30, v96
	v_cmp_gt_f32_e64 s[24:25], s30, v97
	v_cmp_gt_f32_e64 s[26:27], s30, v98
	v_cmp_gt_f32_e64 s[28:29], s30, v99
	v_cndmask_b32_e64 v92, 0, 32, s[22:23]
	v_cndmask_b32_e64 v93, 0, 32, s[24:25]
	v_cndmask_b32_e64 v94, 0, 32, s[26:27]
	v_cndmask_b32_e64 v95, 0, 32, s[28:29]
	v_ldexp_f32 v92, v96, v92
	v_ldexp_f32 v93, v97, v93
	v_ldexp_f32 v94, v98, v94
	v_ldexp_f32 v95, v99, v95
	v_log_f32_e32 v92, v92
	v_log_f32_e32 v93, v93
	v_log_f32_e32 v94, v94
	v_log_f32_e32 v95, v95
	v_mul_f32_e32 v100, 0x3f317217, v92
	v_mul_f32_e32 v101, 0x3f317217, v93
	v_mul_f32_e32 v102, 0x3f317217, v94
	v_mul_f32_e32 v103, 0x3f317217, v95
	v_fma_f32 v100, v92, s31, -v100
	v_fma_f32 v101, v93, s31, -v101
	v_fma_f32 v102, v94, s31, -v102
	v_fma_f32 v103, v95, s31, -v103
	v_fmac_f32_e32 v100, 0x3377d1cf, v92
	v_fmac_f32_e32 v101, 0x3377d1cf, v93
	v_fmac_f32_e32 v102, 0x3377d1cf, v94
	v_fmac_f32_e32 v103, 0x3377d1cf, v95
	v_fmac_f32_e32 v100, 0x3f317217, v92
	v_fmac_f32_e32 v101, 0x3f317217, v93
	v_fmac_f32_e32 v102, 0x3f317217, v94
	v_fmac_f32_e32 v103, 0x3f317217, v95
	v_cmp_lt_f32_e64 vcc, |v92|, s34
	v_cndmask_b32_e32 v92, v92, v100, vcc
	v_cmp_lt_f32_e64 vcc, |v93|, s34
	v_cndmask_b32_e32 v93, v93, v101, vcc
	v_cmp_lt_f32_e64 vcc, |v94|, s34
	v_cndmask_b32_e32 v94, v94, v102, vcc
	v_cmp_lt_f32_e64 vcc, |v95|, s34
	v_cndmask_b32_e32 v95, v95, v103, vcc
	v_cndmask_b32_e64 v100, 0, v213, s[22:23]
	v_cndmask_b32_e64 v101, 0, v213, s[24:25]
	v_cndmask_b32_e64 v102, 0, v213, s[26:27]
	v_cndmask_b32_e64 v103, 0, v213, s[28:29]
	v_sub_f32_e32 v92, v92, v100
	v_sub_f32_e32 v93, v93, v101
	v_sub_f32_e32 v94, v94, v102
	v_sub_f32_e32 v95, v95, v103
	v_add_f32_e32 v64, v64, v92
	v_add_f32_e32 v65, v65, v93
	v_add_f32_e32 v66, v66, v94
	v_add_f32_e32 v67, v67, v95
	v_mul_f32_e32 v92, 0xbfb8aa3b, v64
	v_mul_f32_e32 v93, 0xbfb8aa3b, v65
	v_mul_f32_e32 v94, 0xbfb8aa3b, v66
	v_mul_f32_e32 v95, 0xbfb8aa3b, v67
	v_mul_f32_e32 v100, 0x3fb8aa3b, v64
	v_mul_f32_e32 v101, 0x3fb8aa3b, v65
	v_mul_f32_e32 v102, 0x3fb8aa3b, v66
	v_mul_f32_e32 v103, 0x3fb8aa3b, v67
	v_exp_f32_e32 v92, v92
	v_exp_f32_e32 v93, v93
	v_exp_f32_e32 v94, v94
	v_exp_f32_e32 v95, v95
	v_exp_f32_e32 v100, v100
	v_exp_f32_e32 v101, v101
	v_exp_f32_e32 v102, v102
	v_exp_f32_e32 v103, v103
	v_sub_f32_e32 v96, 1.0, v96
	v_sub_f32_e32 v97, 1.0, v97
	v_sub_f32_e32 v98, 1.0, v98
	v_sub_f32_e32 v99, 1.0, v99
	v_mul_f32_e32 v96, v96, v92
; DEV u16 f2bf(float f) { return (u16)(pack2(f, f) & 0xffffu); }
; DEV float bf2f(u16 h) { return __uint_as_float(((unsigned)h) << 16); }
; DEV float sigmoid_f(float x) { return __builtin_amdgcn_rcpf(1.f + __expf(-x)); }
; DEV void phase_p15(const Params& p, int g) {
;     ...
;         for (int e = 0; e < 8; ++e) {
;           const int jj = j8 * 8 + e;
;           const int j = dir ? 63 - jj : jj;
;           const size_t tok = (size_t)cidx * 64 + j;
;           const float f = lb[cc] + (1.f - lb[cc]) * sigmoid_f(bf2f(xr[st][cc][e]));
;           G[cc] += __logf(f);
;           const float eg = __expf(G[cc]), ig = __expf(-G[cc]);
;           Qp[tok * 512 + c] = f2bf(bf2f(qr[st][cc][e]) * eg);
;           const u16 kk = f2bf((1.f - f) * ig);
;           Kp[tok * 512 + c] = kk;
;           kb[e] = kk;
;         }
	v_mul_f32_e32 v97, v97, v93
	v_mul_f32_e32 v98, v98, v94
	v_mul_f32_e32 v99, v99, v95
	v_lshlrev_b32_e32 v92, 16, v14
	v_and_b32_e32 v93, 0xffff0000, v14
	v_lshlrev_b32_e32 v94, 16, v15
	v_and_b32_e32 v95, 0xffff0000, v15
	v_mul_f32_e32 v92, v92, v100
	v_mul_f32_e32 v93, v93, v101
	v_mul_f32_e32 v94, v94, v102
	v_mul_f32_e32 v95, v95, v103
	v_cvt_pk_bf16_f32 v125, v125, v96
	v_cvt_pk_bf16_f32 v141, v141, v97
	v_cvt_pk_bf16_f32 v175, v175, v98
	v_cvt_pk_bf16_f32 v191, v191, v99
	v_cvt_pk_bf16_f32 v92, v92, v93
	v_cvt_pk_bf16_f32 v93, v94, v95
	v_cvt_pk_bf16_f32 v96, v96, v97
	v_cvt_pk_bf16_f32 v97, v98, v99
	global_store_dwordx2 v112, v[92:93], s[2:3]
	global_store_dwordx2 v114, v[96:97], s[2:3]
	s_add_u32 s2, s2, 0x400
	s_addc_u32 s3, s3, 0
	v_lshlrev_b32_e32 v92, 16, v16
	v_and_b32_e32 v93, 0xffff0000, v16
	v_lshlrev_b32_e32 v94, 16, v17
	v_and_b32_e32 v95, 0xffff0000, v17
	v_mul_f32_e32 v92, 0xbfb8aa3b, v92
	v_mul_f32_e32 v93, 0xbfb8aa3b, v93
	v_mul_f32_e32 v94, 0xbfb8aa3b, v94
	v_mul_f32_e32 v95, 0xbfb8aa3b, v95
	v_exp_f32_e32 v92, v92
	v_exp_f32_e32 v93, v93
	v_exp_f32_e32 v94, v94
	v_exp_f32_e32 v95, v95
	v_add_f32_e32 v92, 1.0, v92
	v_add_f32_e32 v93, 1.0, v93
	v_add_f32_e32 v94, 1.0, v94
	v_add_f32_e32 v95, 1.0, v95
	v_rcp_f32_e32 v92, v92
	v_rcp_f32_e32 v93, v93
	v_rcp_f32_e32 v94, v94
	v_rcp_f32_e32 v95, v95
	v_fma_f32 v96, v72, v92, v68
	v_fma_f32 v97, v73, v93, v69
	v_fma_f32 v98, v74, v94, v70
	v_fma_f32 v99, v75, v95, v71
	v_cmp_gt_f32_e64 s[22:23], s30, v96
	v_cmp_gt_f32_e64 s[24:25], s30, v97
	v_cmp_gt_f32_e64 s[26:27], s30, v98
	v_cmp_gt_f32_e64 s[28:29], s30, v99
	v_cndmask_b32_e64 v92, 0, 32, s[22:23]
	v_cndmask_b32_e64 v93, 0, 32, s[24:25]
	v_cndmask_b32_e64 v94, 0, 32, s[26:27]
	v_cndmask_b32_e64 v95, 0, 32, s[28:29]
	v_ldexp_f32 v92, v96, v92
	v_ldexp_f32 v93, v97, v93
	v_ldexp_f32 v94, v98, v94
	v_ldexp_f32 v95, v99, v95
	v_log_f32_e32 v92, v92
	v_log_f32_e32 v93, v93
	v_log_f32_e32 v94, v94
	v_log_f32_e32 v95, v95
	v_mul_f32_e32 v100, 0x3f317217, v92
	v_mul_f32_e32 v101, 0x3f317217, v93
	v_mul_f32_e32 v102, 0x3f317217, v94
	v_mul_f32_e32 v103, 0x3f317217, v95
	v_fma_f32 v100, v92, s31, -v100
	v_fma_f32 v101, v93, s31, -v101
	v_fma_f32 v102, v94, s31, -v102
	v_fma_f32 v103, v95, s31, -v103
	v_fmac_f32_e32 v100, 0x3377d1cf, v92
	v_fmac_f32_e32 v101, 0x3377d1cf, v93
	v_fmac_f32_e32 v102, 0x3377d1cf, v94
	v_fmac_f32_e32 v103, 0x3377d1cf, v95
	v_fmac_f32_e32 v100, 0x3f317217, v92
	v_fmac_f32_e32 v101, 0x3f317217, v93
	v_fmac_f32_e32 v102, 0x3f317217, v94
	v_fmac_f32_e32 v103, 0x3f317217, v95
	v_cmp_lt_f32_e64 vcc, |v92|, s34
	v_cndmask_b32_e32 v92, v92, v100, vcc
	v_cmp_lt_f32_e64 vcc, |v93|, s34
	v_cndmask_b32_e32 v93, v93, v101, vcc
	v_cmp_lt_f32_e64 vcc, |v94|, s34
	v_cndmask_b32_e32 v94, v94, v102, vcc
	v_cmp_lt_f32_e64 vcc, |v95|, s34
	v_cndmask_b32_e32 v95, v95, v103, vcc
	v_cndmask_b32_e64 v100, 0, v213, s[22:23]
	v_cndmask_b32_e64 v101, 0, v213, s[24:25]
	v_cndmask_b32_e64 v102, 0, v213, s[26:27]
	v_cndmask_b32_e64 v103, 0, v213, s[28:29]
	v_sub_f32_e32 v92, v92, v100
	v_sub_f32_e32 v93, v93, v101
	v_sub_f32_e32 v94, v94, v102
	v_sub_f32_e32 v95, v95, v103
	v_add_f32_e32 v64, v64, v92
	v_add_f32_e32 v65, v65, v93
	v_add_f32_e32 v66, v66, v94
	v_add_f32_e32 v67, v67, v95
	v_mul_f32_e32 v92, 0xbfb8aa3b, v64
	v_mul_f32_e32 v93, 0xbfb8aa3b, v65
	v_mul_f32_e32 v94, 0xbfb8aa3b, v66
	v_mul_f32_e32 v95, 0xbfb8aa3b, v67
	v_mul_f32_e32 v100, 0x3fb8aa3b, v64
	v_mul_f32_e32 v101, 0x3fb8aa3b, v65
	v_mul_f32_e32 v102, 0x3fb8aa3b, v66
	v_mul_f32_e32 v103, 0x3fb8aa3b, v67
	v_exp_f32_e32 v92, v92
	v_exp_f32_e32 v93, v93
	v_exp_f32_e32 v94, v94
	v_exp_f32_e32 v95, v95
	v_exp_f32_e32 v100, v100
	v_exp_f32_e32 v101, v101
	v_exp_f32_e32 v102, v102
	v_exp_f32_e32 v103, v103
	v_sub_f32_e32 v96, 1.0, v96
	v_sub_f32_e32 v97, 1.0, v97
	v_sub_f32_e32 v98, 1.0, v98
	v_sub_f32_e32 v99, 1.0, v99
	v_mul_f32_e32 v96, v96, v92
	v_mul_f32_e32 v97, v97, v93
	v_mul_f32_e32 v98, v98, v94
	v_mul_f32_e32 v99, v99, v95
	v_lshlrev_b32_e32 v92, 16, v18
	v_and_b32_e32 v93, 0xffff0000, v18
	v_lshlrev_b32_e32 v94, 16, v19
	v_and_b32_e32 v95, 0xffff0000, v19
	v_mul_f32_e32 v92, v92, v100
	v_mul_f32_e32 v93, v93, v101
	v_mul_f32_e32 v94, v94, v102
	v_mul_f32_e32 v95, v95, v103
	v_mov_b32_e32 v126, v96
	v_mov_b32_e32 v142, v97
	v_mov_b32_e32 v176, v98
	v_mov_b32_e32 v192, v99
	v_cvt_pk_bf16_f32 v92, v92, v93
	v_cvt_pk_bf16_f32 v93, v94, v95
	v_cvt_pk_bf16_f32 v96, v96, v97
	v_cvt_pk_bf16_f32 v97, v98, v99
	global_store_dwordx2 v112, v[92:93], s[2:3]
	global_store_dwordx2 v114, v[96:97], s[2:3]
	s_add_u32 s2, s2, 0x400
	s_addc_u32 s3, s3, 0
	v_lshlrev_b32_e32 v92, 16, v20
	v_and_b32_e32 v93, 0xffff0000, v20
	v_lshlrev_b32_e32 v94, 16, v21
	v_and_b32_e32 v95, 0xffff0000, v21
	v_mul_f32_e32 v92, 0xbfb8aa3b, v92
	v_mul_f32_e32 v93, 0xbfb8aa3b, v93
	v_mul_f32_e32 v94, 0xbfb8aa3b, v94
	v_mul_f32_e32 v95, 0xbfb8aa3b, v95
	v_exp_f32_e32 v92, v92
	v_exp_f32_e32 v93, v93
	v_exp_f32_e32 v94, v94
	v_exp_f32_e32 v95, v95
	v_add_f32_e32 v92, 1.0, v92
	v_add_f32_e32 v93, 1.0, v93
	v_add_f32_e32 v94, 1.0, v94
	v_add_f32_e32 v95, 1.0, v95
	v_rcp_f32_e32 v92, v92
	v_rcp_f32_e32 v93, v93
	v_rcp_f32_e32 v94, v94
	v_rcp_f32_e32 v95, v95
	v_fma_f32 v96, v72, v92, v68
	v_fma_f32 v97, v73, v93, v69
	v_fma_f32 v98, v74, v94, v70
	v_fma_f32 v99, v75, v95, v71
	v_cmp_gt_f32_e64 s[22:23], s30, v96
	v_cmp_gt_f32_e64 s[24:25], s30, v97
	v_cmp_gt_f32_e64 s[26:27], s30, v98
	v_cmp_gt_f32_e64 s[28:29], s30, v99
	v_cndmask_b32_e64 v92, 0, 32, s[22:23]
	v_cndmask_b32_e64 v93, 0, 32, s[24:25]
	v_cndmask_b32_e64 v94, 0, 32, s[26:27]
	v_cndmask_b32_e64 v95, 0, 32, s[28:29]
	v_ldexp_f32 v92, v96, v92
; DEV u16 f2bf(float f) { return (u16)(pack2(f, f) & 0xffffu); }
; DEV float bf2f(u16 h) { return __uint_as_float(((unsigned)h) << 16); }
; DEV float sigmoid_f(float x) { return __builtin_amdgcn_rcpf(1.f + __expf(-x)); }
; DEV void phase_p15(const Params& p, int g) {
;     ...
;         for (int e = 0; e < 8; ++e) {
;           const int jj = j8 * 8 + e;
;           const int j = dir ? 63 - jj : jj;
;           const size_t tok = (size_t)cidx * 64 + j;
;           const float f = lb[cc] + (1.f - lb[cc]) * sigmoid_f(bf2f(xr[st][cc][e]));
;           G[cc] += __logf(f);
;           const float eg = __expf(G[cc]), ig = __expf(-G[cc]);
;           Qp[tok * 512 + c] = f2bf(bf2f(qr[st][cc][e]) * eg);
;           const u16 kk = f2bf((1.f - f) * ig);
;           Kp[tok * 512 + c] = kk;
;           kb[e] = kk;
;         }
	v_ldexp_f32 v93, v97, v93
	v_ldexp_f32 v94, v98, v94
	v_ldexp_f32 v95, v99, v95
	v_log_f32_e32 v92, v92
	v_log_f32_e32 v93, v93
	v_log_f32_e32 v94, v94
	v_log_f32_e32 v95, v95
	v_mul_f32_e32 v100, 0x3f317217, v92
	v_mul_f32_e32 v101, 0x3f317217, v93
	v_mul_f32_e32 v102, 0x3f317217, v94
	v_mul_f32_e32 v103, 0x3f317217, v95
	v_fma_f32 v100, v92, s31, -v100
	v_fma_f32 v101, v93, s31, -v101
	v_fma_f32 v102, v94, s31, -v102
	v_fma_f32 v103, v95, s31, -v103
	v_fmac_f32_e32 v100, 0x3377d1cf, v92
	v_fmac_f32_e32 v101, 0x3377d1cf, v93
	v_fmac_f32_e32 v102, 0x3377d1cf, v94
	v_fmac_f32_e32 v103, 0x3377d1cf, v95
	v_fmac_f32_e32 v100, 0x3f317217, v92
	v_fmac_f32_e32 v101, 0x3f317217, v93
	v_fmac_f32_e32 v102, 0x3f317217, v94
	v_fmac_f32_e32 v103, 0x3f317217, v95
	v_cmp_lt_f32_e64 vcc, |v92|, s34
	v_cndmask_b32_e32 v92, v92, v100, vcc
	v_cmp_lt_f32_e64 vcc, |v93|, s34
	v_cndmask_b32_e32 v93, v93, v101, vcc
	v_cmp_lt_f32_e64 vcc, |v94|, s34
	v_cndmask_b32_e32 v94, v94, v102, vcc
	v_cmp_lt_f32_e64 vcc, |v95|, s34
	v_cndmask_b32_e32 v95, v95, v103, vcc
	v_cndmask_b32_e64 v100, 0, v213, s[22:23]
	v_cndmask_b32_e64 v101, 0, v213, s[24:25]
	v_cndmask_b32_e64 v102, 0, v213, s[26:27]
	v_cndmask_b32_e64 v103, 0, v213, s[28:29]
	v_sub_f32_e32 v92, v92, v100
	v_sub_f32_e32 v93, v93, v101
	v_sub_f32_e32 v94, v94, v102
	v_sub_f32_e32 v95, v95, v103
	v_add_f32_e32 v64, v64, v92
	v_add_f32_e32 v65, v65, v93
	v_add_f32_e32 v66, v66, v94
	v_add_f32_e32 v67, v67, v95
	v_mul_f32_e32 v92, 0xbfb8aa3b, v64
	v_mul_f32_e32 v93, 0xbfb8aa3b, v65
	v_mul_f32_e32 v94, 0xbfb8aa3b, v66
	v_mul_f32_e32 v95, 0xbfb8aa3b, v67
	v_mul_f32_e32 v100, 0x3fb8aa3b, v64
	v_mul_f32_e32 v101, 0x3fb8aa3b, v65
	v_mul_f32_e32 v102, 0x3fb8aa3b, v66
	v_mul_f32_e32 v103, 0x3fb8aa3b, v67
	v_exp_f32_e32 v92, v92
	v_exp_f32_e32 v93, v93
	v_exp_f32_e32 v94, v94
	v_exp_f32_e32 v95, v95
	v_exp_f32_e32 v100, v100
	v_exp_f32_e32 v101, v101
	v_exp_f32_e32 v102, v102
	v_exp_f32_e32 v103, v103
	v_sub_f32_e32 v96, 1.0, v96
	v_sub_f32_e32 v97, 1.0, v97
	v_sub_f32_e32 v98, 1.0, v98
	v_sub_f32_e32 v99, 1.0, v99
	v_mul_f32_e32 v96, v96, v92
	v_mul_f32_e32 v97, v97, v93
	v_mul_f32_e32 v98, v98, v94
	v_mul_f32_e32 v99, v99, v95
	v_lshlrev_b32_e32 v92, 16, v22
	v_and_b32_e32 v93, 0xffff0000, v22
	v_lshlrev_b32_e32 v94, 16, v23
	v_and_b32_e32 v95, 0xffff0000, v23
	v_mul_f32_e32 v92, v92, v100
	v_mul_f32_e32 v93, v93, v101
	v_mul_f32_e32 v94, v94, v102
	v_mul_f32_e32 v95, v95, v103
	v_cvt_pk_bf16_f32 v126, v126, v96
	v_cvt_pk_bf16_f32 v142, v142, v97
	v_cvt_pk_bf16_f32 v176, v176, v98
	v_cvt_pk_bf16_f32 v192, v192, v99
	v_cvt_pk_bf16_f32 v92, v92, v93
	v_cvt_pk_bf16_f32 v93, v94, v95
	v_cvt_pk_bf16_f32 v96, v96, v97
	v_cvt_pk_bf16_f32 v97, v98, v99
	global_store_dwordx2 v112, v[92:93], s[2:3]
	global_store_dwordx2 v114, v[96:97], s[2:3]
	s_add_u32 s2, s2, 0x400
	s_addc_u32 s3, s3, 0
	v_lshlrev_b32_e32 v92, 16, v24
	v_and_b32_e32 v93, 0xffff0000, v24
	v_lshlrev_b32_e32 v94, 16, v25
	v_and_b32_e32 v95, 0xffff0000, v25
	v_mul_f32_e32 v92, 0xbfb8aa3b, v92
	v_mul_f32_e32 v93, 0xbfb8aa3b, v93
	v_mul_f32_e32 v94, 0xbfb8aa3b, v94
	v_mul_f32_e32 v95, 0xbfb8aa3b, v95
	v_exp_f32_e32 v92, v92
	v_exp_f32_e32 v93, v93
	v_exp_f32_e32 v94, v94
	v_exp_f32_e32 v95, v95
	v_add_f32_e32 v92, 1.0, v92
	v_add_f32_e32 v93, 1.0, v93
	v_add_f32_e32 v94, 1.0, v94
	v_add_f32_e32 v95, 1.0, v95
	v_rcp_f32_e32 v92, v92
	v_rcp_f32_e32 v93, v93
	v_rcp_f32_e32 v94, v94
	v_rcp_f32_e32 v95, v95
	v_fma_f32 v96, v72, v92, v68
	v_fma_f32 v97, v73, v93, v69
	v_fma_f32 v98, v74, v94, v70
	v_fma_f32 v99, v75, v95, v71
	v_cmp_gt_f32_e64 s[22:23], s30, v96
	v_cmp_gt_f32_e64 s[24:25], s30, v97
	v_cmp_gt_f32_e64 s[26:27], s30, v98
	v_cmp_gt_f32_e64 s[28:29], s30, v99
	v_cndmask_b32_e64 v92, 0, 32, s[22:23]
	v_cndmask_b32_e64 v93, 0, 32, s[24:25]
	v_cndmask_b32_e64 v94, 0, 32, s[26:27]
	v_cndmask_b32_e64 v95, 0, 32, s[28:29]
	v_ldexp_f32 v92, v96, v92
	v_ldexp_f32 v93, v97, v93
	v_ldexp_f32 v94, v98, v94
	v_ldexp_f32 v95, v99, v95
	v_log_f32_e32 v92, v92
	v_log_f32_e32 v93, v93
	v_log_f32_e32 v94, v94
	v_log_f32_e32 v95, v95
	v_mul_f32_e32 v100, 0x3f317217, v92
	v_mul_f32_e32 v101, 0x3f317217, v93
	v_mul_f32_e32 v102, 0x3f317217, v94
	v_mul_f32_e32 v103, 0x3f317217, v95
	v_fma_f32 v100, v92, s31, -v100
	v_fma_f32 v101, v93, s31, -v101
	v_fma_f32 v102, v94, s31, -v102
	v_fma_f32 v103, v95, s31, -v103
	v_fmac_f32_e32 v100, 0x3377d1cf, v92
	v_fmac_f32_e32 v101, 0x3377d1cf, v93
	v_fmac_f32_e32 v102, 0x3377d1cf, v94
	v_fmac_f32_e32 v103, 0x3377d1cf, v95
	v_fmac_f32_e32 v100, 0x3f317217, v92
	v_fmac_f32_e32 v101, 0x3f317217, v93
	v_fmac_f32_e32 v102, 0x3f317217, v94
	v_fmac_f32_e32 v103, 0x3f317217, v95
	v_cmp_lt_f32_e64 vcc, |v92|, s34
	v_cndmask_b32_e32 v92, v92, v100, vcc
	v_cmp_lt_f32_e64 vcc, |v93|, s34
	v_cndmask_b32_e32 v93, v93, v101, vcc
	v_cmp_lt_f32_e64 vcc, |v94|, s34
	v_cndmask_b32_e32 v94, v94, v102, vcc
	v_cmp_lt_f32_e64 vcc, |v95|, s34
	v_cndmask_b32_e32 v95, v95, v103, vcc
	v_cndmask_b32_e64 v100, 0, v213, s[22:23]
	v_cndmask_b32_e64 v101, 0, v213, s[24:25]
	v_cndmask_b32_e64 v102, 0, v213, s[26:27]
	v_cndmask_b32_e64 v103, 0, v213, s[28:29]
	v_sub_f32_e32 v92, v92, v100
	v_sub_f32_e32 v93, v93, v101
	v_sub_f32_e32 v94, v94, v102
	v_sub_f32_e32 v95, v95, v103
	v_add_f32_e32 v64, v64, v92
	v_add_f32_e32 v65, v65, v93
	v_add_f32_e32 v66, v66, v94
	v_add_f32_e32 v67, v67, v95
	v_mul_f32_e32 v92, 0xbfb8aa3b, v64
	v_mul_f32_e32 v93, 0xbfb8aa3b, v65
	v_mul_f32_e32 v94, 0xbfb8aa3b, v66
	v_mul_f32_e32 v95, 0xbfb8aa3b, v67
	v_mul_f32_e32 v100, 0x3fb8aa3b, v64
	v_mul_f32_e32 v101, 0x3fb8aa3b, v65
	v_mul_f32_e32 v102, 0x3fb8aa3b, v66
	v_mul_f32_e32 v103, 0x3fb8aa3b, v67
; DEV u16 f2bf(float f) { return (u16)(pack2(f, f) & 0xffffu); }
; DEV float bf2f(u16 h) { return __uint_as_float(((unsigned)h) << 16); }
; DEV float sigmoid_f(float x) { return __builtin_amdgcn_rcpf(1.f + __expf(-x)); }
; DEV void phase_p15(const Params& p, int g) {
;     ...
;     P15_LOAD(0, 0);
;     P15_LOAD(1, 1);
; #pragma unroll
;     for (int j8 = 0; j8 < 8; ++j8) {
;       const int st = j8 % 3;
;       if (j8 < 6) { P15_LOAD((j8 + 2) % 3, j8 + 2); }
;     ...
;         for (int e = 0; e < 8; ++e) {
;           const int jj = j8 * 8 + e;
;           const int j = dir ? 63 - jj : jj;
;           const size_t tok = (size_t)cidx * 64 + j;
;           const float f = lb[cc] + (1.f - lb[cc]) * sigmoid_f(bf2f(xr[st][cc][e]));
;           G[cc] += __logf(f);
;           const float eg = __expf(G[cc]), ig = __expf(-G[cc]);
;           Qp[tok * 512 + c] = f2bf(bf2f(qr[st][cc][e]) * eg);
;           const u16 kk = f2bf((1.f - f) * ig);
;           Kp[tok * 512 + c] = kk;
;           kb[e] = kk;
;         }
	v_exp_f32_e32 v92, v92
	v_exp_f32_e32 v93, v93
	v_exp_f32_e32 v94, v94
	v_exp_f32_e32 v95, v95
	v_exp_f32_e32 v100, v100
	v_exp_f32_e32 v101, v101
	v_exp_f32_e32 v102, v102
	v_exp_f32_e32 v103, v103
	v_sub_f32_e32 v96, 1.0, v96
	v_sub_f32_e32 v97, 1.0, v97
	v_sub_f32_e32 v98, 1.0, v98
	v_sub_f32_e32 v99, 1.0, v99
	v_mul_f32_e32 v96, v96, v92
	v_mul_f32_e32 v97, v97, v93
	v_mul_f32_e32 v98, v98, v94
	v_mul_f32_e32 v99, v99, v95
	v_lshlrev_b32_e32 v92, 16, v26
	v_and_b32_e32 v93, 0xffff0000, v26
	v_lshlrev_b32_e32 v94, 16, v27
	v_and_b32_e32 v95, 0xffff0000, v27
	v_mul_f32_e32 v92, v92, v100
	v_mul_f32_e32 v93, v93, v101
	v_mul_f32_e32 v94, v94, v102
	v_mul_f32_e32 v95, v95, v103
	v_mov_b32_e32 v127, v96
	v_mov_b32_e32 v143, v97
	v_mov_b32_e32 v177, v98
	v_mov_b32_e32 v193, v99
	v_cvt_pk_bf16_f32 v92, v92, v93
	v_cvt_pk_bf16_f32 v93, v94, v95
	v_cvt_pk_bf16_f32 v96, v96, v97
	v_cvt_pk_bf16_f32 v97, v98, v99
	global_store_dwordx2 v112, v[92:93], s[2:3]
	global_store_dwordx2 v114, v[96:97], s[2:3]
	s_add_u32 s2, s2, 0x400
	s_addc_u32 s3, s3, 0
	v_lshlrev_b32_e32 v92, 16, v28
	v_and_b32_e32 v93, 0xffff0000, v28
	v_lshlrev_b32_e32 v94, 16, v29
	v_and_b32_e32 v95, 0xffff0000, v29
	v_mul_f32_e32 v92, 0xbfb8aa3b, v92
	v_mul_f32_e32 v93, 0xbfb8aa3b, v93
	v_mul_f32_e32 v94, 0xbfb8aa3b, v94
	v_mul_f32_e32 v95, 0xbfb8aa3b, v95
	v_exp_f32_e32 v92, v92
	v_exp_f32_e32 v93, v93
	v_exp_f32_e32 v94, v94
	v_exp_f32_e32 v95, v95
	v_add_f32_e32 v92, 1.0, v92
	v_add_f32_e32 v93, 1.0, v93
	v_add_f32_e32 v94, 1.0, v94
	v_add_f32_e32 v95, 1.0, v95
	v_rcp_f32_e32 v92, v92
	v_rcp_f32_e32 v93, v93
	v_rcp_f32_e32 v94, v94
	v_rcp_f32_e32 v95, v95
	v_fma_f32 v96, v72, v92, v68
	v_fma_f32 v97, v73, v93, v69
	v_fma_f32 v98, v74, v94, v70
	v_fma_f32 v99, v75, v95, v71
	v_cmp_gt_f32_e64 s[22:23], s30, v96
	v_cmp_gt_f32_e64 s[24:25], s30, v97
	v_cmp_gt_f32_e64 s[26:27], s30, v98
	v_cmp_gt_f32_e64 s[28:29], s30, v99
	v_cndmask_b32_e64 v92, 0, 32, s[22:23]
	v_cndmask_b32_e64 v93, 0, 32, s[24:25]
	v_cndmask_b32_e64 v94, 0, 32, s[26:27]
	v_cndmask_b32_e64 v95, 0, 32, s[28:29]
	v_ldexp_f32 v92, v96, v92
	v_ldexp_f32 v93, v97, v93
	v_ldexp_f32 v94, v98, v94
	v_ldexp_f32 v95, v99, v95
	v_log_f32_e32 v92, v92
	v_log_f32_e32 v93, v93
	v_log_f32_e32 v94, v94
	v_log_f32_e32 v95, v95
	v_mul_f32_e32 v100, 0x3f317217, v92
	v_mul_f32_e32 v101, 0x3f317217, v93
	v_mul_f32_e32 v102, 0x3f317217, v94
	v_mul_f32_e32 v103, 0x3f317217, v95
	v_fma_f32 v100, v92, s31, -v100
	v_fma_f32 v101, v93, s31, -v101
	v_fma_f32 v102, v94, s31, -v102
	v_fma_f32 v103, v95, s31, -v103
	v_fmac_f32_e32 v100, 0x3377d1cf, v92
	v_fmac_f32_e32 v101, 0x3377d1cf, v93
	v_fmac_f32_e32 v102, 0x3377d1cf, v94
	v_fmac_f32_e32 v103, 0x3377d1cf, v95
	v_fmac_f32_e32 v100, 0x3f317217, v92
	v_fmac_f32_e32 v101, 0x3f317217, v93
	v_fmac_f32_e32 v102, 0x3f317217, v94
	v_fmac_f32_e32 v103, 0x3f317217, v95
	v_cmp_lt_f32_e64 vcc, |v92|, s34
	v_cndmask_b32_e32 v92, v92, v100, vcc
	v_cmp_lt_f32_e64 vcc, |v93|, s34
	v_cndmask_b32_e32 v93, v93, v101, vcc
	v_cmp_lt_f32_e64 vcc, |v94|, s34
	v_cndmask_b32_e32 v94, v94, v102, vcc
	v_cmp_lt_f32_e64 vcc, |v95|, s34
	v_cndmask_b32_e32 v95, v95, v103, vcc
	v_cndmask_b32_e64 v100, 0, v213, s[22:23]
	v_cndmask_b32_e64 v101, 0, v213, s[24:25]
	v_cndmask_b32_e64 v102, 0, v213, s[26:27]
	v_cndmask_b32_e64 v103, 0, v213, s[28:29]
	v_sub_f32_e32 v92, v92, v100
	v_sub_f32_e32 v93, v93, v101
	v_sub_f32_e32 v94, v94, v102
	v_sub_f32_e32 v95, v95, v103
	v_add_f32_e32 v64, v64, v92
	v_add_f32_e32 v65, v65, v93
	v_add_f32_e32 v66, v66, v94
	v_add_f32_e32 v67, v67, v95
	v_mul_f32_e32 v92, 0xbfb8aa3b, v64
	v_mul_f32_e32 v93, 0xbfb8aa3b, v65
	v_mul_f32_e32 v94, 0xbfb8aa3b, v66
	v_mul_f32_e32 v95, 0xbfb8aa3b, v67
	v_mul_f32_e32 v100, 0x3fb8aa3b, v64
	v_mul_f32_e32 v101, 0x3fb8aa3b, v65
	v_mul_f32_e32 v102, 0x3fb8aa3b, v66
	v_mul_f32_e32 v103, 0x3fb8aa3b, v67
	v_exp_f32_e32 v92, v92
	v_exp_f32_e32 v93, v93
	v_exp_f32_e32 v94, v94
	v_exp_f32_e32 v95, v95
	v_exp_f32_e32 v100, v100
	v_exp_f32_e32 v101, v101
	v_exp_f32_e32 v102, v102
	v_exp_f32_e32 v103, v103
	v_sub_f32_e32 v96, 1.0, v96
	v_sub_f32_e32 v97, 1.0, v97
	v_sub_f32_e32 v98, 1.0, v98
	v_sub_f32_e32 v99, 1.0, v99
	v_mul_f32_e32 v96, v96, v92
	v_mul_f32_e32 v97, v97, v93
	v_mul_f32_e32 v98, v98, v94
	v_mul_f32_e32 v99, v99, v95
	v_lshlrev_b32_e32 v92, 16, v30
	v_and_b32_e32 v93, 0xffff0000, v30
	v_lshlrev_b32_e32 v94, 16, v31
	v_and_b32_e32 v95, 0xffff0000, v31
	v_mul_f32_e32 v92, v92, v100
	v_mul_f32_e32 v93, v93, v101
	v_mul_f32_e32 v94, v94, v102
	v_mul_f32_e32 v95, v95, v103
	v_cvt_pk_bf16_f32 v127, v127, v96
	v_cvt_pk_bf16_f32 v143, v143, v97
	v_cvt_pk_bf16_f32 v177, v177, v98
	v_cvt_pk_bf16_f32 v193, v193, v99
	v_cvt_pk_bf16_f32 v92, v92, v93
	v_cvt_pk_bf16_f32 v93, v94, v95
	v_cvt_pk_bf16_f32 v96, v96, v97
	v_cvt_pk_bf16_f32 v97, v98, v99
	global_store_dwordx2 v112, v[92:93], s[2:3]
	global_store_dwordx2 v114, v[96:97], s[2:3]
	s_add_u32 s2, s2, 0x400
	s_addc_u32 s3, s3, 0
	s_cmp_eq_u32 s35, 1
	s_cbranch_scc1 .Lp15_d0_nl2
	global_load_dwordx2 v[0:1], v113, s[0:1]
	global_load_dwordx2 v[2:3], v112, s[0:1]
	s_add_u32 s0, s0, 0x1400
	s_addc_u32 s1, s1, 0
	global_load_dwordx2 v[4:5], v113, s[0:1]
	global_load_dwordx2 v[6:7], v112, s[0:1]
	s_add_u32 s0, s0, 0x1400
	s_addc_u32 s1, s1, 0
	global_load_dwordx2 v[8:9], v113, s[0:1]
	global_load_dwordx2 v[10:11], v112, s[0:1]
	s_add_u32 s0, s0, 0x1400
	s_addc_u32 s1, s1, 0
	global_load_dwordx2 v[12:13], v113, s[0:1]
	global_load_dwordx2 v[14:15], v112, s[0:1]
	s_add_u32 s0, s0, 0x1400
	s_addc_u32 s1, s1, 0
	global_load_dwordx2 v[16:17], v113, s[0:1]
	global_load_dwordx2 v[18:19], v112, s[0:1]
	s_add_u32 s0, s0, 0x1400
	s_addc_u32 s1, s1, 0
	global_load_dwordx2 v[20:21], v113, s[0:1]
	global_load_dwordx2 v[22:23], v112, s[0:1]
	s_add_u32 s0, s0, 0x1400
	s_addc_u32 s1, s1, 0
	global_load_dwordx2 v[24:25], v113, s[0:1]
	global_load_dwordx2 v[26:27], v112, s[0:1]
	s_add_u32 s0, s0, 0x1400
	s_addc_u32 s1, s1, 0
	global_load_dwordx2 v[28:29], v113, s[0:1]
	global_load_dwordx2 v[30:31], v112, s[0:1]
	s_add_u32 s0, s0, 0x1400
	s_addc_u32 s1, s1, 0
; DEV u16 f2bf(float f) { return (u16)(pack2(f, f) & 0xffffu); }
; DEV float bf2f(u16 h) { return __uint_as_float(((unsigned)h) << 16); }
; DEV float sigmoid_f(float x) { return __builtin_amdgcn_rcpf(1.f + __expf(-x)); }
; DEV void phase_p15(const Params& p, int g) {
;     ...
;         for (int e = 0; e < 8; ++e) {
;           const int jj = j8 * 8 + e;
;           const int j = dir ? 63 - jj : jj;
;           const size_t tok = (size_t)cidx * 64 + j;
;           const float f = lb[cc] + (1.f - lb[cc]) * sigmoid_f(bf2f(xr[st][cc][e]));
;           G[cc] += __logf(f);
;           const float eg = __expf(G[cc]), ig = __expf(-G[cc]);
;           Qp[tok * 512 + c] = f2bf(bf2f(qr[st][cc][e]) * eg);
;           const u16 kk = f2bf((1.f - f) * ig);
;           Kp[tok * 512 + c] = kk;
;           kb[e] = kk;
;         }
.Lp15_d0_nl2:
	s_waitcnt vmcnt(16)
	v_lshlrev_b32_e32 v92, 16, v32
	v_and_b32_e32 v93, 0xffff0000, v32
	v_lshlrev_b32_e32 v94, 16, v33
	v_and_b32_e32 v95, 0xffff0000, v33
	v_mul_f32_e32 v92, 0xbfb8aa3b, v92
	v_mul_f32_e32 v93, 0xbfb8aa3b, v93
	v_mul_f32_e32 v94, 0xbfb8aa3b, v94
	v_mul_f32_e32 v95, 0xbfb8aa3b, v95
	v_exp_f32_e32 v92, v92
	v_exp_f32_e32 v93, v93
	v_exp_f32_e32 v94, v94
	v_exp_f32_e32 v95, v95
	v_add_f32_e32 v92, 1.0, v92
	v_add_f32_e32 v93, 1.0, v93
	v_add_f32_e32 v94, 1.0, v94
	v_add_f32_e32 v95, 1.0, v95
	v_rcp_f32_e32 v92, v92
	v_rcp_f32_e32 v93, v93
	v_rcp_f32_e32 v94, v94
	v_rcp_f32_e32 v95, v95
	v_fma_f32 v96, v72, v92, v68
	v_fma_f32 v97, v73, v93, v69
	v_fma_f32 v98, v74, v94, v70
	v_fma_f32 v99, v75, v95, v71
	v_cmp_gt_f32_e64 s[22:23], s30, v96
	v_cmp_gt_f32_e64 s[24:25], s30, v97
	v_cmp_gt_f32_e64 s[26:27], s30, v98
	v_cmp_gt_f32_e64 s[28:29], s30, v99
	v_cndmask_b32_e64 v92, 0, 32, s[22:23]
	v_cndmask_b32_e64 v93, 0, 32, s[24:25]
	v_cndmask_b32_e64 v94, 0, 32, s[26:27]
	v_cndmask_b32_e64 v95, 0, 32, s[28:29]
	v_ldexp_f32 v92, v96, v92
	v_ldexp_f32 v93, v97, v93
	v_ldexp_f32 v94, v98, v94
	v_ldexp_f32 v95, v99, v95
	v_log_f32_e32 v92, v92
	v_log_f32_e32 v93, v93
	v_log_f32_e32 v94, v94
	v_log_f32_e32 v95, v95
	v_mul_f32_e32 v100, 0x3f317217, v92
	v_mul_f32_e32 v101, 0x3f317217, v93
	v_mul_f32_e32 v102, 0x3f317217, v94
	v_mul_f32_e32 v103, 0x3f317217, v95
	v_fma_f32 v100, v92, s31, -v100
	v_fma_f32 v101, v93, s31, -v101
	v_fma_f32 v102, v94, s31, -v102
	v_fma_f32 v103, v95, s31, -v103
	v_fmac_f32_e32 v100, 0x3377d1cf, v92
	v_fmac_f32_e32 v101, 0x3377d1cf, v93
	v_fmac_f32_e32 v102, 0x3377d1cf, v94
	v_fmac_f32_e32 v103, 0x3377d1cf, v95
	v_fmac_f32_e32 v100, 0x3f317217, v92
	v_fmac_f32_e32 v101, 0x3f317217, v93
	v_fmac_f32_e32 v102, 0x3f317217, v94
	v_fmac_f32_e32 v103, 0x3f317217, v95
	v_cmp_lt_f32_e64 vcc, |v92|, s34
	v_cndmask_b32_e32 v92, v92, v100, vcc
	v_cmp_lt_f32_e64 vcc, |v93|, s34
	v_cndmask_b32_e32 v93, v93, v101, vcc
	v_cmp_lt_f32_e64 vcc, |v94|, s34
	v_cndmask_b32_e32 v94, v94, v102, vcc
	v_cmp_lt_f32_e64 vcc, |v95|, s34
	v_cndmask_b32_e32 v95, v95, v103, vcc
	v_cndmask_b32_e64 v100, 0, v213, s[22:23]
	v_cndmask_b32_e64 v101, 0, v213, s[24:25]
	v_cndmask_b32_e64 v102, 0, v213, s[26:27]
	v_cndmask_b32_e64 v103, 0, v213, s[28:29]
	v_sub_f32_e32 v92, v92, v100
	v_sub_f32_e32 v93, v93, v101
	v_sub_f32_e32 v94, v94, v102
	v_sub_f32_e32 v95, v95, v103
	v_add_f32_e32 v64, v64, v92
	v_add_f32_e32 v65, v65, v93
	v_add_f32_e32 v66, v66, v94
	v_add_f32_e32 v67, v67, v95
	v_mul_f32_e32 v92, 0xbfb8aa3b, v64
	v_mul_f32_e32 v93, 0xbfb8aa3b, v65
	v_mul_f32_e32 v94, 0xbfb8aa3b, v66
	v_mul_f32_e32 v95, 0xbfb8aa3b, v67
	v_mul_f32_e32 v100, 0x3fb8aa3b, v64
	v_mul_f32_e32 v101, 0x3fb8aa3b, v65
	v_mul_f32_e32 v102, 0x3fb8aa3b, v66
	v_mul_f32_e32 v103, 0x3fb8aa3b, v67
	v_exp_f32_e32 v92, v92
	v_exp_f32_e32 v93, v93
	v_exp_f32_e32 v94, v94
	v_exp_f32_e32 v95, v95
	v_exp_f32_e32 v100, v100
	v_exp_f32_e32 v101, v101
	v_exp_f32_e32 v102, v102
	v_exp_f32_e32 v103, v103
	v_sub_f32_e32 v96, 1.0, v96
	v_sub_f32_e32 v97, 1.0, v97
	v_sub_f32_e32 v98, 1.0, v98
	v_sub_f32_e32 v99, 1.0, v99
	v_mul_f32_e32 v96, v96, v92
	v_mul_f32_e32 v97, v97, v93
	v_mul_f32_e32 v98, v98, v94
	v_mul_f32_e32 v99, v99, v95
	v_lshlrev_b32_e32 v92, 16, v34
	v_and_b32_e32 v93, 0xffff0000, v34
	v_lshlrev_b32_e32 v94, 16, v35
	v_and_b32_e32 v95, 0xffff0000, v35
	v_mul_f32_e32 v92, v92, v100
	v_mul_f32_e32 v93, v93, v101
	v_mul_f32_e32 v94, v94, v102
	v_mul_f32_e32 v95, v95, v103
	v_mov_b32_e32 v128, v96
	v_mov_b32_e32 v144, v97
	v_mov_b32_e32 v178, v98
	v_mov_b32_e32 v194, v99
	v_cvt_pk_bf16_f32 v92, v92, v93
	v_cvt_pk_bf16_f32 v93, v94, v95
	v_cvt_pk_bf16_f32 v96, v96, v97
	v_cvt_pk_bf16_f32 v97, v98, v99
	global_store_dwordx2 v112, v[92:93], s[2:3]
	global_store_dwordx2 v114, v[96:97], s[2:3]
	s_add_u32 s2, s2, 0x400
	s_addc_u32 s3, s3, 0
	v_lshlrev_b32_e32 v92, 16, v36
	v_and_b32_e32 v93, 0xffff0000, v36
	v_lshlrev_b32_e32 v94, 16, v37
	v_and_b32_e32 v95, 0xffff0000, v37
	v_mul_f32_e32 v92, 0xbfb8aa3b, v92
	v_mul_f32_e32 v93, 0xbfb8aa3b, v93
	v_mul_f32_e32 v94, 0xbfb8aa3b, v94
	v_mul_f32_e32 v95, 0xbfb8aa3b, v95
	v_exp_f32_e32 v92, v92
	v_exp_f32_e32 v93, v93
	v_exp_f32_e32 v94, v94
	v_exp_f32_e32 v95, v95
	v_add_f32_e32 v92, 1.0, v92
	v_add_f32_e32 v93, 1.0, v93
	v_add_f32_e32 v94, 1.0, v94
	v_add_f32_e32 v95, 1.0, v95
	v_rcp_f32_e32 v92, v92
	v_rcp_f32_e32 v93, v93
	v_rcp_f32_e32 v94, v94
	v_rcp_f32_e32 v95, v95
	v_fma_f32 v96, v72, v92, v68
	v_fma_f32 v97, v73, v93, v69
	v_fma_f32 v98, v74, v94, v70
	v_fma_f32 v99, v75, v95, v71
	v_cmp_gt_f32_e64 s[22:23], s30, v96
	v_cmp_gt_f32_e64 s[24:25], s30, v97
	v_cmp_gt_f32_e64 s[26:27], s30, v98
	v_cmp_gt_f32_e64 s[28:29], s30, v99
	v_cndmask_b32_e64 v92, 0, 32, s[22:23]
	v_cndmask_b32_e64 v93, 0, 32, s[24:25]
	v_cndmask_b32_e64 v94, 0, 32, s[26:27]
	v_cndmask_b32_e64 v95, 0, 32, s[28:29]
	v_ldexp_f32 v92, v96, v92
	v_ldexp_f32 v93, v97, v93
	v_ldexp_f32 v94, v98, v94
	v_ldexp_f32 v95, v99, v95
	v_log_f32_e32 v92, v92
	v_log_f32_e32 v93, v93
	v_log_f32_e32 v94, v94
	v_log_f32_e32 v95, v95
	v_mul_f32_e32 v100, 0x3f317217, v92
	v_mul_f32_e32 v101, 0x3f317217, v93
	v_mul_f32_e32 v102, 0x3f317217, v94
	v_mul_f32_e32 v103, 0x3f317217, v95
	v_fma_f32 v100, v92, s31, -v100
	v_fma_f32 v101, v93, s31, -v101
	v_fma_f32 v102, v94, s31, -v102
	v_fma_f32 v103, v95, s31, -v103
	v_fmac_f32_e32 v100, 0x3377d1cf, v92
	v_fmac_f32_e32 v101, 0x3377d1cf, v93
	v_fmac_f32_e32 v102, 0x3377d1cf, v94
	v_fmac_f32_e32 v103, 0x3377d1cf, v95
	v_fmac_f32_e32 v100, 0x3f317217, v92
	v_fmac_f32_e32 v101, 0x3f317217, v93
	v_fmac_f32_e32 v102, 0x3f317217, v94
; DEV u16 f2bf(float f) { return (u16)(pack2(f, f) & 0xffffu); }
; DEV float bf2f(u16 h) { return __uint_as_float(((unsigned)h) << 16); }
; DEV float sigmoid_f(float x) { return __builtin_amdgcn_rcpf(1.f + __expf(-x)); }
; DEV void phase_p15(const Params& p, int g) {
;     ...
;         for (int e = 0; e < 8; ++e) {
;           const int jj = j8 * 8 + e;
;           const int j = dir ? 63 - jj : jj;
;           const size_t tok = (size_t)cidx * 64 + j;
;           const float f = lb[cc] + (1.f - lb[cc]) * sigmoid_f(bf2f(xr[st][cc][e]));
;           G[cc] += __logf(f);
;           const float eg = __expf(G[cc]), ig = __expf(-G[cc]);
;           Qp[tok * 512 + c] = f2bf(bf2f(qr[st][cc][e]) * eg);
;           const u16 kk = f2bf((1.f - f) * ig);
;           Kp[tok * 512 + c] = kk;
;           kb[e] = kk;
;         }
	v_fmac_f32_e32 v103, 0x3f317217, v95
	v_cmp_lt_f32_e64 vcc, |v92|, s34
	v_cndmask_b32_e32 v92, v92, v100, vcc
	v_cmp_lt_f32_e64 vcc, |v93|, s34
	v_cndmask_b32_e32 v93, v93, v101, vcc
	v_cmp_lt_f32_e64 vcc, |v94|, s34
	v_cndmask_b32_e32 v94, v94, v102, vcc
	v_cmp_lt_f32_e64 vcc, |v95|, s34
	v_cndmask_b32_e32 v95, v95, v103, vcc
	v_cndmask_b32_e64 v100, 0, v213, s[22:23]
	v_cndmask_b32_e64 v101, 0, v213, s[24:25]
	v_cndmask_b32_e64 v102, 0, v213, s[26:27]
	v_cndmask_b32_e64 v103, 0, v213, s[28:29]
	v_sub_f32_e32 v92, v92, v100
	v_sub_f32_e32 v93, v93, v101
	v_sub_f32_e32 v94, v94, v102
	v_sub_f32_e32 v95, v95, v103
	v_add_f32_e32 v64, v64, v92
	v_add_f32_e32 v65, v65, v93
	v_add_f32_e32 v66, v66, v94
	v_add_f32_e32 v67, v67, v95
	v_mul_f32_e32 v92, 0xbfb8aa3b, v64
	v_mul_f32_e32 v93, 0xbfb8aa3b, v65
	v_mul_f32_e32 v94, 0xbfb8aa3b, v66
	v_mul_f32_e32 v95, 0xbfb8aa3b, v67
	v_mul_f32_e32 v100, 0x3fb8aa3b, v64
	v_mul_f32_e32 v101, 0x3fb8aa3b, v65
	v_mul_f32_e32 v102, 0x3fb8aa3b, v66
	v_mul_f32_e32 v103, 0x3fb8aa3b, v67
	v_exp_f32_e32 v92, v92
	v_exp_f32_e32 v93, v93
	v_exp_f32_e32 v94, v94
	v_exp_f32_e32 v95, v95
	v_exp_f32_e32 v100, v100
	v_exp_f32_e32 v101, v101
	v_exp_f32_e32 v102, v102
	v_exp_f32_e32 v103, v103
	v_sub_f32_e32 v96, 1.0, v96
	v_sub_f32_e32 v97, 1.0, v97
	v_sub_f32_e32 v98, 1.0, v98
	v_sub_f32_e32 v99, 1.0, v99
	v_mul_f32_e32 v96, v96, v92
	v_mul_f32_e32 v97, v97, v93
	v_mul_f32_e32 v98, v98, v94
	v_mul_f32_e32 v99, v99, v95
	v_lshlrev_b32_e32 v92, 16, v38
	v_and_b32_e32 v93, 0xffff0000, v38
	v_lshlrev_b32_e32 v94, 16, v39
	v_and_b32_e32 v95, 0xffff0000, v39
	v_mul_f32_e32 v92, v92, v100
	v_mul_f32_e32 v93, v93, v101
	v_mul_f32_e32 v94, v94, v102
	v_mul_f32_e32 v95, v95, v103
	v_cvt_pk_bf16_f32 v128, v128, v96
	v_cvt_pk_bf16_f32 v144, v144, v97
	v_cvt_pk_bf16_f32 v178, v178, v98
	v_cvt_pk_bf16_f32 v194, v194, v99
	v_cvt_pk_bf16_f32 v92, v92, v93
	v_cvt_pk_bf16_f32 v93, v94, v95
	v_cvt_pk_bf16_f32 v96, v96, v97
	v_cvt_pk_bf16_f32 v97, v98, v99
	global_store_dwordx2 v112, v[92:93], s[2:3]
	global_store_dwordx2 v114, v[96:97], s[2:3]
	s_add_u32 s2, s2, 0x400
	s_addc_u32 s3, s3, 0
	v_lshlrev_b32_e32 v92, 16, v40
	v_and_b32_e32 v93, 0xffff0000, v40
	v_lshlrev_b32_e32 v94, 16, v41
	v_and_b32_e32 v95, 0xffff0000, v41
	v_mul_f32_e32 v92, 0xbfb8aa3b, v92
	v_mul_f32_e32 v93, 0xbfb8aa3b, v93
	v_mul_f32_e32 v94, 0xbfb8aa3b, v94
	v_mul_f32_e32 v95, 0xbfb8aa3b, v95
	v_exp_f32_e32 v92, v92
	v_exp_f32_e32 v93, v93
	v_exp_f32_e32 v94, v94
	v_exp_f32_e32 v95, v95
	v_add_f32_e32 v92, 1.0, v92
	v_add_f32_e32 v93, 1.0, v93
	v_add_f32_e32 v94, 1.0, v94
	v_add_f32_e32 v95, 1.0, v95
	v_rcp_f32_e32 v92, v92
	v_rcp_f32_e32 v93, v93
	v_rcp_f32_e32 v94, v94
	v_rcp_f32_e32 v95, v95
	v_fma_f32 v96, v72, v92, v68
	v_fma_f32 v97, v73, v93, v69
	v_fma_f32 v98, v74, v94, v70
	v_fma_f32 v99, v75, v95, v71
	v_cmp_gt_f32_e64 s[22:23], s30, v96
	v_cmp_gt_f32_e64 s[24:25], s30, v97
	v_cmp_gt_f32_e64 s[26:27], s30, v98
	v_cmp_gt_f32_e64 s[28:29], s30, v99
	v_cndmask_b32_e64 v92, 0, 32, s[22:23]
	v_cndmask_b32_e64 v93, 0, 32, s[24:25]
	v_cndmask_b32_e64 v94, 0, 32, s[26:27]
	v_cndmask_b32_e64 v95, 0, 32, s[28:29]
	v_ldexp_f32 v92, v96, v92
	v_ldexp_f32 v93, v97, v93
	v_ldexp_f32 v94, v98, v94
	v_ldexp_f32 v95, v99, v95
	v_log_f32_e32 v92, v92
	v_log_f32_e32 v93, v93
	v_log_f32_e32 v94, v94
	v_log_f32_e32 v95, v95
	v_mul_f32_e32 v100, 0x3f317217, v92
	v_mul_f32_e32 v101, 0x3f317217, v93
	v_mul_f32_e32 v102, 0x3f317217, v94
	v_mul_f32_e32 v103, 0x3f317217, v95
	v_fma_f32 v100, v92, s31, -v100
	v_fma_f32 v101, v93, s31, -v101
	v_fma_f32 v102, v94, s31, -v102
	v_fma_f32 v103, v95, s31, -v103
	v_fmac_f32_e32 v100, 0x3377d1cf, v92
	v_fmac_f32_e32 v101, 0x3377d1cf, v93
	v_fmac_f32_e32 v102, 0x3377d1cf, v94
	v_fmac_f32_e32 v103, 0x3377d1cf, v95
	v_fmac_f32_e32 v100, 0x3f317217, v92
	v_fmac_f32_e32 v101, 0x3f317217, v93
	v_fmac_f32_e32 v102, 0x3f317217, v94
	v_fmac_f32_e32 v103, 0x3f317217, v95
	v_cmp_lt_f32_e64 vcc, |v92|, s34
	v_cndmask_b32_e32 v92, v92, v100, vcc
	v_cmp_lt_f32_e64 vcc, |v93|, s34
	v_cndmask_b32_e32 v93, v93, v101, vcc
	v_cmp_lt_f32_e64 vcc, |v94|, s34
	v_cndmask_b32_e32 v94, v94, v102, vcc
	v_cmp_lt_f32_e64 vcc, |v95|, s34
	v_cndmask_b32_e32 v95, v95, v103, vcc
	v_cndmask_b32_e64 v100, 0, v213, s[22:23]
	v_cndmask_b32_e64 v101, 0, v213, s[24:25]
	v_cndmask_b32_e64 v102, 0, v213, s[26:27]
	v_cndmask_b32_e64 v103, 0, v213, s[28:29]
	v_sub_f32_e32 v92, v92, v100
	v_sub_f32_e32 v93, v93, v101
	v_sub_f32_e32 v94, v94, v102
	v_sub_f32_e32 v95, v95, v103
	v_add_f32_e32 v64, v64, v92
	v_add_f32_e32 v65, v65, v93
	v_add_f32_e32 v66, v66, v94
	v_add_f32_e32 v67, v67, v95
	v_mul_f32_e32 v92, 0xbfb8aa3b, v64
	v_mul_f32_e32 v93, 0xbfb8aa3b, v65
	v_mul_f32_e32 v94, 0xbfb8aa3b, v66
	v_mul_f32_e32 v95, 0xbfb8aa3b, v67
	v_mul_f32_e32 v100, 0x3fb8aa3b, v64
	v_mul_f32_e32 v101, 0x3fb8aa3b, v65
	v_mul_f32_e32 v102, 0x3fb8aa3b, v66
	v_mul_f32_e32 v103, 0x3fb8aa3b, v67
	v_exp_f32_e32 v92, v92
	v_exp_f32_e32 v93, v93
	v_exp_f32_e32 v94, v94
	v_exp_f32_e32 v95, v95
	v_exp_f32_e32 v100, v100
	v_exp_f32_e32 v101, v101
	v_exp_f32_e32 v102, v102
	v_exp_f32_e32 v103, v103
	v_sub_f32_e32 v96, 1.0, v96
	v_sub_f32_e32 v97, 1.0, v97
	v_sub_f32_e32 v98, 1.0, v98
	v_sub_f32_e32 v99, 1.0, v99
	v_mul_f32_e32 v96, v96, v92
	v_mul_f32_e32 v97, v97, v93
	v_mul_f32_e32 v98, v98, v94
	v_mul_f32_e32 v99, v99, v95
	v_lshlrev_b32_e32 v92, 16, v42
	v_and_b32_e32 v93, 0xffff0000, v42
	v_lshlrev_b32_e32 v94, 16, v43
	v_and_b32_e32 v95, 0xffff0000, v43
	v_mul_f32_e32 v92, v92, v100
	v_mul_f32_e32 v93, v93, v101
	v_mul_f32_e32 v94, v94, v102
	v_mul_f32_e32 v95, v95, v103
	v_mov_b32_e32 v129, v96
; DEV u16 f2bf(float f) { return (u16)(pack2(f, f) & 0xffffu); }
; DEV float bf2f(u16 h) { return __uint_as_float(((unsigned)h) << 16); }
; DEV float sigmoid_f(float x) { return __builtin_amdgcn_rcpf(1.f + __expf(-x)); }
; DEV void phase_p15(const Params& p, int g) {
;     ...
;           const float f = lb[cc] + (1.f - lb[cc]) * sigmoid_f(bf2f(xr[st][cc][e]));
;           G[cc] += __logf(f);
;           const float eg = __expf(G[cc]), ig = __expf(-G[cc]);
;           Qp[tok * 512 + c] = f2bf(bf2f(qr[st][cc][e]) * eg);
;           const u16 kk = f2bf((1.f - f) * ig);
;           Kp[tok * 512 + c] = kk;
;           kb[e] = kk;
;         }
;         const int s0 = dir ? 56 - 8 * j8 : 8 * j8;
;         uint4 w;
;         w.x = dir ? (kb[7] | (kb[6] << 16)) : (kb[0] | (kb[1] << 16));
;         w.y = dir ? (kb[5] | (kb[4] << 16)) : (kb[2] | (kb[3] << 16));
;         w.z = dir ? (kb[3] | (kb[2] << 16)) : (kb[4] | (kb[5] << 16));
;         w.w = dir ? (kb[1] | (kb[0] << 16)) : (kb[6] | (kb[7] << 16));
	v_mov_b32_e32 v145, v97
	v_mov_b32_e32 v179, v98
	v_mov_b32_e32 v195, v99
	v_cvt_pk_bf16_f32 v92, v92, v93
	v_cvt_pk_bf16_f32 v93, v94, v95
	v_cvt_pk_bf16_f32 v96, v96, v97
	v_cvt_pk_bf16_f32 v97, v98, v99
	global_store_dwordx2 v112, v[92:93], s[2:3]
	global_store_dwordx2 v114, v[96:97], s[2:3]
	s_add_u32 s2, s2, 0x400
	s_addc_u32 s3, s3, 0
	v_lshlrev_b32_e32 v92, 16, v44
	v_and_b32_e32 v93, 0xffff0000, v44
	v_lshlrev_b32_e32 v94, 16, v45
	v_and_b32_e32 v95, 0xffff0000, v45
	v_mul_f32_e32 v92, 0xbfb8aa3b, v92
	v_mul_f32_e32 v93, 0xbfb8aa3b, v93
	v_mul_f32_e32 v94, 0xbfb8aa3b, v94
	v_mul_f32_e32 v95, 0xbfb8aa3b, v95
	v_exp_f32_e32 v92, v92
	v_exp_f32_e32 v93, v93
	v_exp_f32_e32 v94, v94
	v_exp_f32_e32 v95, v95
	v_add_f32_e32 v92, 1.0, v92
	v_add_f32_e32 v93, 1.0, v93
	v_add_f32_e32 v94, 1.0, v94
	v_add_f32_e32 v95, 1.0, v95
	v_rcp_f32_e32 v92, v92
	v_rcp_f32_e32 v93, v93
	v_rcp_f32_e32 v94, v94
	v_rcp_f32_e32 v95, v95
	v_fma_f32 v96, v72, v92, v68
	v_fma_f32 v97, v73, v93, v69
	v_fma_f32 v98, v74, v94, v70
	v_fma_f32 v99, v75, v95, v71
	v_cmp_gt_f32_e64 s[22:23], s30, v96
	v_cmp_gt_f32_e64 s[24:25], s30, v97
	v_cmp_gt_f32_e64 s[26:27], s30, v98
	v_cmp_gt_f32_e64 s[28:29], s30, v99
	v_cndmask_b32_e64 v92, 0, 32, s[22:23]
	v_cndmask_b32_e64 v93, 0, 32, s[24:25]
	v_cndmask_b32_e64 v94, 0, 32, s[26:27]
	v_cndmask_b32_e64 v95, 0, 32, s[28:29]
	v_ldexp_f32 v92, v96, v92
	v_ldexp_f32 v93, v97, v93
	v_ldexp_f32 v94, v98, v94
	v_ldexp_f32 v95, v99, v95
	v_log_f32_e32 v92, v92
	v_log_f32_e32 v93, v93
	v_log_f32_e32 v94, v94
	v_log_f32_e32 v95, v95
	v_mul_f32_e32 v100, 0x3f317217, v92
	v_mul_f32_e32 v101, 0x3f317217, v93
	v_mul_f32_e32 v102, 0x3f317217, v94
	v_mul_f32_e32 v103, 0x3f317217, v95
	v_fma_f32 v100, v92, s31, -v100
	v_fma_f32 v101, v93, s31, -v101
	v_fma_f32 v102, v94, s31, -v102
	v_fma_f32 v103, v95, s31, -v103
	v_fmac_f32_e32 v100, 0x3377d1cf, v92
	v_fmac_f32_e32 v101, 0x3377d1cf, v93
	v_fmac_f32_e32 v102, 0x3377d1cf, v94
	v_fmac_f32_e32 v103, 0x3377d1cf, v95
	v_fmac_f32_e32 v100, 0x3f317217, v92
	v_fmac_f32_e32 v101, 0x3f317217, v93
	v_fmac_f32_e32 v102, 0x3f317217, v94
	v_fmac_f32_e32 v103, 0x3f317217, v95
	v_cmp_lt_f32_e64 vcc, |v92|, s34
	v_cndmask_b32_e32 v92, v92, v100, vcc
	v_cmp_lt_f32_e64 vcc, |v93|, s34
	v_cndmask_b32_e32 v93, v93, v101, vcc
	v_cmp_lt_f32_e64 vcc, |v94|, s34
	v_cndmask_b32_e32 v94, v94, v102, vcc
	v_cmp_lt_f32_e64 vcc, |v95|, s34
	v_cndmask_b32_e32 v95, v95, v103, vcc
	v_cndmask_b32_e64 v100, 0, v213, s[22:23]
	v_cndmask_b32_e64 v101, 0, v213, s[24:25]
	v_cndmask_b32_e64 v102, 0, v213, s[26:27]
	v_cndmask_b32_e64 v103, 0, v213, s[28:29]
	v_sub_f32_e32 v92, v92, v100
	v_sub_f32_e32 v93, v93, v101
	v_sub_f32_e32 v94, v94, v102
	v_sub_f32_e32 v95, v95, v103
	v_add_f32_e32 v64, v64, v92
	v_add_f32_e32 v65, v65, v93
	v_add_f32_e32 v66, v66, v94
	v_add_f32_e32 v67, v67, v95
	v_mul_f32_e32 v92, 0xbfb8aa3b, v64
	v_mul_f32_e32 v93, 0xbfb8aa3b, v65
	v_mul_f32_e32 v94, 0xbfb8aa3b, v66
	v_mul_f32_e32 v95, 0xbfb8aa3b, v67
	v_mul_f32_e32 v100, 0x3fb8aa3b, v64
	v_mul_f32_e32 v101, 0x3fb8aa3b, v65
	v_mul_f32_e32 v102, 0x3fb8aa3b, v66
	v_mul_f32_e32 v103, 0x3fb8aa3b, v67
	v_exp_f32_e32 v92, v92
	v_exp_f32_e32 v93, v93
	v_exp_f32_e32 v94, v94
	v_exp_f32_e32 v95, v95
	v_exp_f32_e32 v100, v100
	v_exp_f32_e32 v101, v101
	v_exp_f32_e32 v102, v102
	v_exp_f32_e32 v103, v103
	v_sub_f32_e32 v96, 1.0, v96
	v_sub_f32_e32 v97, 1.0, v97
	v_sub_f32_e32 v98, 1.0, v98
	v_sub_f32_e32 v99, 1.0, v99
	v_mul_f32_e32 v96, v96, v92
	v_mul_f32_e32 v97, v97, v93
	v_mul_f32_e32 v98, v98, v94
	v_mul_f32_e32 v99, v99, v95
	v_lshlrev_b32_e32 v92, 16, v46
	v_and_b32_e32 v93, 0xffff0000, v46
	v_lshlrev_b32_e32 v94, 16, v47
	v_and_b32_e32 v95, 0xffff0000, v47
	v_mul_f32_e32 v92, v92, v100
	v_mul_f32_e32 v93, v93, v101
	v_mul_f32_e32 v94, v94, v102
	v_mul_f32_e32 v95, v95, v103
	v_cvt_pk_bf16_f32 v129, v129, v96
	v_cvt_pk_bf16_f32 v145, v145, v97
	v_cvt_pk_bf16_f32 v179, v179, v98
	v_cvt_pk_bf16_f32 v195, v195, v99
	v_cvt_pk_bf16_f32 v92, v92, v93
	v_cvt_pk_bf16_f32 v93, v94, v95
	v_cvt_pk_bf16_f32 v96, v96, v97
	v_cvt_pk_bf16_f32 v97, v98, v99
	global_store_dwordx2 v112, v[92:93], s[2:3]
	global_store_dwordx2 v114, v[96:97], s[2:3]
	s_add_u32 s2, s2, 0x400
	s_addc_u32 s3, s3, 0
	v_lshlrev_b32_e32 v92, 16, v48
	v_and_b32_e32 v93, 0xffff0000, v48
	v_lshlrev_b32_e32 v94, 16, v49
	v_and_b32_e32 v95, 0xffff0000, v49
	v_mul_f32_e32 v92, 0xbfb8aa3b, v92
	v_mul_f32_e32 v93, 0xbfb8aa3b, v93
	v_mul_f32_e32 v94, 0xbfb8aa3b, v94
	v_mul_f32_e32 v95, 0xbfb8aa3b, v95
	v_exp_f32_e32 v92, v92
	v_exp_f32_e32 v93, v93
	v_exp_f32_e32 v94, v94
	v_exp_f32_e32 v95, v95
	v_add_f32_e32 v92, 1.0, v92
	v_add_f32_e32 v93, 1.0, v93
	v_add_f32_e32 v94, 1.0, v94
	v_add_f32_e32 v95, 1.0, v95
	v_rcp_f32_e32 v92, v92
	v_rcp_f32_e32 v93, v93
	v_rcp_f32_e32 v94, v94
	v_rcp_f32_e32 v95, v95
	v_fma_f32 v96, v72, v92, v68
	v_fma_f32 v97, v73, v93, v69
	v_fma_f32 v98, v74, v94, v70
	v_fma_f32 v99, v75, v95, v71
	v_cmp_gt_f32_e64 s[22:23], s30, v96
	v_cmp_gt_f32_e64 s[24:25], s30, v97
	v_cmp_gt_f32_e64 s[26:27], s30, v98
	v_cmp_gt_f32_e64 s[28:29], s30, v99
	v_cndmask_b32_e64 v92, 0, 32, s[22:23]
	v_cndmask_b32_e64 v93, 0, 32, s[24:25]
	v_cndmask_b32_e64 v94, 0, 32, s[26:27]
	v_cndmask_b32_e64 v95, 0, 32, s[28:29]
	v_ldexp_f32 v92, v96, v92
	v_ldexp_f32 v93, v97, v93
	v_ldexp_f32 v94, v98, v94
	v_ldexp_f32 v95, v99, v95
	v_log_f32_e32 v92, v92
	v_log_f32_e32 v93, v93
	v_log_f32_e32 v94, v94
	v_log_f32_e32 v95, v95
	v_mul_f32_e32 v100, 0x3f317217, v92
	v_mul_f32_e32 v101, 0x3f317217, v93
	v_mul_f32_e32 v102, 0x3f317217, v94
	v_mul_f32_e32 v103, 0x3f317217, v95
	v_fma_f32 v100, v92, s31, -v100
; DEV u16 f2bf(float f) { return (u16)(pack2(f, f) & 0xffffu); }
; DEV float bf2f(u16 h) { return __uint_as_float(((unsigned)h) << 16); }
; DEV float sigmoid_f(float x) { return __builtin_amdgcn_rcpf(1.f + __expf(-x)); }
; DEV void phase_p15(const Params& p, int g) {
;     ...
;           const float f = lb[cc] + (1.f - lb[cc]) * sigmoid_f(bf2f(xr[st][cc][e]));
;           G[cc] += __logf(f);
;           const float eg = __expf(G[cc]), ig = __expf(-G[cc]);
;           Qp[tok * 512 + c] = f2bf(bf2f(qr[st][cc][e]) * eg);
;           const u16 kk = f2bf((1.f - f) * ig);
;           Kp[tok * 512 + c] = kk;
;           kb[e] = kk;
;         }
;         const int s0 = dir ? 56 - 8 * j8 : 8 * j8;
;         uint4 w;
;         w.x = dir ? (kb[7] | (kb[6] << 16)) : (kb[0] | (kb[1] << 16));
;         w.y = dir ? (kb[5] | (kb[4] << 16)) : (kb[2] | (kb[3] << 16));
;         w.z = dir ? (kb[3] | (kb[2] << 16)) : (kb[4] | (kb[5] << 16));
;         w.w = dir ? (kb[1] | (kb[0] << 16)) : (kb[6] | (kb[7] << 16));
	v_fma_f32 v101, v93, s31, -v101
	v_fma_f32 v102, v94, s31, -v102
	v_fma_f32 v103, v95, s31, -v103
	v_fmac_f32_e32 v100, 0x3377d1cf, v92
	v_fmac_f32_e32 v101, 0x3377d1cf, v93
	v_fmac_f32_e32 v102, 0x3377d1cf, v94
	v_fmac_f32_e32 v103, 0x3377d1cf, v95
	v_fmac_f32_e32 v100, 0x3f317217, v92
	v_fmac_f32_e32 v101, 0x3f317217, v93
	v_fmac_f32_e32 v102, 0x3f317217, v94
	v_fmac_f32_e32 v103, 0x3f317217, v95
	v_cmp_lt_f32_e64 vcc, |v92|, s34
	v_cndmask_b32_e32 v92, v92, v100, vcc
	v_cmp_lt_f32_e64 vcc, |v93|, s34
	v_cndmask_b32_e32 v93, v93, v101, vcc
	v_cmp_lt_f32_e64 vcc, |v94|, s34
	v_cndmask_b32_e32 v94, v94, v102, vcc
	v_cmp_lt_f32_e64 vcc, |v95|, s34
	v_cndmask_b32_e32 v95, v95, v103, vcc
	v_cndmask_b32_e64 v100, 0, v213, s[22:23]
	v_cndmask_b32_e64 v101, 0, v213, s[24:25]
	v_cndmask_b32_e64 v102, 0, v213, s[26:27]
	v_cndmask_b32_e64 v103, 0, v213, s[28:29]
	v_sub_f32_e32 v92, v92, v100
	v_sub_f32_e32 v93, v93, v101
	v_sub_f32_e32 v94, v94, v102
	v_sub_f32_e32 v95, v95, v103
	v_add_f32_e32 v64, v64, v92
	v_add_f32_e32 v65, v65, v93
	v_add_f32_e32 v66, v66, v94
	v_add_f32_e32 v67, v67, v95
	v_mul_f32_e32 v92, 0xbfb8aa3b, v64
	v_mul_f32_e32 v93, 0xbfb8aa3b, v65
	v_mul_f32_e32 v94, 0xbfb8aa3b, v66
	v_mul_f32_e32 v95, 0xbfb8aa3b, v67
	v_mul_f32_e32 v100, 0x3fb8aa3b, v64
	v_mul_f32_e32 v101, 0x3fb8aa3b, v65
	v_mul_f32_e32 v102, 0x3fb8aa3b, v66
	v_mul_f32_e32 v103, 0x3fb8aa3b, v67
	v_exp_f32_e32 v92, v92
	v_exp_f32_e32 v93, v93
	v_exp_f32_e32 v94, v94
	v_exp_f32_e32 v95, v95
	v_exp_f32_e32 v100, v100
	v_exp_f32_e32 v101, v101
	v_exp_f32_e32 v102, v102
	v_exp_f32_e32 v103, v103
	v_sub_f32_e32 v96, 1.0, v96
	v_sub_f32_e32 v97, 1.0, v97
	v_sub_f32_e32 v98, 1.0, v98
	v_sub_f32_e32 v99, 1.0, v99
	v_mul_f32_e32 v96, v96, v92
	v_mul_f32_e32 v97, v97, v93
	v_mul_f32_e32 v98, v98, v94
	v_mul_f32_e32 v99, v99, v95
	v_lshlrev_b32_e32 v92, 16, v50
	v_and_b32_e32 v93, 0xffff0000, v50
	v_lshlrev_b32_e32 v94, 16, v51
	v_and_b32_e32 v95, 0xffff0000, v51
	v_mul_f32_e32 v92, v92, v100
	v_mul_f32_e32 v93, v93, v101
	v_mul_f32_e32 v94, v94, v102
	v_mul_f32_e32 v95, v95, v103
	v_mov_b32_e32 v130, v96
	v_mov_b32_e32 v146, v97
	v_mov_b32_e32 v180, v98
	v_mov_b32_e32 v196, v99
	v_cvt_pk_bf16_f32 v92, v92, v93
	v_cvt_pk_bf16_f32 v93, v94, v95
	v_cvt_pk_bf16_f32 v96, v96, v97
	v_cvt_pk_bf16_f32 v97, v98, v99
	global_store_dwordx2 v112, v[92:93], s[2:3]
	global_store_dwordx2 v114, v[96:97], s[2:3]
	s_add_u32 s2, s2, 0x400
	s_addc_u32 s3, s3, 0
	v_lshlrev_b32_e32 v92, 16, v52
	v_and_b32_e32 v93, 0xffff0000, v52
	v_lshlrev_b32_e32 v94, 16, v53
	v_and_b32_e32 v95, 0xffff0000, v53
	v_mul_f32_e32 v92, 0xbfb8aa3b, v92
	v_mul_f32_e32 v93, 0xbfb8aa3b, v93
	v_mul_f32_e32 v94, 0xbfb8aa3b, v94
	v_mul_f32_e32 v95, 0xbfb8aa3b, v95
	v_exp_f32_e32 v92, v92
	v_exp_f32_e32 v93, v93
	v_exp_f32_e32 v94, v94
	v_exp_f32_e32 v95, v95
	v_add_f32_e32 v92, 1.0, v92
	v_add_f32_e32 v93, 1.0, v93
	v_add_f32_e32 v94, 1.0, v94
	v_add_f32_e32 v95, 1.0, v95
	v_rcp_f32_e32 v92, v92
	v_rcp_f32_e32 v93, v93
	v_rcp_f32_e32 v94, v94
	v_rcp_f32_e32 v95, v95
	v_fma_f32 v96, v72, v92, v68
	v_fma_f32 v97, v73, v93, v69
	v_fma_f32 v98, v74, v94, v70
	v_fma_f32 v99, v75, v95, v71
	v_cmp_gt_f32_e64 s[22:23], s30, v96
	v_cmp_gt_f32_e64 s[24:25], s30, v97
	v_cmp_gt_f32_e64 s[26:27], s30, v98
	v_cmp_gt_f32_e64 s[28:29], s30, v99
	v_cndmask_b32_e64 v92, 0, 32, s[22:23]
	v_cndmask_b32_e64 v93, 0, 32, s[24:25]
	v_cndmask_b32_e64 v94, 0, 32, s[26:27]
	v_cndmask_b32_e64 v95, 0, 32, s[28:29]
	v_ldexp_f32 v92, v96, v92
	v_ldexp_f32 v93, v97, v93
	v_ldexp_f32 v94, v98, v94
	v_ldexp_f32 v95, v99, v95
	v_log_f32_e32 v92, v92
	v_log_f32_e32 v93, v93
	v_log_f32_e32 v94, v94
	v_log_f32_e32 v95, v95
	v_mul_f32_e32 v100, 0x3f317217, v92
	v_mul_f32_e32 v101, 0x3f317217, v93
	v_mul_f32_e32 v102, 0x3f317217, v94
	v_mul_f32_e32 v103, 0x3f317217, v95
	v_fma_f32 v100, v92, s31, -v100
	v_fma_f32 v101, v93, s31, -v101
	v_fma_f32 v102, v94, s31, -v102
	v_fma_f32 v103, v95, s31, -v103
	v_fmac_f32_e32 v100, 0x3377d1cf, v92
	v_fmac_f32_e32 v101, 0x3377d1cf, v93
	v_fmac_f32_e32 v102, 0x3377d1cf, v94
	v_fmac_f32_e32 v103, 0x3377d1cf, v95
	v_fmac_f32_e32 v100, 0x3f317217, v92
	v_fmac_f32_e32 v101, 0x3f317217, v93
	v_fmac_f32_e32 v102, 0x3f317217, v94
	v_fmac_f32_e32 v103, 0x3f317217, v95
	v_cmp_lt_f32_e64 vcc, |v92|, s34
	v_cndmask_b32_e32 v92, v92, v100, vcc
	v_cmp_lt_f32_e64 vcc, |v93|, s34
	v_cndmask_b32_e32 v93, v93, v101, vcc
	v_cmp_lt_f32_e64 vcc, |v94|, s34
	v_cndmask_b32_e32 v94, v94, v102, vcc
	v_cmp_lt_f32_e64 vcc, |v95|, s34
	v_cndmask_b32_e32 v95, v95, v103, vcc
	v_cndmask_b32_e64 v100, 0, v213, s[22:23]
	v_cndmask_b32_e64 v101, 0, v213, s[24:25]
	v_cndmask_b32_e64 v102, 0, v213, s[26:27]
	v_cndmask_b32_e64 v103, 0, v213, s[28:29]
	v_sub_f32_e32 v92, v92, v100
	v_sub_f32_e32 v93, v93, v101
	v_sub_f32_e32 v94, v94, v102
	v_sub_f32_e32 v95, v95, v103
	v_add_f32_e32 v64, v64, v92
	v_add_f32_e32 v65, v65, v93
	v_add_f32_e32 v66, v66, v94
	v_add_f32_e32 v67, v67, v95
	v_mul_f32_e32 v92, 0xbfb8aa3b, v64
	v_mul_f32_e32 v93, 0xbfb8aa3b, v65
	v_mul_f32_e32 v94, 0xbfb8aa3b, v66
	v_mul_f32_e32 v95, 0xbfb8aa3b, v67
	v_mul_f32_e32 v100, 0x3fb8aa3b, v64
	v_mul_f32_e32 v101, 0x3fb8aa3b, v65
	v_mul_f32_e32 v102, 0x3fb8aa3b, v66
	v_mul_f32_e32 v103, 0x3fb8aa3b, v67
	v_exp_f32_e32 v92, v92
	v_exp_f32_e32 v93, v93
	v_exp_f32_e32 v94, v94
	v_exp_f32_e32 v95, v95
	v_exp_f32_e32 v100, v100
	v_exp_f32_e32 v101, v101
	v_exp_f32_e32 v102, v102
	v_exp_f32_e32 v103, v103
	v_sub_f32_e32 v96, 1.0, v96
	v_sub_f32_e32 v97, 1.0, v97
	v_sub_f32_e32 v98, 1.0, v98
	v_sub_f32_e32 v99, 1.0, v99
	v_mul_f32_e32 v96, v96, v92
	v_mul_f32_e32 v97, v97, v93
	v_mul_f32_e32 v98, v98, v94
; DEV u16 f2bf(float f) { return (u16)(pack2(f, f) & 0xffffu); }
; DEV float bf2f(u16 h) { return __uint_as_float(((unsigned)h) << 16); }
; DEV float sigmoid_f(float x) { return __builtin_amdgcn_rcpf(1.f + __expf(-x)); }
; DEV void phase_p15(const Params& p, int g) {
;     ...
;           const float f = lb[cc] + (1.f - lb[cc]) * sigmoid_f(bf2f(xr[st][cc][e]));
;           G[cc] += __logf(f);
;           const float eg = __expf(G[cc]), ig = __expf(-G[cc]);
;           Qp[tok * 512 + c] = f2bf(bf2f(qr[st][cc][e]) * eg);
;           const u16 kk = f2bf((1.f - f) * ig);
;           Kp[tok * 512 + c] = kk;
;           kb[e] = kk;
;         }
;         const int s0 = dir ? 56 - 8 * j8 : 8 * j8;
;         uint4 w;
;         w.x = dir ? (kb[7] | (kb[6] << 16)) : (kb[0] | (kb[1] << 16));
;         w.y = dir ? (kb[5] | (kb[4] << 16)) : (kb[2] | (kb[3] << 16));
;         w.z = dir ? (kb[3] | (kb[2] << 16)) : (kb[4] | (kb[5] << 16));
;         w.w = dir ? (kb[1] | (kb[0] << 16)) : (kb[6] | (kb[7] << 16));
	v_mul_f32_e32 v99, v99, v95
	v_lshlrev_b32_e32 v92, 16, v54
	v_and_b32_e32 v93, 0xffff0000, v54
	v_lshlrev_b32_e32 v94, 16, v55
	v_and_b32_e32 v95, 0xffff0000, v55
	v_mul_f32_e32 v92, v92, v100
	v_mul_f32_e32 v93, v93, v101
	v_mul_f32_e32 v94, v94, v102
	v_mul_f32_e32 v95, v95, v103
	v_cvt_pk_bf16_f32 v130, v130, v96
	v_cvt_pk_bf16_f32 v146, v146, v97
	v_cvt_pk_bf16_f32 v180, v180, v98
	v_cvt_pk_bf16_f32 v196, v196, v99
	v_cvt_pk_bf16_f32 v92, v92, v93
	v_cvt_pk_bf16_f32 v93, v94, v95
	v_cvt_pk_bf16_f32 v96, v96, v97
	v_cvt_pk_bf16_f32 v97, v98, v99
	global_store_dwordx2 v112, v[92:93], s[2:3]
	global_store_dwordx2 v114, v[96:97], s[2:3]
	s_add_u32 s2, s2, 0x400
	s_addc_u32 s3, s3, 0
	v_lshlrev_b32_e32 v92, 16, v56
	v_and_b32_e32 v93, 0xffff0000, v56
	v_lshlrev_b32_e32 v94, 16, v57
	v_and_b32_e32 v95, 0xffff0000, v57
	v_mul_f32_e32 v92, 0xbfb8aa3b, v92
	v_mul_f32_e32 v93, 0xbfb8aa3b, v93
	v_mul_f32_e32 v94, 0xbfb8aa3b, v94
	v_mul_f32_e32 v95, 0xbfb8aa3b, v95
	v_exp_f32_e32 v92, v92
	v_exp_f32_e32 v93, v93
	v_exp_f32_e32 v94, v94
	v_exp_f32_e32 v95, v95
	v_add_f32_e32 v92, 1.0, v92
	v_add_f32_e32 v93, 1.0, v93
	v_add_f32_e32 v94, 1.0, v94
	v_add_f32_e32 v95, 1.0, v95
	v_rcp_f32_e32 v92, v92
	v_rcp_f32_e32 v93, v93
	v_rcp_f32_e32 v94, v94
	v_rcp_f32_e32 v95, v95
	v_fma_f32 v96, v72, v92, v68
	v_fma_f32 v97, v73, v93, v69
	v_fma_f32 v98, v74, v94, v70
	v_fma_f32 v99, v75, v95, v71
	v_cmp_gt_f32_e64 s[22:23], s30, v96
	v_cmp_gt_f32_e64 s[24:25], s30, v97
	v_cmp_gt_f32_e64 s[26:27], s30, v98
	v_cmp_gt_f32_e64 s[28:29], s30, v99
	v_cndmask_b32_e64 v92, 0, 32, s[22:23]
	v_cndmask_b32_e64 v93, 0, 32, s[24:25]
	v_cndmask_b32_e64 v94, 0, 32, s[26:27]
	v_cndmask_b32_e64 v95, 0, 32, s[28:29]
	v_ldexp_f32 v92, v96, v92
	v_ldexp_f32 v93, v97, v93
	v_ldexp_f32 v94, v98, v94
	v_ldexp_f32 v95, v99, v95
	v_log_f32_e32 v92, v92
	v_log_f32_e32 v93, v93
	v_log_f32_e32 v94, v94
	v_log_f32_e32 v95, v95
	v_mul_f32_e32 v100, 0x3f317217, v92
	v_mul_f32_e32 v101, 0x3f317217, v93
	v_mul_f32_e32 v102, 0x3f317217, v94
	v_mul_f32_e32 v103, 0x3f317217, v95
	v_fma_f32 v100, v92, s31, -v100
	v_fma_f32 v101, v93, s31, -v101
	v_fma_f32 v102, v94, s31, -v102
	v_fma_f32 v103, v95, s31, -v103
	v_fmac_f32_e32 v100, 0x3377d1cf, v92
	v_fmac_f32_e32 v101, 0x3377d1cf, v93
	v_fmac_f32_e32 v102, 0x3377d1cf, v94
	v_fmac_f32_e32 v103, 0x3377d1cf, v95
	v_fmac_f32_e32 v100, 0x3f317217, v92
	v_fmac_f32_e32 v101, 0x3f317217, v93
	v_fmac_f32_e32 v102, 0x3f317217, v94
	v_fmac_f32_e32 v103, 0x3f317217, v95
	v_cmp_lt_f32_e64 vcc, |v92|, s34
	v_cndmask_b32_e32 v92, v92, v100, vcc
	v_cmp_lt_f32_e64 vcc, |v93|, s34
	v_cndmask_b32_e32 v93, v93, v101, vcc
	v_cmp_lt_f32_e64 vcc, |v94|, s34
	v_cndmask_b32_e32 v94, v94, v102, vcc
	v_cmp_lt_f32_e64 vcc, |v95|, s34
	v_cndmask_b32_e32 v95, v95, v103, vcc
	v_cndmask_b32_e64 v100, 0, v213, s[22:23]
	v_cndmask_b32_e64 v101, 0, v213, s[24:25]
	v_cndmask_b32_e64 v102, 0, v213, s[26:27]
	v_cndmask_b32_e64 v103, 0, v213, s[28:29]
	v_sub_f32_e32 v92, v92, v100
	v_sub_f32_e32 v93, v93, v101
	v_sub_f32_e32 v94, v94, v102
	v_sub_f32_e32 v95, v95, v103
	v_add_f32_e32 v64, v64, v92
	v_add_f32_e32 v65, v65, v93
	v_add_f32_e32 v66, v66, v94
	v_add_f32_e32 v67, v67, v95
	v_mul_f32_e32 v92, 0xbfb8aa3b, v64
	v_mul_f32_e32 v93, 0xbfb8aa3b, v65
	v_mul_f32_e32 v94, 0xbfb8aa3b, v66
	v_mul_f32_e32 v95, 0xbfb8aa3b, v67
	v_mul_f32_e32 v100, 0x3fb8aa3b, v64
	v_mul_f32_e32 v101, 0x3fb8aa3b, v65
	v_mul_f32_e32 v102, 0x3fb8aa3b, v66
	v_mul_f32_e32 v103, 0x3fb8aa3b, v67
	v_exp_f32_e32 v92, v92
	v_exp_f32_e32 v93, v93
	v_exp_f32_e32 v94, v94
	v_exp_f32_e32 v95, v95
	v_exp_f32_e32 v100, v100
	v_exp_f32_e32 v101, v101
	v_exp_f32_e32 v102, v102
	v_exp_f32_e32 v103, v103
	v_sub_f32_e32 v96, 1.0, v96
	v_sub_f32_e32 v97, 1.0, v97
	v_sub_f32_e32 v98, 1.0, v98
	v_sub_f32_e32 v99, 1.0, v99
	v_mul_f32_e32 v96, v96, v92
	v_mul_f32_e32 v97, v97, v93
	v_mul_f32_e32 v98, v98, v94
	v_mul_f32_e32 v99, v99, v95
	v_lshlrev_b32_e32 v92, 16, v58
	v_and_b32_e32 v93, 0xffff0000, v58
	v_lshlrev_b32_e32 v94, 16, v59
	v_and_b32_e32 v95, 0xffff0000, v59
	v_mul_f32_e32 v92, v92, v100
	v_mul_f32_e32 v93, v93, v101
	v_mul_f32_e32 v94, v94, v102
	v_mul_f32_e32 v95, v95, v103
	v_mov_b32_e32 v131, v96
	v_mov_b32_e32 v147, v97
	v_mov_b32_e32 v181, v98
	v_mov_b32_e32 v197, v99
	v_cvt_pk_bf16_f32 v92, v92, v93
	v_cvt_pk_bf16_f32 v93, v94, v95
	v_cvt_pk_bf16_f32 v96, v96, v97
	v_cvt_pk_bf16_f32 v97, v98, v99
	global_store_dwordx2 v112, v[92:93], s[2:3]
	global_store_dwordx2 v114, v[96:97], s[2:3]
	s_add_u32 s2, s2, 0x400
	s_addc_u32 s3, s3, 0
	v_lshlrev_b32_e32 v92, 16, v60
	v_and_b32_e32 v93, 0xffff0000, v60
	v_lshlrev_b32_e32 v94, 16, v61
	v_and_b32_e32 v95, 0xffff0000, v61
	v_mul_f32_e32 v92, 0xbfb8aa3b, v92
	v_mul_f32_e32 v93, 0xbfb8aa3b, v93
	v_mul_f32_e32 v94, 0xbfb8aa3b, v94
	v_mul_f32_e32 v95, 0xbfb8aa3b, v95
	v_exp_f32_e32 v92, v92
	v_exp_f32_e32 v93, v93
	v_exp_f32_e32 v94, v94
	v_exp_f32_e32 v95, v95
	v_add_f32_e32 v92, 1.0, v92
	v_add_f32_e32 v93, 1.0, v93
	v_add_f32_e32 v94, 1.0, v94
	v_add_f32_e32 v95, 1.0, v95
	v_rcp_f32_e32 v92, v92
	v_rcp_f32_e32 v93, v93
	v_rcp_f32_e32 v94, v94
	v_rcp_f32_e32 v95, v95
	v_fma_f32 v96, v72, v92, v68
	v_fma_f32 v97, v73, v93, v69
	v_fma_f32 v98, v74, v94, v70
	v_fma_f32 v99, v75, v95, v71
	v_cmp_gt_f32_e64 s[22:23], s30, v96
	v_cmp_gt_f32_e64 s[24:25], s30, v97
	v_cmp_gt_f32_e64 s[26:27], s30, v98
	v_cmp_gt_f32_e64 s[28:29], s30, v99
	v_cndmask_b32_e64 v92, 0, 32, s[22:23]
	v_cndmask_b32_e64 v93, 0, 32, s[24:25]
	v_cndmask_b32_e64 v94, 0, 32, s[26:27]
	v_cndmask_b32_e64 v95, 0, 32, s[28:29]
	v_ldexp_f32 v92, v96, v92
	v_ldexp_f32 v93, v97, v93
	v_ldexp_f32 v94, v98, v94
; DEV u16 f2bf(float f) { return (u16)(pack2(f, f) & 0xffffu); }
; DEV float bf2f(u16 h) { return __uint_as_float(((unsigned)h) << 16); }
; DEV float sigmoid_f(float x) { return __builtin_amdgcn_rcpf(1.f + __expf(-x)); }
; DEV void phase_p15(const Params& p, int g) {
;     ...
;     P15_LOAD(0, 0);
;     P15_LOAD(1, 1);
; #pragma unroll
;     for (int j8 = 0; j8 < 8; ++j8) {
;       const int st = j8 % 3;
;       if (j8 < 6) { P15_LOAD((j8 + 2) % 3, j8 + 2); }
;     ...
;           const float f = lb[cc] + (1.f - lb[cc]) * sigmoid_f(bf2f(xr[st][cc][e]));
;           G[cc] += __logf(f);
;           const float eg = __expf(G[cc]), ig = __expf(-G[cc]);
;           Qp[tok * 512 + c] = f2bf(bf2f(qr[st][cc][e]) * eg);
;           const u16 kk = f2bf((1.f - f) * ig);
;           Kp[tok * 512 + c] = kk;
;           kb[e] = kk;
;         }
;         const int s0 = dir ? 56 - 8 * j8 : 8 * j8;
;         uint4 w;
;         w.x = dir ? (kb[7] | (kb[6] << 16)) : (kb[0] | (kb[1] << 16));
;         w.y = dir ? (kb[5] | (kb[4] << 16)) : (kb[2] | (kb[3] << 16));
;         w.z = dir ? (kb[3] | (kb[2] << 16)) : (kb[4] | (kb[5] << 16));
;         w.w = dir ? (kb[1] | (kb[0] << 16)) : (kb[6] | (kb[7] << 16));
	v_ldexp_f32 v95, v99, v95
	v_log_f32_e32 v92, v92
	v_log_f32_e32 v93, v93
	v_log_f32_e32 v94, v94
	v_log_f32_e32 v95, v95
	v_mul_f32_e32 v100, 0x3f317217, v92
	v_mul_f32_e32 v101, 0x3f317217, v93
	v_mul_f32_e32 v102, 0x3f317217, v94
	v_mul_f32_e32 v103, 0x3f317217, v95
	v_fma_f32 v100, v92, s31, -v100
	v_fma_f32 v101, v93, s31, -v101
	v_fma_f32 v102, v94, s31, -v102
	v_fma_f32 v103, v95, s31, -v103
	v_fmac_f32_e32 v100, 0x3377d1cf, v92
	v_fmac_f32_e32 v101, 0x3377d1cf, v93
	v_fmac_f32_e32 v102, 0x3377d1cf, v94
	v_fmac_f32_e32 v103, 0x3377d1cf, v95
	v_fmac_f32_e32 v100, 0x3f317217, v92
	v_fmac_f32_e32 v101, 0x3f317217, v93
	v_fmac_f32_e32 v102, 0x3f317217, v94
	v_fmac_f32_e32 v103, 0x3f317217, v95
	v_cmp_lt_f32_e64 vcc, |v92|, s34
	v_cndmask_b32_e32 v92, v92, v100, vcc
	v_cmp_lt_f32_e64 vcc, |v93|, s34
	v_cndmask_b32_e32 v93, v93, v101, vcc
	v_cmp_lt_f32_e64 vcc, |v94|, s34
	v_cndmask_b32_e32 v94, v94, v102, vcc
	v_cmp_lt_f32_e64 vcc, |v95|, s34
	v_cndmask_b32_e32 v95, v95, v103, vcc
	v_cndmask_b32_e64 v100, 0, v213, s[22:23]
	v_cndmask_b32_e64 v101, 0, v213, s[24:25]
	v_cndmask_b32_e64 v102, 0, v213, s[26:27]
	v_cndmask_b32_e64 v103, 0, v213, s[28:29]
	v_sub_f32_e32 v92, v92, v100
	v_sub_f32_e32 v93, v93, v101
	v_sub_f32_e32 v94, v94, v102
	v_sub_f32_e32 v95, v95, v103
	v_add_f32_e32 v64, v64, v92
	v_add_f32_e32 v65, v65, v93
	v_add_f32_e32 v66, v66, v94
	v_add_f32_e32 v67, v67, v95
	v_mul_f32_e32 v92, 0xbfb8aa3b, v64
	v_mul_f32_e32 v93, 0xbfb8aa3b, v65
	v_mul_f32_e32 v94, 0xbfb8aa3b, v66
	v_mul_f32_e32 v95, 0xbfb8aa3b, v67
	v_mul_f32_e32 v100, 0x3fb8aa3b, v64
	v_mul_f32_e32 v101, 0x3fb8aa3b, v65
	v_mul_f32_e32 v102, 0x3fb8aa3b, v66
	v_mul_f32_e32 v103, 0x3fb8aa3b, v67
	v_exp_f32_e32 v92, v92
	v_exp_f32_e32 v93, v93
	v_exp_f32_e32 v94, v94
	v_exp_f32_e32 v95, v95
	v_exp_f32_e32 v100, v100
	v_exp_f32_e32 v101, v101
	v_exp_f32_e32 v102, v102
	v_exp_f32_e32 v103, v103
	v_sub_f32_e32 v96, 1.0, v96
	v_sub_f32_e32 v97, 1.0, v97
	v_sub_f32_e32 v98, 1.0, v98
	v_sub_f32_e32 v99, 1.0, v99
	v_mul_f32_e32 v96, v96, v92
	v_mul_f32_e32 v97, v97, v93
	v_mul_f32_e32 v98, v98, v94
	v_mul_f32_e32 v99, v99, v95
	v_lshlrev_b32_e32 v92, 16, v62
	v_and_b32_e32 v93, 0xffff0000, v62
	v_lshlrev_b32_e32 v94, 16, v63
	v_and_b32_e32 v95, 0xffff0000, v63
	v_mul_f32_e32 v92, v92, v100
	v_mul_f32_e32 v93, v93, v101
	v_mul_f32_e32 v94, v94, v102
	v_mul_f32_e32 v95, v95, v103
	v_cvt_pk_bf16_f32 v131, v131, v96
	v_cvt_pk_bf16_f32 v147, v147, v97
	v_cvt_pk_bf16_f32 v181, v181, v98
	v_cvt_pk_bf16_f32 v197, v197, v99
	v_cvt_pk_bf16_f32 v92, v92, v93
	v_cvt_pk_bf16_f32 v93, v94, v95
	v_cvt_pk_bf16_f32 v96, v96, v97
	v_cvt_pk_bf16_f32 v97, v98, v99
	global_store_dwordx2 v112, v[92:93], s[2:3]
	global_store_dwordx2 v114, v[96:97], s[2:3]
	s_add_u32 s2, s2, 0x400
	s_addc_u32 s3, s3, 0
	s_cmp_eq_u32 s35, 1
	s_cbranch_scc1 .Lp15_d0_nl3
	global_load_dwordx2 v[32:33], v113, s[0:1]
	global_load_dwordx2 v[34:35], v112, s[0:1]
	s_add_u32 s0, s0, 0x1400
	s_addc_u32 s1, s1, 0
	global_load_dwordx2 v[36:37], v113, s[0:1]
	global_load_dwordx2 v[38:39], v112, s[0:1]
	s_add_u32 s0, s0, 0x1400
	s_addc_u32 s1, s1, 0
	global_load_dwordx2 v[40:41], v113, s[0:1]
	global_load_dwordx2 v[42:43], v112, s[0:1]
	s_add_u32 s0, s0, 0x1400
	s_addc_u32 s1, s1, 0
	global_load_dwordx2 v[44:45], v113, s[0:1]
	global_load_dwordx2 v[46:47], v112, s[0:1]
	s_add_u32 s0, s0, 0x1400
	s_addc_u32 s1, s1, 0
	global_load_dwordx2 v[48:49], v113, s[0:1]
	global_load_dwordx2 v[50:51], v112, s[0:1]
	s_add_u32 s0, s0, 0x1400
	s_addc_u32 s1, s1, 0
	global_load_dwordx2 v[52:53], v113, s[0:1]
	global_load_dwordx2 v[54:55], v112, s[0:1]
	s_add_u32 s0, s0, 0x1400
	s_addc_u32 s1, s1, 0
	global_load_dwordx2 v[56:57], v113, s[0:1]
	global_load_dwordx2 v[58:59], v112, s[0:1]
	s_add_u32 s0, s0, 0x1400
	s_addc_u32 s1, s1, 0
	global_load_dwordx2 v[60:61], v113, s[0:1]
	global_load_dwordx2 v[62:63], v112, s[0:1]
	s_add_u32 s0, s0, 0x1400
	s_addc_u32 s1, s1, 0
.Lp15_d0_nl3:
	s_cmp_eq_u32 s35, 0
	s_cbranch_scc0 .Lp15_d0_nopark
	v_mov_b32_e32 v148, v116
	v_mov_b32_e32 v149, v117
	v_mov_b32_e32 v150, v118
	v_mov_b32_e32 v151, v119
	v_mov_b32_e32 v152, v120
	v_mov_b32_e32 v153, v121
	v_mov_b32_e32 v154, v122
	v_mov_b32_e32 v155, v123
	v_mov_b32_e32 v156, v124
	v_mov_b32_e32 v157, v125
	v_mov_b32_e32 v158, v126
	v_mov_b32_e32 v159, v127
	v_mov_b32_e32 v198, v128
	v_mov_b32_e32 v199, v129
	v_mov_b32_e32 v200, v130
	v_mov_b32_e32 v201, v131
	v_mov_b32_e32 v222, v132
	v_mov_b32_e32 v223, v133
	v_mov_b32_e32 v224, v134
	v_mov_b32_e32 v225, v135
	v_mov_b32_e32 v226, v136
	v_mov_b32_e32 v227, v137
	v_mov_b32_e32 v228, v138
	v_mov_b32_e32 v229, v139
	v_mov_b32_e32 v230, v140
	v_mov_b32_e32 v231, v141
	v_mov_b32_e32 v232, v142
	v_mov_b32_e32 v233, v143
	v_mov_b32_e32 v234, v144
	v_mov_b32_e32 v235, v145
	v_mov_b32_e32 v236, v146
	v_mov_b32_e32 v237, v147
	v_mov_b32_e32 v238, v166
	v_mov_b32_e32 v239, v167
	v_mov_b32_e32 v240, v168
	v_mov_b32_e32 v241, v169
	v_mov_b32_e32 v242, v170
	v_mov_b32_e32 v243, v171
	v_mov_b32_e32 v244, v172
	v_mov_b32_e32 v245, v173
	v_mov_b32_e32 v76, v174
	v_mov_b32_e32 v77, v175
	v_mov_b32_e32 v78, v176
	v_mov_b32_e32 v79, v177
	v_mov_b32_e32 v80, v178
	v_mov_b32_e32 v81, v179
	v_mov_b32_e32 v82, v180
	v_mov_b32_e32 v83, v181
	v_mov_b32_e32 v84, v182
	v_mov_b32_e32 v85, v183
	v_mov_b32_e32 v86, v184
	v_mov_b32_e32 v87, v185
	v_mov_b32_e32 v88, v186
	v_mov_b32_e32 v89, v187
	v_mov_b32_e32 v90, v188
	v_mov_b32_e32 v91, v189
	v_mov_b32_e32 v104, v190
	v_mov_b32_e32 v105, v191
	v_mov_b32_e32 v106, v192
	v_mov_b32_e32 v107, v193
	v_mov_b32_e32 v108, v194
	v_mov_b32_e32 v109, v195
	v_mov_b32_e32 v110, v196
	v_mov_b32_e32 v111, v197

; DEV u16 f2bf(float f) { return (u16)(pack2(f, f) & 0xffffu); }
; DEV float bf2f(u16 h) { return __uint_as_float(((unsigned)h) << 16); }
; DEV float sigmoid_f(float x) { return __builtin_amdgcn_rcpf(1.f + __expf(-x)); }
; DEV void phase_p15(const Params& p, int g) {
;     ...
;     for (int j8 = 0; j8 < 8; ++j8) {
;       const int st = j8 % 3;
;       if (j8 < 6) { P15_LOAD((j8 + 2) % 3, j8 + 2); }
; #pragma unroll
;       for (int cc = 0; cc < 2; ++cc) {
;         const int c = tid + 256 * cc;
;         unsigned kb[8];
; #pragma unroll
;         for (int e = 0; e < 8; ++e) {
;           const int jj = j8 * 8 + e;
;           const int j = dir ? 63 - jj : jj;
;           const size_t tok = (size_t)cidx * 64 + j;
;           const float f = lb[cc] + (1.f - lb[cc]) * sigmoid_f(bf2f(xr[st][cc][e]));
;           G[cc] += __logf(f);
;           const float eg = __expf(G[cc]), ig = __expf(-G[cc]);
;           Qp[tok * 512 + c] = f2bf(bf2f(qr[st][cc][e]) * eg);
;           const u16 kk = f2bf((1.f - f) * ig);
;           Kp[tok * 512 + c] = kk;
;           kb[e] = kk;
.Lp15_d1_loop:
	s_waitcnt vmcnt(32)
	v_lshlrev_b32_e32 v92, 16, v0
	v_and_b32_e32 v93, 0xffff0000, v0
	v_lshlrev_b32_e32 v94, 16, v1
	v_and_b32_e32 v95, 0xffff0000, v1
	v_mul_f32_e32 v92, 0xbfb8aa3b, v92
	v_mul_f32_e32 v93, 0xbfb8aa3b, v93
	v_mul_f32_e32 v94, 0xbfb8aa3b, v94
	v_mul_f32_e32 v95, 0xbfb8aa3b, v95
	v_exp_f32_e32 v92, v92
	v_exp_f32_e32 v93, v93
	v_exp_f32_e32 v94, v94
	v_exp_f32_e32 v95, v95
	v_add_f32_e32 v92, 1.0, v92
	v_add_f32_e32 v93, 1.0, v93
	v_add_f32_e32 v94, 1.0, v94
	v_add_f32_e32 v95, 1.0, v95
	v_rcp_f32_e32 v92, v92
	v_rcp_f32_e32 v93, v93
	v_rcp_f32_e32 v94, v94
	v_rcp_f32_e32 v95, v95
	v_fma_f32 v96, v72, v92, v68
	v_fma_f32 v97, v73, v93, v69
	v_fma_f32 v98, v74, v94, v70
	v_fma_f32 v99, v75, v95, v71
	v_cmp_gt_f32_e64 s[22:23], s30, v96
	v_cmp_gt_f32_e64 s[24:25], s30, v97
	v_cmp_gt_f32_e64 s[26:27], s30, v98
	v_cmp_gt_f32_e64 s[28:29], s30, v99
	v_cndmask_b32_e64 v92, 0, 32, s[22:23]
	v_cndmask_b32_e64 v93, 0, 32, s[24:25]
	v_cndmask_b32_e64 v94, 0, 32, s[26:27]
	v_cndmask_b32_e64 v95, 0, 32, s[28:29]
	v_ldexp_f32 v92, v96, v92
	v_ldexp_f32 v93, v97, v93
	v_ldexp_f32 v94, v98, v94
	v_ldexp_f32 v95, v99, v95
	v_log_f32_e32 v92, v92
	v_log_f32_e32 v93, v93
	v_log_f32_e32 v94, v94
	v_log_f32_e32 v95, v95
	v_mul_f32_e32 v100, 0x3f317217, v92
	v_mul_f32_e32 v101, 0x3f317217, v93
	v_mul_f32_e32 v102, 0x3f317217, v94
	v_mul_f32_e32 v103, 0x3f317217, v95
	v_fma_f32 v100, v92, s31, -v100
	v_fma_f32 v101, v93, s31, -v101
	v_fma_f32 v102, v94, s31, -v102
	v_fma_f32 v103, v95, s31, -v103
	v_fmac_f32_e32 v100, 0x3377d1cf, v92
	v_fmac_f32_e32 v101, 0x3377d1cf, v93
	v_fmac_f32_e32 v102, 0x3377d1cf, v94
	v_fmac_f32_e32 v103, 0x3377d1cf, v95
	v_fmac_f32_e32 v100, 0x3f317217, v92
	v_fmac_f32_e32 v101, 0x3f317217, v93
	v_fmac_f32_e32 v102, 0x3f317217, v94
	v_fmac_f32_e32 v103, 0x3f317217, v95
	v_cmp_lt_f32_e64 vcc, |v92|, s34
	v_cndmask_b32_e32 v92, v92, v100, vcc
	v_cmp_lt_f32_e64 vcc, |v93|, s34
	v_cndmask_b32_e32 v93, v93, v101, vcc
	v_cmp_lt_f32_e64 vcc, |v94|, s34
	v_cndmask_b32_e32 v94, v94, v102, vcc
	v_cmp_lt_f32_e64 vcc, |v95|, s34
	v_cndmask_b32_e32 v95, v95, v103, vcc
	v_cndmask_b32_e64 v100, 0, v213, s[22:23]
	v_cndmask_b32_e64 v101, 0, v213, s[24:25]
	v_cndmask_b32_e64 v102, 0, v213, s[26:27]
	v_cndmask_b32_e64 v103, 0, v213, s[28:29]
	v_sub_f32_e32 v92, v92, v100
	v_sub_f32_e32 v93, v93, v101
	v_sub_f32_e32 v94, v94, v102
	v_sub_f32_e32 v95, v95, v103
	v_add_f32_e32 v64, v64, v92
	v_add_f32_e32 v65, v65, v93
	v_add_f32_e32 v66, v66, v94
	v_add_f32_e32 v67, v67, v95
	v_mul_f32_e32 v92, 0xbfb8aa3b, v64
	v_mul_f32_e32 v93, 0xbfb8aa3b, v65
	v_mul_f32_e32 v94, 0xbfb8aa3b, v66
	v_mul_f32_e32 v95, 0xbfb8aa3b, v67
	v_mul_f32_e32 v100, 0x3fb8aa3b, v64
	v_mul_f32_e32 v101, 0x3fb8aa3b, v65
	v_mul_f32_e32 v102, 0x3fb8aa3b, v66
	v_mul_f32_e32 v103, 0x3fb8aa3b, v67
	v_exp_f32_e32 v92, v92
	v_exp_f32_e32 v93, v93
	v_exp_f32_e32 v94, v94
	v_exp_f32_e32 v95, v95
	v_exp_f32_e32 v100, v100
	v_exp_f32_e32 v101, v101
	v_exp_f32_e32 v102, v102
	v_exp_f32_e32 v103, v103
	v_sub_f32_e32 v96, 1.0, v96
	v_sub_f32_e32 v97, 1.0, v97
	v_sub_f32_e32 v98, 1.0, v98
	v_sub_f32_e32 v99, 1.0, v99
	v_mul_f32_e32 v96, v96, v92
	v_mul_f32_e32 v97, v97, v93
	v_mul_f32_e32 v98, v98, v94
	v_mul_f32_e32 v99, v99, v95
	v_lshlrev_b32_e32 v92, 16, v2
	v_and_b32_e32 v93, 0xffff0000, v2
	v_lshlrev_b32_e32 v94, 16, v3
	v_and_b32_e32 v95, 0xffff0000, v3
	v_mul_f32_e32 v92, v92, v100
	v_mul_f32_e32 v93, v93, v101
	v_mul_f32_e32 v94, v94, v102
	v_mul_f32_e32 v95, v95, v103
	v_mov_b32_e32 v131, v96
	v_mov_b32_e32 v147, v97
	v_mov_b32_e32 v181, v98
	v_mov_b32_e32 v197, v99
	v_cvt_pk_bf16_f32 v92, v92, v93
	v_cvt_pk_bf16_f32 v93, v94, v95
	v_cvt_pk_bf16_f32 v96, v96, v97
	v_cvt_pk_bf16_f32 v97, v98, v99
	global_store_dwordx2 v112, v[92:93], s[2:3]
	global_store_dwordx2 v114, v[96:97], s[2:3]
	s_sub_u32 s2, s2, 0x400
	s_subb_u32 s3, s3, 0
	v_lshlrev_b32_e32 v92, 16, v4
	v_and_b32_e32 v93, 0xffff0000, v4
	v_lshlrev_b32_e32 v94, 16, v5
	v_and_b32_e32 v95, 0xffff0000, v5
	v_mul_f32_e32 v92, 0xbfb8aa3b, v92
	v_mul_f32_e32 v93, 0xbfb8aa3b, v93
	v_mul_f32_e32 v94, 0xbfb8aa3b, v94
	v_mul_f32_e32 v95, 0xbfb8aa3b, v95
	v_exp_f32_e32 v92, v92
	v_exp_f32_e32 v93, v93
	v_exp_f32_e32 v94, v94
	v_exp_f32_e32 v95, v95
	v_add_f32_e32 v92, 1.0, v92
	v_add_f32_e32 v93, 1.0, v93
	v_add_f32_e32 v94, 1.0, v94
	v_add_f32_e32 v95, 1.0, v95
	v_rcp_f32_e32 v92, v92
	v_rcp_f32_e32 v93, v93
	v_rcp_f32_e32 v94, v94
	v_rcp_f32_e32 v95, v95
	v_fma_f32 v96, v72, v92, v68
	v_fma_f32 v97, v73, v93, v69
	v_fma_f32 v98, v74, v94, v70
	v_fma_f32 v99, v75, v95, v71
	v_cmp_gt_f32_e64 s[22:23], s30, v96
	v_cmp_gt_f32_e64 s[24:25], s30, v97
	v_cmp_gt_f32_e64 s[26:27], s30, v98
	v_cmp_gt_f32_e64 s[28:29], s30, v99
	v_cndmask_b32_e64 v92, 0, 32, s[22:23]
	v_cndmask_b32_e64 v93, 0, 32, s[24:25]
	v_cndmask_b32_e64 v94, 0, 32, s[26:27]
	v_cndmask_b32_e64 v95, 0, 32, s[28:29]
	v_ldexp_f32 v92, v96, v92
	v_ldexp_f32 v93, v97, v93
	v_ldexp_f32 v94, v98, v94
	v_ldexp_f32 v95, v99, v95
	v_log_f32_e32 v92, v92
	v_log_f32_e32 v93, v93
	v_log_f32_e32 v94, v94
	v_log_f32_e32 v95, v95
	v_mul_f32_e32 v100, 0x3f317217, v92
	v_mul_f32_e32 v101, 0x3f317217, v93
	v_mul_f32_e32 v102, 0x3f317217, v94
	v_mul_f32_e32 v103, 0x3f317217, v95
	v_fma_f32 v100, v92, s31, -v100
	v_fma_f32 v101, v93, s31, -v101
	v_fma_f32 v102, v94, s31, -v102
	v_fma_f32 v103, v95, s31, -v103
	v_fmac_f32_e32 v100, 0x3377d1cf, v92
	v_fmac_f32_e32 v101, 0x3377d1cf, v93
	v_fmac_f32_e32 v102, 0x3377d1cf, v94
	v_fmac_f32_e32 v103, 0x3377d1cf, v95
	v_fmac_f32_e32 v100, 0x3f317217, v92
	v_fmac_f32_e32 v101, 0x3f317217, v93
	v_fmac_f32_e32 v102, 0x3f317217, v94
; DEV u16 f2bf(float f) { return (u16)(pack2(f, f) & 0xffffu); }
; DEV float bf2f(u16 h) { return __uint_as_float(((unsigned)h) << 16); }
; DEV float sigmoid_f(float x) { return __builtin_amdgcn_rcpf(1.f + __expf(-x)); }
; DEV void phase_p15(const Params& p, int g) {
;     ...
;           const float f = lb[cc] + (1.f - lb[cc]) * sigmoid_f(bf2f(xr[st][cc][e]));
;           G[cc] += __logf(f);
;           const float eg = __expf(G[cc]), ig = __expf(-G[cc]);
;           Qp[tok * 512 + c] = f2bf(bf2f(qr[st][cc][e]) * eg);
;           const u16 kk = f2bf((1.f - f) * ig);
;           Kp[tok * 512 + c] = kk;
;           kb[e] = kk;
;         }
;         const int s0 = dir ? 56 - 8 * j8 : 8 * j8;
;         uint4 w;
;         w.x = dir ? (kb[7] | (kb[6] << 16)) : (kb[0] | (kb[1] << 16));
;         w.y = dir ? (kb[5] | (kb[4] << 16)) : (kb[2] | (kb[3] << 16));
;         w.z = dir ? (kb[3] | (kb[2] << 16)) : (kb[4] | (kb[5] << 16));
;         w.w = dir ? (kb[1] | (kb[0] << 16)) : (kb[6] | (kb[7] << 16));
	v_fmac_f32_e32 v103, 0x3f317217, v95
	v_cmp_lt_f32_e64 vcc, |v92|, s34
	v_cndmask_b32_e32 v92, v92, v100, vcc
	v_cmp_lt_f32_e64 vcc, |v93|, s34
	v_cndmask_b32_e32 v93, v93, v101, vcc
	v_cmp_lt_f32_e64 vcc, |v94|, s34
	v_cndmask_b32_e32 v94, v94, v102, vcc
	v_cmp_lt_f32_e64 vcc, |v95|, s34
	v_cndmask_b32_e32 v95, v95, v103, vcc
	v_cndmask_b32_e64 v100, 0, v213, s[22:23]
	v_cndmask_b32_e64 v101, 0, v213, s[24:25]
	v_cndmask_b32_e64 v102, 0, v213, s[26:27]
	v_cndmask_b32_e64 v103, 0, v213, s[28:29]
	v_sub_f32_e32 v92, v92, v100
	v_sub_f32_e32 v93, v93, v101
	v_sub_f32_e32 v94, v94, v102
	v_sub_f32_e32 v95, v95, v103
	v_add_f32_e32 v64, v64, v92
	v_add_f32_e32 v65, v65, v93
	v_add_f32_e32 v66, v66, v94
	v_add_f32_e32 v67, v67, v95
	v_mul_f32_e32 v92, 0xbfb8aa3b, v64
	v_mul_f32_e32 v93, 0xbfb8aa3b, v65
	v_mul_f32_e32 v94, 0xbfb8aa3b, v66
	v_mul_f32_e32 v95, 0xbfb8aa3b, v67
	v_mul_f32_e32 v100, 0x3fb8aa3b, v64
	v_mul_f32_e32 v101, 0x3fb8aa3b, v65
	v_mul_f32_e32 v102, 0x3fb8aa3b, v66
	v_mul_f32_e32 v103, 0x3fb8aa3b, v67
	v_exp_f32_e32 v92, v92
	v_exp_f32_e32 v93, v93
	v_exp_f32_e32 v94, v94
	v_exp_f32_e32 v95, v95
	v_exp_f32_e32 v100, v100
	v_exp_f32_e32 v101, v101
	v_exp_f32_e32 v102, v102
	v_exp_f32_e32 v103, v103
	v_sub_f32_e32 v96, 1.0, v96
	v_sub_f32_e32 v97, 1.0, v97
	v_sub_f32_e32 v98, 1.0, v98
	v_sub_f32_e32 v99, 1.0, v99
	v_mul_f32_e32 v96, v96, v92
	v_mul_f32_e32 v97, v97, v93
	v_mul_f32_e32 v98, v98, v94
	v_mul_f32_e32 v99, v99, v95
	v_lshlrev_b32_e32 v92, 16, v6
	v_and_b32_e32 v93, 0xffff0000, v6
	v_lshlrev_b32_e32 v94, 16, v7
	v_and_b32_e32 v95, 0xffff0000, v7
	v_mul_f32_e32 v92, v92, v100
	v_mul_f32_e32 v93, v93, v101
	v_mul_f32_e32 v94, v94, v102
	v_mul_f32_e32 v95, v95, v103
	v_cvt_pk_bf16_f32 v131, v96, v131
	v_cvt_pk_bf16_f32 v147, v97, v147
	v_cvt_pk_bf16_f32 v181, v98, v181
	v_cvt_pk_bf16_f32 v197, v99, v197
	v_cvt_pk_bf16_f32 v92, v92, v93
	v_cvt_pk_bf16_f32 v93, v94, v95
	v_cvt_pk_bf16_f32 v96, v96, v97
	v_cvt_pk_bf16_f32 v97, v98, v99
	global_store_dwordx2 v112, v[92:93], s[2:3]
	global_store_dwordx2 v114, v[96:97], s[2:3]
	s_sub_u32 s2, s2, 0x400
	s_subb_u32 s3, s3, 0
	v_lshlrev_b32_e32 v92, 16, v8
	v_and_b32_e32 v93, 0xffff0000, v8
	v_lshlrev_b32_e32 v94, 16, v9
	v_and_b32_e32 v95, 0xffff0000, v9
	v_mul_f32_e32 v92, 0xbfb8aa3b, v92
	v_mul_f32_e32 v93, 0xbfb8aa3b, v93
	v_mul_f32_e32 v94, 0xbfb8aa3b, v94
	v_mul_f32_e32 v95, 0xbfb8aa3b, v95
	v_exp_f32_e32 v92, v92
	v_exp_f32_e32 v93, v93
	v_exp_f32_e32 v94, v94
	v_exp_f32_e32 v95, v95
	v_add_f32_e32 v92, 1.0, v92
	v_add_f32_e32 v93, 1.0, v93
	v_add_f32_e32 v94, 1.0, v94
	v_add_f32_e32 v95, 1.0, v95
	v_rcp_f32_e32 v92, v92
	v_rcp_f32_e32 v93, v93
	v_rcp_f32_e32 v94, v94
	v_rcp_f32_e32 v95, v95
	v_fma_f32 v96, v72, v92, v68
	v_fma_f32 v97, v73, v93, v69
	v_fma_f32 v98, v74, v94, v70
	v_fma_f32 v99, v75, v95, v71
	v_cmp_gt_f32_e64 s[22:23], s30, v96
	v_cmp_gt_f32_e64 s[24:25], s30, v97
	v_cmp_gt_f32_e64 s[26:27], s30, v98
	v_cmp_gt_f32_e64 s[28:29], s30, v99
	v_cndmask_b32_e64 v92, 0, 32, s[22:23]
	v_cndmask_b32_e64 v93, 0, 32, s[24:25]
	v_cndmask_b32_e64 v94, 0, 32, s[26:27]
	v_cndmask_b32_e64 v95, 0, 32, s[28:29]
	v_ldexp_f32 v92, v96, v92
	v_ldexp_f32 v93, v97, v93
	v_ldexp_f32 v94, v98, v94
	v_ldexp_f32 v95, v99, v95
	v_log_f32_e32 v92, v92
	v_log_f32_e32 v93, v93
	v_log_f32_e32 v94, v94
	v_log_f32_e32 v95, v95
	v_mul_f32_e32 v100, 0x3f317217, v92
	v_mul_f32_e32 v101, 0x3f317217, v93
	v_mul_f32_e32 v102, 0x3f317217, v94
	v_mul_f32_e32 v103, 0x3f317217, v95
	v_fma_f32 v100, v92, s31, -v100
	v_fma_f32 v101, v93, s31, -v101
	v_fma_f32 v102, v94, s31, -v102
	v_fma_f32 v103, v95, s31, -v103
	v_fmac_f32_e32 v100, 0x3377d1cf, v92
	v_fmac_f32_e32 v101, 0x3377d1cf, v93
	v_fmac_f32_e32 v102, 0x3377d1cf, v94
	v_fmac_f32_e32 v103, 0x3377d1cf, v95
	v_fmac_f32_e32 v100, 0x3f317217, v92
	v_fmac_f32_e32 v101, 0x3f317217, v93
	v_fmac_f32_e32 v102, 0x3f317217, v94
	v_fmac_f32_e32 v103, 0x3f317217, v95
	v_cmp_lt_f32_e64 vcc, |v92|, s34
	v_cndmask_b32_e32 v92, v92, v100, vcc
	v_cmp_lt_f32_e64 vcc, |v93|, s34
	v_cndmask_b32_e32 v93, v93, v101, vcc
	v_cmp_lt_f32_e64 vcc, |v94|, s34
	v_cndmask_b32_e32 v94, v94, v102, vcc
	v_cmp_lt_f32_e64 vcc, |v95|, s34
	v_cndmask_b32_e32 v95, v95, v103, vcc
	v_cndmask_b32_e64 v100, 0, v213, s[22:23]
	v_cndmask_b32_e64 v101, 0, v213, s[24:25]
	v_cndmask_b32_e64 v102, 0, v213, s[26:27]
	v_cndmask_b32_e64 v103, 0, v213, s[28:29]
	v_sub_f32_e32 v92, v92, v100
	v_sub_f32_e32 v93, v93, v101
	v_sub_f32_e32 v94, v94, v102
	v_sub_f32_e32 v95, v95, v103
	v_add_f32_e32 v64, v64, v92
	v_add_f32_e32 v65, v65, v93
	v_add_f32_e32 v66, v66, v94
	v_add_f32_e32 v67, v67, v95
	v_mul_f32_e32 v92, 0xbfb8aa3b, v64
	v_mul_f32_e32 v93, 0xbfb8aa3b, v65
	v_mul_f32_e32 v94, 0xbfb8aa3b, v66
	v_mul_f32_e32 v95, 0xbfb8aa3b, v67
	v_mul_f32_e32 v100, 0x3fb8aa3b, v64
	v_mul_f32_e32 v101, 0x3fb8aa3b, v65
	v_mul_f32_e32 v102, 0x3fb8aa3b, v66
	v_mul_f32_e32 v103, 0x3fb8aa3b, v67
	v_exp_f32_e32 v92, v92
	v_exp_f32_e32 v93, v93
	v_exp_f32_e32 v94, v94
	v_exp_f32_e32 v95, v95
	v_exp_f32_e32 v100, v100
	v_exp_f32_e32 v101, v101
	v_exp_f32_e32 v102, v102
	v_exp_f32_e32 v103, v103
	v_sub_f32_e32 v96, 1.0, v96
	v_sub_f32_e32 v97, 1.0, v97
	v_sub_f32_e32 v98, 1.0, v98
	v_sub_f32_e32 v99, 1.0, v99
	v_mul_f32_e32 v96, v96, v92
	v_mul_f32_e32 v97, v97, v93
	v_mul_f32_e32 v98, v98, v94
	v_mul_f32_e32 v99, v99, v95
	v_lshlrev_b32_e32 v92, 16, v10
	v_and_b32_e32 v93, 0xffff0000, v10
	v_lshlrev_b32_e32 v94, 16, v11
	v_and_b32_e32 v95, 0xffff0000, v11
	v_mul_f32_e32 v92, v92, v100
	v_mul_f32_e32 v93, v93, v101
	v_mul_f32_e32 v94, v94, v102
	v_mul_f32_e32 v95, v95, v103
	v_mov_b32_e32 v130, v96
; DEV u16 f2bf(float f) { return (u16)(pack2(f, f) & 0xffffu); }
; DEV float bf2f(u16 h) { return __uint_as_float(((unsigned)h) << 16); }
; DEV float sigmoid_f(float x) { return __builtin_amdgcn_rcpf(1.f + __expf(-x)); }
; DEV void phase_p15(const Params& p, int g) {
;     ...
;           const float f = lb[cc] + (1.f - lb[cc]) * sigmoid_f(bf2f(xr[st][cc][e]));
;           G[cc] += __logf(f);
;           const float eg = __expf(G[cc]), ig = __expf(-G[cc]);
;           Qp[tok * 512 + c] = f2bf(bf2f(qr[st][cc][e]) * eg);
;           const u16 kk = f2bf((1.f - f) * ig);
;           Kp[tok * 512 + c] = kk;
;           kb[e] = kk;
;         }
;         const int s0 = dir ? 56 - 8 * j8 : 8 * j8;
;         uint4 w;
;         w.x = dir ? (kb[7] | (kb[6] << 16)) : (kb[0] | (kb[1] << 16));
;         w.y = dir ? (kb[5] | (kb[4] << 16)) : (kb[2] | (kb[3] << 16));
;         w.z = dir ? (kb[3] | (kb[2] << 16)) : (kb[4] | (kb[5] << 16));
;         w.w = dir ? (kb[1] | (kb[0] << 16)) : (kb[6] | (kb[7] << 16));
	v_mov_b32_e32 v146, v97
	v_mov_b32_e32 v180, v98
	v_mov_b32_e32 v196, v99
	v_cvt_pk_bf16_f32 v92, v92, v93
	v_cvt_pk_bf16_f32 v93, v94, v95
	v_cvt_pk_bf16_f32 v96, v96, v97
	v_cvt_pk_bf16_f32 v97, v98, v99
	global_store_dwordx2 v112, v[92:93], s[2:3]
	global_store_dwordx2 v114, v[96:97], s[2:3]
	s_sub_u32 s2, s2, 0x400
	s_subb_u32 s3, s3, 0
	v_lshlrev_b32_e32 v92, 16, v12
	v_and_b32_e32 v93, 0xffff0000, v12
	v_lshlrev_b32_e32 v94, 16, v13
	v_and_b32_e32 v95, 0xffff0000, v13
	v_mul_f32_e32 v92, 0xbfb8aa3b, v92
	v_mul_f32_e32 v93, 0xbfb8aa3b, v93
	v_mul_f32_e32 v94, 0xbfb8aa3b, v94
	v_mul_f32_e32 v95, 0xbfb8aa3b, v95
	v_exp_f32_e32 v92, v92
	v_exp_f32_e32 v93, v93
	v_exp_f32_e32 v94, v94
	v_exp_f32_e32 v95, v95
	v_add_f32_e32 v92, 1.0, v92
	v_add_f32_e32 v93, 1.0, v93
	v_add_f32_e32 v94, 1.0, v94
	v_add_f32_e32 v95, 1.0, v95
	v_rcp_f32_e32 v92, v92
	v_rcp_f32_e32 v93, v93
	v_rcp_f32_e32 v94, v94
	v_rcp_f32_e32 v95, v95
	v_fma_f32 v96, v72, v92, v68
	v_fma_f32 v97, v73, v93, v69
	v_fma_f32 v98, v74, v94, v70
	v_fma_f32 v99, v75, v95, v71
	v_cmp_gt_f32_e64 s[22:23], s30, v96
	v_cmp_gt_f32_e64 s[24:25], s30, v97
	v_cmp_gt_f32_e64 s[26:27], s30, v98
	v_cmp_gt_f32_e64 s[28:29], s30, v99
	v_cndmask_b32_e64 v92, 0, 32, s[22:23]
	v_cndmask_b32_e64 v93, 0, 32, s[24:25]
	v_cndmask_b32_e64 v94, 0, 32, s[26:27]
	v_cndmask_b32_e64 v95, 0, 32, s[28:29]
	v_ldexp_f32 v92, v96, v92
	v_ldexp_f32 v93, v97, v93
	v_ldexp_f32 v94, v98, v94
	v_ldexp_f32 v95, v99, v95
	v_log_f32_e32 v92, v92
	v_log_f32_e32 v93, v93
	v_log_f32_e32 v94, v94
	v_log_f32_e32 v95, v95
	v_mul_f32_e32 v100, 0x3f317217, v92
	v_mul_f32_e32 v101, 0x3f317217, v93
	v_mul_f32_e32 v102, 0x3f317217, v94
	v_mul_f32_e32 v103, 0x3f317217, v95
	v_fma_f32 v100, v92, s31, -v100
	v_fma_f32 v101, v93, s31, -v101
	v_fma_f32 v102, v94, s31, -v102
	v_fma_f32 v103, v95, s31, -v103
	v_fmac_f32_e32 v100, 0x3377d1cf, v92
	v_fmac_f32_e32 v101, 0x3377d1cf, v93
	v_fmac_f32_e32 v102, 0x3377d1cf, v94
	v_fmac_f32_e32 v103, 0x3377d1cf, v95
	v_fmac_f32_e32 v100, 0x3f317217, v92
	v_fmac_f32_e32 v101, 0x3f317217, v93
	v_fmac_f32_e32 v102, 0x3f317217, v94
	v_fmac_f32_e32 v103, 0x3f317217, v95
	v_cmp_lt_f32_e64 vcc, |v92|, s34
	v_cndmask_b32_e32 v92, v92, v100, vcc
	v_cmp_lt_f32_e64 vcc, |v93|, s34
	v_cndmask_b32_e32 v93, v93, v101, vcc
	v_cmp_lt_f32_e64 vcc, |v94|, s34
	v_cndmask_b32_e32 v94, v94, v102, vcc
	v_cmp_lt_f32_e64 vcc, |v95|, s34
	v_cndmask_b32_e32 v95, v95, v103, vcc
	v_cndmask_b32_e64 v100, 0, v213, s[22:23]
	v_cndmask_b32_e64 v101, 0, v213, s[24:25]
	v_cndmask_b32_e64 v102, 0, v213, s[26:27]
	v_cndmask_b32_e64 v103, 0, v213, s[28:29]
	v_sub_f32_e32 v92, v92, v100
	v_sub_f32_e32 v93, v93, v101
	v_sub_f32_e32 v94, v94, v102
	v_sub_f32_e32 v95, v95, v103
	v_add_f32_e32 v64, v64, v92
	v_add_f32_e32 v65, v65, v93
	v_add_f32_e32 v66, v66, v94
	v_add_f32_e32 v67, v67, v95
	v_mul_f32_e32 v92, 0xbfb8aa3b, v64
	v_mul_f32_e32 v93, 0xbfb8aa3b, v65
	v_mul_f32_e32 v94, 0xbfb8aa3b, v66
	v_mul_f32_e32 v95, 0xbfb8aa3b, v67
	v_mul_f32_e32 v100, 0x3fb8aa3b, v64
	v_mul_f32_e32 v101, 0x3fb8aa3b, v65
	v_mul_f32_e32 v102, 0x3fb8aa3b, v66
	v_mul_f32_e32 v103, 0x3fb8aa3b, v67
	v_exp_f32_e32 v92, v92
	v_exp_f32_e32 v93, v93
	v_exp_f32_e32 v94, v94
	v_exp_f32_e32 v95, v95
	v_exp_f32_e32 v100, v100
	v_exp_f32_e32 v101, v101
	v_exp_f32_e32 v102, v102
	v_exp_f32_e32 v103, v103
	v_sub_f32_e32 v96, 1.0, v96
	v_sub_f32_e32 v97, 1.0, v97
	v_sub_f32_e32 v98, 1.0, v98
	v_sub_f32_e32 v99, 1.0, v99
	v_mul_f32_e32 v96, v96, v92
	v_mul_f32_e32 v97, v97, v93
	v_mul_f32_e32 v98, v98, v94
	v_mul_f32_e32 v99, v99, v95
	v_lshlrev_b32_e32 v92, 16, v14
	v_and_b32_e32 v93, 0xffff0000, v14
	v_lshlrev_b32_e32 v94, 16, v15
	v_and_b32_e32 v95, 0xffff0000, v15
	v_mul_f32_e32 v92, v92, v100
	v_mul_f32_e32 v93, v93, v101
	v_mul_f32_e32 v94, v94, v102
	v_mul_f32_e32 v95, v95, v103
	v_cvt_pk_bf16_f32 v130, v96, v130
	v_cvt_pk_bf16_f32 v146, v97, v146
	v_cvt_pk_bf16_f32 v180, v98, v180
	v_cvt_pk_bf16_f32 v196, v99, v196
	v_cvt_pk_bf16_f32 v92, v92, v93
	v_cvt_pk_bf16_f32 v93, v94, v95
	v_cvt_pk_bf16_f32 v96, v96, v97
	v_cvt_pk_bf16_f32 v97, v98, v99
	global_store_dwordx2 v112, v[92:93], s[2:3]
	global_store_dwordx2 v114, v[96:97], s[2:3]
	s_sub_u32 s2, s2, 0x400
	s_subb_u32 s3, s3, 0
	v_lshlrev_b32_e32 v92, 16, v16
	v_and_b32_e32 v93, 0xffff0000, v16
	v_lshlrev_b32_e32 v94, 16, v17
	v_and_b32_e32 v95, 0xffff0000, v17
	v_mul_f32_e32 v92, 0xbfb8aa3b, v92
	v_mul_f32_e32 v93, 0xbfb8aa3b, v93
	v_mul_f32_e32 v94, 0xbfb8aa3b, v94
	v_mul_f32_e32 v95, 0xbfb8aa3b, v95
	v_exp_f32_e32 v92, v92
	v_exp_f32_e32 v93, v93
	v_exp_f32_e32 v94, v94
	v_exp_f32_e32 v95, v95
	v_add_f32_e32 v92, 1.0, v92
	v_add_f32_e32 v93, 1.0, v93
	v_add_f32_e32 v94, 1.0, v94
	v_add_f32_e32 v95, 1.0, v95
	v_rcp_f32_e32 v92, v92
	v_rcp_f32_e32 v93, v93
	v_rcp_f32_e32 v94, v94
	v_rcp_f32_e32 v95, v95
	v_fma_f32 v96, v72, v92, v68
	v_fma_f32 v97, v73, v93, v69
	v_fma_f32 v98, v74, v94, v70
	v_fma_f32 v99, v75, v95, v71
	v_cmp_gt_f32_e64 s[22:23], s30, v96
	v_cmp_gt_f32_e64 s[24:25], s30, v97
	v_cmp_gt_f32_e64 s[26:27], s30, v98
	v_cmp_gt_f32_e64 s[28:29], s30, v99
	v_cndmask_b32_e64 v92, 0, 32, s[22:23]
	v_cndmask_b32_e64 v93, 0, 32, s[24:25]
	v_cndmask_b32_e64 v94, 0, 32, s[26:27]
	v_cndmask_b32_e64 v95, 0, 32, s[28:29]
	v_ldexp_f32 v92, v96, v92
	v_ldexp_f32 v93, v97, v93
	v_ldexp_f32 v94, v98, v94
	v_ldexp_f32 v95, v99, v95
	v_log_f32_e32 v92, v92
	v_log_f32_e32 v93, v93
	v_log_f32_e32 v94, v94
	v_log_f32_e32 v95, v95
	v_mul_f32_e32 v100, 0x3f317217, v92
	v_mul_f32_e32 v101, 0x3f317217, v93
	v_mul_f32_e32 v102, 0x3f317217, v94
	v_mul_f32_e32 v103, 0x3f317217, v95
	v_fma_f32 v100, v92, s31, -v100
; DEV u16 f2bf(float f) { return (u16)(pack2(f, f) & 0xffffu); }
; DEV float bf2f(u16 h) { return __uint_as_float(((unsigned)h) << 16); }
; DEV float sigmoid_f(float x) { return __builtin_amdgcn_rcpf(1.f + __expf(-x)); }
; DEV void phase_p15(const Params& p, int g) {
;     ...
;           const float f = lb[cc] + (1.f - lb[cc]) * sigmoid_f(bf2f(xr[st][cc][e]));
;           G[cc] += __logf(f);
;           const float eg = __expf(G[cc]), ig = __expf(-G[cc]);
;           Qp[tok * 512 + c] = f2bf(bf2f(qr[st][cc][e]) * eg);
;           const u16 kk = f2bf((1.f - f) * ig);
;           Kp[tok * 512 + c] = kk;
;           kb[e] = kk;
;         }
;         const int s0 = dir ? 56 - 8 * j8 : 8 * j8;
;         uint4 w;
;         w.x = dir ? (kb[7] | (kb[6] << 16)) : (kb[0] | (kb[1] << 16));
;         w.y = dir ? (kb[5] | (kb[4] << 16)) : (kb[2] | (kb[3] << 16));
;         w.z = dir ? (kb[3] | (kb[2] << 16)) : (kb[4] | (kb[5] << 16));
;         w.w = dir ? (kb[1] | (kb[0] << 16)) : (kb[6] | (kb[7] << 16));
	v_fma_f32 v101, v93, s31, -v101
	v_fma_f32 v102, v94, s31, -v102
	v_fma_f32 v103, v95, s31, -v103
	v_fmac_f32_e32 v100, 0x3377d1cf, v92
	v_fmac_f32_e32 v101, 0x3377d1cf, v93
	v_fmac_f32_e32 v102, 0x3377d1cf, v94
	v_fmac_f32_e32 v103, 0x3377d1cf, v95
	v_fmac_f32_e32 v100, 0x3f317217, v92
	v_fmac_f32_e32 v101, 0x3f317217, v93
	v_fmac_f32_e32 v102, 0x3f317217, v94
	v_fmac_f32_e32 v103, 0x3f317217, v95
	v_cmp_lt_f32_e64 vcc, |v92|, s34
	v_cndmask_b32_e32 v92, v92, v100, vcc
	v_cmp_lt_f32_e64 vcc, |v93|, s34
	v_cndmask_b32_e32 v93, v93, v101, vcc
	v_cmp_lt_f32_e64 vcc, |v94|, s34
	v_cndmask_b32_e32 v94, v94, v102, vcc
	v_cmp_lt_f32_e64 vcc, |v95|, s34
	v_cndmask_b32_e32 v95, v95, v103, vcc
	v_cndmask_b32_e64 v100, 0, v213, s[22:23]
	v_cndmask_b32_e64 v101, 0, v213, s[24:25]
	v_cndmask_b32_e64 v102, 0, v213, s[26:27]
	v_cndmask_b32_e64 v103, 0, v213, s[28:29]
	v_sub_f32_e32 v92, v92, v100
	v_sub_f32_e32 v93, v93, v101
	v_sub_f32_e32 v94, v94, v102
	v_sub_f32_e32 v95, v95, v103
	v_add_f32_e32 v64, v64, v92
	v_add_f32_e32 v65, v65, v93
	v_add_f32_e32 v66, v66, v94
	v_add_f32_e32 v67, v67, v95
	v_mul_f32_e32 v92, 0xbfb8aa3b, v64
	v_mul_f32_e32 v93, 0xbfb8aa3b, v65
	v_mul_f32_e32 v94, 0xbfb8aa3b, v66
	v_mul_f32_e32 v95, 0xbfb8aa3b, v67
	v_mul_f32_e32 v100, 0x3fb8aa3b, v64
	v_mul_f32_e32 v101, 0x3fb8aa3b, v65
	v_mul_f32_e32 v102, 0x3fb8aa3b, v66
	v_mul_f32_e32 v103, 0x3fb8aa3b, v67
	v_exp_f32_e32 v92, v92
	v_exp_f32_e32 v93, v93
	v_exp_f32_e32 v94, v94
	v_exp_f32_e32 v95, v95
	v_exp_f32_e32 v100, v100
	v_exp_f32_e32 v101, v101
	v_exp_f32_e32 v102, v102
	v_exp_f32_e32 v103, v103
	v_sub_f32_e32 v96, 1.0, v96
	v_sub_f32_e32 v97, 1.0, v97
	v_sub_f32_e32 v98, 1.0, v98
	v_sub_f32_e32 v99, 1.0, v99
	v_mul_f32_e32 v96, v96, v92
	v_mul_f32_e32 v97, v97, v93
	v_mul_f32_e32 v98, v98, v94
	v_mul_f32_e32 v99, v99, v95
	v_lshlrev_b32_e32 v92, 16, v18
	v_and_b32_e32 v93, 0xffff0000, v18
	v_lshlrev_b32_e32 v94, 16, v19
	v_and_b32_e32 v95, 0xffff0000, v19
	v_mul_f32_e32 v92, v92, v100
	v_mul_f32_e32 v93, v93, v101
	v_mul_f32_e32 v94, v94, v102
	v_mul_f32_e32 v95, v95, v103
	v_mov_b32_e32 v129, v96
	v_mov_b32_e32 v145, v97
	v_mov_b32_e32 v179, v98
	v_mov_b32_e32 v195, v99
	v_cvt_pk_bf16_f32 v92, v92, v93
	v_cvt_pk_bf16_f32 v93, v94, v95
	v_cvt_pk_bf16_f32 v96, v96, v97
	v_cvt_pk_bf16_f32 v97, v98, v99
	global_store_dwordx2 v112, v[92:93], s[2:3]
	global_store_dwordx2 v114, v[96:97], s[2:3]
	s_sub_u32 s2, s2, 0x400
	s_subb_u32 s3, s3, 0
	v_lshlrev_b32_e32 v92, 16, v20
	v_and_b32_e32 v93, 0xffff0000, v20
	v_lshlrev_b32_e32 v94, 16, v21
	v_and_b32_e32 v95, 0xffff0000, v21
	v_mul_f32_e32 v92, 0xbfb8aa3b, v92
	v_mul_f32_e32 v93, 0xbfb8aa3b, v93
	v_mul_f32_e32 v94, 0xbfb8aa3b, v94
	v_mul_f32_e32 v95, 0xbfb8aa3b, v95
	v_exp_f32_e32 v92, v92
	v_exp_f32_e32 v93, v93
	v_exp_f32_e32 v94, v94
	v_exp_f32_e32 v95, v95
	v_add_f32_e32 v92, 1.0, v92
	v_add_f32_e32 v93, 1.0, v93
	v_add_f32_e32 v94, 1.0, v94
	v_add_f32_e32 v95, 1.0, v95
	v_rcp_f32_e32 v92, v92
	v_rcp_f32_e32 v93, v93
	v_rcp_f32_e32 v94, v94
	v_rcp_f32_e32 v95, v95
	v_fma_f32 v96, v72, v92, v68
	v_fma_f32 v97, v73, v93, v69
	v_fma_f32 v98, v74, v94, v70
	v_fma_f32 v99, v75, v95, v71
	v_cmp_gt_f32_e64 s[22:23], s30, v96
	v_cmp_gt_f32_e64 s[24:25], s30, v97
	v_cmp_gt_f32_e64 s[26:27], s30, v98
	v_cmp_gt_f32_e64 s[28:29], s30, v99
	v_cndmask_b32_e64 v92, 0, 32, s[22:23]
	v_cndmask_b32_e64 v93, 0, 32, s[24:25]
	v_cndmask_b32_e64 v94, 0, 32, s[26:27]
	v_cndmask_b32_e64 v95, 0, 32, s[28:29]
	v_ldexp_f32 v92, v96, v92
	v_ldexp_f32 v93, v97, v93
	v_ldexp_f32 v94, v98, v94
	v_ldexp_f32 v95, v99, v95
	v_log_f32_e32 v92, v92
	v_log_f32_e32 v93, v93
	v_log_f32_e32 v94, v94
	v_log_f32_e32 v95, v95
	v_mul_f32_e32 v100, 0x3f317217, v92
	v_mul_f32_e32 v101, 0x3f317217, v93
	v_mul_f32_e32 v102, 0x3f317217, v94
	v_mul_f32_e32 v103, 0x3f317217, v95
	v_fma_f32 v100, v92, s31, -v100
	v_fma_f32 v101, v93, s31, -v101
	v_fma_f32 v102, v94, s31, -v102
	v_fma_f32 v103, v95, s31, -v103
	v_fmac_f32_e32 v100, 0x3377d1cf, v92
	v_fmac_f32_e32 v101, 0x3377d1cf, v93
	v_fmac_f32_e32 v102, 0x3377d1cf, v94
	v_fmac_f32_e32 v103, 0x3377d1cf, v95
	v_fmac_f32_e32 v100, 0x3f317217, v92
	v_fmac_f32_e32 v101, 0x3f317217, v93
	v_fmac_f32_e32 v102, 0x3f317217, v94
	v_fmac_f32_e32 v103, 0x3f317217, v95
	v_cmp_lt_f32_e64 vcc, |v92|, s34
	v_cndmask_b32_e32 v92, v92, v100, vcc
	v_cmp_lt_f32_e64 vcc, |v93|, s34
	v_cndmask_b32_e32 v93, v93, v101, vcc
	v_cmp_lt_f32_e64 vcc, |v94|, s34
	v_cndmask_b32_e32 v94, v94, v102, vcc
	v_cmp_lt_f32_e64 vcc, |v95|, s34
	v_cndmask_b32_e32 v95, v95, v103, vcc
	v_cndmask_b32_e64 v100, 0, v213, s[22:23]
	v_cndmask_b32_e64 v101, 0, v213, s[24:25]
	v_cndmask_b32_e64 v102, 0, v213, s[26:27]
	v_cndmask_b32_e64 v103, 0, v213, s[28:29]
	v_sub_f32_e32 v92, v92, v100
	v_sub_f32_e32 v93, v93, v101
	v_sub_f32_e32 v94, v94, v102
	v_sub_f32_e32 v95, v95, v103
	v_add_f32_e32 v64, v64, v92
	v_add_f32_e32 v65, v65, v93
	v_add_f32_e32 v66, v66, v94
	v_add_f32_e32 v67, v67, v95
	v_mul_f32_e32 v92, 0xbfb8aa3b, v64
	v_mul_f32_e32 v93, 0xbfb8aa3b, v65
	v_mul_f32_e32 v94, 0xbfb8aa3b, v66
	v_mul_f32_e32 v95, 0xbfb8aa3b, v67
	v_mul_f32_e32 v100, 0x3fb8aa3b, v64
	v_mul_f32_e32 v101, 0x3fb8aa3b, v65
	v_mul_f32_e32 v102, 0x3fb8aa3b, v66
	v_mul_f32_e32 v103, 0x3fb8aa3b, v67
	v_exp_f32_e32 v92, v92
	v_exp_f32_e32 v93, v93
	v_exp_f32_e32 v94, v94
	v_exp_f32_e32 v95, v95
	v_exp_f32_e32 v100, v100
	v_exp_f32_e32 v101, v101
	v_exp_f32_e32 v102, v102
	v_exp_f32_e32 v103, v103
	v_sub_f32_e32 v96, 1.0, v96
	v_sub_f32_e32 v97, 1.0, v97
	v_sub_f32_e32 v98, 1.0, v98
	v_sub_f32_e32 v99, 1.0, v99
	v_mul_f32_e32 v96, v96, v92
	v_mul_f32_e32 v97, v97, v93
	v_mul_f32_e32 v98, v98, v94
; DEV u16 f2bf(float f) { return (u16)(pack2(f, f) & 0xffffu); }
; DEV float bf2f(u16 h) { return __uint_as_float(((unsigned)h) << 16); }
; DEV float sigmoid_f(float x) { return __builtin_amdgcn_rcpf(1.f + __expf(-x)); }
; DEV void phase_p15(const Params& p, int g) {
;     ...
;           const float f = lb[cc] + (1.f - lb[cc]) * sigmoid_f(bf2f(xr[st][cc][e]));
;           G[cc] += __logf(f);
;           const float eg = __expf(G[cc]), ig = __expf(-G[cc]);
;           Qp[tok * 512 + c] = f2bf(bf2f(qr[st][cc][e]) * eg);
;           const u16 kk = f2bf((1.f - f) * ig);
;           Kp[tok * 512 + c] = kk;
;           kb[e] = kk;
;         }
;         const int s0 = dir ? 56 - 8 * j8 : 8 * j8;
;         uint4 w;
;         w.x = dir ? (kb[7] | (kb[6] << 16)) : (kb[0] | (kb[1] << 16));
;         w.y = dir ? (kb[5] | (kb[4] << 16)) : (kb[2] | (kb[3] << 16));
;         w.z = dir ? (kb[3] | (kb[2] << 16)) : (kb[4] | (kb[5] << 16));
;         w.w = dir ? (kb[1] | (kb[0] << 16)) : (kb[6] | (kb[7] << 16));
	v_mul_f32_e32 v99, v99, v95
	v_lshlrev_b32_e32 v92, 16, v22
	v_and_b32_e32 v93, 0xffff0000, v22
	v_lshlrev_b32_e32 v94, 16, v23
	v_and_b32_e32 v95, 0xffff0000, v23
	v_mul_f32_e32 v92, v92, v100
	v_mul_f32_e32 v93, v93, v101
	v_mul_f32_e32 v94, v94, v102
	v_mul_f32_e32 v95, v95, v103
	v_cvt_pk_bf16_f32 v129, v96, v129
	v_cvt_pk_bf16_f32 v145, v97, v145
	v_cvt_pk_bf16_f32 v179, v98, v179
	v_cvt_pk_bf16_f32 v195, v99, v195
	v_cvt_pk_bf16_f32 v92, v92, v93
	v_cvt_pk_bf16_f32 v93, v94, v95
	v_cvt_pk_bf16_f32 v96, v96, v97
	v_cvt_pk_bf16_f32 v97, v98, v99
	global_store_dwordx2 v112, v[92:93], s[2:3]
	global_store_dwordx2 v114, v[96:97], s[2:3]
	s_sub_u32 s2, s2, 0x400
	s_subb_u32 s3, s3, 0
	v_lshlrev_b32_e32 v92, 16, v24
	v_and_b32_e32 v93, 0xffff0000, v24
	v_lshlrev_b32_e32 v94, 16, v25
	v_and_b32_e32 v95, 0xffff0000, v25
	v_mul_f32_e32 v92, 0xbfb8aa3b, v92
	v_mul_f32_e32 v93, 0xbfb8aa3b, v93
	v_mul_f32_e32 v94, 0xbfb8aa3b, v94
	v_mul_f32_e32 v95, 0xbfb8aa3b, v95
	v_exp_f32_e32 v92, v92
	v_exp_f32_e32 v93, v93
	v_exp_f32_e32 v94, v94
	v_exp_f32_e32 v95, v95
	v_add_f32_e32 v92, 1.0, v92
	v_add_f32_e32 v93, 1.0, v93
	v_add_f32_e32 v94, 1.0, v94
	v_add_f32_e32 v95, 1.0, v95
	v_rcp_f32_e32 v92, v92
	v_rcp_f32_e32 v93, v93
	v_rcp_f32_e32 v94, v94
	v_rcp_f32_e32 v95, v95
	v_fma_f32 v96, v72, v92, v68
	v_fma_f32 v97, v73, v93, v69
	v_fma_f32 v98, v74, v94, v70
	v_fma_f32 v99, v75, v95, v71
	v_cmp_gt_f32_e64 s[22:23], s30, v96
	v_cmp_gt_f32_e64 s[24:25], s30, v97
	v_cmp_gt_f32_e64 s[26:27], s30, v98
	v_cmp_gt_f32_e64 s[28:29], s30, v99
	v_cndmask_b32_e64 v92, 0, 32, s[22:23]
	v_cndmask_b32_e64 v93, 0, 32, s[24:25]
	v_cndmask_b32_e64 v94, 0, 32, s[26:27]
	v_cndmask_b32_e64 v95, 0, 32, s[28:29]
	v_ldexp_f32 v92, v96, v92
	v_ldexp_f32 v93, v97, v93
	v_ldexp_f32 v94, v98, v94
	v_ldexp_f32 v95, v99, v95
	v_log_f32_e32 v92, v92
	v_log_f32_e32 v93, v93
	v_log_f32_e32 v94, v94
	v_log_f32_e32 v95, v95
	v_mul_f32_e32 v100, 0x3f317217, v92
	v_mul_f32_e32 v101, 0x3f317217, v93
	v_mul_f32_e32 v102, 0x3f317217, v94
	v_mul_f32_e32 v103, 0x3f317217, v95
	v_fma_f32 v100, v92, s31, -v100
	v_fma_f32 v101, v93, s31, -v101
	v_fma_f32 v102, v94, s31, -v102
	v_fma_f32 v103, v95, s31, -v103
	v_fmac_f32_e32 v100, 0x3377d1cf, v92
	v_fmac_f32_e32 v101, 0x3377d1cf, v93
	v_fmac_f32_e32 v102, 0x3377d1cf, v94
	v_fmac_f32_e32 v103, 0x3377d1cf, v95
	v_fmac_f32_e32 v100, 0x3f317217, v92
	v_fmac_f32_e32 v101, 0x3f317217, v93
	v_fmac_f32_e32 v102, 0x3f317217, v94
	v_fmac_f32_e32 v103, 0x3f317217, v95
	v_cmp_lt_f32_e64 vcc, |v92|, s34
	v_cndmask_b32_e32 v92, v92, v100, vcc
	v_cmp_lt_f32_e64 vcc, |v93|, s34
	v_cndmask_b32_e32 v93, v93, v101, vcc
	v_cmp_lt_f32_e64 vcc, |v94|, s34
	v_cndmask_b32_e32 v94, v94, v102, vcc
	v_cmp_lt_f32_e64 vcc, |v95|, s34
	v_cndmask_b32_e32 v95, v95, v103, vcc
	v_cndmask_b32_e64 v100, 0, v213, s[22:23]
	v_cndmask_b32_e64 v101, 0, v213, s[24:25]
	v_cndmask_b32_e64 v102, 0, v213, s[26:27]
	v_cndmask_b32_e64 v103, 0, v213, s[28:29]
	v_sub_f32_e32 v92, v92, v100
	v_sub_f32_e32 v93, v93, v101
	v_sub_f32_e32 v94, v94, v102
	v_sub_f32_e32 v95, v95, v103
	v_add_f32_e32 v64, v64, v92
	v_add_f32_e32 v65, v65, v93
	v_add_f32_e32 v66, v66, v94
	v_add_f32_e32 v67, v67, v95
	v_mul_f32_e32 v92, 0xbfb8aa3b, v64
	v_mul_f32_e32 v93, 0xbfb8aa3b, v65
	v_mul_f32_e32 v94, 0xbfb8aa3b, v66
	v_mul_f32_e32 v95, 0xbfb8aa3b, v67
	v_mul_f32_e32 v100, 0x3fb8aa3b, v64
	v_mul_f32_e32 v101, 0x3fb8aa3b, v65
	v_mul_f32_e32 v102, 0x3fb8aa3b, v66
	v_mul_f32_e32 v103, 0x3fb8aa3b, v67
	v_exp_f32_e32 v92, v92
	v_exp_f32_e32 v93, v93
	v_exp_f32_e32 v94, v94
	v_exp_f32_e32 v95, v95
	v_exp_f32_e32 v100, v100
	v_exp_f32_e32 v101, v101
	v_exp_f32_e32 v102, v102
	v_exp_f32_e32 v103, v103
	v_sub_f32_e32 v96, 1.0, v96
	v_sub_f32_e32 v97, 1.0, v97
	v_sub_f32_e32 v98, 1.0, v98
	v_sub_f32_e32 v99, 1.0, v99
	v_mul_f32_e32 v96, v96, v92
	v_mul_f32_e32 v97, v97, v93
	v_mul_f32_e32 v98, v98, v94
	v_mul_f32_e32 v99, v99, v95
	v_lshlrev_b32_e32 v92, 16, v26
	v_and_b32_e32 v93, 0xffff0000, v26
	v_lshlrev_b32_e32 v94, 16, v27
	v_and_b32_e32 v95, 0xffff0000, v27
	v_mul_f32_e32 v92, v92, v100
	v_mul_f32_e32 v93, v93, v101
	v_mul_f32_e32 v94, v94, v102
	v_mul_f32_e32 v95, v95, v103
	v_mov_b32_e32 v128, v96
	v_mov_b32_e32 v144, v97
	v_mov_b32_e32 v178, v98
	v_mov_b32_e32 v194, v99
	v_cvt_pk_bf16_f32 v92, v92, v93
	v_cvt_pk_bf16_f32 v93, v94, v95
	v_cvt_pk_bf16_f32 v96, v96, v97
	v_cvt_pk_bf16_f32 v97, v98, v99
	global_store_dwordx2 v112, v[92:93], s[2:3]
	global_store_dwordx2 v114, v[96:97], s[2:3]
	s_sub_u32 s2, s2, 0x400
	s_subb_u32 s3, s3, 0
	v_lshlrev_b32_e32 v92, 16, v28
	v_and_b32_e32 v93, 0xffff0000, v28
	v_lshlrev_b32_e32 v94, 16, v29
	v_and_b32_e32 v95, 0xffff0000, v29
	v_mul_f32_e32 v92, 0xbfb8aa3b, v92
	v_mul_f32_e32 v93, 0xbfb8aa3b, v93
	v_mul_f32_e32 v94, 0xbfb8aa3b, v94
	v_mul_f32_e32 v95, 0xbfb8aa3b, v95
	v_exp_f32_e32 v92, v92
	v_exp_f32_e32 v93, v93
	v_exp_f32_e32 v94, v94
	v_exp_f32_e32 v95, v95
	v_add_f32_e32 v92, 1.0, v92
	v_add_f32_e32 v93, 1.0, v93
	v_add_f32_e32 v94, 1.0, v94
	v_add_f32_e32 v95, 1.0, v95
	v_rcp_f32_e32 v92, v92
	v_rcp_f32_e32 v93, v93
	v_rcp_f32_e32 v94, v94
	v_rcp_f32_e32 v95, v95
	v_fma_f32 v96, v72, v92, v68
	v_fma_f32 v97, v73, v93, v69
	v_fma_f32 v98, v74, v94, v70
	v_fma_f32 v99, v75, v95, v71
	v_cmp_gt_f32_e64 s[22:23], s30, v96
	v_cmp_gt_f32_e64 s[24:25], s30, v97
	v_cmp_gt_f32_e64 s[26:27], s30, v98
	v_cmp_gt_f32_e64 s[28:29], s30, v99
	v_cndmask_b32_e64 v92, 0, 32, s[22:23]
	v_cndmask_b32_e64 v93, 0, 32, s[24:25]
	v_cndmask_b32_e64 v94, 0, 32, s[26:27]
	v_cndmask_b32_e64 v95, 0, 32, s[28:29]
	v_ldexp_f32 v92, v96, v92
	v_ldexp_f32 v93, v97, v93
	v_ldexp_f32 v94, v98, v94
; DEV u16 f2bf(float f) { return (u16)(pack2(f, f) & 0xffffu); }
; DEV float bf2f(u16 h) { return __uint_as_float(((unsigned)h) << 16); }
; DEV float sigmoid_f(float x) { return __builtin_amdgcn_rcpf(1.f + __expf(-x)); }
; DEV void phase_p15(const Params& p, int g) {
;     ...
;     P15_LOAD(0, 0);
;     P15_LOAD(1, 1);
; #pragma unroll
;     for (int j8 = 0; j8 < 8; ++j8) {
;       const int st = j8 % 3;
;       if (j8 < 6) { P15_LOAD((j8 + 2) % 3, j8 + 2); }
;     ...
;           const float f = lb[cc] + (1.f - lb[cc]) * sigmoid_f(bf2f(xr[st][cc][e]));
;           G[cc] += __logf(f);
;           const float eg = __expf(G[cc]), ig = __expf(-G[cc]);
;           Qp[tok * 512 + c] = f2bf(bf2f(qr[st][cc][e]) * eg);
;           const u16 kk = f2bf((1.f - f) * ig);
;           Kp[tok * 512 + c] = kk;
;           kb[e] = kk;
;         }
;         const int s0 = dir ? 56 - 8 * j8 : 8 * j8;
;         uint4 w;
;         w.x = dir ? (kb[7] | (kb[6] << 16)) : (kb[0] | (kb[1] << 16));
;         w.y = dir ? (kb[5] | (kb[4] << 16)) : (kb[2] | (kb[3] << 16));
;         w.z = dir ? (kb[3] | (kb[2] << 16)) : (kb[4] | (kb[5] << 16));
;         w.w = dir ? (kb[1] | (kb[0] << 16)) : (kb[6] | (kb[7] << 16));
	v_ldexp_f32 v95, v99, v95
	v_log_f32_e32 v92, v92
	v_log_f32_e32 v93, v93
	v_log_f32_e32 v94, v94
	v_log_f32_e32 v95, v95
	v_mul_f32_e32 v100, 0x3f317217, v92
	v_mul_f32_e32 v101, 0x3f317217, v93
	v_mul_f32_e32 v102, 0x3f317217, v94
	v_mul_f32_e32 v103, 0x3f317217, v95
	v_fma_f32 v100, v92, s31, -v100
	v_fma_f32 v101, v93, s31, -v101
	v_fma_f32 v102, v94, s31, -v102
	v_fma_f32 v103, v95, s31, -v103
	v_fmac_f32_e32 v100, 0x3377d1cf, v92
	v_fmac_f32_e32 v101, 0x3377d1cf, v93
	v_fmac_f32_e32 v102, 0x3377d1cf, v94
	v_fmac_f32_e32 v103, 0x3377d1cf, v95
	v_fmac_f32_e32 v100, 0x3f317217, v92
	v_fmac_f32_e32 v101, 0x3f317217, v93
	v_fmac_f32_e32 v102, 0x3f317217, v94
	v_fmac_f32_e32 v103, 0x3f317217, v95
	v_cmp_lt_f32_e64 vcc, |v92|, s34
	v_cndmask_b32_e32 v92, v92, v100, vcc
	v_cmp_lt_f32_e64 vcc, |v93|, s34
	v_cndmask_b32_e32 v93, v93, v101, vcc
	v_cmp_lt_f32_e64 vcc, |v94|, s34
	v_cndmask_b32_e32 v94, v94, v102, vcc
	v_cmp_lt_f32_e64 vcc, |v95|, s34
	v_cndmask_b32_e32 v95, v95, v103, vcc
	v_cndmask_b32_e64 v100, 0, v213, s[22:23]
	v_cndmask_b32_e64 v101, 0, v213, s[24:25]
	v_cndmask_b32_e64 v102, 0, v213, s[26:27]
	v_cndmask_b32_e64 v103, 0, v213, s[28:29]
	v_sub_f32_e32 v92, v92, v100
	v_sub_f32_e32 v93, v93, v101
	v_sub_f32_e32 v94, v94, v102
	v_sub_f32_e32 v95, v95, v103
	v_add_f32_e32 v64, v64, v92
	v_add_f32_e32 v65, v65, v93
	v_add_f32_e32 v66, v66, v94
	v_add_f32_e32 v67, v67, v95
	v_mul_f32_e32 v92, 0xbfb8aa3b, v64
	v_mul_f32_e32 v93, 0xbfb8aa3b, v65
	v_mul_f32_e32 v94, 0xbfb8aa3b, v66
	v_mul_f32_e32 v95, 0xbfb8aa3b, v67
	v_mul_f32_e32 v100, 0x3fb8aa3b, v64
	v_mul_f32_e32 v101, 0x3fb8aa3b, v65
	v_mul_f32_e32 v102, 0x3fb8aa3b, v66
	v_mul_f32_e32 v103, 0x3fb8aa3b, v67
	v_exp_f32_e32 v92, v92
	v_exp_f32_e32 v93, v93
	v_exp_f32_e32 v94, v94
	v_exp_f32_e32 v95, v95
	v_exp_f32_e32 v100, v100
	v_exp_f32_e32 v101, v101
	v_exp_f32_e32 v102, v102
	v_exp_f32_e32 v103, v103
	v_sub_f32_e32 v96, 1.0, v96
	v_sub_f32_e32 v97, 1.0, v97
	v_sub_f32_e32 v98, 1.0, v98
	v_sub_f32_e32 v99, 1.0, v99
	v_mul_f32_e32 v96, v96, v92
	v_mul_f32_e32 v97, v97, v93
	v_mul_f32_e32 v98, v98, v94
	v_mul_f32_e32 v99, v99, v95
	v_lshlrev_b32_e32 v92, 16, v30
	v_and_b32_e32 v93, 0xffff0000, v30
	v_lshlrev_b32_e32 v94, 16, v31
	v_and_b32_e32 v95, 0xffff0000, v31
	v_mul_f32_e32 v92, v92, v100
	v_mul_f32_e32 v93, v93, v101
	v_mul_f32_e32 v94, v94, v102
	v_mul_f32_e32 v95, v95, v103
	v_cvt_pk_bf16_f32 v128, v96, v128
	v_cvt_pk_bf16_f32 v144, v97, v144
	v_cvt_pk_bf16_f32 v178, v98, v178
	v_cvt_pk_bf16_f32 v194, v99, v194
	v_cvt_pk_bf16_f32 v92, v92, v93
	v_cvt_pk_bf16_f32 v93, v94, v95
	v_cvt_pk_bf16_f32 v96, v96, v97
	v_cvt_pk_bf16_f32 v97, v98, v99
	global_store_dwordx2 v112, v[92:93], s[2:3]
	global_store_dwordx2 v114, v[96:97], s[2:3]
	s_sub_u32 s2, s2, 0x400
	s_subb_u32 s3, s3, 0
	global_load_dwordx2 v[0:1], v113, s[0:1]
	global_load_dwordx2 v[2:3], v112, s[0:1]
	s_sub_u32 s0, s0, 0x1400
	s_subb_u32 s1, s1, 0
	global_load_dwordx2 v[4:5], v113, s[0:1]
	global_load_dwordx2 v[6:7], v112, s[0:1]
	s_sub_u32 s0, s0, 0x1400
	s_subb_u32 s1, s1, 0
	global_load_dwordx2 v[8:9], v113, s[0:1]
	global_load_dwordx2 v[10:11], v112, s[0:1]
	s_sub_u32 s0, s0, 0x1400
	s_subb_u32 s1, s1, 0
	global_load_dwordx2 v[12:13], v113, s[0:1]
	global_load_dwordx2 v[14:15], v112, s[0:1]
	s_sub_u32 s0, s0, 0x1400
	s_subb_u32 s1, s1, 0
	global_load_dwordx2 v[16:17], v113, s[0:1]
	global_load_dwordx2 v[18:19], v112, s[0:1]
	s_sub_u32 s0, s0, 0x1400
	s_subb_u32 s1, s1, 0
	global_load_dwordx2 v[20:21], v113, s[0:1]
	global_load_dwordx2 v[22:23], v112, s[0:1]
	s_sub_u32 s0, s0, 0x1400
	s_subb_u32 s1, s1, 0
	global_load_dwordx2 v[24:25], v113, s[0:1]
	global_load_dwordx2 v[26:27], v112, s[0:1]
	s_sub_u32 s0, s0, 0x1400
	s_subb_u32 s1, s1, 0
	global_load_dwordx2 v[28:29], v113, s[0:1]
	global_load_dwordx2 v[30:31], v112, s[0:1]
	s_sub_u32 s0, s0, 0x1400
	s_subb_u32 s1, s1, 0
	s_waitcnt vmcnt(32)
	v_lshlrev_b32_e32 v92, 16, v32
	v_and_b32_e32 v93, 0xffff0000, v32
	v_lshlrev_b32_e32 v94, 16, v33
	v_and_b32_e32 v95, 0xffff0000, v33
	v_mul_f32_e32 v92, 0xbfb8aa3b, v92
	v_mul_f32_e32 v93, 0xbfb8aa3b, v93
	v_mul_f32_e32 v94, 0xbfb8aa3b, v94
	v_mul_f32_e32 v95, 0xbfb8aa3b, v95
	v_exp_f32_e32 v92, v92
	v_exp_f32_e32 v93, v93
	v_exp_f32_e32 v94, v94
	v_exp_f32_e32 v95, v95
	v_add_f32_e32 v92, 1.0, v92
	v_add_f32_e32 v93, 1.0, v93
	v_add_f32_e32 v94, 1.0, v94
	v_add_f32_e32 v95, 1.0, v95
	v_rcp_f32_e32 v92, v92
	v_rcp_f32_e32 v93, v93
	v_rcp_f32_e32 v94, v94
	v_rcp_f32_e32 v95, v95
	v_fma_f32 v96, v72, v92, v68
	v_fma_f32 v97, v73, v93, v69
	v_fma_f32 v98, v74, v94, v70
	v_fma_f32 v99, v75, v95, v71
	v_cmp_gt_f32_e64 s[22:23], s30, v96
	v_cmp_gt_f32_e64 s[24:25], s30, v97
	v_cmp_gt_f32_e64 s[26:27], s30, v98
	v_cmp_gt_f32_e64 s[28:29], s30, v99
	v_cndmask_b32_e64 v92, 0, 32, s[22:23]
	v_cndmask_b32_e64 v93, 0, 32, s[24:25]
	v_cndmask_b32_e64 v94, 0, 32, s[26:27]
	v_cndmask_b32_e64 v95, 0, 32, s[28:29]
	v_ldexp_f32 v92, v96, v92
	v_ldexp_f32 v93, v97, v93
	v_ldexp_f32 v94, v98, v94
	v_ldexp_f32 v95, v99, v95
	v_log_f32_e32 v92, v92
	v_log_f32_e32 v93, v93
	v_log_f32_e32 v94, v94
	v_log_f32_e32 v95, v95
	v_mul_f32_e32 v100, 0x3f317217, v92
	v_mul_f32_e32 v101, 0x3f317217, v93
	v_mul_f32_e32 v102, 0x3f317217, v94
	v_mul_f32_e32 v103, 0x3f317217, v95
	v_fma_f32 v100, v92, s31, -v100
	v_fma_f32 v101, v93, s31, -v101
	v_fma_f32 v102, v94, s31, -v102
	v_fma_f32 v103, v95, s31, -v103
	v_fmac_f32_e32 v100, 0x3377d1cf, v92
	v_fmac_f32_e32 v101, 0x3377d1cf, v93
	v_fmac_f32_e32 v102, 0x3377d1cf, v94
	v_fmac_f32_e32 v103, 0x3377d1cf, v95
	v_fmac_f32_e32 v100, 0x3f317217, v92
	v_fmac_f32_e32 v101, 0x3f317217, v93
; DEV u16 f2bf(float f) { return (u16)(pack2(f, f) & 0xffffu); }
; DEV float bf2f(u16 h) { return __uint_as_float(((unsigned)h) << 16); }
; DEV float sigmoid_f(float x) { return __builtin_amdgcn_rcpf(1.f + __expf(-x)); }
; DEV void phase_p15(const Params& p, int g) {
;     ...
;           const float f = lb[cc] + (1.f - lb[cc]) * sigmoid_f(bf2f(xr[st][cc][e]));
;           G[cc] += __logf(f);
;           const float eg = __expf(G[cc]), ig = __expf(-G[cc]);
;           Qp[tok * 512 + c] = f2bf(bf2f(qr[st][cc][e]) * eg);
;           const u16 kk = f2bf((1.f - f) * ig);
;           Kp[tok * 512 + c] = kk;
;           kb[e] = kk;
;         }
;         const int s0 = dir ? 56 - 8 * j8 : 8 * j8;
;         uint4 w;
;         w.x = dir ? (kb[7] | (kb[6] << 16)) : (kb[0] | (kb[1] << 16));
;         w.y = dir ? (kb[5] | (kb[4] << 16)) : (kb[2] | (kb[3] << 16));
;         w.z = dir ? (kb[3] | (kb[2] << 16)) : (kb[4] | (kb[5] << 16));
;         w.w = dir ? (kb[1] | (kb[0] << 16)) : (kb[6] | (kb[7] << 16));
	v_fmac_f32_e32 v102, 0x3f317217, v94
	v_fmac_f32_e32 v103, 0x3f317217, v95
	v_cmp_lt_f32_e64 vcc, |v92|, s34
	v_cndmask_b32_e32 v92, v92, v100, vcc
	v_cmp_lt_f32_e64 vcc, |v93|, s34
	v_cndmask_b32_e32 v93, v93, v101, vcc
	v_cmp_lt_f32_e64 vcc, |v94|, s34
	v_cndmask_b32_e32 v94, v94, v102, vcc
	v_cmp_lt_f32_e64 vcc, |v95|, s34
	v_cndmask_b32_e32 v95, v95, v103, vcc
	v_cndmask_b32_e64 v100, 0, v213, s[22:23]
	v_cndmask_b32_e64 v101, 0, v213, s[24:25]
	v_cndmask_b32_e64 v102, 0, v213, s[26:27]
	v_cndmask_b32_e64 v103, 0, v213, s[28:29]
	v_sub_f32_e32 v92, v92, v100
	v_sub_f32_e32 v93, v93, v101
	v_sub_f32_e32 v94, v94, v102
	v_sub_f32_e32 v95, v95, v103
	v_add_f32_e32 v64, v64, v92
	v_add_f32_e32 v65, v65, v93
	v_add_f32_e32 v66, v66, v94
	v_add_f32_e32 v67, v67, v95
	v_mul_f32_e32 v92, 0xbfb8aa3b, v64
	v_mul_f32_e32 v93, 0xbfb8aa3b, v65
	v_mul_f32_e32 v94, 0xbfb8aa3b, v66
	v_mul_f32_e32 v95, 0xbfb8aa3b, v67
	v_mul_f32_e32 v100, 0x3fb8aa3b, v64
	v_mul_f32_e32 v101, 0x3fb8aa3b, v65
	v_mul_f32_e32 v102, 0x3fb8aa3b, v66
	v_mul_f32_e32 v103, 0x3fb8aa3b, v67
	v_exp_f32_e32 v92, v92
	v_exp_f32_e32 v93, v93
	v_exp_f32_e32 v94, v94
	v_exp_f32_e32 v95, v95
	v_exp_f32_e32 v100, v100
	v_exp_f32_e32 v101, v101
	v_exp_f32_e32 v102, v102
	v_exp_f32_e32 v103, v103
	v_sub_f32_e32 v96, 1.0, v96
	v_sub_f32_e32 v97, 1.0, v97
	v_sub_f32_e32 v98, 1.0, v98
	v_sub_f32_e32 v99, 1.0, v99
	v_mul_f32_e32 v96, v96, v92
	v_mul_f32_e32 v97, v97, v93
	v_mul_f32_e32 v98, v98, v94
	v_mul_f32_e32 v99, v99, v95
	v_lshlrev_b32_e32 v92, 16, v34
	v_and_b32_e32 v93, 0xffff0000, v34
	v_lshlrev_b32_e32 v94, 16, v35
	v_and_b32_e32 v95, 0xffff0000, v35
	v_mul_f32_e32 v92, v92, v100
	v_mul_f32_e32 v93, v93, v101
	v_mul_f32_e32 v94, v94, v102
	v_mul_f32_e32 v95, v95, v103
	v_mov_b32_e32 v127, v96
	v_mov_b32_e32 v143, v97
	v_mov_b32_e32 v177, v98
	v_mov_b32_e32 v193, v99
	v_cvt_pk_bf16_f32 v92, v92, v93
	v_cvt_pk_bf16_f32 v93, v94, v95
	v_cvt_pk_bf16_f32 v96, v96, v97
	v_cvt_pk_bf16_f32 v97, v98, v99
	global_store_dwordx2 v112, v[92:93], s[2:3]
	global_store_dwordx2 v114, v[96:97], s[2:3]
	s_sub_u32 s2, s2, 0x400
	s_subb_u32 s3, s3, 0
	v_lshlrev_b32_e32 v92, 16, v36
	v_and_b32_e32 v93, 0xffff0000, v36
	v_lshlrev_b32_e32 v94, 16, v37
	v_and_b32_e32 v95, 0xffff0000, v37
	v_mul_f32_e32 v92, 0xbfb8aa3b, v92
	v_mul_f32_e32 v93, 0xbfb8aa3b, v93
	v_mul_f32_e32 v94, 0xbfb8aa3b, v94
	v_mul_f32_e32 v95, 0xbfb8aa3b, v95
	v_exp_f32_e32 v92, v92
	v_exp_f32_e32 v93, v93
	v_exp_f32_e32 v94, v94
	v_exp_f32_e32 v95, v95
	v_add_f32_e32 v92, 1.0, v92
	v_add_f32_e32 v93, 1.0, v93
	v_add_f32_e32 v94, 1.0, v94
	v_add_f32_e32 v95, 1.0, v95
	v_rcp_f32_e32 v92, v92
	v_rcp_f32_e32 v93, v93
	v_rcp_f32_e32 v94, v94
	v_rcp_f32_e32 v95, v95
	v_fma_f32 v96, v72, v92, v68
	v_fma_f32 v97, v73, v93, v69
	v_fma_f32 v98, v74, v94, v70
	v_fma_f32 v99, v75, v95, v71
	v_cmp_gt_f32_e64 s[22:23], s30, v96
	v_cmp_gt_f32_e64 s[24:25], s30, v97
	v_cmp_gt_f32_e64 s[26:27], s30, v98
	v_cmp_gt_f32_e64 s[28:29], s30, v99
	v_cndmask_b32_e64 v92, 0, 32, s[22:23]
	v_cndmask_b32_e64 v93, 0, 32, s[24:25]
	v_cndmask_b32_e64 v94, 0, 32, s[26:27]
	v_cndmask_b32_e64 v95, 0, 32, s[28:29]
	v_ldexp_f32 v92, v96, v92
	v_ldexp_f32 v93, v97, v93
	v_ldexp_f32 v94, v98, v94
	v_ldexp_f32 v95, v99, v95
	v_log_f32_e32 v92, v92
	v_log_f32_e32 v93, v93
	v_log_f32_e32 v94, v94
	v_log_f32_e32 v95, v95
	v_mul_f32_e32 v100, 0x3f317217, v92
	v_mul_f32_e32 v101, 0x3f317217, v93
	v_mul_f32_e32 v102, 0x3f317217, v94
	v_mul_f32_e32 v103, 0x3f317217, v95
	v_fma_f32 v100, v92, s31, -v100
	v_fma_f32 v101, v93, s31, -v101
	v_fma_f32 v102, v94, s31, -v102
	v_fma_f32 v103, v95, s31, -v103
	v_fmac_f32_e32 v100, 0x3377d1cf, v92
	v_fmac_f32_e32 v101, 0x3377d1cf, v93
	v_fmac_f32_e32 v102, 0x3377d1cf, v94
	v_fmac_f32_e32 v103, 0x3377d1cf, v95
	v_fmac_f32_e32 v100, 0x3f317217, v92
	v_fmac_f32_e32 v101, 0x3f317217, v93
	v_fmac_f32_e32 v102, 0x3f317217, v94
	v_fmac_f32_e32 v103, 0x3f317217, v95
	v_cmp_lt_f32_e64 vcc, |v92|, s34
	v_cndmask_b32_e32 v92, v92, v100, vcc
	v_cmp_lt_f32_e64 vcc, |v93|, s34
	v_cndmask_b32_e32 v93, v93, v101, vcc
	v_cmp_lt_f32_e64 vcc, |v94|, s34
	v_cndmask_b32_e32 v94, v94, v102, vcc
	v_cmp_lt_f32_e64 vcc, |v95|, s34
	v_cndmask_b32_e32 v95, v95, v103, vcc
	v_cndmask_b32_e64 v100, 0, v213, s[22:23]
	v_cndmask_b32_e64 v101, 0, v213, s[24:25]
	v_cndmask_b32_e64 v102, 0, v213, s[26:27]
	v_cndmask_b32_e64 v103, 0, v213, s[28:29]
	v_sub_f32_e32 v92, v92, v100
	v_sub_f32_e32 v93, v93, v101
	v_sub_f32_e32 v94, v94, v102
	v_sub_f32_e32 v95, v95, v103
	v_add_f32_e32 v64, v64, v92
	v_add_f32_e32 v65, v65, v93
	v_add_f32_e32 v66, v66, v94
	v_add_f32_e32 v67, v67, v95
	v_mul_f32_e32 v92, 0xbfb8aa3b, v64
	v_mul_f32_e32 v93, 0xbfb8aa3b, v65
	v_mul_f32_e32 v94, 0xbfb8aa3b, v66
	v_mul_f32_e32 v95, 0xbfb8aa3b, v67
	v_mul_f32_e32 v100, 0x3fb8aa3b, v64
	v_mul_f32_e32 v101, 0x3fb8aa3b, v65
	v_mul_f32_e32 v102, 0x3fb8aa3b, v66
	v_mul_f32_e32 v103, 0x3fb8aa3b, v67
	v_exp_f32_e32 v92, v92
	v_exp_f32_e32 v93, v93
	v_exp_f32_e32 v94, v94
	v_exp_f32_e32 v95, v95
	v_exp_f32_e32 v100, v100
	v_exp_f32_e32 v101, v101
	v_exp_f32_e32 v102, v102
	v_exp_f32_e32 v103, v103
	v_sub_f32_e32 v96, 1.0, v96
	v_sub_f32_e32 v97, 1.0, v97
	v_sub_f32_e32 v98, 1.0, v98
	v_sub_f32_e32 v99, 1.0, v99
	v_mul_f32_e32 v96, v96, v92
	v_mul_f32_e32 v97, v97, v93
	v_mul_f32_e32 v98, v98, v94
	v_mul_f32_e32 v99, v99, v95
	v_lshlrev_b32_e32 v92, 16, v38
	v_and_b32_e32 v93, 0xffff0000, v38
	v_lshlrev_b32_e32 v94, 16, v39
	v_and_b32_e32 v95, 0xffff0000, v39
	v_mul_f32_e32 v92, v92, v100
	v_mul_f32_e32 v93, v93, v101
	v_mul_f32_e32 v94, v94, v102
	v_mul_f32_e32 v95, v95, v103
	v_cvt_pk_bf16_f32 v127, v96, v127
; DEV u16 f2bf(float f) { return (u16)(pack2(f, f) & 0xffffu); }
; DEV float bf2f(u16 h) { return __uint_as_float(((unsigned)h) << 16); }
; DEV float sigmoid_f(float x) { return __builtin_amdgcn_rcpf(1.f + __expf(-x)); }
; DEV void phase_p15(const Params& p, int g) {
;     ...
;           const float f = lb[cc] + (1.f - lb[cc]) * sigmoid_f(bf2f(xr[st][cc][e]));
;           G[cc] += __logf(f);
;           const float eg = __expf(G[cc]), ig = __expf(-G[cc]);
;           Qp[tok * 512 + c] = f2bf(bf2f(qr[st][cc][e]) * eg);
;           const u16 kk = f2bf((1.f - f) * ig);
;           Kp[tok * 512 + c] = kk;
;           kb[e] = kk;
;         }
;         const int s0 = dir ? 56 - 8 * j8 : 8 * j8;
;         uint4 w;
;         w.x = dir ? (kb[7] | (kb[6] << 16)) : (kb[0] | (kb[1] << 16));
;         w.y = dir ? (kb[5] | (kb[4] << 16)) : (kb[2] | (kb[3] << 16));
;         w.z = dir ? (kb[3] | (kb[2] << 16)) : (kb[4] | (kb[5] << 16));
;         w.w = dir ? (kb[1] | (kb[0] << 16)) : (kb[6] | (kb[7] << 16));
	v_cvt_pk_bf16_f32 v143, v97, v143
	v_cvt_pk_bf16_f32 v177, v98, v177
	v_cvt_pk_bf16_f32 v193, v99, v193
	v_cvt_pk_bf16_f32 v92, v92, v93
	v_cvt_pk_bf16_f32 v93, v94, v95
	v_cvt_pk_bf16_f32 v96, v96, v97
	v_cvt_pk_bf16_f32 v97, v98, v99
	global_store_dwordx2 v112, v[92:93], s[2:3]
	global_store_dwordx2 v114, v[96:97], s[2:3]
	s_sub_u32 s2, s2, 0x400
	s_subb_u32 s3, s3, 0
	v_lshlrev_b32_e32 v92, 16, v40
	v_and_b32_e32 v93, 0xffff0000, v40
	v_lshlrev_b32_e32 v94, 16, v41
	v_and_b32_e32 v95, 0xffff0000, v41
	v_mul_f32_e32 v92, 0xbfb8aa3b, v92
	v_mul_f32_e32 v93, 0xbfb8aa3b, v93
	v_mul_f32_e32 v94, 0xbfb8aa3b, v94
	v_mul_f32_e32 v95, 0xbfb8aa3b, v95
	v_exp_f32_e32 v92, v92
	v_exp_f32_e32 v93, v93
	v_exp_f32_e32 v94, v94
	v_exp_f32_e32 v95, v95
	v_add_f32_e32 v92, 1.0, v92
	v_add_f32_e32 v93, 1.0, v93
	v_add_f32_e32 v94, 1.0, v94
	v_add_f32_e32 v95, 1.0, v95
	v_rcp_f32_e32 v92, v92
	v_rcp_f32_e32 v93, v93
	v_rcp_f32_e32 v94, v94
	v_rcp_f32_e32 v95, v95
	v_fma_f32 v96, v72, v92, v68
	v_fma_f32 v97, v73, v93, v69
	v_fma_f32 v98, v74, v94, v70
	v_fma_f32 v99, v75, v95, v71
	v_cmp_gt_f32_e64 s[22:23], s30, v96
	v_cmp_gt_f32_e64 s[24:25], s30, v97
	v_cmp_gt_f32_e64 s[26:27], s30, v98
	v_cmp_gt_f32_e64 s[28:29], s30, v99
	v_cndmask_b32_e64 v92, 0, 32, s[22:23]
	v_cndmask_b32_e64 v93, 0, 32, s[24:25]
	v_cndmask_b32_e64 v94, 0, 32, s[26:27]
	v_cndmask_b32_e64 v95, 0, 32, s[28:29]
	v_ldexp_f32 v92, v96, v92
	v_ldexp_f32 v93, v97, v93
	v_ldexp_f32 v94, v98, v94
	v_ldexp_f32 v95, v99, v95
	v_log_f32_e32 v92, v92
	v_log_f32_e32 v93, v93
	v_log_f32_e32 v94, v94
	v_log_f32_e32 v95, v95
	v_mul_f32_e32 v100, 0x3f317217, v92
	v_mul_f32_e32 v101, 0x3f317217, v93
	v_mul_f32_e32 v102, 0x3f317217, v94
	v_mul_f32_e32 v103, 0x3f317217, v95
	v_fma_f32 v100, v92, s31, -v100
	v_fma_f32 v101, v93, s31, -v101
	v_fma_f32 v102, v94, s31, -v102
	v_fma_f32 v103, v95, s31, -v103
	v_fmac_f32_e32 v100, 0x3377d1cf, v92
	v_fmac_f32_e32 v101, 0x3377d1cf, v93
	v_fmac_f32_e32 v102, 0x3377d1cf, v94
	v_fmac_f32_e32 v103, 0x3377d1cf, v95
	v_fmac_f32_e32 v100, 0x3f317217, v92
	v_fmac_f32_e32 v101, 0x3f317217, v93
	v_fmac_f32_e32 v102, 0x3f317217, v94
	v_fmac_f32_e32 v103, 0x3f317217, v95
	v_cmp_lt_f32_e64 vcc, |v92|, s34
	v_cndmask_b32_e32 v92, v92, v100, vcc
	v_cmp_lt_f32_e64 vcc, |v93|, s34
	v_cndmask_b32_e32 v93, v93, v101, vcc
	v_cmp_lt_f32_e64 vcc, |v94|, s34
	v_cndmask_b32_e32 v94, v94, v102, vcc
	v_cmp_lt_f32_e64 vcc, |v95|, s34
	v_cndmask_b32_e32 v95, v95, v103, vcc
	v_cndmask_b32_e64 v100, 0, v213, s[22:23]
	v_cndmask_b32_e64 v101, 0, v213, s[24:25]
	v_cndmask_b32_e64 v102, 0, v213, s[26:27]
	v_cndmask_b32_e64 v103, 0, v213, s[28:29]
	v_sub_f32_e32 v92, v92, v100
	v_sub_f32_e32 v93, v93, v101
	v_sub_f32_e32 v94, v94, v102
	v_sub_f32_e32 v95, v95, v103
	v_add_f32_e32 v64, v64, v92
	v_add_f32_e32 v65, v65, v93
	v_add_f32_e32 v66, v66, v94
	v_add_f32_e32 v67, v67, v95
	v_mul_f32_e32 v92, 0xbfb8aa3b, v64
	v_mul_f32_e32 v93, 0xbfb8aa3b, v65
	v_mul_f32_e32 v94, 0xbfb8aa3b, v66
	v_mul_f32_e32 v95, 0xbfb8aa3b, v67
	v_mul_f32_e32 v100, 0x3fb8aa3b, v64
	v_mul_f32_e32 v101, 0x3fb8aa3b, v65
	v_mul_f32_e32 v102, 0x3fb8aa3b, v66
	v_mul_f32_e32 v103, 0x3fb8aa3b, v67
	v_exp_f32_e32 v92, v92
	v_exp_f32_e32 v93, v93
	v_exp_f32_e32 v94, v94
	v_exp_f32_e32 v95, v95
	v_exp_f32_e32 v100, v100
	v_exp_f32_e32 v101, v101
	v_exp_f32_e32 v102, v102
	v_exp_f32_e32 v103, v103
	v_sub_f32_e32 v96, 1.0, v96
	v_sub_f32_e32 v97, 1.0, v97
	v_sub_f32_e32 v98, 1.0, v98
	v_sub_f32_e32 v99, 1.0, v99
	v_mul_f32_e32 v96, v96, v92
	v_mul_f32_e32 v97, v97, v93
	v_mul_f32_e32 v98, v98, v94
	v_mul_f32_e32 v99, v99, v95
	v_lshlrev_b32_e32 v92, 16, v42
	v_and_b32_e32 v93, 0xffff0000, v42
	v_lshlrev_b32_e32 v94, 16, v43
	v_and_b32_e32 v95, 0xffff0000, v43
	v_mul_f32_e32 v92, v92, v100
	v_mul_f32_e32 v93, v93, v101
	v_mul_f32_e32 v94, v94, v102
	v_mul_f32_e32 v95, v95, v103
	v_mov_b32_e32 v126, v96
	v_mov_b32_e32 v142, v97
	v_mov_b32_e32 v176, v98
	v_mov_b32_e32 v192, v99
	v_cvt_pk_bf16_f32 v92, v92, v93
	v_cvt_pk_bf16_f32 v93, v94, v95
	v_cvt_pk_bf16_f32 v96, v96, v97
	v_cvt_pk_bf16_f32 v97, v98, v99
	global_store_dwordx2 v112, v[92:93], s[2:3]
	global_store_dwordx2 v114, v[96:97], s[2:3]
	s_sub_u32 s2, s2, 0x400
	s_subb_u32 s3, s3, 0
	v_lshlrev_b32_e32 v92, 16, v44
	v_and_b32_e32 v93, 0xffff0000, v44
	v_lshlrev_b32_e32 v94, 16, v45
	v_and_b32_e32 v95, 0xffff0000, v45
	v_mul_f32_e32 v92, 0xbfb8aa3b, v92
	v_mul_f32_e32 v93, 0xbfb8aa3b, v93
	v_mul_f32_e32 v94, 0xbfb8aa3b, v94
	v_mul_f32_e32 v95, 0xbfb8aa3b, v95
	v_exp_f32_e32 v92, v92
	v_exp_f32_e32 v93, v93
	v_exp_f32_e32 v94, v94
	v_exp_f32_e32 v95, v95
	v_add_f32_e32 v92, 1.0, v92
	v_add_f32_e32 v93, 1.0, v93
	v_add_f32_e32 v94, 1.0, v94
	v_add_f32_e32 v95, 1.0, v95
	v_rcp_f32_e32 v92, v92
	v_rcp_f32_e32 v93, v93
	v_rcp_f32_e32 v94, v94
	v_rcp_f32_e32 v95, v95
	v_fma_f32 v96, v72, v92, v68
	v_fma_f32 v97, v73, v93, v69
	v_fma_f32 v98, v74, v94, v70
	v_fma_f32 v99, v75, v95, v71
	v_cmp_gt_f32_e64 s[22:23], s30, v96
	v_cmp_gt_f32_e64 s[24:25], s30, v97
	v_cmp_gt_f32_e64 s[26:27], s30, v98
	v_cmp_gt_f32_e64 s[28:29], s30, v99
	v_cndmask_b32_e64 v92, 0, 32, s[22:23]
	v_cndmask_b32_e64 v93, 0, 32, s[24:25]
	v_cndmask_b32_e64 v94, 0, 32, s[26:27]
	v_cndmask_b32_e64 v95, 0, 32, s[28:29]
	v_ldexp_f32 v92, v96, v92
	v_ldexp_f32 v93, v97, v93
	v_ldexp_f32 v94, v98, v94
	v_ldexp_f32 v95, v99, v95
	v_log_f32_e32 v92, v92
	v_log_f32_e32 v93, v93
	v_log_f32_e32 v94, v94
	v_log_f32_e32 v95, v95
	v_mul_f32_e32 v100, 0x3f317217, v92
	v_mul_f32_e32 v101, 0x3f317217, v93
	v_mul_f32_e32 v102, 0x3f317217, v94
	v_mul_f32_e32 v103, 0x3f317217, v95
	v_fma_f32 v100, v92, s31, -v100
; DEV u16 f2bf(float f) { return (u16)(pack2(f, f) & 0xffffu); }
; DEV float bf2f(u16 h) { return __uint_as_float(((unsigned)h) << 16); }
; DEV float sigmoid_f(float x) { return __builtin_amdgcn_rcpf(1.f + __expf(-x)); }
; DEV void phase_p15(const Params& p, int g) {
;     ...
;           const float f = lb[cc] + (1.f - lb[cc]) * sigmoid_f(bf2f(xr[st][cc][e]));
;           G[cc] += __logf(f);
;           const float eg = __expf(G[cc]), ig = __expf(-G[cc]);
;           Qp[tok * 512 + c] = f2bf(bf2f(qr[st][cc][e]) * eg);
;           const u16 kk = f2bf((1.f - f) * ig);
;           Kp[tok * 512 + c] = kk;
;           kb[e] = kk;
;         }
;         const int s0 = dir ? 56 - 8 * j8 : 8 * j8;
;         uint4 w;
;         w.x = dir ? (kb[7] | (kb[6] << 16)) : (kb[0] | (kb[1] << 16));
;         w.y = dir ? (kb[5] | (kb[4] << 16)) : (kb[2] | (kb[3] << 16));
;         w.z = dir ? (kb[3] | (kb[2] << 16)) : (kb[4] | (kb[5] << 16));
;         w.w = dir ? (kb[1] | (kb[0] << 16)) : (kb[6] | (kb[7] << 16));
	v_fma_f32 v101, v93, s31, -v101
	v_fma_f32 v102, v94, s31, -v102
	v_fma_f32 v103, v95, s31, -v103
	v_fmac_f32_e32 v100, 0x3377d1cf, v92
	v_fmac_f32_e32 v101, 0x3377d1cf, v93
	v_fmac_f32_e32 v102, 0x3377d1cf, v94
	v_fmac_f32_e32 v103, 0x3377d1cf, v95
	v_fmac_f32_e32 v100, 0x3f317217, v92
	v_fmac_f32_e32 v101, 0x3f317217, v93
	v_fmac_f32_e32 v102, 0x3f317217, v94
	v_fmac_f32_e32 v103, 0x3f317217, v95
	v_cmp_lt_f32_e64 vcc, |v92|, s34
	v_cndmask_b32_e32 v92, v92, v100, vcc
	v_cmp_lt_f32_e64 vcc, |v93|, s34
	v_cndmask_b32_e32 v93, v93, v101, vcc
	v_cmp_lt_f32_e64 vcc, |v94|, s34
	v_cndmask_b32_e32 v94, v94, v102, vcc
	v_cmp_lt_f32_e64 vcc, |v95|, s34
	v_cndmask_b32_e32 v95, v95, v103, vcc
	v_cndmask_b32_e64 v100, 0, v213, s[22:23]
	v_cndmask_b32_e64 v101, 0, v213, s[24:25]
	v_cndmask_b32_e64 v102, 0, v213, s[26:27]
	v_cndmask_b32_e64 v103, 0, v213, s[28:29]
	v_sub_f32_e32 v92, v92, v100
	v_sub_f32_e32 v93, v93, v101
	v_sub_f32_e32 v94, v94, v102
	v_sub_f32_e32 v95, v95, v103
	v_add_f32_e32 v64, v64, v92
	v_add_f32_e32 v65, v65, v93
	v_add_f32_e32 v66, v66, v94
	v_add_f32_e32 v67, v67, v95
	v_mul_f32_e32 v92, 0xbfb8aa3b, v64
	v_mul_f32_e32 v93, 0xbfb8aa3b, v65
	v_mul_f32_e32 v94, 0xbfb8aa3b, v66
	v_mul_f32_e32 v95, 0xbfb8aa3b, v67
	v_mul_f32_e32 v100, 0x3fb8aa3b, v64
	v_mul_f32_e32 v101, 0x3fb8aa3b, v65
	v_mul_f32_e32 v102, 0x3fb8aa3b, v66
	v_mul_f32_e32 v103, 0x3fb8aa3b, v67
	v_exp_f32_e32 v92, v92
	v_exp_f32_e32 v93, v93
	v_exp_f32_e32 v94, v94
	v_exp_f32_e32 v95, v95
	v_exp_f32_e32 v100, v100
	v_exp_f32_e32 v101, v101
	v_exp_f32_e32 v102, v102
	v_exp_f32_e32 v103, v103
	v_sub_f32_e32 v96, 1.0, v96
	v_sub_f32_e32 v97, 1.0, v97
	v_sub_f32_e32 v98, 1.0, v98
	v_sub_f32_e32 v99, 1.0, v99
	v_mul_f32_e32 v96, v96, v92
	v_mul_f32_e32 v97, v97, v93
	v_mul_f32_e32 v98, v98, v94
	v_mul_f32_e32 v99, v99, v95
	v_lshlrev_b32_e32 v92, 16, v46
	v_and_b32_e32 v93, 0xffff0000, v46
	v_lshlrev_b32_e32 v94, 16, v47
	v_and_b32_e32 v95, 0xffff0000, v47
	v_mul_f32_e32 v92, v92, v100
	v_mul_f32_e32 v93, v93, v101
	v_mul_f32_e32 v94, v94, v102
	v_mul_f32_e32 v95, v95, v103
	v_cvt_pk_bf16_f32 v126, v96, v126
	v_cvt_pk_bf16_f32 v142, v97, v142
	v_cvt_pk_bf16_f32 v176, v98, v176
	v_cvt_pk_bf16_f32 v192, v99, v192
	v_cvt_pk_bf16_f32 v92, v92, v93
	v_cvt_pk_bf16_f32 v93, v94, v95
	v_cvt_pk_bf16_f32 v96, v96, v97
	v_cvt_pk_bf16_f32 v97, v98, v99
	global_store_dwordx2 v112, v[92:93], s[2:3]
	global_store_dwordx2 v114, v[96:97], s[2:3]
	s_sub_u32 s2, s2, 0x400
	s_subb_u32 s3, s3, 0
	v_lshlrev_b32_e32 v92, 16, v48
	v_and_b32_e32 v93, 0xffff0000, v48
	v_lshlrev_b32_e32 v94, 16, v49
	v_and_b32_e32 v95, 0xffff0000, v49
	v_mul_f32_e32 v92, 0xbfb8aa3b, v92
	v_mul_f32_e32 v93, 0xbfb8aa3b, v93
	v_mul_f32_e32 v94, 0xbfb8aa3b, v94
	v_mul_f32_e32 v95, 0xbfb8aa3b, v95
	v_exp_f32_e32 v92, v92
	v_exp_f32_e32 v93, v93
	v_exp_f32_e32 v94, v94
	v_exp_f32_e32 v95, v95
	v_add_f32_e32 v92, 1.0, v92
	v_add_f32_e32 v93, 1.0, v93
	v_add_f32_e32 v94, 1.0, v94
	v_add_f32_e32 v95, 1.0, v95
	v_rcp_f32_e32 v92, v92
	v_rcp_f32_e32 v93, v93
	v_rcp_f32_e32 v94, v94
	v_rcp_f32_e32 v95, v95
	v_fma_f32 v96, v72, v92, v68
	v_fma_f32 v97, v73, v93, v69
	v_fma_f32 v98, v74, v94, v70
	v_fma_f32 v99, v75, v95, v71
	v_cmp_gt_f32_e64 s[22:23], s30, v96
	v_cmp_gt_f32_e64 s[24:25], s30, v97
	v_cmp_gt_f32_e64 s[26:27], s30, v98
	v_cmp_gt_f32_e64 s[28:29], s30, v99
	v_cndmask_b32_e64 v92, 0, 32, s[22:23]
	v_cndmask_b32_e64 v93, 0, 32, s[24:25]
	v_cndmask_b32_e64 v94, 0, 32, s[26:27]
	v_cndmask_b32_e64 v95, 0, 32, s[28:29]
	v_ldexp_f32 v92, v96, v92
	v_ldexp_f32 v93, v97, v93
	v_ldexp_f32 v94, v98, v94
	v_ldexp_f32 v95, v99, v95
	v_log_f32_e32 v92, v92
	v_log_f32_e32 v93, v93
	v_log_f32_e32 v94, v94
	v_log_f32_e32 v95, v95
	v_mul_f32_e32 v100, 0x3f317217, v92
	v_mul_f32_e32 v101, 0x3f317217, v93
	v_mul_f32_e32 v102, 0x3f317217, v94
	v_mul_f32_e32 v103, 0x3f317217, v95
	v_fma_f32 v100, v92, s31, -v100
	v_fma_f32 v101, v93, s31, -v101
	v_fma_f32 v102, v94, s31, -v102
	v_fma_f32 v103, v95, s31, -v103
	v_fmac_f32_e32 v100, 0x3377d1cf, v92
	v_fmac_f32_e32 v101, 0x3377d1cf, v93
	v_fmac_f32_e32 v102, 0x3377d1cf, v94
	v_fmac_f32_e32 v103, 0x3377d1cf, v95
	v_fmac_f32_e32 v100, 0x3f317217, v92
	v_fmac_f32_e32 v101, 0x3f317217, v93
	v_fmac_f32_e32 v102, 0x3f317217, v94
	v_fmac_f32_e32 v103, 0x3f317217, v95
	v_cmp_lt_f32_e64 vcc, |v92|, s34
	v_cndmask_b32_e32 v92, v92, v100, vcc
	v_cmp_lt_f32_e64 vcc, |v93|, s34
	v_cndmask_b32_e32 v93, v93, v101, vcc
	v_cmp_lt_f32_e64 vcc, |v94|, s34
	v_cndmask_b32_e32 v94, v94, v102, vcc
	v_cmp_lt_f32_e64 vcc, |v95|, s34
	v_cndmask_b32_e32 v95, v95, v103, vcc
	v_cndmask_b32_e64 v100, 0, v213, s[22:23]
	v_cndmask_b32_e64 v101, 0, v213, s[24:25]
	v_cndmask_b32_e64 v102, 0, v213, s[26:27]
	v_cndmask_b32_e64 v103, 0, v213, s[28:29]
	v_sub_f32_e32 v92, v92, v100
	v_sub_f32_e32 v93, v93, v101
	v_sub_f32_e32 v94, v94, v102
	v_sub_f32_e32 v95, v95, v103
	v_add_f32_e32 v64, v64, v92
	v_add_f32_e32 v65, v65, v93
	v_add_f32_e32 v66, v66, v94
	v_add_f32_e32 v67, v67, v95
	v_mul_f32_e32 v92, 0xbfb8aa3b, v64
	v_mul_f32_e32 v93, 0xbfb8aa3b, v65
	v_mul_f32_e32 v94, 0xbfb8aa3b, v66
	v_mul_f32_e32 v95, 0xbfb8aa3b, v67
	v_mul_f32_e32 v100, 0x3fb8aa3b, v64
	v_mul_f32_e32 v101, 0x3fb8aa3b, v65
	v_mul_f32_e32 v102, 0x3fb8aa3b, v66
	v_mul_f32_e32 v103, 0x3fb8aa3b, v67
	v_exp_f32_e32 v92, v92
	v_exp_f32_e32 v93, v93
	v_exp_f32_e32 v94, v94
	v_exp_f32_e32 v95, v95
	v_exp_f32_e32 v100, v100
	v_exp_f32_e32 v101, v101
	v_exp_f32_e32 v102, v102
	v_exp_f32_e32 v103, v103
	v_sub_f32_e32 v96, 1.0, v96
	v_sub_f32_e32 v97, 1.0, v97
	v_sub_f32_e32 v98, 1.0, v98
	v_sub_f32_e32 v99, 1.0, v99
	v_mul_f32_e32 v96, v96, v92
; DEV u16 f2bf(float f) { return (u16)(pack2(f, f) & 0xffffu); }
; DEV float bf2f(u16 h) { return __uint_as_float(((unsigned)h) << 16); }
; DEV float sigmoid_f(float x) { return __builtin_amdgcn_rcpf(1.f + __expf(-x)); }
; DEV void phase_p15(const Params& p, int g) {
;     ...
;           const float f = lb[cc] + (1.f - lb[cc]) * sigmoid_f(bf2f(xr[st][cc][e]));
;           G[cc] += __logf(f);
;           const float eg = __expf(G[cc]), ig = __expf(-G[cc]);
;           Qp[tok * 512 + c] = f2bf(bf2f(qr[st][cc][e]) * eg);
;           const u16 kk = f2bf((1.f - f) * ig);
;           Kp[tok * 512 + c] = kk;
;           kb[e] = kk;
;         }
;         const int s0 = dir ? 56 - 8 * j8 : 8 * j8;
;         uint4 w;
;         w.x = dir ? (kb[7] | (kb[6] << 16)) : (kb[0] | (kb[1] << 16));
;         w.y = dir ? (kb[5] | (kb[4] << 16)) : (kb[2] | (kb[3] << 16));
;         w.z = dir ? (kb[3] | (kb[2] << 16)) : (kb[4] | (kb[5] << 16));
;         w.w = dir ? (kb[1] | (kb[0] << 16)) : (kb[6] | (kb[7] << 16));
	v_mul_f32_e32 v97, v97, v93
	v_mul_f32_e32 v98, v98, v94
	v_mul_f32_e32 v99, v99, v95
	v_lshlrev_b32_e32 v92, 16, v50
	v_and_b32_e32 v93, 0xffff0000, v50
	v_lshlrev_b32_e32 v94, 16, v51
	v_and_b32_e32 v95, 0xffff0000, v51
	v_mul_f32_e32 v92, v92, v100
	v_mul_f32_e32 v93, v93, v101
	v_mul_f32_e32 v94, v94, v102
	v_mul_f32_e32 v95, v95, v103
	v_mov_b32_e32 v125, v96
	v_mov_b32_e32 v141, v97
	v_mov_b32_e32 v175, v98
	v_mov_b32_e32 v191, v99
	v_cvt_pk_bf16_f32 v92, v92, v93
	v_cvt_pk_bf16_f32 v93, v94, v95
	v_cvt_pk_bf16_f32 v96, v96, v97
	v_cvt_pk_bf16_f32 v97, v98, v99
	global_store_dwordx2 v112, v[92:93], s[2:3]
	global_store_dwordx2 v114, v[96:97], s[2:3]
	s_sub_u32 s2, s2, 0x400
	s_subb_u32 s3, s3, 0
	v_lshlrev_b32_e32 v92, 16, v52
	v_and_b32_e32 v93, 0xffff0000, v52
	v_lshlrev_b32_e32 v94, 16, v53
	v_and_b32_e32 v95, 0xffff0000, v53
	v_mul_f32_e32 v92, 0xbfb8aa3b, v92
	v_mul_f32_e32 v93, 0xbfb8aa3b, v93
	v_mul_f32_e32 v94, 0xbfb8aa3b, v94
	v_mul_f32_e32 v95, 0xbfb8aa3b, v95
	v_exp_f32_e32 v92, v92
	v_exp_f32_e32 v93, v93
	v_exp_f32_e32 v94, v94
	v_exp_f32_e32 v95, v95
	v_add_f32_e32 v92, 1.0, v92
	v_add_f32_e32 v93, 1.0, v93
	v_add_f32_e32 v94, 1.0, v94
	v_add_f32_e32 v95, 1.0, v95
	v_rcp_f32_e32 v92, v92
	v_rcp_f32_e32 v93, v93
	v_rcp_f32_e32 v94, v94
	v_rcp_f32_e32 v95, v95
	v_fma_f32 v96, v72, v92, v68
	v_fma_f32 v97, v73, v93, v69
	v_fma_f32 v98, v74, v94, v70
	v_fma_f32 v99, v75, v95, v71
	v_cmp_gt_f32_e64 s[22:23], s30, v96
	v_cmp_gt_f32_e64 s[24:25], s30, v97
	v_cmp_gt_f32_e64 s[26:27], s30, v98
	v_cmp_gt_f32_e64 s[28:29], s30, v99
	v_cndmask_b32_e64 v92, 0, 32, s[22:23]
	v_cndmask_b32_e64 v93, 0, 32, s[24:25]
	v_cndmask_b32_e64 v94, 0, 32, s[26:27]
	v_cndmask_b32_e64 v95, 0, 32, s[28:29]
	v_ldexp_f32 v92, v96, v92
	v_ldexp_f32 v93, v97, v93
	v_ldexp_f32 v94, v98, v94
	v_ldexp_f32 v95, v99, v95
	v_log_f32_e32 v92, v92
	v_log_f32_e32 v93, v93
	v_log_f32_e32 v94, v94
	v_log_f32_e32 v95, v95
	v_mul_f32_e32 v100, 0x3f317217, v92
	v_mul_f32_e32 v101, 0x3f317217, v93
	v_mul_f32_e32 v102, 0x3f317217, v94
	v_mul_f32_e32 v103, 0x3f317217, v95
	v_fma_f32 v100, v92, s31, -v100
	v_fma_f32 v101, v93, s31, -v101
	v_fma_f32 v102, v94, s31, -v102
	v_fma_f32 v103, v95, s31, -v103
	v_fmac_f32_e32 v100, 0x3377d1cf, v92
	v_fmac_f32_e32 v101, 0x3377d1cf, v93
	v_fmac_f32_e32 v102, 0x3377d1cf, v94
	v_fmac_f32_e32 v103, 0x3377d1cf, v95
	v_fmac_f32_e32 v100, 0x3f317217, v92
	v_fmac_f32_e32 v101, 0x3f317217, v93
	v_fmac_f32_e32 v102, 0x3f317217, v94
	v_fmac_f32_e32 v103, 0x3f317217, v95
	v_cmp_lt_f32_e64 vcc, |v92|, s34
	v_cndmask_b32_e32 v92, v92, v100, vcc
	v_cmp_lt_f32_e64 vcc, |v93|, s34
	v_cndmask_b32_e32 v93, v93, v101, vcc
	v_cmp_lt_f32_e64 vcc, |v94|, s34
	v_cndmask_b32_e32 v94, v94, v102, vcc
	v_cmp_lt_f32_e64 vcc, |v95|, s34
	v_cndmask_b32_e32 v95, v95, v103, vcc
	v_cndmask_b32_e64 v100, 0, v213, s[22:23]
	v_cndmask_b32_e64 v101, 0, v213, s[24:25]
	v_cndmask_b32_e64 v102, 0, v213, s[26:27]
	v_cndmask_b32_e64 v103, 0, v213, s[28:29]
	v_sub_f32_e32 v92, v92, v100
	v_sub_f32_e32 v93, v93, v101
	v_sub_f32_e32 v94, v94, v102
	v_sub_f32_e32 v95, v95, v103
	v_add_f32_e32 v64, v64, v92
	v_add_f32_e32 v65, v65, v93
	v_add_f32_e32 v66, v66, v94
	v_add_f32_e32 v67, v67, v95
	v_mul_f32_e32 v92, 0xbfb8aa3b, v64
	v_mul_f32_e32 v93, 0xbfb8aa3b, v65
	v_mul_f32_e32 v94, 0xbfb8aa3b, v66
	v_mul_f32_e32 v95, 0xbfb8aa3b, v67
	v_mul_f32_e32 v100, 0x3fb8aa3b, v64
	v_mul_f32_e32 v101, 0x3fb8aa3b, v65
	v_mul_f32_e32 v102, 0x3fb8aa3b, v66
	v_mul_f32_e32 v103, 0x3fb8aa3b, v67
	v_exp_f32_e32 v92, v92
	v_exp_f32_e32 v93, v93
	v_exp_f32_e32 v94, v94
	v_exp_f32_e32 v95, v95
	v_exp_f32_e32 v100, v100
	v_exp_f32_e32 v101, v101
	v_exp_f32_e32 v102, v102
	v_exp_f32_e32 v103, v103
	v_sub_f32_e32 v96, 1.0, v96
	v_sub_f32_e32 v97, 1.0, v97
	v_sub_f32_e32 v98, 1.0, v98
	v_sub_f32_e32 v99, 1.0, v99
	v_mul_f32_e32 v96, v96, v92
	v_mul_f32_e32 v97, v97, v93
	v_mul_f32_e32 v98, v98, v94
	v_mul_f32_e32 v99, v99, v95
	v_lshlrev_b32_e32 v92, 16, v54
	v_and_b32_e32 v93, 0xffff0000, v54
	v_lshlrev_b32_e32 v94, 16, v55
	v_and_b32_e32 v95, 0xffff0000, v55
	v_mul_f32_e32 v92, v92, v100
	v_mul_f32_e32 v93, v93, v101
	v_mul_f32_e32 v94, v94, v102
	v_mul_f32_e32 v95, v95, v103
	v_cvt_pk_bf16_f32 v125, v96, v125
	v_cvt_pk_bf16_f32 v141, v97, v141
	v_cvt_pk_bf16_f32 v175, v98, v175
	v_cvt_pk_bf16_f32 v191, v99, v191
	v_cvt_pk_bf16_f32 v92, v92, v93
	v_cvt_pk_bf16_f32 v93, v94, v95
	v_cvt_pk_bf16_f32 v96, v96, v97
	v_cvt_pk_bf16_f32 v97, v98, v99
	global_store_dwordx2 v112, v[92:93], s[2:3]
	global_store_dwordx2 v114, v[96:97], s[2:3]
	s_sub_u32 s2, s2, 0x400
	s_subb_u32 s3, s3, 0
	v_lshlrev_b32_e32 v92, 16, v56
	v_and_b32_e32 v93, 0xffff0000, v56
	v_lshlrev_b32_e32 v94, 16, v57
	v_and_b32_e32 v95, 0xffff0000, v57
	v_mul_f32_e32 v92, 0xbfb8aa3b, v92
	v_mul_f32_e32 v93, 0xbfb8aa3b, v93
	v_mul_f32_e32 v94, 0xbfb8aa3b, v94
	v_mul_f32_e32 v95, 0xbfb8aa3b, v95
	v_exp_f32_e32 v92, v92
	v_exp_f32_e32 v93, v93
	v_exp_f32_e32 v94, v94
	v_exp_f32_e32 v95, v95
	v_add_f32_e32 v92, 1.0, v92
	v_add_f32_e32 v93, 1.0, v93
	v_add_f32_e32 v94, 1.0, v94
	v_add_f32_e32 v95, 1.0, v95
	v_rcp_f32_e32 v92, v92
	v_rcp_f32_e32 v93, v93
	v_rcp_f32_e32 v94, v94
	v_rcp_f32_e32 v95, v95
	v_fma_f32 v96, v72, v92, v68
	v_fma_f32 v97, v73, v93, v69
	v_fma_f32 v98, v74, v94, v70
	v_fma_f32 v99, v75, v95, v71
	v_cmp_gt_f32_e64 s[22:23], s30, v96
	v_cmp_gt_f32_e64 s[24:25], s30, v97
	v_cmp_gt_f32_e64 s[26:27], s30, v98
	v_cmp_gt_f32_e64 s[28:29], s30, v99
	v_cndmask_b32_e64 v92, 0, 32, s[22:23]
	v_cndmask_b32_e64 v93, 0, 32, s[24:25]
	v_cndmask_b32_e64 v94, 0, 32, s[26:27]
	v_cndmask_b32_e64 v95, 0, 32, s[28:29]
	v_ldexp_f32 v92, v96, v92
; DEV u16 f2bf(float f) { return (u16)(pack2(f, f) & 0xffffu); }
; DEV float bf2f(u16 h) { return __uint_as_float(((unsigned)h) << 16); }
; DEV float sigmoid_f(float x) { return __builtin_amdgcn_rcpf(1.f + __expf(-x)); }
; DEV void phase_p15(const Params& p, int g) {
;     ...
;           const float f = lb[cc] + (1.f - lb[cc]) * sigmoid_f(bf2f(xr[st][cc][e]));
;           G[cc] += __logf(f);
;           const float eg = __expf(G[cc]), ig = __expf(-G[cc]);
;           Qp[tok * 512 + c] = f2bf(bf2f(qr[st][cc][e]) * eg);
;           const u16 kk = f2bf((1.f - f) * ig);
;           Kp[tok * 512 + c] = kk;
;           kb[e] = kk;
;         }
;         const int s0 = dir ? 56 - 8 * j8 : 8 * j8;
;         uint4 w;
;         w.x = dir ? (kb[7] | (kb[6] << 16)) : (kb[0] | (kb[1] << 16));
;         w.y = dir ? (kb[5] | (kb[4] << 16)) : (kb[2] | (kb[3] << 16));
;         w.z = dir ? (kb[3] | (kb[2] << 16)) : (kb[4] | (kb[5] << 16));
;         w.w = dir ? (kb[1] | (kb[0] << 16)) : (kb[6] | (kb[7] << 16));
	v_ldexp_f32 v93, v97, v93
	v_ldexp_f32 v94, v98, v94
	v_ldexp_f32 v95, v99, v95
	v_log_f32_e32 v92, v92
	v_log_f32_e32 v93, v93
	v_log_f32_e32 v94, v94
	v_log_f32_e32 v95, v95
	v_mul_f32_e32 v100, 0x3f317217, v92
	v_mul_f32_e32 v101, 0x3f317217, v93
	v_mul_f32_e32 v102, 0x3f317217, v94
	v_mul_f32_e32 v103, 0x3f317217, v95
	v_fma_f32 v100, v92, s31, -v100
	v_fma_f32 v101, v93, s31, -v101
	v_fma_f32 v102, v94, s31, -v102
	v_fma_f32 v103, v95, s31, -v103
	v_fmac_f32_e32 v100, 0x3377d1cf, v92
	v_fmac_f32_e32 v101, 0x3377d1cf, v93
	v_fmac_f32_e32 v102, 0x3377d1cf, v94
	v_fmac_f32_e32 v103, 0x3377d1cf, v95
	v_fmac_f32_e32 v100, 0x3f317217, v92
	v_fmac_f32_e32 v101, 0x3f317217, v93
	v_fmac_f32_e32 v102, 0x3f317217, v94
	v_fmac_f32_e32 v103, 0x3f317217, v95
	v_cmp_lt_f32_e64 vcc, |v92|, s34
	v_cndmask_b32_e32 v92, v92, v100, vcc
	v_cmp_lt_f32_e64 vcc, |v93|, s34
	v_cndmask_b32_e32 v93, v93, v101, vcc
	v_cmp_lt_f32_e64 vcc, |v94|, s34
	v_cndmask_b32_e32 v94, v94, v102, vcc
	v_cmp_lt_f32_e64 vcc, |v95|, s34
	v_cndmask_b32_e32 v95, v95, v103, vcc
	v_cndmask_b32_e64 v100, 0, v213, s[22:23]
	v_cndmask_b32_e64 v101, 0, v213, s[24:25]
	v_cndmask_b32_e64 v102, 0, v213, s[26:27]
	v_cndmask_b32_e64 v103, 0, v213, s[28:29]
	v_sub_f32_e32 v92, v92, v100
	v_sub_f32_e32 v93, v93, v101
	v_sub_f32_e32 v94, v94, v102
	v_sub_f32_e32 v95, v95, v103
	v_add_f32_e32 v64, v64, v92
	v_add_f32_e32 v65, v65, v93
	v_add_f32_e32 v66, v66, v94
	v_add_f32_e32 v67, v67, v95
	v_mul_f32_e32 v92, 0xbfb8aa3b, v64
	v_mul_f32_e32 v93, 0xbfb8aa3b, v65
	v_mul_f32_e32 v94, 0xbfb8aa3b, v66
	v_mul_f32_e32 v95, 0xbfb8aa3b, v67
	v_mul_f32_e32 v100, 0x3fb8aa3b, v64
	v_mul_f32_e32 v101, 0x3fb8aa3b, v65
	v_mul_f32_e32 v102, 0x3fb8aa3b, v66
	v_mul_f32_e32 v103, 0x3fb8aa3b, v67
	v_exp_f32_e32 v92, v92
	v_exp_f32_e32 v93, v93
	v_exp_f32_e32 v94, v94
	v_exp_f32_e32 v95, v95
	v_exp_f32_e32 v100, v100
	v_exp_f32_e32 v101, v101
	v_exp_f32_e32 v102, v102
	v_exp_f32_e32 v103, v103
	v_sub_f32_e32 v96, 1.0, v96
	v_sub_f32_e32 v97, 1.0, v97
	v_sub_f32_e32 v98, 1.0, v98
	v_sub_f32_e32 v99, 1.0, v99
	v_mul_f32_e32 v96, v96, v92
	v_mul_f32_e32 v97, v97, v93
	v_mul_f32_e32 v98, v98, v94
	v_mul_f32_e32 v99, v99, v95
	v_lshlrev_b32_e32 v92, 16, v58
	v_and_b32_e32 v93, 0xffff0000, v58
	v_lshlrev_b32_e32 v94, 16, v59
	v_and_b32_e32 v95, 0xffff0000, v59
	v_mul_f32_e32 v92, v92, v100
	v_mul_f32_e32 v93, v93, v101
	v_mul_f32_e32 v94, v94, v102
	v_mul_f32_e32 v95, v95, v103
	v_mov_b32_e32 v124, v96
	v_mov_b32_e32 v140, v97
	v_mov_b32_e32 v174, v98
	v_mov_b32_e32 v190, v99
	v_cvt_pk_bf16_f32 v92, v92, v93
	v_cvt_pk_bf16_f32 v93, v94, v95
	v_cvt_pk_bf16_f32 v96, v96, v97
	v_cvt_pk_bf16_f32 v97, v98, v99
	global_store_dwordx2 v112, v[92:93], s[2:3]
	global_store_dwordx2 v114, v[96:97], s[2:3]
	s_sub_u32 s2, s2, 0x400
	s_subb_u32 s3, s3, 0
	v_lshlrev_b32_e32 v92, 16, v60
	v_and_b32_e32 v93, 0xffff0000, v60
	v_lshlrev_b32_e32 v94, 16, v61
	v_and_b32_e32 v95, 0xffff0000, v61
	v_mul_f32_e32 v92, 0xbfb8aa3b, v92
	v_mul_f32_e32 v93, 0xbfb8aa3b, v93
	v_mul_f32_e32 v94, 0xbfb8aa3b, v94
	v_mul_f32_e32 v95, 0xbfb8aa3b, v95
	v_exp_f32_e32 v92, v92
	v_exp_f32_e32 v93, v93
	v_exp_f32_e32 v94, v94
	v_exp_f32_e32 v95, v95
	v_add_f32_e32 v92, 1.0, v92
	v_add_f32_e32 v93, 1.0, v93
	v_add_f32_e32 v94, 1.0, v94
	v_add_f32_e32 v95, 1.0, v95
	v_rcp_f32_e32 v92, v92
	v_rcp_f32_e32 v93, v93
	v_rcp_f32_e32 v94, v94
	v_rcp_f32_e32 v95, v95
	v_fma_f32 v96, v72, v92, v68
	v_fma_f32 v97, v73, v93, v69
	v_fma_f32 v98, v74, v94, v70
	v_fma_f32 v99, v75, v95, v71
	v_cmp_gt_f32_e64 s[22:23], s30, v96
	v_cmp_gt_f32_e64 s[24:25], s30, v97
	v_cmp_gt_f32_e64 s[26:27], s30, v98
	v_cmp_gt_f32_e64 s[28:29], s30, v99
	v_cndmask_b32_e64 v92, 0, 32, s[22:23]
	v_cndmask_b32_e64 v93, 0, 32, s[24:25]
	v_cndmask_b32_e64 v94, 0, 32, s[26:27]
	v_cndmask_b32_e64 v95, 0, 32, s[28:29]
	v_ldexp_f32 v92, v96, v92
	v_ldexp_f32 v93, v97, v93
	v_ldexp_f32 v94, v98, v94
	v_ldexp_f32 v95, v99, v95
	v_log_f32_e32 v92, v92
	v_log_f32_e32 v93, v93
	v_log_f32_e32 v94, v94
	v_log_f32_e32 v95, v95
	v_mul_f32_e32 v100, 0x3f317217, v92
	v_mul_f32_e32 v101, 0x3f317217, v93
	v_mul_f32_e32 v102, 0x3f317217, v94
	v_mul_f32_e32 v103, 0x3f317217, v95
	v_fma_f32 v100, v92, s31, -v100
	v_fma_f32 v101, v93, s31, -v101
	v_fma_f32 v102, v94, s31, -v102
	v_fma_f32 v103, v95, s31, -v103
	v_fmac_f32_e32 v100, 0x3377d1cf, v92
	v_fmac_f32_e32 v101, 0x3377d1cf, v93
	v_fmac_f32_e32 v102, 0x3377d1cf, v94
	v_fmac_f32_e32 v103, 0x3377d1cf, v95
	v_fmac_f32_e32 v100, 0x3f317217, v92
	v_fmac_f32_e32 v101, 0x3f317217, v93
	v_fmac_f32_e32 v102, 0x3f317217, v94
	v_fmac_f32_e32 v103, 0x3f317217, v95
	v_cmp_lt_f32_e64 vcc, |v92|, s34
	v_cndmask_b32_e32 v92, v92, v100, vcc
	v_cmp_lt_f32_e64 vcc, |v93|, s34
	v_cndmask_b32_e32 v93, v93, v101, vcc
	v_cmp_lt_f32_e64 vcc, |v94|, s34
	v_cndmask_b32_e32 v94, v94, v102, vcc
	v_cmp_lt_f32_e64 vcc, |v95|, s34
	v_cndmask_b32_e32 v95, v95, v103, vcc
	v_cndmask_b32_e64 v100, 0, v213, s[22:23]
	v_cndmask_b32_e64 v101, 0, v213, s[24:25]
	v_cndmask_b32_e64 v102, 0, v213, s[26:27]
	v_cndmask_b32_e64 v103, 0, v213, s[28:29]
	v_sub_f32_e32 v92, v92, v100
	v_sub_f32_e32 v93, v93, v101
	v_sub_f32_e32 v94, v94, v102
	v_sub_f32_e32 v95, v95, v103
	v_add_f32_e32 v64, v64, v92
	v_add_f32_e32 v65, v65, v93
	v_add_f32_e32 v66, v66, v94
	v_add_f32_e32 v67, v67, v95
	v_mul_f32_e32 v92, 0xbfb8aa3b, v64
	v_mul_f32_e32 v93, 0xbfb8aa3b, v65
	v_mul_f32_e32 v94, 0xbfb8aa3b, v66
	v_mul_f32_e32 v95, 0xbfb8aa3b, v67
	v_mul_f32_e32 v100, 0x3fb8aa3b, v64
	v_mul_f32_e32 v101, 0x3fb8aa3b, v65
	v_mul_f32_e32 v102, 0x3fb8aa3b, v66
	v_mul_f32_e32 v103, 0x3fb8aa3b, v67
	v_exp_f32_e32 v92, v92
; DEV u16 f2bf(float f) { return (u16)(pack2(f, f) & 0xffffu); }
; DEV float bf2f(u16 h) { return __uint_as_float(((unsigned)h) << 16); }
; DEV float sigmoid_f(float x) { return __builtin_amdgcn_rcpf(1.f + __expf(-x)); }
; DEV void phase_p15(const Params& p, int g) {
;     ...
;     P15_LOAD(0, 0);
;     P15_LOAD(1, 1);
; #pragma unroll
;     for (int j8 = 0; j8 < 8; ++j8) {
;       const int st = j8 % 3;
;       if (j8 < 6) { P15_LOAD((j8 + 2) % 3, j8 + 2); }
;     ...
;           const float f = lb[cc] + (1.f - lb[cc]) * sigmoid_f(bf2f(xr[st][cc][e]));
;           G[cc] += __logf(f);
;           const float eg = __expf(G[cc]), ig = __expf(-G[cc]);
;           Qp[tok * 512 + c] = f2bf(bf2f(qr[st][cc][e]) * eg);
;           const u16 kk = f2bf((1.f - f) * ig);
;           Kp[tok * 512 + c] = kk;
;           kb[e] = kk;
;         }
;         const int s0 = dir ? 56 - 8 * j8 : 8 * j8;
;         uint4 w;
;         w.x = dir ? (kb[7] | (kb[6] << 16)) : (kb[0] | (kb[1] << 16));
;         w.y = dir ? (kb[5] | (kb[4] << 16)) : (kb[2] | (kb[3] << 16));
;         w.z = dir ? (kb[3] | (kb[2] << 16)) : (kb[4] | (kb[5] << 16));
;         w.w = dir ? (kb[1] | (kb[0] << 16)) : (kb[6] | (kb[7] << 16));
	v_exp_f32_e32 v93, v93
	v_exp_f32_e32 v94, v94
	v_exp_f32_e32 v95, v95
	v_exp_f32_e32 v100, v100
	v_exp_f32_e32 v101, v101
	v_exp_f32_e32 v102, v102
	v_exp_f32_e32 v103, v103
	v_sub_f32_e32 v96, 1.0, v96
	v_sub_f32_e32 v97, 1.0, v97
	v_sub_f32_e32 v98, 1.0, v98
	v_sub_f32_e32 v99, 1.0, v99
	v_mul_f32_e32 v96, v96, v92
	v_mul_f32_e32 v97, v97, v93
	v_mul_f32_e32 v98, v98, v94
	v_mul_f32_e32 v99, v99, v95
	v_lshlrev_b32_e32 v92, 16, v62
	v_and_b32_e32 v93, 0xffff0000, v62
	v_lshlrev_b32_e32 v94, 16, v63
	v_and_b32_e32 v95, 0xffff0000, v63
	v_mul_f32_e32 v92, v92, v100
	v_mul_f32_e32 v93, v93, v101
	v_mul_f32_e32 v94, v94, v102
	v_mul_f32_e32 v95, v95, v103
	v_cvt_pk_bf16_f32 v124, v96, v124
	v_cvt_pk_bf16_f32 v140, v97, v140
	v_cvt_pk_bf16_f32 v174, v98, v174
	v_cvt_pk_bf16_f32 v190, v99, v190
	v_cvt_pk_bf16_f32 v92, v92, v93
	v_cvt_pk_bf16_f32 v93, v94, v95
	v_cvt_pk_bf16_f32 v96, v96, v97
	v_cvt_pk_bf16_f32 v97, v98, v99
	global_store_dwordx2 v112, v[92:93], s[2:3]
	global_store_dwordx2 v114, v[96:97], s[2:3]
	s_sub_u32 s2, s2, 0x400
	s_subb_u32 s3, s3, 0
	global_load_dwordx2 v[32:33], v113, s[0:1]
	global_load_dwordx2 v[34:35], v112, s[0:1]
	s_sub_u32 s0, s0, 0x1400
	s_subb_u32 s1, s1, 0
	global_load_dwordx2 v[36:37], v113, s[0:1]
	global_load_dwordx2 v[38:39], v112, s[0:1]
	s_sub_u32 s0, s0, 0x1400
	s_subb_u32 s1, s1, 0
	global_load_dwordx2 v[40:41], v113, s[0:1]
	global_load_dwordx2 v[42:43], v112, s[0:1]
	s_sub_u32 s0, s0, 0x1400
	s_subb_u32 s1, s1, 0
	global_load_dwordx2 v[44:45], v113, s[0:1]
	global_load_dwordx2 v[46:47], v112, s[0:1]
	s_sub_u32 s0, s0, 0x1400
	s_subb_u32 s1, s1, 0
	global_load_dwordx2 v[48:49], v113, s[0:1]
	global_load_dwordx2 v[50:51], v112, s[0:1]
	s_sub_u32 s0, s0, 0x1400
	s_subb_u32 s1, s1, 0
	global_load_dwordx2 v[52:53], v113, s[0:1]
	global_load_dwordx2 v[54:55], v112, s[0:1]
	s_sub_u32 s0, s0, 0x1400
	s_subb_u32 s1, s1, 0
	global_load_dwordx2 v[56:57], v113, s[0:1]
	global_load_dwordx2 v[58:59], v112, s[0:1]
	s_sub_u32 s0, s0, 0x1400
	s_subb_u32 s1, s1, 0
	global_load_dwordx2 v[60:61], v113, s[0:1]
	global_load_dwordx2 v[62:63], v112, s[0:1]
	s_sub_u32 s0, s0, 0x1400
	s_subb_u32 s1, s1, 0
	s_waitcnt vmcnt(32)
	v_lshlrev_b32_e32 v92, 16, v0
	v_and_b32_e32 v93, 0xffff0000, v0
	v_lshlrev_b32_e32 v94, 16, v1
	v_and_b32_e32 v95, 0xffff0000, v1
	v_mul_f32_e32 v92, 0xbfb8aa3b, v92
	v_mul_f32_e32 v93, 0xbfb8aa3b, v93
	v_mul_f32_e32 v94, 0xbfb8aa3b, v94
	v_mul_f32_e32 v95, 0xbfb8aa3b, v95
	v_exp_f32_e32 v92, v92
	v_exp_f32_e32 v93, v93
	v_exp_f32_e32 v94, v94
	v_exp_f32_e32 v95, v95
	v_add_f32_e32 v92, 1.0, v92
	v_add_f32_e32 v93, 1.0, v93
	v_add_f32_e32 v94, 1.0, v94
	v_add_f32_e32 v95, 1.0, v95
	v_rcp_f32_e32 v92, v92
	v_rcp_f32_e32 v93, v93
	v_rcp_f32_e32 v94, v94
	v_rcp_f32_e32 v95, v95
	v_fma_f32 v96, v72, v92, v68
	v_fma_f32 v97, v73, v93, v69
	v_fma_f32 v98, v74, v94, v70
	v_fma_f32 v99, v75, v95, v71
	v_cmp_gt_f32_e64 s[22:23], s30, v96
	v_cmp_gt_f32_e64 s[24:25], s30, v97
	v_cmp_gt_f32_e64 s[26:27], s30, v98
	v_cmp_gt_f32_e64 s[28:29], s30, v99
	v_cndmask_b32_e64 v92, 0, 32, s[22:23]
	v_cndmask_b32_e64 v93, 0, 32, s[24:25]
	v_cndmask_b32_e64 v94, 0, 32, s[26:27]
	v_cndmask_b32_e64 v95, 0, 32, s[28:29]
	v_ldexp_f32 v92, v96, v92
	v_ldexp_f32 v93, v97, v93
	v_ldexp_f32 v94, v98, v94
	v_ldexp_f32 v95, v99, v95
	v_log_f32_e32 v92, v92
	v_log_f32_e32 v93, v93
	v_log_f32_e32 v94, v94
	v_log_f32_e32 v95, v95
	v_mul_f32_e32 v100, 0x3f317217, v92
	v_mul_f32_e32 v101, 0x3f317217, v93
	v_mul_f32_e32 v102, 0x3f317217, v94
	v_mul_f32_e32 v103, 0x3f317217, v95
	v_fma_f32 v100, v92, s31, -v100
	v_fma_f32 v101, v93, s31, -v101
	v_fma_f32 v102, v94, s31, -v102
	v_fma_f32 v103, v95, s31, -v103
	v_fmac_f32_e32 v100, 0x3377d1cf, v92
	v_fmac_f32_e32 v101, 0x3377d1cf, v93
	v_fmac_f32_e32 v102, 0x3377d1cf, v94
	v_fmac_f32_e32 v103, 0x3377d1cf, v95
	v_fmac_f32_e32 v100, 0x3f317217, v92
	v_fmac_f32_e32 v101, 0x3f317217, v93
	v_fmac_f32_e32 v102, 0x3f317217, v94
	v_fmac_f32_e32 v103, 0x3f317217, v95
	v_cmp_lt_f32_e64 vcc, |v92|, s34
	v_cndmask_b32_e32 v92, v92, v100, vcc
	v_cmp_lt_f32_e64 vcc, |v93|, s34
	v_cndmask_b32_e32 v93, v93, v101, vcc
	v_cmp_lt_f32_e64 vcc, |v94|, s34
	v_cndmask_b32_e32 v94, v94, v102, vcc
	v_cmp_lt_f32_e64 vcc, |v95|, s34
	v_cndmask_b32_e32 v95, v95, v103, vcc
	v_cndmask_b32_e64 v100, 0, v213, s[22:23]
	v_cndmask_b32_e64 v101, 0, v213, s[24:25]
	v_cndmask_b32_e64 v102, 0, v213, s[26:27]
	v_cndmask_b32_e64 v103, 0, v213, s[28:29]
	v_sub_f32_e32 v92, v92, v100
	v_sub_f32_e32 v93, v93, v101
	v_sub_f32_e32 v94, v94, v102
	v_sub_f32_e32 v95, v95, v103
	v_add_f32_e32 v64, v64, v92
	v_add_f32_e32 v65, v65, v93
	v_add_f32_e32 v66, v66, v94
	v_add_f32_e32 v67, v67, v95
	v_mul_f32_e32 v92, 0xbfb8aa3b, v64
	v_mul_f32_e32 v93, 0xbfb8aa3b, v65
	v_mul_f32_e32 v94, 0xbfb8aa3b, v66
	v_mul_f32_e32 v95, 0xbfb8aa3b, v67
	v_mul_f32_e32 v100, 0x3fb8aa3b, v64
	v_mul_f32_e32 v101, 0x3fb8aa3b, v65
	v_mul_f32_e32 v102, 0x3fb8aa3b, v66
	v_mul_f32_e32 v103, 0x3fb8aa3b, v67
	v_exp_f32_e32 v92, v92
	v_exp_f32_e32 v93, v93
	v_exp_f32_e32 v94, v94
	v_exp_f32_e32 v95, v95
	v_exp_f32_e32 v100, v100
	v_exp_f32_e32 v101, v101
	v_exp_f32_e32 v102, v102
	v_exp_f32_e32 v103, v103
	v_sub_f32_e32 v96, 1.0, v96
	v_sub_f32_e32 v97, 1.0, v97
	v_sub_f32_e32 v98, 1.0, v98
	v_sub_f32_e32 v99, 1.0, v99
	v_mul_f32_e32 v96, v96, v92
	v_mul_f32_e32 v97, v97, v93
	v_mul_f32_e32 v98, v98, v94
	v_mul_f32_e32 v99, v99, v95
	v_lshlrev_b32_e32 v92, 16, v2
	v_and_b32_e32 v93, 0xffff0000, v2
	v_lshlrev_b32_e32 v94, 16, v3
	v_and_b32_e32 v95, 0xffff0000, v3
	v_mul_f32_e32 v92, v92, v100
	v_mul_f32_e32 v93, v93, v101
	v_mul_f32_e32 v94, v94, v102
; DEV u16 f2bf(float f) { return (u16)(pack2(f, f) & 0xffffu); }
; DEV float bf2f(u16 h) { return __uint_as_float(((unsigned)h) << 16); }
; DEV float sigmoid_f(float x) { return __builtin_amdgcn_rcpf(1.f + __expf(-x)); }
; DEV void phase_p15(const Params& p, int g) {
;     ...
;           const float f = lb[cc] + (1.f - lb[cc]) * sigmoid_f(bf2f(xr[st][cc][e]));
;           G[cc] += __logf(f);
;           const float eg = __expf(G[cc]), ig = __expf(-G[cc]);
;           Qp[tok * 512 + c] = f2bf(bf2f(qr[st][cc][e]) * eg);
;           const u16 kk = f2bf((1.f - f) * ig);
;           Kp[tok * 512 + c] = kk;
;           kb[e] = kk;
;         }
;         const int s0 = dir ? 56 - 8 * j8 : 8 * j8;
;         uint4 w;
;         w.x = dir ? (kb[7] | (kb[6] << 16)) : (kb[0] | (kb[1] << 16));
;         w.y = dir ? (kb[5] | (kb[4] << 16)) : (kb[2] | (kb[3] << 16));
;         w.z = dir ? (kb[3] | (kb[2] << 16)) : (kb[4] | (kb[5] << 16));
;         w.w = dir ? (kb[1] | (kb[0] << 16)) : (kb[6] | (kb[7] << 16));
	v_mul_f32_e32 v95, v95, v103
	v_mov_b32_e32 v123, v96
	v_mov_b32_e32 v139, v97
	v_mov_b32_e32 v173, v98
	v_mov_b32_e32 v189, v99
	v_cvt_pk_bf16_f32 v92, v92, v93
	v_cvt_pk_bf16_f32 v93, v94, v95
	v_cvt_pk_bf16_f32 v96, v96, v97
	v_cvt_pk_bf16_f32 v97, v98, v99
	global_store_dwordx2 v112, v[92:93], s[2:3]
	global_store_dwordx2 v114, v[96:97], s[2:3]
	s_sub_u32 s2, s2, 0x400
	s_subb_u32 s3, s3, 0
	v_lshlrev_b32_e32 v92, 16, v4
	v_and_b32_e32 v93, 0xffff0000, v4
	v_lshlrev_b32_e32 v94, 16, v5
	v_and_b32_e32 v95, 0xffff0000, v5
	v_mul_f32_e32 v92, 0xbfb8aa3b, v92
	v_mul_f32_e32 v93, 0xbfb8aa3b, v93
	v_mul_f32_e32 v94, 0xbfb8aa3b, v94
	v_mul_f32_e32 v95, 0xbfb8aa3b, v95
	v_exp_f32_e32 v92, v92
	v_exp_f32_e32 v93, v93
	v_exp_f32_e32 v94, v94
	v_exp_f32_e32 v95, v95
	v_add_f32_e32 v92, 1.0, v92
	v_add_f32_e32 v93, 1.0, v93
	v_add_f32_e32 v94, 1.0, v94
	v_add_f32_e32 v95, 1.0, v95
	v_rcp_f32_e32 v92, v92
	v_rcp_f32_e32 v93, v93
	v_rcp_f32_e32 v94, v94
	v_rcp_f32_e32 v95, v95
	v_fma_f32 v96, v72, v92, v68
	v_fma_f32 v97, v73, v93, v69
	v_fma_f32 v98, v74, v94, v70
	v_fma_f32 v99, v75, v95, v71
	v_cmp_gt_f32_e64 s[22:23], s30, v96
	v_cmp_gt_f32_e64 s[24:25], s30, v97
	v_cmp_gt_f32_e64 s[26:27], s30, v98
	v_cmp_gt_f32_e64 s[28:29], s30, v99
	v_cndmask_b32_e64 v92, 0, 32, s[22:23]
	v_cndmask_b32_e64 v93, 0, 32, s[24:25]
	v_cndmask_b32_e64 v94, 0, 32, s[26:27]
	v_cndmask_b32_e64 v95, 0, 32, s[28:29]
	v_ldexp_f32 v92, v96, v92
	v_ldexp_f32 v93, v97, v93
	v_ldexp_f32 v94, v98, v94
	v_ldexp_f32 v95, v99, v95
	v_log_f32_e32 v92, v92
	v_log_f32_e32 v93, v93
	v_log_f32_e32 v94, v94
	v_log_f32_e32 v95, v95
	v_mul_f32_e32 v100, 0x3f317217, v92
	v_mul_f32_e32 v101, 0x3f317217, v93
	v_mul_f32_e32 v102, 0x3f317217, v94
	v_mul_f32_e32 v103, 0x3f317217, v95
	v_fma_f32 v100, v92, s31, -v100
	v_fma_f32 v101, v93, s31, -v101
	v_fma_f32 v102, v94, s31, -v102
	v_fma_f32 v103, v95, s31, -v103
	v_fmac_f32_e32 v100, 0x3377d1cf, v92
	v_fmac_f32_e32 v101, 0x3377d1cf, v93
	v_fmac_f32_e32 v102, 0x3377d1cf, v94
	v_fmac_f32_e32 v103, 0x3377d1cf, v95
	v_fmac_f32_e32 v100, 0x3f317217, v92
	v_fmac_f32_e32 v101, 0x3f317217, v93
	v_fmac_f32_e32 v102, 0x3f317217, v94
	v_fmac_f32_e32 v103, 0x3f317217, v95
	v_cmp_lt_f32_e64 vcc, |v92|, s34
	v_cndmask_b32_e32 v92, v92, v100, vcc
	v_cmp_lt_f32_e64 vcc, |v93|, s34
	v_cndmask_b32_e32 v93, v93, v101, vcc
	v_cmp_lt_f32_e64 vcc, |v94|, s34
	v_cndmask_b32_e32 v94, v94, v102, vcc
	v_cmp_lt_f32_e64 vcc, |v95|, s34
	v_cndmask_b32_e32 v95, v95, v103, vcc
	v_cndmask_b32_e64 v100, 0, v213, s[22:23]
	v_cndmask_b32_e64 v101, 0, v213, s[24:25]
	v_cndmask_b32_e64 v102, 0, v213, s[26:27]
	v_cndmask_b32_e64 v103, 0, v213, s[28:29]
	v_sub_f32_e32 v92, v92, v100
	v_sub_f32_e32 v93, v93, v101
	v_sub_f32_e32 v94, v94, v102
	v_sub_f32_e32 v95, v95, v103
	v_add_f32_e32 v64, v64, v92
	v_add_f32_e32 v65, v65, v93
	v_add_f32_e32 v66, v66, v94
	v_add_f32_e32 v67, v67, v95
	v_mul_f32_e32 v92, 0xbfb8aa3b, v64
	v_mul_f32_e32 v93, 0xbfb8aa3b, v65
	v_mul_f32_e32 v94, 0xbfb8aa3b, v66
	v_mul_f32_e32 v95, 0xbfb8aa3b, v67
	v_mul_f32_e32 v100, 0x3fb8aa3b, v64
	v_mul_f32_e32 v101, 0x3fb8aa3b, v65
	v_mul_f32_e32 v102, 0x3fb8aa3b, v66
	v_mul_f32_e32 v103, 0x3fb8aa3b, v67
	v_exp_f32_e32 v92, v92
	v_exp_f32_e32 v93, v93
	v_exp_f32_e32 v94, v94
	v_exp_f32_e32 v95, v95
	v_exp_f32_e32 v100, v100
	v_exp_f32_e32 v101, v101
	v_exp_f32_e32 v102, v102
	v_exp_f32_e32 v103, v103
	v_sub_f32_e32 v96, 1.0, v96
	v_sub_f32_e32 v97, 1.0, v97
	v_sub_f32_e32 v98, 1.0, v98
	v_sub_f32_e32 v99, 1.0, v99
	v_mul_f32_e32 v96, v96, v92
	v_mul_f32_e32 v97, v97, v93
	v_mul_f32_e32 v98, v98, v94
	v_mul_f32_e32 v99, v99, v95
	v_lshlrev_b32_e32 v92, 16, v6
	v_and_b32_e32 v93, 0xffff0000, v6
	v_lshlrev_b32_e32 v94, 16, v7
	v_and_b32_e32 v95, 0xffff0000, v7
	v_mul_f32_e32 v92, v92, v100
	v_mul_f32_e32 v93, v93, v101
	v_mul_f32_e32 v94, v94, v102
	v_mul_f32_e32 v95, v95, v103
	v_cvt_pk_bf16_f32 v123, v96, v123
	v_cvt_pk_bf16_f32 v139, v97, v139
	v_cvt_pk_bf16_f32 v173, v98, v173
	v_cvt_pk_bf16_f32 v189, v99, v189
	v_cvt_pk_bf16_f32 v92, v92, v93
	v_cvt_pk_bf16_f32 v93, v94, v95
	v_cvt_pk_bf16_f32 v96, v96, v97
	v_cvt_pk_bf16_f32 v97, v98, v99
	global_store_dwordx2 v112, v[92:93], s[2:3]
	global_store_dwordx2 v114, v[96:97], s[2:3]
	s_sub_u32 s2, s2, 0x400
	s_subb_u32 s3, s3, 0
	v_lshlrev_b32_e32 v92, 16, v8
	v_and_b32_e32 v93, 0xffff0000, v8
	v_lshlrev_b32_e32 v94, 16, v9
	v_and_b32_e32 v95, 0xffff0000, v9
	v_mul_f32_e32 v92, 0xbfb8aa3b, v92
	v_mul_f32_e32 v93, 0xbfb8aa3b, v93
	v_mul_f32_e32 v94, 0xbfb8aa3b, v94
	v_mul_f32_e32 v95, 0xbfb8aa3b, v95
	v_exp_f32_e32 v92, v92
	v_exp_f32_e32 v93, v93
	v_exp_f32_e32 v94, v94
	v_exp_f32_e32 v95, v95
	v_add_f32_e32 v92, 1.0, v92
	v_add_f32_e32 v93, 1.0, v93
	v_add_f32_e32 v94, 1.0, v94
	v_add_f32_e32 v95, 1.0, v95
	v_rcp_f32_e32 v92, v92
	v_rcp_f32_e32 v93, v93
	v_rcp_f32_e32 v94, v94
	v_rcp_f32_e32 v95, v95
	v_fma_f32 v96, v72, v92, v68
	v_fma_f32 v97, v73, v93, v69
	v_fma_f32 v98, v74, v94, v70
	v_fma_f32 v99, v75, v95, v71
	v_cmp_gt_f32_e64 s[22:23], s30, v96
	v_cmp_gt_f32_e64 s[24:25], s30, v97
	v_cmp_gt_f32_e64 s[26:27], s30, v98
	v_cmp_gt_f32_e64 s[28:29], s30, v99
	v_cndmask_b32_e64 v92, 0, 32, s[22:23]
	v_cndmask_b32_e64 v93, 0, 32, s[24:25]
	v_cndmask_b32_e64 v94, 0, 32, s[26:27]
	v_cndmask_b32_e64 v95, 0, 32, s[28:29]
	v_ldexp_f32 v92, v96, v92
	v_ldexp_f32 v93, v97, v93
	v_ldexp_f32 v94, v98, v94
	v_ldexp_f32 v95, v99, v95
	v_log_f32_e32 v92, v92
	v_log_f32_e32 v93, v93
	v_log_f32_e32 v94, v94
	v_log_f32_e32 v95, v95
	v_mul_f32_e32 v100, 0x3f317217, v92
	v_mul_f32_e32 v101, 0x3f317217, v93
	v_mul_f32_e32 v102, 0x3f317217, v94
	v_mul_f32_e32 v103, 0x3f317217, v95
; DEV u16 f2bf(float f) { return (u16)(pack2(f, f) & 0xffffu); }
; DEV float bf2f(u16 h) { return __uint_as_float(((unsigned)h) << 16); }
; DEV float sigmoid_f(float x) { return __builtin_amdgcn_rcpf(1.f + __expf(-x)); }
; DEV void phase_p15(const Params& p, int g) {
;     ...
;           const float f = lb[cc] + (1.f - lb[cc]) * sigmoid_f(bf2f(xr[st][cc][e]));
;           G[cc] += __logf(f);
;           const float eg = __expf(G[cc]), ig = __expf(-G[cc]);
;           Qp[tok * 512 + c] = f2bf(bf2f(qr[st][cc][e]) * eg);
;           const u16 kk = f2bf((1.f - f) * ig);
;           Kp[tok * 512 + c] = kk;
;           kb[e] = kk;
;         }
;         const int s0 = dir ? 56 - 8 * j8 : 8 * j8;
;         uint4 w;
;         w.x = dir ? (kb[7] | (kb[6] << 16)) : (kb[0] | (kb[1] << 16));
;         w.y = dir ? (kb[5] | (kb[4] << 16)) : (kb[2] | (kb[3] << 16));
;         w.z = dir ? (kb[3] | (kb[2] << 16)) : (kb[4] | (kb[5] << 16));
;         w.w = dir ? (kb[1] | (kb[0] << 16)) : (kb[6] | (kb[7] << 16));
	v_fma_f32 v100, v92, s31, -v100
	v_fma_f32 v101, v93, s31, -v101
	v_fma_f32 v102, v94, s31, -v102
	v_fma_f32 v103, v95, s31, -v103
	v_fmac_f32_e32 v100, 0x3377d1cf, v92
	v_fmac_f32_e32 v101, 0x3377d1cf, v93
	v_fmac_f32_e32 v102, 0x3377d1cf, v94
	v_fmac_f32_e32 v103, 0x3377d1cf, v95
	v_fmac_f32_e32 v100, 0x3f317217, v92
	v_fmac_f32_e32 v101, 0x3f317217, v93
	v_fmac_f32_e32 v102, 0x3f317217, v94
	v_fmac_f32_e32 v103, 0x3f317217, v95
	v_cmp_lt_f32_e64 vcc, |v92|, s34
	v_cndmask_b32_e32 v92, v92, v100, vcc
	v_cmp_lt_f32_e64 vcc, |v93|, s34
	v_cndmask_b32_e32 v93, v93, v101, vcc
	v_cmp_lt_f32_e64 vcc, |v94|, s34
	v_cndmask_b32_e32 v94, v94, v102, vcc
	v_cmp_lt_f32_e64 vcc, |v95|, s34
	v_cndmask_b32_e32 v95, v95, v103, vcc
	v_cndmask_b32_e64 v100, 0, v213, s[22:23]
	v_cndmask_b32_e64 v101, 0, v213, s[24:25]
	v_cndmask_b32_e64 v102, 0, v213, s[26:27]
	v_cndmask_b32_e64 v103, 0, v213, s[28:29]
	v_sub_f32_e32 v92, v92, v100
	v_sub_f32_e32 v93, v93, v101
	v_sub_f32_e32 v94, v94, v102
	v_sub_f32_e32 v95, v95, v103
	v_add_f32_e32 v64, v64, v92
	v_add_f32_e32 v65, v65, v93
	v_add_f32_e32 v66, v66, v94
	v_add_f32_e32 v67, v67, v95
	v_mul_f32_e32 v92, 0xbfb8aa3b, v64
	v_mul_f32_e32 v93, 0xbfb8aa3b, v65
	v_mul_f32_e32 v94, 0xbfb8aa3b, v66
	v_mul_f32_e32 v95, 0xbfb8aa3b, v67
	v_mul_f32_e32 v100, 0x3fb8aa3b, v64
	v_mul_f32_e32 v101, 0x3fb8aa3b, v65
	v_mul_f32_e32 v102, 0x3fb8aa3b, v66
	v_mul_f32_e32 v103, 0x3fb8aa3b, v67
	v_exp_f32_e32 v92, v92
	v_exp_f32_e32 v93, v93
	v_exp_f32_e32 v94, v94
	v_exp_f32_e32 v95, v95
	v_exp_f32_e32 v100, v100
	v_exp_f32_e32 v101, v101
	v_exp_f32_e32 v102, v102
	v_exp_f32_e32 v103, v103
	v_sub_f32_e32 v96, 1.0, v96
	v_sub_f32_e32 v97, 1.0, v97
	v_sub_f32_e32 v98, 1.0, v98
	v_sub_f32_e32 v99, 1.0, v99
	v_mul_f32_e32 v96, v96, v92
	v_mul_f32_e32 v97, v97, v93
	v_mul_f32_e32 v98, v98, v94
	v_mul_f32_e32 v99, v99, v95
	v_lshlrev_b32_e32 v92, 16, v10
	v_and_b32_e32 v93, 0xffff0000, v10
	v_lshlrev_b32_e32 v94, 16, v11
	v_and_b32_e32 v95, 0xffff0000, v11
	v_mul_f32_e32 v92, v92, v100
	v_mul_f32_e32 v93, v93, v101
	v_mul_f32_e32 v94, v94, v102
	v_mul_f32_e32 v95, v95, v103
	v_mov_b32_e32 v122, v96
	v_mov_b32_e32 v138, v97
	v_mov_b32_e32 v172, v98
	v_mov_b32_e32 v188, v99
	v_cvt_pk_bf16_f32 v92, v92, v93
	v_cvt_pk_bf16_f32 v93, v94, v95
	v_cvt_pk_bf16_f32 v96, v96, v97
	v_cvt_pk_bf16_f32 v97, v98, v99
	global_store_dwordx2 v112, v[92:93], s[2:3]
	global_store_dwordx2 v114, v[96:97], s[2:3]
	s_sub_u32 s2, s2, 0x400
	s_subb_u32 s3, s3, 0
	v_lshlrev_b32_e32 v92, 16, v12
	v_and_b32_e32 v93, 0xffff0000, v12
	v_lshlrev_b32_e32 v94, 16, v13
	v_and_b32_e32 v95, 0xffff0000, v13
	v_mul_f32_e32 v92, 0xbfb8aa3b, v92
	v_mul_f32_e32 v93, 0xbfb8aa3b, v93
	v_mul_f32_e32 v94, 0xbfb8aa3b, v94
	v_mul_f32_e32 v95, 0xbfb8aa3b, v95
	v_exp_f32_e32 v92, v92
	v_exp_f32_e32 v93, v93
	v_exp_f32_e32 v94, v94
	v_exp_f32_e32 v95, v95
	v_add_f32_e32 v92, 1.0, v92
	v_add_f32_e32 v93, 1.0, v93
	v_add_f32_e32 v94, 1.0, v94
	v_add_f32_e32 v95, 1.0, v95
	v_rcp_f32_e32 v92, v92
	v_rcp_f32_e32 v93, v93
	v_rcp_f32_e32 v94, v94
	v_rcp_f32_e32 v95, v95
	v_fma_f32 v96, v72, v92, v68
	v_fma_f32 v97, v73, v93, v69
	v_fma_f32 v98, v74, v94, v70
	v_fma_f32 v99, v75, v95, v71
	v_cmp_gt_f32_e64 s[22:23], s30, v96
	v_cmp_gt_f32_e64 s[24:25], s30, v97
	v_cmp_gt_f32_e64 s[26:27], s30, v98
	v_cmp_gt_f32_e64 s[28:29], s30, v99
	v_cndmask_b32_e64 v92, 0, 32, s[22:23]
	v_cndmask_b32_e64 v93, 0, 32, s[24:25]
	v_cndmask_b32_e64 v94, 0, 32, s[26:27]
	v_cndmask_b32_e64 v95, 0, 32, s[28:29]
	v_ldexp_f32 v92, v96, v92
	v_ldexp_f32 v93, v97, v93
	v_ldexp_f32 v94, v98, v94
	v_ldexp_f32 v95, v99, v95
	v_log_f32_e32 v92, v92
	v_log_f32_e32 v93, v93
	v_log_f32_e32 v94, v94
	v_log_f32_e32 v95, v95
	v_mul_f32_e32 v100, 0x3f317217, v92
	v_mul_f32_e32 v101, 0x3f317217, v93
	v_mul_f32_e32 v102, 0x3f317217, v94
	v_mul_f32_e32 v103, 0x3f317217, v95
	v_fma_f32 v100, v92, s31, -v100
	v_fma_f32 v101, v93, s31, -v101
	v_fma_f32 v102, v94, s31, -v102
	v_fma_f32 v103, v95, s31, -v103
	v_fmac_f32_e32 v100, 0x3377d1cf, v92
	v_fmac_f32_e32 v101, 0x3377d1cf, v93
	v_fmac_f32_e32 v102, 0x3377d1cf, v94
	v_fmac_f32_e32 v103, 0x3377d1cf, v95
	v_fmac_f32_e32 v100, 0x3f317217, v92
	v_fmac_f32_e32 v101, 0x3f317217, v93
	v_fmac_f32_e32 v102, 0x3f317217, v94
	v_fmac_f32_e32 v103, 0x3f317217, v95
	v_cmp_lt_f32_e64 vcc, |v92|, s34
	v_cndmask_b32_e32 v92, v92, v100, vcc
	v_cmp_lt_f32_e64 vcc, |v93|, s34
	v_cndmask_b32_e32 v93, v93, v101, vcc
	v_cmp_lt_f32_e64 vcc, |v94|, s34
	v_cndmask_b32_e32 v94, v94, v102, vcc
	v_cmp_lt_f32_e64 vcc, |v95|, s34
	v_cndmask_b32_e32 v95, v95, v103, vcc
	v_cndmask_b32_e64 v100, 0, v213, s[22:23]
	v_cndmask_b32_e64 v101, 0, v213, s[24:25]
	v_cndmask_b32_e64 v102, 0, v213, s[26:27]
	v_cndmask_b32_e64 v103, 0, v213, s[28:29]
	v_sub_f32_e32 v92, v92, v100
	v_sub_f32_e32 v93, v93, v101
	v_sub_f32_e32 v94, v94, v102
	v_sub_f32_e32 v95, v95, v103
	v_add_f32_e32 v64, v64, v92
	v_add_f32_e32 v65, v65, v93
	v_add_f32_e32 v66, v66, v94
	v_add_f32_e32 v67, v67, v95
	v_mul_f32_e32 v92, 0xbfb8aa3b, v64
	v_mul_f32_e32 v93, 0xbfb8aa3b, v65
	v_mul_f32_e32 v94, 0xbfb8aa3b, v66
	v_mul_f32_e32 v95, 0xbfb8aa3b, v67
	v_mul_f32_e32 v100, 0x3fb8aa3b, v64
	v_mul_f32_e32 v101, 0x3fb8aa3b, v65
	v_mul_f32_e32 v102, 0x3fb8aa3b, v66
	v_mul_f32_e32 v103, 0x3fb8aa3b, v67
	v_exp_f32_e32 v92, v92
	v_exp_f32_e32 v93, v93
	v_exp_f32_e32 v94, v94
	v_exp_f32_e32 v95, v95
	v_exp_f32_e32 v100, v100
	v_exp_f32_e32 v101, v101
	v_exp_f32_e32 v102, v102
	v_exp_f32_e32 v103, v103
	v_sub_f32_e32 v96, 1.0, v96
	v_sub_f32_e32 v97, 1.0, v97
	v_sub_f32_e32 v98, 1.0, v98
	v_sub_f32_e32 v99, 1.0, v99
	v_mul_f32_e32 v96, v96, v92
; DEV u16 f2bf(float f) { return (u16)(pack2(f, f) & 0xffffu); }
; DEV float bf2f(u16 h) { return __uint_as_float(((unsigned)h) << 16); }
; DEV float sigmoid_f(float x) { return __builtin_amdgcn_rcpf(1.f + __expf(-x)); }
; DEV void phase_p15(const Params& p, int g) {
;     ...
;           const float f = lb[cc] + (1.f - lb[cc]) * sigmoid_f(bf2f(xr[st][cc][e]));
;           G[cc] += __logf(f);
;           const float eg = __expf(G[cc]), ig = __expf(-G[cc]);
;           Qp[tok * 512 + c] = f2bf(bf2f(qr[st][cc][e]) * eg);
;           const u16 kk = f2bf((1.f - f) * ig);
;           Kp[tok * 512 + c] = kk;
;           kb[e] = kk;
;         }
;         const int s0 = dir ? 56 - 8 * j8 : 8 * j8;
;         uint4 w;
;         w.x = dir ? (kb[7] | (kb[6] << 16)) : (kb[0] | (kb[1] << 16));
;         w.y = dir ? (kb[5] | (kb[4] << 16)) : (kb[2] | (kb[3] << 16));
;         w.z = dir ? (kb[3] | (kb[2] << 16)) : (kb[4] | (kb[5] << 16));
;         w.w = dir ? (kb[1] | (kb[0] << 16)) : (kb[6] | (kb[7] << 16));
	v_mul_f32_e32 v97, v97, v93
	v_mul_f32_e32 v98, v98, v94
	v_mul_f32_e32 v99, v99, v95
	v_lshlrev_b32_e32 v92, 16, v14
	v_and_b32_e32 v93, 0xffff0000, v14
	v_lshlrev_b32_e32 v94, 16, v15
	v_and_b32_e32 v95, 0xffff0000, v15
	v_mul_f32_e32 v92, v92, v100
	v_mul_f32_e32 v93, v93, v101
	v_mul_f32_e32 v94, v94, v102
	v_mul_f32_e32 v95, v95, v103
	v_cvt_pk_bf16_f32 v122, v96, v122
	v_cvt_pk_bf16_f32 v138, v97, v138
	v_cvt_pk_bf16_f32 v172, v98, v172
	v_cvt_pk_bf16_f32 v188, v99, v188
	v_cvt_pk_bf16_f32 v92, v92, v93
	v_cvt_pk_bf16_f32 v93, v94, v95
	v_cvt_pk_bf16_f32 v96, v96, v97
	v_cvt_pk_bf16_f32 v97, v98, v99
	global_store_dwordx2 v112, v[92:93], s[2:3]
	global_store_dwordx2 v114, v[96:97], s[2:3]
	s_sub_u32 s2, s2, 0x400
	s_subb_u32 s3, s3, 0
	v_lshlrev_b32_e32 v92, 16, v16
	v_and_b32_e32 v93, 0xffff0000, v16
	v_lshlrev_b32_e32 v94, 16, v17
	v_and_b32_e32 v95, 0xffff0000, v17
	v_mul_f32_e32 v92, 0xbfb8aa3b, v92
	v_mul_f32_e32 v93, 0xbfb8aa3b, v93
	v_mul_f32_e32 v94, 0xbfb8aa3b, v94
	v_mul_f32_e32 v95, 0xbfb8aa3b, v95
	v_exp_f32_e32 v92, v92
	v_exp_f32_e32 v93, v93
	v_exp_f32_e32 v94, v94
	v_exp_f32_e32 v95, v95
	v_add_f32_e32 v92, 1.0, v92
	v_add_f32_e32 v93, 1.0, v93
	v_add_f32_e32 v94, 1.0, v94
	v_add_f32_e32 v95, 1.0, v95
	v_rcp_f32_e32 v92, v92
	v_rcp_f32_e32 v93, v93
	v_rcp_f32_e32 v94, v94
	v_rcp_f32_e32 v95, v95
	v_fma_f32 v96, v72, v92, v68
	v_fma_f32 v97, v73, v93, v69
	v_fma_f32 v98, v74, v94, v70
	v_fma_f32 v99, v75, v95, v71
	v_cmp_gt_f32_e64 s[22:23], s30, v96
	v_cmp_gt_f32_e64 s[24:25], s30, v97
	v_cmp_gt_f32_e64 s[26:27], s30, v98
	v_cmp_gt_f32_e64 s[28:29], s30, v99
	v_cndmask_b32_e64 v92, 0, 32, s[22:23]
	v_cndmask_b32_e64 v93, 0, 32, s[24:25]
	v_cndmask_b32_e64 v94, 0, 32, s[26:27]
	v_cndmask_b32_e64 v95, 0, 32, s[28:29]
	v_ldexp_f32 v92, v96, v92
	v_ldexp_f32 v93, v97, v93
	v_ldexp_f32 v94, v98, v94
	v_ldexp_f32 v95, v99, v95
	v_log_f32_e32 v92, v92
	v_log_f32_e32 v93, v93
	v_log_f32_e32 v94, v94
	v_log_f32_e32 v95, v95
	v_mul_f32_e32 v100, 0x3f317217, v92
	v_mul_f32_e32 v101, 0x3f317217, v93
	v_mul_f32_e32 v102, 0x3f317217, v94
	v_mul_f32_e32 v103, 0x3f317217, v95
	v_fma_f32 v100, v92, s31, -v100
	v_fma_f32 v101, v93, s31, -v101
	v_fma_f32 v102, v94, s31, -v102
	v_fma_f32 v103, v95, s31, -v103
	v_fmac_f32_e32 v100, 0x3377d1cf, v92
	v_fmac_f32_e32 v101, 0x3377d1cf, v93
	v_fmac_f32_e32 v102, 0x3377d1cf, v94
	v_fmac_f32_e32 v103, 0x3377d1cf, v95
	v_fmac_f32_e32 v100, 0x3f317217, v92
	v_fmac_f32_e32 v101, 0x3f317217, v93
	v_fmac_f32_e32 v102, 0x3f317217, v94
	v_fmac_f32_e32 v103, 0x3f317217, v95
	v_cmp_lt_f32_e64 vcc, |v92|, s34
	v_cndmask_b32_e32 v92, v92, v100, vcc
	v_cmp_lt_f32_e64 vcc, |v93|, s34
	v_cndmask_b32_e32 v93, v93, v101, vcc
	v_cmp_lt_f32_e64 vcc, |v94|, s34
	v_cndmask_b32_e32 v94, v94, v102, vcc
	v_cmp_lt_f32_e64 vcc, |v95|, s34
	v_cndmask_b32_e32 v95, v95, v103, vcc
	v_cndmask_b32_e64 v100, 0, v213, s[22:23]
	v_cndmask_b32_e64 v101, 0, v213, s[24:25]
	v_cndmask_b32_e64 v102, 0, v213, s[26:27]
	v_cndmask_b32_e64 v103, 0, v213, s[28:29]
	v_sub_f32_e32 v92, v92, v100
	v_sub_f32_e32 v93, v93, v101
	v_sub_f32_e32 v94, v94, v102
	v_sub_f32_e32 v95, v95, v103
	v_add_f32_e32 v64, v64, v92
	v_add_f32_e32 v65, v65, v93
	v_add_f32_e32 v66, v66, v94
	v_add_f32_e32 v67, v67, v95
	v_mul_f32_e32 v92, 0xbfb8aa3b, v64
	v_mul_f32_e32 v93, 0xbfb8aa3b, v65
	v_mul_f32_e32 v94, 0xbfb8aa3b, v66
	v_mul_f32_e32 v95, 0xbfb8aa3b, v67
	v_mul_f32_e32 v100, 0x3fb8aa3b, v64
	v_mul_f32_e32 v101, 0x3fb8aa3b, v65
	v_mul_f32_e32 v102, 0x3fb8aa3b, v66
	v_mul_f32_e32 v103, 0x3fb8aa3b, v67
	v_exp_f32_e32 v92, v92
	v_exp_f32_e32 v93, v93
	v_exp_f32_e32 v94, v94
	v_exp_f32_e32 v95, v95
	v_exp_f32_e32 v100, v100
	v_exp_f32_e32 v101, v101
	v_exp_f32_e32 v102, v102
	v_exp_f32_e32 v103, v103
	v_sub_f32_e32 v96, 1.0, v96
	v_sub_f32_e32 v97, 1.0, v97
	v_sub_f32_e32 v98, 1.0, v98
	v_sub_f32_e32 v99, 1.0, v99
	v_mul_f32_e32 v96, v96, v92
	v_mul_f32_e32 v97, v97, v93
	v_mul_f32_e32 v98, v98, v94
	v_mul_f32_e32 v99, v99, v95
	v_lshlrev_b32_e32 v92, 16, v18
	v_and_b32_e32 v93, 0xffff0000, v18
	v_lshlrev_b32_e32 v94, 16, v19
	v_and_b32_e32 v95, 0xffff0000, v19
	v_mul_f32_e32 v92, v92, v100
	v_mul_f32_e32 v93, v93, v101
	v_mul_f32_e32 v94, v94, v102
	v_mul_f32_e32 v95, v95, v103
	v_mov_b32_e32 v121, v96
	v_mov_b32_e32 v137, v97
	v_mov_b32_e32 v171, v98
	v_mov_b32_e32 v187, v99
	v_cvt_pk_bf16_f32 v92, v92, v93
	v_cvt_pk_bf16_f32 v93, v94, v95
	v_cvt_pk_bf16_f32 v96, v96, v97
	v_cvt_pk_bf16_f32 v97, v98, v99
	global_store_dwordx2 v112, v[92:93], s[2:3]
	global_store_dwordx2 v114, v[96:97], s[2:3]
	s_sub_u32 s2, s2, 0x400
	s_subb_u32 s3, s3, 0
	v_lshlrev_b32_e32 v92, 16, v20
	v_and_b32_e32 v93, 0xffff0000, v20
	v_lshlrev_b32_e32 v94, 16, v21
	v_and_b32_e32 v95, 0xffff0000, v21
	v_mul_f32_e32 v92, 0xbfb8aa3b, v92
	v_mul_f32_e32 v93, 0xbfb8aa3b, v93
	v_mul_f32_e32 v94, 0xbfb8aa3b, v94
	v_mul_f32_e32 v95, 0xbfb8aa3b, v95
	v_exp_f32_e32 v92, v92
	v_exp_f32_e32 v93, v93
	v_exp_f32_e32 v94, v94
	v_exp_f32_e32 v95, v95
	v_add_f32_e32 v92, 1.0, v92
	v_add_f32_e32 v93, 1.0, v93
	v_add_f32_e32 v94, 1.0, v94
	v_add_f32_e32 v95, 1.0, v95
	v_rcp_f32_e32 v92, v92
	v_rcp_f32_e32 v93, v93
	v_rcp_f32_e32 v94, v94
	v_rcp_f32_e32 v95, v95
	v_fma_f32 v96, v72, v92, v68
	v_fma_f32 v97, v73, v93, v69
	v_fma_f32 v98, v74, v94, v70
	v_fma_f32 v99, v75, v95, v71
	v_cmp_gt_f32_e64 s[22:23], s30, v96
	v_cmp_gt_f32_e64 s[24:25], s30, v97
	v_cmp_gt_f32_e64 s[26:27], s30, v98
	v_cmp_gt_f32_e64 s[28:29], s30, v99
	v_cndmask_b32_e64 v92, 0, 32, s[22:23]
	v_cndmask_b32_e64 v93, 0, 32, s[24:25]
	v_cndmask_b32_e64 v94, 0, 32, s[26:27]
	v_cndmask_b32_e64 v95, 0, 32, s[28:29]
	v_ldexp_f32 v92, v96, v92
; DEV u16 f2bf(float f) { return (u16)(pack2(f, f) & 0xffffu); }
; DEV float bf2f(u16 h) { return __uint_as_float(((unsigned)h) << 16); }
; DEV float sigmoid_f(float x) { return __builtin_amdgcn_rcpf(1.f + __expf(-x)); }
; DEV void phase_p15(const Params& p, int g) {
;     ...
;           const float f = lb[cc] + (1.f - lb[cc]) * sigmoid_f(bf2f(xr[st][cc][e]));
;           G[cc] += __logf(f);
;           const float eg = __expf(G[cc]), ig = __expf(-G[cc]);
;           Qp[tok * 512 + c] = f2bf(bf2f(qr[st][cc][e]) * eg);
;           const u16 kk = f2bf((1.f - f) * ig);
;           Kp[tok * 512 + c] = kk;
;           kb[e] = kk;
;         }
;         const int s0 = dir ? 56 - 8 * j8 : 8 * j8;
;         uint4 w;
;         w.x = dir ? (kb[7] | (kb[6] << 16)) : (kb[0] | (kb[1] << 16));
;         w.y = dir ? (kb[5] | (kb[4] << 16)) : (kb[2] | (kb[3] << 16));
;         w.z = dir ? (kb[3] | (kb[2] << 16)) : (kb[4] | (kb[5] << 16));
;         w.w = dir ? (kb[1] | (kb[0] << 16)) : (kb[6] | (kb[7] << 16));
	v_ldexp_f32 v93, v97, v93
	v_ldexp_f32 v94, v98, v94
	v_ldexp_f32 v95, v99, v95
	v_log_f32_e32 v92, v92
	v_log_f32_e32 v93, v93
	v_log_f32_e32 v94, v94
	v_log_f32_e32 v95, v95
	v_mul_f32_e32 v100, 0x3f317217, v92
	v_mul_f32_e32 v101, 0x3f317217, v93
	v_mul_f32_e32 v102, 0x3f317217, v94
	v_mul_f32_e32 v103, 0x3f317217, v95
	v_fma_f32 v100, v92, s31, -v100
	v_fma_f32 v101, v93, s31, -v101
	v_fma_f32 v102, v94, s31, -v102
	v_fma_f32 v103, v95, s31, -v103
	v_fmac_f32_e32 v100, 0x3377d1cf, v92
	v_fmac_f32_e32 v101, 0x3377d1cf, v93
	v_fmac_f32_e32 v102, 0x3377d1cf, v94
	v_fmac_f32_e32 v103, 0x3377d1cf, v95
	v_fmac_f32_e32 v100, 0x3f317217, v92
	v_fmac_f32_e32 v101, 0x3f317217, v93
	v_fmac_f32_e32 v102, 0x3f317217, v94
	v_fmac_f32_e32 v103, 0x3f317217, v95
	v_cmp_lt_f32_e64 vcc, |v92|, s34
	v_cndmask_b32_e32 v92, v92, v100, vcc
	v_cmp_lt_f32_e64 vcc, |v93|, s34
	v_cndmask_b32_e32 v93, v93, v101, vcc
	v_cmp_lt_f32_e64 vcc, |v94|, s34
	v_cndmask_b32_e32 v94, v94, v102, vcc
	v_cmp_lt_f32_e64 vcc, |v95|, s34
	v_cndmask_b32_e32 v95, v95, v103, vcc
	v_cndmask_b32_e64 v100, 0, v213, s[22:23]
	v_cndmask_b32_e64 v101, 0, v213, s[24:25]
	v_cndmask_b32_e64 v102, 0, v213, s[26:27]
	v_cndmask_b32_e64 v103, 0, v213, s[28:29]
	v_sub_f32_e32 v92, v92, v100
	v_sub_f32_e32 v93, v93, v101
	v_sub_f32_e32 v94, v94, v102
	v_sub_f32_e32 v95, v95, v103
	v_add_f32_e32 v64, v64, v92
	v_add_f32_e32 v65, v65, v93
	v_add_f32_e32 v66, v66, v94
	v_add_f32_e32 v67, v67, v95
	v_mul_f32_e32 v92, 0xbfb8aa3b, v64
	v_mul_f32_e32 v93, 0xbfb8aa3b, v65
	v_mul_f32_e32 v94, 0xbfb8aa3b, v66
	v_mul_f32_e32 v95, 0xbfb8aa3b, v67
	v_mul_f32_e32 v100, 0x3fb8aa3b, v64
	v_mul_f32_e32 v101, 0x3fb8aa3b, v65
	v_mul_f32_e32 v102, 0x3fb8aa3b, v66
	v_mul_f32_e32 v103, 0x3fb8aa3b, v67
	v_exp_f32_e32 v92, v92
	v_exp_f32_e32 v93, v93
	v_exp_f32_e32 v94, v94
	v_exp_f32_e32 v95, v95
	v_exp_f32_e32 v100, v100
	v_exp_f32_e32 v101, v101
	v_exp_f32_e32 v102, v102
	v_exp_f32_e32 v103, v103
	v_sub_f32_e32 v96, 1.0, v96
	v_sub_f32_e32 v97, 1.0, v97
	v_sub_f32_e32 v98, 1.0, v98
	v_sub_f32_e32 v99, 1.0, v99
	v_mul_f32_e32 v96, v96, v92
	v_mul_f32_e32 v97, v97, v93
	v_mul_f32_e32 v98, v98, v94
	v_mul_f32_e32 v99, v99, v95
	v_lshlrev_b32_e32 v92, 16, v22
	v_and_b32_e32 v93, 0xffff0000, v22
	v_lshlrev_b32_e32 v94, 16, v23
	v_and_b32_e32 v95, 0xffff0000, v23
	v_mul_f32_e32 v92, v92, v100
	v_mul_f32_e32 v93, v93, v101
	v_mul_f32_e32 v94, v94, v102
	v_mul_f32_e32 v95, v95, v103
	v_cvt_pk_bf16_f32 v121, v96, v121
	v_cvt_pk_bf16_f32 v137, v97, v137
	v_cvt_pk_bf16_f32 v171, v98, v171
	v_cvt_pk_bf16_f32 v187, v99, v187
	v_cvt_pk_bf16_f32 v92, v92, v93
	v_cvt_pk_bf16_f32 v93, v94, v95
	v_cvt_pk_bf16_f32 v96, v96, v97
	v_cvt_pk_bf16_f32 v97, v98, v99
	global_store_dwordx2 v112, v[92:93], s[2:3]
	global_store_dwordx2 v114, v[96:97], s[2:3]
	s_sub_u32 s2, s2, 0x400
	s_subb_u32 s3, s3, 0
	v_lshlrev_b32_e32 v92, 16, v24
	v_and_b32_e32 v93, 0xffff0000, v24
	v_lshlrev_b32_e32 v94, 16, v25
	v_and_b32_e32 v95, 0xffff0000, v25
	v_mul_f32_e32 v92, 0xbfb8aa3b, v92
	v_mul_f32_e32 v93, 0xbfb8aa3b, v93
	v_mul_f32_e32 v94, 0xbfb8aa3b, v94
	v_mul_f32_e32 v95, 0xbfb8aa3b, v95
	v_exp_f32_e32 v92, v92
	v_exp_f32_e32 v93, v93
	v_exp_f32_e32 v94, v94
	v_exp_f32_e32 v95, v95
	v_add_f32_e32 v92, 1.0, v92
	v_add_f32_e32 v93, 1.0, v93
	v_add_f32_e32 v94, 1.0, v94
	v_add_f32_e32 v95, 1.0, v95
	v_rcp_f32_e32 v92, v92
	v_rcp_f32_e32 v93, v93
	v_rcp_f32_e32 v94, v94
	v_rcp_f32_e32 v95, v95
	v_fma_f32 v96, v72, v92, v68
	v_fma_f32 v97, v73, v93, v69
	v_fma_f32 v98, v74, v94, v70
	v_fma_f32 v99, v75, v95, v71
	v_cmp_gt_f32_e64 s[22:23], s30, v96
	v_cmp_gt_f32_e64 s[24:25], s30, v97
	v_cmp_gt_f32_e64 s[26:27], s30, v98
	v_cmp_gt_f32_e64 s[28:29], s30, v99
	v_cndmask_b32_e64 v92, 0, 32, s[22:23]
	v_cndmask_b32_e64 v93, 0, 32, s[24:25]
	v_cndmask_b32_e64 v94, 0, 32, s[26:27]
	v_cndmask_b32_e64 v95, 0, 32, s[28:29]
	v_ldexp_f32 v92, v96, v92
	v_ldexp_f32 v93, v97, v93
	v_ldexp_f32 v94, v98, v94
	v_ldexp_f32 v95, v99, v95
	v_log_f32_e32 v92, v92
	v_log_f32_e32 v93, v93
	v_log_f32_e32 v94, v94
	v_log_f32_e32 v95, v95
	v_mul_f32_e32 v100, 0x3f317217, v92
	v_mul_f32_e32 v101, 0x3f317217, v93
	v_mul_f32_e32 v102, 0x3f317217, v94
	v_mul_f32_e32 v103, 0x3f317217, v95
	v_fma_f32 v100, v92, s31, -v100
	v_fma_f32 v101, v93, s31, -v101
	v_fma_f32 v102, v94, s31, -v102
	v_fma_f32 v103, v95, s31, -v103
	v_fmac_f32_e32 v100, 0x3377d1cf, v92
	v_fmac_f32_e32 v101, 0x3377d1cf, v93
	v_fmac_f32_e32 v102, 0x3377d1cf, v94
	v_fmac_f32_e32 v103, 0x3377d1cf, v95
	v_fmac_f32_e32 v100, 0x3f317217, v92
	v_fmac_f32_e32 v101, 0x3f317217, v93
	v_fmac_f32_e32 v102, 0x3f317217, v94
	v_fmac_f32_e32 v103, 0x3f317217, v95
	v_cmp_lt_f32_e64 vcc, |v92|, s34
	v_cndmask_b32_e32 v92, v92, v100, vcc
	v_cmp_lt_f32_e64 vcc, |v93|, s34
	v_cndmask_b32_e32 v93, v93, v101, vcc
	v_cmp_lt_f32_e64 vcc, |v94|, s34
	v_cndmask_b32_e32 v94, v94, v102, vcc
	v_cmp_lt_f32_e64 vcc, |v95|, s34
	v_cndmask_b32_e32 v95, v95, v103, vcc
	v_cndmask_b32_e64 v100, 0, v213, s[22:23]
	v_cndmask_b32_e64 v101, 0, v213, s[24:25]
	v_cndmask_b32_e64 v102, 0, v213, s[26:27]
	v_cndmask_b32_e64 v103, 0, v213, s[28:29]
	v_sub_f32_e32 v92, v92, v100
	v_sub_f32_e32 v93, v93, v101
	v_sub_f32_e32 v94, v94, v102
	v_sub_f32_e32 v95, v95, v103
	v_add_f32_e32 v64, v64, v92
	v_add_f32_e32 v65, v65, v93
	v_add_f32_e32 v66, v66, v94
	v_add_f32_e32 v67, v67, v95
	v_mul_f32_e32 v92, 0xbfb8aa3b, v64
	v_mul_f32_e32 v93, 0xbfb8aa3b, v65
	v_mul_f32_e32 v94, 0xbfb8aa3b, v66
	v_mul_f32_e32 v95, 0xbfb8aa3b, v67
	v_mul_f32_e32 v100, 0x3fb8aa3b, v64
	v_mul_f32_e32 v101, 0x3fb8aa3b, v65
	v_mul_f32_e32 v102, 0x3fb8aa3b, v66
	v_mul_f32_e32 v103, 0x3fb8aa3b, v67
; DEV u16 f2bf(float f) { return (u16)(pack2(f, f) & 0xffffu); }
; DEV float bf2f(u16 h) { return __uint_as_float(((unsigned)h) << 16); }
; DEV float sigmoid_f(float x) { return __builtin_amdgcn_rcpf(1.f + __expf(-x)); }
; DEV void phase_p15(const Params& p, int g) {
;     ...
;     P15_LOAD(0, 0);
;     P15_LOAD(1, 1);
; #pragma unroll
;     for (int j8 = 0; j8 < 8; ++j8) {
;       const int st = j8 % 3;
;       if (j8 < 6) { P15_LOAD((j8 + 2) % 3, j8 + 2); }
;     ...
;           const float f = lb[cc] + (1.f - lb[cc]) * sigmoid_f(bf2f(xr[st][cc][e]));
;           G[cc] += __logf(f);
;           const float eg = __expf(G[cc]), ig = __expf(-G[cc]);
;           Qp[tok * 512 + c] = f2bf(bf2f(qr[st][cc][e]) * eg);
;           const u16 kk = f2bf((1.f - f) * ig);
;           Kp[tok * 512 + c] = kk;
;           kb[e] = kk;
;         }
;         const int s0 = dir ? 56 - 8 * j8 : 8 * j8;
;         uint4 w;
;         w.x = dir ? (kb[7] | (kb[6] << 16)) : (kb[0] | (kb[1] << 16));
;         w.y = dir ? (kb[5] | (kb[4] << 16)) : (kb[2] | (kb[3] << 16));
;         w.z = dir ? (kb[3] | (kb[2] << 16)) : (kb[4] | (kb[5] << 16));
;         w.w = dir ? (kb[1] | (kb[0] << 16)) : (kb[6] | (kb[7] << 16));
	v_exp_f32_e32 v92, v92
	v_exp_f32_e32 v93, v93
	v_exp_f32_e32 v94, v94
	v_exp_f32_e32 v95, v95
	v_exp_f32_e32 v100, v100
	v_exp_f32_e32 v101, v101
	v_exp_f32_e32 v102, v102
	v_exp_f32_e32 v103, v103
	v_sub_f32_e32 v96, 1.0, v96
	v_sub_f32_e32 v97, 1.0, v97
	v_sub_f32_e32 v98, 1.0, v98
	v_sub_f32_e32 v99, 1.0, v99
	v_mul_f32_e32 v96, v96, v92
	v_mul_f32_e32 v97, v97, v93
	v_mul_f32_e32 v98, v98, v94
	v_mul_f32_e32 v99, v99, v95
	v_lshlrev_b32_e32 v92, 16, v26
	v_and_b32_e32 v93, 0xffff0000, v26
	v_lshlrev_b32_e32 v94, 16, v27
	v_and_b32_e32 v95, 0xffff0000, v27
	v_mul_f32_e32 v92, v92, v100
	v_mul_f32_e32 v93, v93, v101
	v_mul_f32_e32 v94, v94, v102
	v_mul_f32_e32 v95, v95, v103
	v_mov_b32_e32 v120, v96
	v_mov_b32_e32 v136, v97
	v_mov_b32_e32 v170, v98
	v_mov_b32_e32 v186, v99
	v_cvt_pk_bf16_f32 v92, v92, v93
	v_cvt_pk_bf16_f32 v93, v94, v95
	v_cvt_pk_bf16_f32 v96, v96, v97
	v_cvt_pk_bf16_f32 v97, v98, v99
	global_store_dwordx2 v112, v[92:93], s[2:3]
	global_store_dwordx2 v114, v[96:97], s[2:3]
	s_sub_u32 s2, s2, 0x400
	s_subb_u32 s3, s3, 0
	v_lshlrev_b32_e32 v92, 16, v28
	v_and_b32_e32 v93, 0xffff0000, v28
	v_lshlrev_b32_e32 v94, 16, v29
	v_and_b32_e32 v95, 0xffff0000, v29
	v_mul_f32_e32 v92, 0xbfb8aa3b, v92
	v_mul_f32_e32 v93, 0xbfb8aa3b, v93
	v_mul_f32_e32 v94, 0xbfb8aa3b, v94
	v_mul_f32_e32 v95, 0xbfb8aa3b, v95
	v_exp_f32_e32 v92, v92
	v_exp_f32_e32 v93, v93
	v_exp_f32_e32 v94, v94
	v_exp_f32_e32 v95, v95
	v_add_f32_e32 v92, 1.0, v92
	v_add_f32_e32 v93, 1.0, v93
	v_add_f32_e32 v94, 1.0, v94
	v_add_f32_e32 v95, 1.0, v95
	v_rcp_f32_e32 v92, v92
	v_rcp_f32_e32 v93, v93
	v_rcp_f32_e32 v94, v94
	v_rcp_f32_e32 v95, v95
	v_fma_f32 v96, v72, v92, v68
	v_fma_f32 v97, v73, v93, v69
	v_fma_f32 v98, v74, v94, v70
	v_fma_f32 v99, v75, v95, v71
	v_cmp_gt_f32_e64 s[22:23], s30, v96
	v_cmp_gt_f32_e64 s[24:25], s30, v97
	v_cmp_gt_f32_e64 s[26:27], s30, v98
	v_cmp_gt_f32_e64 s[28:29], s30, v99
	v_cndmask_b32_e64 v92, 0, 32, s[22:23]
	v_cndmask_b32_e64 v93, 0, 32, s[24:25]
	v_cndmask_b32_e64 v94, 0, 32, s[26:27]
	v_cndmask_b32_e64 v95, 0, 32, s[28:29]
	v_ldexp_f32 v92, v96, v92
	v_ldexp_f32 v93, v97, v93
	v_ldexp_f32 v94, v98, v94
	v_ldexp_f32 v95, v99, v95
	v_log_f32_e32 v92, v92
	v_log_f32_e32 v93, v93
	v_log_f32_e32 v94, v94
	v_log_f32_e32 v95, v95
	v_mul_f32_e32 v100, 0x3f317217, v92
	v_mul_f32_e32 v101, 0x3f317217, v93
	v_mul_f32_e32 v102, 0x3f317217, v94
	v_mul_f32_e32 v103, 0x3f317217, v95
	v_fma_f32 v100, v92, s31, -v100
	v_fma_f32 v101, v93, s31, -v101
	v_fma_f32 v102, v94, s31, -v102
	v_fma_f32 v103, v95, s31, -v103
	v_fmac_f32_e32 v100, 0x3377d1cf, v92
	v_fmac_f32_e32 v101, 0x3377d1cf, v93
	v_fmac_f32_e32 v102, 0x3377d1cf, v94
	v_fmac_f32_e32 v103, 0x3377d1cf, v95
	v_fmac_f32_e32 v100, 0x3f317217, v92
	v_fmac_f32_e32 v101, 0x3f317217, v93
	v_fmac_f32_e32 v102, 0x3f317217, v94
	v_fmac_f32_e32 v103, 0x3f317217, v95
	v_cmp_lt_f32_e64 vcc, |v92|, s34
	v_cndmask_b32_e32 v92, v92, v100, vcc
	v_cmp_lt_f32_e64 vcc, |v93|, s34
	v_cndmask_b32_e32 v93, v93, v101, vcc
	v_cmp_lt_f32_e64 vcc, |v94|, s34
	v_cndmask_b32_e32 v94, v94, v102, vcc
	v_cmp_lt_f32_e64 vcc, |v95|, s34
	v_cndmask_b32_e32 v95, v95, v103, vcc
	v_cndmask_b32_e64 v100, 0, v213, s[22:23]
	v_cndmask_b32_e64 v101, 0, v213, s[24:25]
	v_cndmask_b32_e64 v102, 0, v213, s[26:27]
	v_cndmask_b32_e64 v103, 0, v213, s[28:29]
	v_sub_f32_e32 v92, v92, v100
	v_sub_f32_e32 v93, v93, v101
	v_sub_f32_e32 v94, v94, v102
	v_sub_f32_e32 v95, v95, v103
	v_add_f32_e32 v64, v64, v92
	v_add_f32_e32 v65, v65, v93
	v_add_f32_e32 v66, v66, v94
	v_add_f32_e32 v67, v67, v95
	v_mul_f32_e32 v92, 0xbfb8aa3b, v64
	v_mul_f32_e32 v93, 0xbfb8aa3b, v65
	v_mul_f32_e32 v94, 0xbfb8aa3b, v66
	v_mul_f32_e32 v95, 0xbfb8aa3b, v67
	v_mul_f32_e32 v100, 0x3fb8aa3b, v64
	v_mul_f32_e32 v101, 0x3fb8aa3b, v65
	v_mul_f32_e32 v102, 0x3fb8aa3b, v66
	v_mul_f32_e32 v103, 0x3fb8aa3b, v67
	v_exp_f32_e32 v92, v92
	v_exp_f32_e32 v93, v93
	v_exp_f32_e32 v94, v94
	v_exp_f32_e32 v95, v95
	v_exp_f32_e32 v100, v100
	v_exp_f32_e32 v101, v101
	v_exp_f32_e32 v102, v102
	v_exp_f32_e32 v103, v103
	v_sub_f32_e32 v96, 1.0, v96
	v_sub_f32_e32 v97, 1.0, v97
	v_sub_f32_e32 v98, 1.0, v98
	v_sub_f32_e32 v99, 1.0, v99
	v_mul_f32_e32 v96, v96, v92
	v_mul_f32_e32 v97, v97, v93
	v_mul_f32_e32 v98, v98, v94
	v_mul_f32_e32 v99, v99, v95
	v_lshlrev_b32_e32 v92, 16, v30
	v_and_b32_e32 v93, 0xffff0000, v30
	v_lshlrev_b32_e32 v94, 16, v31
	v_and_b32_e32 v95, 0xffff0000, v31
	v_mul_f32_e32 v92, v92, v100
	v_mul_f32_e32 v93, v93, v101
	v_mul_f32_e32 v94, v94, v102
	v_mul_f32_e32 v95, v95, v103
	v_cvt_pk_bf16_f32 v120, v96, v120
	v_cvt_pk_bf16_f32 v136, v97, v136
	v_cvt_pk_bf16_f32 v170, v98, v170
	v_cvt_pk_bf16_f32 v186, v99, v186
	v_cvt_pk_bf16_f32 v92, v92, v93
	v_cvt_pk_bf16_f32 v93, v94, v95
	v_cvt_pk_bf16_f32 v96, v96, v97
	v_cvt_pk_bf16_f32 v97, v98, v99
	global_store_dwordx2 v112, v[92:93], s[2:3]
	global_store_dwordx2 v114, v[96:97], s[2:3]
	s_sub_u32 s2, s2, 0x400
	s_subb_u32 s3, s3, 0
	s_cmp_eq_u32 s35, 1
	s_cbranch_scc1 .Lp15_d1_nl2
	global_load_dwordx2 v[0:1], v113, s[0:1]
	global_load_dwordx2 v[2:3], v112, s[0:1]
	s_sub_u32 s0, s0, 0x1400
	s_subb_u32 s1, s1, 0
	global_load_dwordx2 v[4:5], v113, s[0:1]
	global_load_dwordx2 v[6:7], v112, s[0:1]
	s_sub_u32 s0, s0, 0x1400
	s_subb_u32 s1, s1, 0
	global_load_dwordx2 v[8:9], v113, s[0:1]
	global_load_dwordx2 v[10:11], v112, s[0:1]
	s_sub_u32 s0, s0, 0x1400
	s_subb_u32 s1, s1, 0
	global_load_dwordx2 v[12:13], v113, s[0:1]
	global_load_dwordx2 v[14:15], v112, s[0:1]
	s_sub_u32 s0, s0, 0x1400
	s_subb_u32 s1, s1, 0
	global_load_dwordx2 v[16:17], v113, s[0:1]
	global_load_dwordx2 v[18:19], v112, s[0:1]
	s_sub_u32 s0, s0, 0x1400
	s_subb_u32 s1, s1, 0
	global_load_dwordx2 v[20:21], v113, s[0:1]
	global_load_dwordx2 v[22:23], v112, s[0:1]
	s_sub_u32 s0, s0, 0x1400
	s_subb_u32 s1, s1, 0
	global_load_dwordx2 v[24:25], v113, s[0:1]
	global_load_dwordx2 v[26:27], v112, s[0:1]
	s_sub_u32 s0, s0, 0x1400
	s_subb_u32 s1, s1, 0
	global_load_dwordx2 v[28:29], v113, s[0:1]
	global_load_dwordx2 v[30:31], v112, s[0:1]
	s_sub_u32 s0, s0, 0x1400
	s_subb_u32 s1, s1, 0
; DEV u16 f2bf(float f) { return (u16)(pack2(f, f) & 0xffffu); }
; DEV float bf2f(u16 h) { return __uint_as_float(((unsigned)h) << 16); }
; DEV float sigmoid_f(float x) { return __builtin_amdgcn_rcpf(1.f + __expf(-x)); }
; DEV void phase_p15(const Params& p, int g) {
;     ...
; #pragma unroll
;       for (int cc = 0; cc < 2; ++cc) {
;         const int c = tid + 256 * cc;
;         unsigned kb[8];
; #pragma unroll
;         for (int e = 0; e < 8; ++e) {
;           const int jj = j8 * 8 + e;
;           const int j = dir ? 63 - jj : jj;
;           const size_t tok = (size_t)cidx * 64 + j;
;           const float f = lb[cc] + (1.f - lb[cc]) * sigmoid_f(bf2f(xr[st][cc][e]));
;           G[cc] += __logf(f);
;           const float eg = __expf(G[cc]), ig = __expf(-G[cc]);
;           Qp[tok * 512 + c] = f2bf(bf2f(qr[st][cc][e]) * eg);
;           const u16 kk = f2bf((1.f - f) * ig);
;           Kp[tok * 512 + c] = kk;
;           kb[e] = kk;
;         }
;         const int s0 = dir ? 56 - 8 * j8 : 8 * j8;
;         uint4 w;
;         w.x = dir ? (kb[7] | (kb[6] << 16)) : (kb[0] | (kb[1] << 16));
;         w.y = dir ? (kb[5] | (kb[4] << 16)) : (kb[2] | (kb[3] << 16));
;         w.z = dir ? (kb[3] | (kb[2] << 16)) : (kb[4] | (kb[5] << 16));
;         w.w = dir ? (kb[1] | (kb[0] << 16)) : (kb[6] | (kb[7] << 16));
;         *(uint4*)(KT + (((size_t)cidx * 2 + dir) * 512 + c) * 64 + s0) = w;
;       }
.Lp15_d1_nl2:
	s_waitcnt vmcnt(16)
	v_lshlrev_b32_e32 v92, 16, v32
	v_and_b32_e32 v93, 0xffff0000, v32
	v_lshlrev_b32_e32 v94, 16, v33
	v_and_b32_e32 v95, 0xffff0000, v33
	v_mul_f32_e32 v92, 0xbfb8aa3b, v92
	v_mul_f32_e32 v93, 0xbfb8aa3b, v93
	v_mul_f32_e32 v94, 0xbfb8aa3b, v94
	v_mul_f32_e32 v95, 0xbfb8aa3b, v95
	v_exp_f32_e32 v92, v92
	v_exp_f32_e32 v93, v93
	v_exp_f32_e32 v94, v94
	v_exp_f32_e32 v95, v95
	v_add_f32_e32 v92, 1.0, v92
	v_add_f32_e32 v93, 1.0, v93
	v_add_f32_e32 v94, 1.0, v94
	v_add_f32_e32 v95, 1.0, v95
	v_rcp_f32_e32 v92, v92
	v_rcp_f32_e32 v93, v93
	v_rcp_f32_e32 v94, v94
	v_rcp_f32_e32 v95, v95
	v_fma_f32 v96, v72, v92, v68
	v_fma_f32 v97, v73, v93, v69
	v_fma_f32 v98, v74, v94, v70
	v_fma_f32 v99, v75, v95, v71
	v_cmp_gt_f32_e64 s[22:23], s30, v96
	v_cmp_gt_f32_e64 s[24:25], s30, v97
	v_cmp_gt_f32_e64 s[26:27], s30, v98
	v_cmp_gt_f32_e64 s[28:29], s30, v99
	v_cndmask_b32_e64 v92, 0, 32, s[22:23]
	v_cndmask_b32_e64 v93, 0, 32, s[24:25]
	v_cndmask_b32_e64 v94, 0, 32, s[26:27]
	v_cndmask_b32_e64 v95, 0, 32, s[28:29]
	v_ldexp_f32 v92, v96, v92
	v_ldexp_f32 v93, v97, v93
	v_ldexp_f32 v94, v98, v94
	v_ldexp_f32 v95, v99, v95
	v_log_f32_e32 v92, v92
	v_log_f32_e32 v93, v93
	v_log_f32_e32 v94, v94
	v_log_f32_e32 v95, v95
	v_mul_f32_e32 v100, 0x3f317217, v92
	v_mul_f32_e32 v101, 0x3f317217, v93
	v_mul_f32_e32 v102, 0x3f317217, v94
	v_mul_f32_e32 v103, 0x3f317217, v95
	v_fma_f32 v100, v92, s31, -v100
	v_fma_f32 v101, v93, s31, -v101
	v_fma_f32 v102, v94, s31, -v102
	v_fma_f32 v103, v95, s31, -v103
	v_fmac_f32_e32 v100, 0x3377d1cf, v92
	v_fmac_f32_e32 v101, 0x3377d1cf, v93
	v_fmac_f32_e32 v102, 0x3377d1cf, v94
	v_fmac_f32_e32 v103, 0x3377d1cf, v95
	v_fmac_f32_e32 v100, 0x3f317217, v92
	v_fmac_f32_e32 v101, 0x3f317217, v93
	v_fmac_f32_e32 v102, 0x3f317217, v94
	v_fmac_f32_e32 v103, 0x3f317217, v95
	v_cmp_lt_f32_e64 vcc, |v92|, s34
	v_cndmask_b32_e32 v92, v92, v100, vcc
	v_cmp_lt_f32_e64 vcc, |v93|, s34
	v_cndmask_b32_e32 v93, v93, v101, vcc
	v_cmp_lt_f32_e64 vcc, |v94|, s34
	v_cndmask_b32_e32 v94, v94, v102, vcc
	v_cmp_lt_f32_e64 vcc, |v95|, s34
	v_cndmask_b32_e32 v95, v95, v103, vcc
	v_cndmask_b32_e64 v100, 0, v213, s[22:23]
	v_cndmask_b32_e64 v101, 0, v213, s[24:25]
	v_cndmask_b32_e64 v102, 0, v213, s[26:27]
	v_cndmask_b32_e64 v103, 0, v213, s[28:29]
	v_sub_f32_e32 v92, v92, v100
	v_sub_f32_e32 v93, v93, v101
	v_sub_f32_e32 v94, v94, v102
	v_sub_f32_e32 v95, v95, v103
	v_add_f32_e32 v64, v64, v92
	v_add_f32_e32 v65, v65, v93
	v_add_f32_e32 v66, v66, v94
	v_add_f32_e32 v67, v67, v95
	v_mul_f32_e32 v92, 0xbfb8aa3b, v64
	v_mul_f32_e32 v93, 0xbfb8aa3b, v65
	v_mul_f32_e32 v94, 0xbfb8aa3b, v66
	v_mul_f32_e32 v95, 0xbfb8aa3b, v67
	v_mul_f32_e32 v100, 0x3fb8aa3b, v64
	v_mul_f32_e32 v101, 0x3fb8aa3b, v65
	v_mul_f32_e32 v102, 0x3fb8aa3b, v66
	v_mul_f32_e32 v103, 0x3fb8aa3b, v67
	v_exp_f32_e32 v92, v92
	v_exp_f32_e32 v93, v93
	v_exp_f32_e32 v94, v94
	v_exp_f32_e32 v95, v95
	v_exp_f32_e32 v100, v100
	v_exp_f32_e32 v101, v101
	v_exp_f32_e32 v102, v102
	v_exp_f32_e32 v103, v103
	v_sub_f32_e32 v96, 1.0, v96
	v_sub_f32_e32 v97, 1.0, v97
	v_sub_f32_e32 v98, 1.0, v98
	v_sub_f32_e32 v99, 1.0, v99
	v_mul_f32_e32 v96, v96, v92
	v_mul_f32_e32 v97, v97, v93
	v_mul_f32_e32 v98, v98, v94
	v_mul_f32_e32 v99, v99, v95
	v_lshlrev_b32_e32 v92, 16, v34
	v_and_b32_e32 v93, 0xffff0000, v34
	v_lshlrev_b32_e32 v94, 16, v35
	v_and_b32_e32 v95, 0xffff0000, v35
	v_mul_f32_e32 v92, v92, v100
	v_mul_f32_e32 v93, v93, v101
	v_mul_f32_e32 v94, v94, v102
	v_mul_f32_e32 v95, v95, v103
	v_mov_b32_e32 v119, v96
	v_mov_b32_e32 v135, v97
	v_mov_b32_e32 v169, v98
	v_mov_b32_e32 v185, v99
	v_cvt_pk_bf16_f32 v92, v92, v93
	v_cvt_pk_bf16_f32 v93, v94, v95
	v_cvt_pk_bf16_f32 v96, v96, v97
	v_cvt_pk_bf16_f32 v97, v98, v99
	global_store_dwordx2 v112, v[92:93], s[2:3]
	global_store_dwordx2 v114, v[96:97], s[2:3]
	s_sub_u32 s2, s2, 0x400
	s_subb_u32 s3, s3, 0
	v_lshlrev_b32_e32 v92, 16, v36
	v_and_b32_e32 v93, 0xffff0000, v36
	v_lshlrev_b32_e32 v94, 16, v37
	v_and_b32_e32 v95, 0xffff0000, v37
	v_mul_f32_e32 v92, 0xbfb8aa3b, v92
	v_mul_f32_e32 v93, 0xbfb8aa3b, v93
	v_mul_f32_e32 v94, 0xbfb8aa3b, v94
	v_mul_f32_e32 v95, 0xbfb8aa3b, v95
	v_exp_f32_e32 v92, v92
	v_exp_f32_e32 v93, v93
	v_exp_f32_e32 v94, v94
	v_exp_f32_e32 v95, v95
	v_add_f32_e32 v92, 1.0, v92
	v_add_f32_e32 v93, 1.0, v93
	v_add_f32_e32 v94, 1.0, v94
	v_add_f32_e32 v95, 1.0, v95
	v_rcp_f32_e32 v92, v92
	v_rcp_f32_e32 v93, v93
	v_rcp_f32_e32 v94, v94
	v_rcp_f32_e32 v95, v95
	v_fma_f32 v96, v72, v92, v68
	v_fma_f32 v97, v73, v93, v69
	v_fma_f32 v98, v74, v94, v70
	v_fma_f32 v99, v75, v95, v71
	v_cmp_gt_f32_e64 s[22:23], s30, v96
	v_cmp_gt_f32_e64 s[24:25], s30, v97
	v_cmp_gt_f32_e64 s[26:27], s30, v98
	v_cmp_gt_f32_e64 s[28:29], s30, v99
	v_cndmask_b32_e64 v92, 0, 32, s[22:23]
	v_cndmask_b32_e64 v93, 0, 32, s[24:25]
	v_cndmask_b32_e64 v94, 0, 32, s[26:27]
	v_cndmask_b32_e64 v95, 0, 32, s[28:29]
	v_ldexp_f32 v92, v96, v92
	v_ldexp_f32 v93, v97, v93
	v_ldexp_f32 v94, v98, v94
	v_ldexp_f32 v95, v99, v95
	v_log_f32_e32 v92, v92
	v_log_f32_e32 v93, v93
	v_log_f32_e32 v94, v94
	v_log_f32_e32 v95, v95
	v_mul_f32_e32 v100, 0x3f317217, v92
	v_mul_f32_e32 v101, 0x3f317217, v93
	v_mul_f32_e32 v102, 0x3f317217, v94
	v_mul_f32_e32 v103, 0x3f317217, v95
	v_fma_f32 v100, v92, s31, -v100
	v_fma_f32 v101, v93, s31, -v101
	v_fma_f32 v102, v94, s31, -v102
	v_fma_f32 v103, v95, s31, -v103
	v_fmac_f32_e32 v100, 0x3377d1cf, v92
	v_fmac_f32_e32 v101, 0x3377d1cf, v93
	v_fmac_f32_e32 v102, 0x3377d1cf, v94
	v_fmac_f32_e32 v103, 0x3377d1cf, v95
	v_fmac_f32_e32 v100, 0x3f317217, v92
	v_fmac_f32_e32 v101, 0x3f317217, v93
	v_fmac_f32_e32 v102, 0x3f317217, v94
; DEV u16 f2bf(float f) { return (u16)(pack2(f, f) & 0xffffu); }
; DEV float bf2f(u16 h) { return __uint_as_float(((unsigned)h) << 16); }
; DEV float sigmoid_f(float x) { return __builtin_amdgcn_rcpf(1.f + __expf(-x)); }
; DEV void phase_p15(const Params& p, int g) {
;     ...
; #pragma unroll
;       for (int cc = 0; cc < 2; ++cc) {
;         const int c = tid + 256 * cc;
;         unsigned kb[8];
; #pragma unroll
;         for (int e = 0; e < 8; ++e) {
;           const int jj = j8 * 8 + e;
;           const int j = dir ? 63 - jj : jj;
;           const size_t tok = (size_t)cidx * 64 + j;
;           const float f = lb[cc] + (1.f - lb[cc]) * sigmoid_f(bf2f(xr[st][cc][e]));
;           G[cc] += __logf(f);
;           const float eg = __expf(G[cc]), ig = __expf(-G[cc]);
;           Qp[tok * 512 + c] = f2bf(bf2f(qr[st][cc][e]) * eg);
;           const u16 kk = f2bf((1.f - f) * ig);
;           Kp[tok * 512 + c] = kk;
;           kb[e] = kk;
;         }
;         const int s0 = dir ? 56 - 8 * j8 : 8 * j8;
;         uint4 w;
;         w.x = dir ? (kb[7] | (kb[6] << 16)) : (kb[0] | (kb[1] << 16));
;         w.y = dir ? (kb[5] | (kb[4] << 16)) : (kb[2] | (kb[3] << 16));
;         w.z = dir ? (kb[3] | (kb[2] << 16)) : (kb[4] | (kb[5] << 16));
;         w.w = dir ? (kb[1] | (kb[0] << 16)) : (kb[6] | (kb[7] << 16));
;         *(uint4*)(KT + (((size_t)cidx * 2 + dir) * 512 + c) * 64 + s0) = w;
;       }
	v_fmac_f32_e32 v103, 0x3f317217, v95
	v_cmp_lt_f32_e64 vcc, |v92|, s34
	v_cndmask_b32_e32 v92, v92, v100, vcc
	v_cmp_lt_f32_e64 vcc, |v93|, s34
	v_cndmask_b32_e32 v93, v93, v101, vcc
	v_cmp_lt_f32_e64 vcc, |v94|, s34
	v_cndmask_b32_e32 v94, v94, v102, vcc
	v_cmp_lt_f32_e64 vcc, |v95|, s34
	v_cndmask_b32_e32 v95, v95, v103, vcc
	v_cndmask_b32_e64 v100, 0, v213, s[22:23]
	v_cndmask_b32_e64 v101, 0, v213, s[24:25]
	v_cndmask_b32_e64 v102, 0, v213, s[26:27]
	v_cndmask_b32_e64 v103, 0, v213, s[28:29]
	v_sub_f32_e32 v92, v92, v100
	v_sub_f32_e32 v93, v93, v101
	v_sub_f32_e32 v94, v94, v102
	v_sub_f32_e32 v95, v95, v103
	v_add_f32_e32 v64, v64, v92
	v_add_f32_e32 v65, v65, v93
	v_add_f32_e32 v66, v66, v94
	v_add_f32_e32 v67, v67, v95
	v_mul_f32_e32 v92, 0xbfb8aa3b, v64
	v_mul_f32_e32 v93, 0xbfb8aa3b, v65
	v_mul_f32_e32 v94, 0xbfb8aa3b, v66
	v_mul_f32_e32 v95, 0xbfb8aa3b, v67
	v_mul_f32_e32 v100, 0x3fb8aa3b, v64
	v_mul_f32_e32 v101, 0x3fb8aa3b, v65
	v_mul_f32_e32 v102, 0x3fb8aa3b, v66
	v_mul_f32_e32 v103, 0x3fb8aa3b, v67
	v_exp_f32_e32 v92, v92
	v_exp_f32_e32 v93, v93
	v_exp_f32_e32 v94, v94
	v_exp_f32_e32 v95, v95
	v_exp_f32_e32 v100, v100
	v_exp_f32_e32 v101, v101
	v_exp_f32_e32 v102, v102
	v_exp_f32_e32 v103, v103
	v_sub_f32_e32 v96, 1.0, v96
	v_sub_f32_e32 v97, 1.0, v97
	v_sub_f32_e32 v98, 1.0, v98
	v_sub_f32_e32 v99, 1.0, v99
	v_mul_f32_e32 v96, v96, v92
	v_mul_f32_e32 v97, v97, v93
	v_mul_f32_e32 v98, v98, v94
	v_mul_f32_e32 v99, v99, v95
	v_lshlrev_b32_e32 v92, 16, v38
	v_and_b32_e32 v93, 0xffff0000, v38
	v_lshlrev_b32_e32 v94, 16, v39
	v_and_b32_e32 v95, 0xffff0000, v39
	v_mul_f32_e32 v92, v92, v100
	v_mul_f32_e32 v93, v93, v101
	v_mul_f32_e32 v94, v94, v102
	v_mul_f32_e32 v95, v95, v103
	v_cvt_pk_bf16_f32 v119, v96, v119
	v_cvt_pk_bf16_f32 v135, v97, v135
	v_cvt_pk_bf16_f32 v169, v98, v169
	v_cvt_pk_bf16_f32 v185, v99, v185
	v_cvt_pk_bf16_f32 v92, v92, v93
	v_cvt_pk_bf16_f32 v93, v94, v95
	v_cvt_pk_bf16_f32 v96, v96, v97
	v_cvt_pk_bf16_f32 v97, v98, v99
	global_store_dwordx2 v112, v[92:93], s[2:3]
	global_store_dwordx2 v114, v[96:97], s[2:3]
	s_sub_u32 s2, s2, 0x400
	s_subb_u32 s3, s3, 0
	v_lshlrev_b32_e32 v92, 16, v40
	v_and_b32_e32 v93, 0xffff0000, v40
	v_lshlrev_b32_e32 v94, 16, v41
	v_and_b32_e32 v95, 0xffff0000, v41
	v_mul_f32_e32 v92, 0xbfb8aa3b, v92
	v_mul_f32_e32 v93, 0xbfb8aa3b, v93
	v_mul_f32_e32 v94, 0xbfb8aa3b, v94
	v_mul_f32_e32 v95, 0xbfb8aa3b, v95
	v_exp_f32_e32 v92, v92
	v_exp_f32_e32 v93, v93
	v_exp_f32_e32 v94, v94
	v_exp_f32_e32 v95, v95
	v_add_f32_e32 v92, 1.0, v92
	v_add_f32_e32 v93, 1.0, v93
	v_add_f32_e32 v94, 1.0, v94
	v_add_f32_e32 v95, 1.0, v95
	v_rcp_f32_e32 v92, v92
	v_rcp_f32_e32 v93, v93
	v_rcp_f32_e32 v94, v94
	v_rcp_f32_e32 v95, v95
	v_fma_f32 v96, v72, v92, v68
	v_fma_f32 v97, v73, v93, v69
	v_fma_f32 v98, v74, v94, v70
	v_fma_f32 v99, v75, v95, v71
	v_cmp_gt_f32_e64 s[22:23], s30, v96
	v_cmp_gt_f32_e64 s[24:25], s30, v97
	v_cmp_gt_f32_e64 s[26:27], s30, v98
	v_cmp_gt_f32_e64 s[28:29], s30, v99
	v_cndmask_b32_e64 v92, 0, 32, s[22:23]
	v_cndmask_b32_e64 v93, 0, 32, s[24:25]
	v_cndmask_b32_e64 v94, 0, 32, s[26:27]
	v_cndmask_b32_e64 v95, 0, 32, s[28:29]
	v_ldexp_f32 v92, v96, v92
	v_ldexp_f32 v93, v97, v93
	v_ldexp_f32 v94, v98, v94
	v_ldexp_f32 v95, v99, v95
	v_log_f32_e32 v92, v92
	v_log_f32_e32 v93, v93
	v_log_f32_e32 v94, v94
	v_log_f32_e32 v95, v95
	v_mul_f32_e32 v100, 0x3f317217, v92
	v_mul_f32_e32 v101, 0x3f317217, v93
	v_mul_f32_e32 v102, 0x3f317217, v94
	v_mul_f32_e32 v103, 0x3f317217, v95
	v_fma_f32 v100, v92, s31, -v100
	v_fma_f32 v101, v93, s31, -v101
	v_fma_f32 v102, v94, s31, -v102
	v_fma_f32 v103, v95, s31, -v103
	v_fmac_f32_e32 v100, 0x3377d1cf, v92
	v_fmac_f32_e32 v101, 0x3377d1cf, v93
	v_fmac_f32_e32 v102, 0x3377d1cf, v94
	v_fmac_f32_e32 v103, 0x3377d1cf, v95
	v_fmac_f32_e32 v100, 0x3f317217, v92
	v_fmac_f32_e32 v101, 0x3f317217, v93
	v_fmac_f32_e32 v102, 0x3f317217, v94
	v_fmac_f32_e32 v103, 0x3f317217, v95
	v_cmp_lt_f32_e64 vcc, |v92|, s34
	v_cndmask_b32_e32 v92, v92, v100, vcc
	v_cmp_lt_f32_e64 vcc, |v93|, s34
	v_cndmask_b32_e32 v93, v93, v101, vcc
	v_cmp_lt_f32_e64 vcc, |v94|, s34
	v_cndmask_b32_e32 v94, v94, v102, vcc
	v_cmp_lt_f32_e64 vcc, |v95|, s34
	v_cndmask_b32_e32 v95, v95, v103, vcc
	v_cndmask_b32_e64 v100, 0, v213, s[22:23]
	v_cndmask_b32_e64 v101, 0, v213, s[24:25]
	v_cndmask_b32_e64 v102, 0, v213, s[26:27]
	v_cndmask_b32_e64 v103, 0, v213, s[28:29]
	v_sub_f32_e32 v92, v92, v100
	v_sub_f32_e32 v93, v93, v101
	v_sub_f32_e32 v94, v94, v102
	v_sub_f32_e32 v95, v95, v103
	v_add_f32_e32 v64, v64, v92
	v_add_f32_e32 v65, v65, v93
	v_add_f32_e32 v66, v66, v94
	v_add_f32_e32 v67, v67, v95
	v_mul_f32_e32 v92, 0xbfb8aa3b, v64
	v_mul_f32_e32 v93, 0xbfb8aa3b, v65
	v_mul_f32_e32 v94, 0xbfb8aa3b, v66
	v_mul_f32_e32 v95, 0xbfb8aa3b, v67
	v_mul_f32_e32 v100, 0x3fb8aa3b, v64
	v_mul_f32_e32 v101, 0x3fb8aa3b, v65
	v_mul_f32_e32 v102, 0x3fb8aa3b, v66
	v_mul_f32_e32 v103, 0x3fb8aa3b, v67
	v_exp_f32_e32 v92, v92
	v_exp_f32_e32 v93, v93
	v_exp_f32_e32 v94, v94
	v_exp_f32_e32 v95, v95
	v_exp_f32_e32 v100, v100
	v_exp_f32_e32 v101, v101
	v_exp_f32_e32 v102, v102
	v_exp_f32_e32 v103, v103
	v_sub_f32_e32 v96, 1.0, v96
	v_sub_f32_e32 v97, 1.0, v97
	v_sub_f32_e32 v98, 1.0, v98
	v_sub_f32_e32 v99, 1.0, v99
	v_mul_f32_e32 v96, v96, v92
	v_mul_f32_e32 v97, v97, v93
	v_mul_f32_e32 v98, v98, v94
	v_mul_f32_e32 v99, v99, v95
	v_lshlrev_b32_e32 v92, 16, v42
	v_and_b32_e32 v93, 0xffff0000, v42
	v_lshlrev_b32_e32 v94, 16, v43
	v_and_b32_e32 v95, 0xffff0000, v43
	v_mul_f32_e32 v92, v92, v100
	v_mul_f32_e32 v93, v93, v101
	v_mul_f32_e32 v94, v94, v102
	v_mul_f32_e32 v95, v95, v103
	v_mov_b32_e32 v118, v96
; DEV u16 f2bf(float f) { return (u16)(pack2(f, f) & 0xffffu); }
; DEV float bf2f(u16 h) { return __uint_as_float(((unsigned)h) << 16); }
; DEV float sigmoid_f(float x) { return __builtin_amdgcn_rcpf(1.f + __expf(-x)); }
; DEV void phase_p15(const Params& p, int g) {
;     ...
; #pragma unroll
;       for (int cc = 0; cc < 2; ++cc) {
;         const int c = tid + 256 * cc;
;         unsigned kb[8];
; #pragma unroll
;         for (int e = 0; e < 8; ++e) {
;           const int jj = j8 * 8 + e;
;           const int j = dir ? 63 - jj : jj;
;           const size_t tok = (size_t)cidx * 64 + j;
;           const float f = lb[cc] + (1.f - lb[cc]) * sigmoid_f(bf2f(xr[st][cc][e]));
;           G[cc] += __logf(f);
;           const float eg = __expf(G[cc]), ig = __expf(-G[cc]);
;           Qp[tok * 512 + c] = f2bf(bf2f(qr[st][cc][e]) * eg);
;           const u16 kk = f2bf((1.f - f) * ig);
;           Kp[tok * 512 + c] = kk;
;           kb[e] = kk;
;         }
;         const int s0 = dir ? 56 - 8 * j8 : 8 * j8;
;         uint4 w;
;         w.x = dir ? (kb[7] | (kb[6] << 16)) : (kb[0] | (kb[1] << 16));
;         w.y = dir ? (kb[5] | (kb[4] << 16)) : (kb[2] | (kb[3] << 16));
;         w.z = dir ? (kb[3] | (kb[2] << 16)) : (kb[4] | (kb[5] << 16));
;         w.w = dir ? (kb[1] | (kb[0] << 16)) : (kb[6] | (kb[7] << 16));
;         *(uint4*)(KT + (((size_t)cidx * 2 + dir) * 512 + c) * 64 + s0) = w;
;       }
	v_mov_b32_e32 v134, v97
	v_mov_b32_e32 v168, v98
	v_mov_b32_e32 v184, v99
	v_cvt_pk_bf16_f32 v92, v92, v93
	v_cvt_pk_bf16_f32 v93, v94, v95
	v_cvt_pk_bf16_f32 v96, v96, v97
	v_cvt_pk_bf16_f32 v97, v98, v99
	global_store_dwordx2 v112, v[92:93], s[2:3]
	global_store_dwordx2 v114, v[96:97], s[2:3]
	s_sub_u32 s2, s2, 0x400
	s_subb_u32 s3, s3, 0
	v_lshlrev_b32_e32 v92, 16, v44
	v_and_b32_e32 v93, 0xffff0000, v44
	v_lshlrev_b32_e32 v94, 16, v45
	v_and_b32_e32 v95, 0xffff0000, v45
	v_mul_f32_e32 v92, 0xbfb8aa3b, v92
	v_mul_f32_e32 v93, 0xbfb8aa3b, v93
	v_mul_f32_e32 v94, 0xbfb8aa3b, v94
	v_mul_f32_e32 v95, 0xbfb8aa3b, v95
	v_exp_f32_e32 v92, v92
	v_exp_f32_e32 v93, v93
	v_exp_f32_e32 v94, v94
	v_exp_f32_e32 v95, v95
	v_add_f32_e32 v92, 1.0, v92
	v_add_f32_e32 v93, 1.0, v93
	v_add_f32_e32 v94, 1.0, v94
	v_add_f32_e32 v95, 1.0, v95
	v_rcp_f32_e32 v92, v92
	v_rcp_f32_e32 v93, v93
	v_rcp_f32_e32 v94, v94
	v_rcp_f32_e32 v95, v95
	v_fma_f32 v96, v72, v92, v68
	v_fma_f32 v97, v73, v93, v69
	v_fma_f32 v98, v74, v94, v70
	v_fma_f32 v99, v75, v95, v71
	v_cmp_gt_f32_e64 s[22:23], s30, v96
	v_cmp_gt_f32_e64 s[24:25], s30, v97
	v_cmp_gt_f32_e64 s[26:27], s30, v98
	v_cmp_gt_f32_e64 s[28:29], s30, v99
	v_cndmask_b32_e64 v92, 0, 32, s[22:23]
	v_cndmask_b32_e64 v93, 0, 32, s[24:25]
	v_cndmask_b32_e64 v94, 0, 32, s[26:27]
	v_cndmask_b32_e64 v95, 0, 32, s[28:29]
	v_ldexp_f32 v92, v96, v92
	v_ldexp_f32 v93, v97, v93
	v_ldexp_f32 v94, v98, v94
	v_ldexp_f32 v95, v99, v95
	v_log_f32_e32 v92, v92
	v_log_f32_e32 v93, v93
	v_log_f32_e32 v94, v94
	v_log_f32_e32 v95, v95
	v_mul_f32_e32 v100, 0x3f317217, v92
	v_mul_f32_e32 v101, 0x3f317217, v93
	v_mul_f32_e32 v102, 0x3f317217, v94
	v_mul_f32_e32 v103, 0x3f317217, v95
	v_fma_f32 v100, v92, s31, -v100
	v_fma_f32 v101, v93, s31, -v101
	v_fma_f32 v102, v94, s31, -v102
	v_fma_f32 v103, v95, s31, -v103
	v_fmac_f32_e32 v100, 0x3377d1cf, v92
	v_fmac_f32_e32 v101, 0x3377d1cf, v93
	v_fmac_f32_e32 v102, 0x3377d1cf, v94
	v_fmac_f32_e32 v103, 0x3377d1cf, v95
	v_fmac_f32_e32 v100, 0x3f317217, v92
	v_fmac_f32_e32 v101, 0x3f317217, v93
	v_fmac_f32_e32 v102, 0x3f317217, v94
	v_fmac_f32_e32 v103, 0x3f317217, v95
	v_cmp_lt_f32_e64 vcc, |v92|, s34
	v_cndmask_b32_e32 v92, v92, v100, vcc
	v_cmp_lt_f32_e64 vcc, |v93|, s34
	v_cndmask_b32_e32 v93, v93, v101, vcc
	v_cmp_lt_f32_e64 vcc, |v94|, s34
	v_cndmask_b32_e32 v94, v94, v102, vcc
	v_cmp_lt_f32_e64 vcc, |v95|, s34
	v_cndmask_b32_e32 v95, v95, v103, vcc
	v_cndmask_b32_e64 v100, 0, v213, s[22:23]
	v_cndmask_b32_e64 v101, 0, v213, s[24:25]
	v_cndmask_b32_e64 v102, 0, v213, s[26:27]
	v_cndmask_b32_e64 v103, 0, v213, s[28:29]
	v_sub_f32_e32 v92, v92, v100
	v_sub_f32_e32 v93, v93, v101
	v_sub_f32_e32 v94, v94, v102
	v_sub_f32_e32 v95, v95, v103
	v_add_f32_e32 v64, v64, v92
	v_add_f32_e32 v65, v65, v93
	v_add_f32_e32 v66, v66, v94
	v_add_f32_e32 v67, v67, v95
	v_mul_f32_e32 v92, 0xbfb8aa3b, v64
	v_mul_f32_e32 v93, 0xbfb8aa3b, v65
	v_mul_f32_e32 v94, 0xbfb8aa3b, v66
	v_mul_f32_e32 v95, 0xbfb8aa3b, v67
	v_mul_f32_e32 v100, 0x3fb8aa3b, v64
	v_mul_f32_e32 v101, 0x3fb8aa3b, v65
	v_mul_f32_e32 v102, 0x3fb8aa3b, v66
	v_mul_f32_e32 v103, 0x3fb8aa3b, v67
	v_exp_f32_e32 v92, v92
	v_exp_f32_e32 v93, v93
	v_exp_f32_e32 v94, v94
	v_exp_f32_e32 v95, v95
	v_exp_f32_e32 v100, v100
	v_exp_f32_e32 v101, v101
	v_exp_f32_e32 v102, v102
	v_exp_f32_e32 v103, v103
	v_sub_f32_e32 v96, 1.0, v96
	v_sub_f32_e32 v97, 1.0, v97
	v_sub_f32_e32 v98, 1.0, v98
	v_sub_f32_e32 v99, 1.0, v99
	v_mul_f32_e32 v96, v96, v92
	v_mul_f32_e32 v97, v97, v93
	v_mul_f32_e32 v98, v98, v94
	v_mul_f32_e32 v99, v99, v95
	v_lshlrev_b32_e32 v92, 16, v46
	v_and_b32_e32 v93, 0xffff0000, v46
	v_lshlrev_b32_e32 v94, 16, v47
	v_and_b32_e32 v95, 0xffff0000, v47
	v_mul_f32_e32 v92, v92, v100
	v_mul_f32_e32 v93, v93, v101
	v_mul_f32_e32 v94, v94, v102
	v_mul_f32_e32 v95, v95, v103
	v_cvt_pk_bf16_f32 v118, v96, v118
	v_cvt_pk_bf16_f32 v134, v97, v134
	v_cvt_pk_bf16_f32 v168, v98, v168
	v_cvt_pk_bf16_f32 v184, v99, v184
	v_cvt_pk_bf16_f32 v92, v92, v93
	v_cvt_pk_bf16_f32 v93, v94, v95
	v_cvt_pk_bf16_f32 v96, v96, v97
	v_cvt_pk_bf16_f32 v97, v98, v99
	global_store_dwordx2 v112, v[92:93], s[2:3]
	global_store_dwordx2 v114, v[96:97], s[2:3]
	s_sub_u32 s2, s2, 0x400
	s_subb_u32 s3, s3, 0
	v_lshlrev_b32_e32 v92, 16, v48
	v_and_b32_e32 v93, 0xffff0000, v48
	v_lshlrev_b32_e32 v94, 16, v49
	v_and_b32_e32 v95, 0xffff0000, v49
	v_mul_f32_e32 v92, 0xbfb8aa3b, v92
	v_mul_f32_e32 v93, 0xbfb8aa3b, v93
	v_mul_f32_e32 v94, 0xbfb8aa3b, v94
	v_mul_f32_e32 v95, 0xbfb8aa3b, v95
	v_exp_f32_e32 v92, v92
	v_exp_f32_e32 v93, v93
	v_exp_f32_e32 v94, v94
	v_exp_f32_e32 v95, v95
	v_add_f32_e32 v92, 1.0, v92
	v_add_f32_e32 v93, 1.0, v93
	v_add_f32_e32 v94, 1.0, v94
	v_add_f32_e32 v95, 1.0, v95
	v_rcp_f32_e32 v92, v92
	v_rcp_f32_e32 v93, v93
	v_rcp_f32_e32 v94, v94
	v_rcp_f32_e32 v95, v95
	v_fma_f32 v96, v72, v92, v68
	v_fma_f32 v97, v73, v93, v69
	v_fma_f32 v98, v74, v94, v70
	v_fma_f32 v99, v75, v95, v71
	v_cmp_gt_f32_e64 s[22:23], s30, v96
	v_cmp_gt_f32_e64 s[24:25], s30, v97
	v_cmp_gt_f32_e64 s[26:27], s30, v98
	v_cmp_gt_f32_e64 s[28:29], s30, v99
	v_cndmask_b32_e64 v92, 0, 32, s[22:23]
	v_cndmask_b32_e64 v93, 0, 32, s[24:25]
	v_cndmask_b32_e64 v94, 0, 32, s[26:27]
	v_cndmask_b32_e64 v95, 0, 32, s[28:29]
	v_ldexp_f32 v92, v96, v92
	v_ldexp_f32 v93, v97, v93
	v_ldexp_f32 v94, v98, v94
	v_ldexp_f32 v95, v99, v95
	v_log_f32_e32 v92, v92
	v_log_f32_e32 v93, v93
	v_log_f32_e32 v94, v94
	v_log_f32_e32 v95, v95
	v_mul_f32_e32 v100, 0x3f317217, v92
	v_mul_f32_e32 v101, 0x3f317217, v93
	v_mul_f32_e32 v102, 0x3f317217, v94
	v_mul_f32_e32 v103, 0x3f317217, v95
	v_fma_f32 v100, v92, s31, -v100
; DEV u16 f2bf(float f) { return (u16)(pack2(f, f) & 0xffffu); }
; DEV float bf2f(u16 h) { return __uint_as_float(((unsigned)h) << 16); }
; DEV float sigmoid_f(float x) { return __builtin_amdgcn_rcpf(1.f + __expf(-x)); }
; DEV void phase_p15(const Params& p, int g) {
;     ...
; #pragma unroll
;       for (int cc = 0; cc < 2; ++cc) {
;         const int c = tid + 256 * cc;
;         unsigned kb[8];
; #pragma unroll
;         for (int e = 0; e < 8; ++e) {
;           const int jj = j8 * 8 + e;
;           const int j = dir ? 63 - jj : jj;
;           const size_t tok = (size_t)cidx * 64 + j;
;           const float f = lb[cc] + (1.f - lb[cc]) * sigmoid_f(bf2f(xr[st][cc][e]));
;           G[cc] += __logf(f);
;           const float eg = __expf(G[cc]), ig = __expf(-G[cc]);
;           Qp[tok * 512 + c] = f2bf(bf2f(qr[st][cc][e]) * eg);
;           const u16 kk = f2bf((1.f - f) * ig);
;           Kp[tok * 512 + c] = kk;
;           kb[e] = kk;
;         }
;         const int s0 = dir ? 56 - 8 * j8 : 8 * j8;
;         uint4 w;
;         w.x = dir ? (kb[7] | (kb[6] << 16)) : (kb[0] | (kb[1] << 16));
;         w.y = dir ? (kb[5] | (kb[4] << 16)) : (kb[2] | (kb[3] << 16));
;         w.z = dir ? (kb[3] | (kb[2] << 16)) : (kb[4] | (kb[5] << 16));
;         w.w = dir ? (kb[1] | (kb[0] << 16)) : (kb[6] | (kb[7] << 16));
;         *(uint4*)(KT + (((size_t)cidx * 2 + dir) * 512 + c) * 64 + s0) = w;
;       }
	v_fma_f32 v101, v93, s31, -v101
	v_fma_f32 v102, v94, s31, -v102
	v_fma_f32 v103, v95, s31, -v103
	v_fmac_f32_e32 v100, 0x3377d1cf, v92
	v_fmac_f32_e32 v101, 0x3377d1cf, v93
	v_fmac_f32_e32 v102, 0x3377d1cf, v94
	v_fmac_f32_e32 v103, 0x3377d1cf, v95
	v_fmac_f32_e32 v100, 0x3f317217, v92
	v_fmac_f32_e32 v101, 0x3f317217, v93
	v_fmac_f32_e32 v102, 0x3f317217, v94
	v_fmac_f32_e32 v103, 0x3f317217, v95
	v_cmp_lt_f32_e64 vcc, |v92|, s34
	v_cndmask_b32_e32 v92, v92, v100, vcc
	v_cmp_lt_f32_e64 vcc, |v93|, s34
	v_cndmask_b32_e32 v93, v93, v101, vcc
	v_cmp_lt_f32_e64 vcc, |v94|, s34
	v_cndmask_b32_e32 v94, v94, v102, vcc
	v_cmp_lt_f32_e64 vcc, |v95|, s34
	v_cndmask_b32_e32 v95, v95, v103, vcc
	v_cndmask_b32_e64 v100, 0, v213, s[22:23]
	v_cndmask_b32_e64 v101, 0, v213, s[24:25]
	v_cndmask_b32_e64 v102, 0, v213, s[26:27]
	v_cndmask_b32_e64 v103, 0, v213, s[28:29]
	v_sub_f32_e32 v92, v92, v100
	v_sub_f32_e32 v93, v93, v101
	v_sub_f32_e32 v94, v94, v102
	v_sub_f32_e32 v95, v95, v103
	v_add_f32_e32 v64, v64, v92
	v_add_f32_e32 v65, v65, v93
	v_add_f32_e32 v66, v66, v94
	v_add_f32_e32 v67, v67, v95
	v_mul_f32_e32 v92, 0xbfb8aa3b, v64
	v_mul_f32_e32 v93, 0xbfb8aa3b, v65
	v_mul_f32_e32 v94, 0xbfb8aa3b, v66
	v_mul_f32_e32 v95, 0xbfb8aa3b, v67
	v_mul_f32_e32 v100, 0x3fb8aa3b, v64
	v_mul_f32_e32 v101, 0x3fb8aa3b, v65
	v_mul_f32_e32 v102, 0x3fb8aa3b, v66
	v_mul_f32_e32 v103, 0x3fb8aa3b, v67
	v_exp_f32_e32 v92, v92
	v_exp_f32_e32 v93, v93
	v_exp_f32_e32 v94, v94
	v_exp_f32_e32 v95, v95
	v_exp_f32_e32 v100, v100
	v_exp_f32_e32 v101, v101
	v_exp_f32_e32 v102, v102
	v_exp_f32_e32 v103, v103
	v_sub_f32_e32 v96, 1.0, v96
	v_sub_f32_e32 v97, 1.0, v97
	v_sub_f32_e32 v98, 1.0, v98
	v_sub_f32_e32 v99, 1.0, v99
	v_mul_f32_e32 v96, v96, v92
	v_mul_f32_e32 v97, v97, v93
	v_mul_f32_e32 v98, v98, v94
	v_mul_f32_e32 v99, v99, v95
	v_lshlrev_b32_e32 v92, 16, v50
	v_and_b32_e32 v93, 0xffff0000, v50
	v_lshlrev_b32_e32 v94, 16, v51
	v_and_b32_e32 v95, 0xffff0000, v51
	v_mul_f32_e32 v92, v92, v100
	v_mul_f32_e32 v93, v93, v101
	v_mul_f32_e32 v94, v94, v102
	v_mul_f32_e32 v95, v95, v103
	v_mov_b32_e32 v117, v96
	v_mov_b32_e32 v133, v97
	v_mov_b32_e32 v167, v98
	v_mov_b32_e32 v183, v99
	v_cvt_pk_bf16_f32 v92, v92, v93
	v_cvt_pk_bf16_f32 v93, v94, v95
	v_cvt_pk_bf16_f32 v96, v96, v97
	v_cvt_pk_bf16_f32 v97, v98, v99
	global_store_dwordx2 v112, v[92:93], s[2:3]
	global_store_dwordx2 v114, v[96:97], s[2:3]
	s_sub_u32 s2, s2, 0x400
	s_subb_u32 s3, s3, 0
	v_lshlrev_b32_e32 v92, 16, v52
	v_and_b32_e32 v93, 0xffff0000, v52
	v_lshlrev_b32_e32 v94, 16, v53
	v_and_b32_e32 v95, 0xffff0000, v53
	v_mul_f32_e32 v92, 0xbfb8aa3b, v92
	v_mul_f32_e32 v93, 0xbfb8aa3b, v93
	v_mul_f32_e32 v94, 0xbfb8aa3b, v94
	v_mul_f32_e32 v95, 0xbfb8aa3b, v95
	v_exp_f32_e32 v92, v92
	v_exp_f32_e32 v93, v93
	v_exp_f32_e32 v94, v94
	v_exp_f32_e32 v95, v95
	v_add_f32_e32 v92, 1.0, v92
	v_add_f32_e32 v93, 1.0, v93
	v_add_f32_e32 v94, 1.0, v94
	v_add_f32_e32 v95, 1.0, v95
	v_rcp_f32_e32 v92, v92
	v_rcp_f32_e32 v93, v93
	v_rcp_f32_e32 v94, v94
	v_rcp_f32_e32 v95, v95
	v_fma_f32 v96, v72, v92, v68
	v_fma_f32 v97, v73, v93, v69
	v_fma_f32 v98, v74, v94, v70
	v_fma_f32 v99, v75, v95, v71
	v_cmp_gt_f32_e64 s[22:23], s30, v96
	v_cmp_gt_f32_e64 s[24:25], s30, v97
	v_cmp_gt_f32_e64 s[26:27], s30, v98
	v_cmp_gt_f32_e64 s[28:29], s30, v99
	v_cndmask_b32_e64 v92, 0, 32, s[22:23]
	v_cndmask_b32_e64 v93, 0, 32, s[24:25]
	v_cndmask_b32_e64 v94, 0, 32, s[26:27]
	v_cndmask_b32_e64 v95, 0, 32, s[28:29]
	v_ldexp_f32 v92, v96, v92
	v_ldexp_f32 v93, v97, v93
	v_ldexp_f32 v94, v98, v94
	v_ldexp_f32 v95, v99, v95
	v_log_f32_e32 v92, v92
	v_log_f32_e32 v93, v93
	v_log_f32_e32 v94, v94
	v_log_f32_e32 v95, v95
	v_mul_f32_e32 v100, 0x3f317217, v92
	v_mul_f32_e32 v101, 0x3f317217, v93
	v_mul_f32_e32 v102, 0x3f317217, v94
	v_mul_f32_e32 v103, 0x3f317217, v95
	v_fma_f32 v100, v92, s31, -v100
	v_fma_f32 v101, v93, s31, -v101
	v_fma_f32 v102, v94, s31, -v102
	v_fma_f32 v103, v95, s31, -v103
	v_fmac_f32_e32 v100, 0x3377d1cf, v92
	v_fmac_f32_e32 v101, 0x3377d1cf, v93
	v_fmac_f32_e32 v102, 0x3377d1cf, v94
	v_fmac_f32_e32 v103, 0x3377d1cf, v95
	v_fmac_f32_e32 v100, 0x3f317217, v92
	v_fmac_f32_e32 v101, 0x3f317217, v93
	v_fmac_f32_e32 v102, 0x3f317217, v94
	v_fmac_f32_e32 v103, 0x3f317217, v95
	v_cmp_lt_f32_e64 vcc, |v92|, s34
	v_cndmask_b32_e32 v92, v92, v100, vcc
	v_cmp_lt_f32_e64 vcc, |v93|, s34
	v_cndmask_b32_e32 v93, v93, v101, vcc
	v_cmp_lt_f32_e64 vcc, |v94|, s34
	v_cndmask_b32_e32 v94, v94, v102, vcc
	v_cmp_lt_f32_e64 vcc, |v95|, s34
	v_cndmask_b32_e32 v95, v95, v103, vcc
	v_cndmask_b32_e64 v100, 0, v213, s[22:23]
	v_cndmask_b32_e64 v101, 0, v213, s[24:25]
	v_cndmask_b32_e64 v102, 0, v213, s[26:27]
	v_cndmask_b32_e64 v103, 0, v213, s[28:29]
	v_sub_f32_e32 v92, v92, v100
	v_sub_f32_e32 v93, v93, v101
	v_sub_f32_e32 v94, v94, v102
	v_sub_f32_e32 v95, v95, v103
	v_add_f32_e32 v64, v64, v92
	v_add_f32_e32 v65, v65, v93
	v_add_f32_e32 v66, v66, v94
	v_add_f32_e32 v67, v67, v95
	v_mul_f32_e32 v92, 0xbfb8aa3b, v64
	v_mul_f32_e32 v93, 0xbfb8aa3b, v65
	v_mul_f32_e32 v94, 0xbfb8aa3b, v66
	v_mul_f32_e32 v95, 0xbfb8aa3b, v67
	v_mul_f32_e32 v100, 0x3fb8aa3b, v64
	v_mul_f32_e32 v101, 0x3fb8aa3b, v65
	v_mul_f32_e32 v102, 0x3fb8aa3b, v66
	v_mul_f32_e32 v103, 0x3fb8aa3b, v67
	v_exp_f32_e32 v92, v92
	v_exp_f32_e32 v93, v93
	v_exp_f32_e32 v94, v94
	v_exp_f32_e32 v95, v95
	v_exp_f32_e32 v100, v100
	v_exp_f32_e32 v101, v101
	v_exp_f32_e32 v102, v102
	v_exp_f32_e32 v103, v103
	v_sub_f32_e32 v96, 1.0, v96
	v_sub_f32_e32 v97, 1.0, v97
	v_sub_f32_e32 v98, 1.0, v98
	v_sub_f32_e32 v99, 1.0, v99
	v_mul_f32_e32 v96, v96, v92
	v_mul_f32_e32 v97, v97, v93
	v_mul_f32_e32 v98, v98, v94
; DEV u16 f2bf(float f) { return (u16)(pack2(f, f) & 0xffffu); }
; DEV float bf2f(u16 h) { return __uint_as_float(((unsigned)h) << 16); }
; DEV float sigmoid_f(float x) { return __builtin_amdgcn_rcpf(1.f + __expf(-x)); }
; DEV void phase_p15(const Params& p, int g) {
;     ...
; #pragma unroll
;       for (int cc = 0; cc < 2; ++cc) {
;         const int c = tid + 256 * cc;
;         unsigned kb[8];
; #pragma unroll
;         for (int e = 0; e < 8; ++e) {
;           const int jj = j8 * 8 + e;
;           const int j = dir ? 63 - jj : jj;
;           const size_t tok = (size_t)cidx * 64 + j;
;           const float f = lb[cc] + (1.f - lb[cc]) * sigmoid_f(bf2f(xr[st][cc][e]));
;           G[cc] += __logf(f);
;           const float eg = __expf(G[cc]), ig = __expf(-G[cc]);
;           Qp[tok * 512 + c] = f2bf(bf2f(qr[st][cc][e]) * eg);
;           const u16 kk = f2bf((1.f - f) * ig);
;           Kp[tok * 512 + c] = kk;
;           kb[e] = kk;
;         }
;         const int s0 = dir ? 56 - 8 * j8 : 8 * j8;
;         uint4 w;
;         w.x = dir ? (kb[7] | (kb[6] << 16)) : (kb[0] | (kb[1] << 16));
;         w.y = dir ? (kb[5] | (kb[4] << 16)) : (kb[2] | (kb[3] << 16));
;         w.z = dir ? (kb[3] | (kb[2] << 16)) : (kb[4] | (kb[5] << 16));
;         w.w = dir ? (kb[1] | (kb[0] << 16)) : (kb[6] | (kb[7] << 16));
;         *(uint4*)(KT + (((size_t)cidx * 2 + dir) * 512 + c) * 64 + s0) = w;
;       }
	v_mul_f32_e32 v99, v99, v95
	v_lshlrev_b32_e32 v92, 16, v54
	v_and_b32_e32 v93, 0xffff0000, v54
	v_lshlrev_b32_e32 v94, 16, v55
	v_and_b32_e32 v95, 0xffff0000, v55
	v_mul_f32_e32 v92, v92, v100
	v_mul_f32_e32 v93, v93, v101
	v_mul_f32_e32 v94, v94, v102
	v_mul_f32_e32 v95, v95, v103
	v_cvt_pk_bf16_f32 v117, v96, v117
	v_cvt_pk_bf16_f32 v133, v97, v133
	v_cvt_pk_bf16_f32 v167, v98, v167
	v_cvt_pk_bf16_f32 v183, v99, v183
	v_cvt_pk_bf16_f32 v92, v92, v93
	v_cvt_pk_bf16_f32 v93, v94, v95
	v_cvt_pk_bf16_f32 v96, v96, v97
	v_cvt_pk_bf16_f32 v97, v98, v99
	global_store_dwordx2 v112, v[92:93], s[2:3]
	global_store_dwordx2 v114, v[96:97], s[2:3]
	s_sub_u32 s2, s2, 0x400
	s_subb_u32 s3, s3, 0
	v_lshlrev_b32_e32 v92, 16, v56
	v_and_b32_e32 v93, 0xffff0000, v56
	v_lshlrev_b32_e32 v94, 16, v57
	v_and_b32_e32 v95, 0xffff0000, v57
	v_mul_f32_e32 v92, 0xbfb8aa3b, v92
	v_mul_f32_e32 v93, 0xbfb8aa3b, v93
	v_mul_f32_e32 v94, 0xbfb8aa3b, v94
	v_mul_f32_e32 v95, 0xbfb8aa3b, v95
	v_exp_f32_e32 v92, v92
	v_exp_f32_e32 v93, v93
	v_exp_f32_e32 v94, v94
	v_exp_f32_e32 v95, v95
	v_add_f32_e32 v92, 1.0, v92
	v_add_f32_e32 v93, 1.0, v93
	v_add_f32_e32 v94, 1.0, v94
	v_add_f32_e32 v95, 1.0, v95
	v_rcp_f32_e32 v92, v92
	v_rcp_f32_e32 v93, v93
	v_rcp_f32_e32 v94, v94
	v_rcp_f32_e32 v95, v95
	v_fma_f32 v96, v72, v92, v68
	v_fma_f32 v97, v73, v93, v69
	v_fma_f32 v98, v74, v94, v70
	v_fma_f32 v99, v75, v95, v71
	v_cmp_gt_f32_e64 s[22:23], s30, v96
	v_cmp_gt_f32_e64 s[24:25], s30, v97
	v_cmp_gt_f32_e64 s[26:27], s30, v98
	v_cmp_gt_f32_e64 s[28:29], s30, v99
	v_cndmask_b32_e64 v92, 0, 32, s[22:23]
	v_cndmask_b32_e64 v93, 0, 32, s[24:25]
	v_cndmask_b32_e64 v94, 0, 32, s[26:27]
	v_cndmask_b32_e64 v95, 0, 32, s[28:29]
	v_ldexp_f32 v92, v96, v92
	v_ldexp_f32 v93, v97, v93
	v_ldexp_f32 v94, v98, v94
	v_ldexp_f32 v95, v99, v95
	v_log_f32_e32 v92, v92
	v_log_f32_e32 v93, v93
	v_log_f32_e32 v94, v94
	v_log_f32_e32 v95, v95
	v_mul_f32_e32 v100, 0x3f317217, v92
	v_mul_f32_e32 v101, 0x3f317217, v93
	v_mul_f32_e32 v102, 0x3f317217, v94
	v_mul_f32_e32 v103, 0x3f317217, v95
	v_fma_f32 v100, v92, s31, -v100
	v_fma_f32 v101, v93, s31, -v101
	v_fma_f32 v102, v94, s31, -v102
	v_fma_f32 v103, v95, s31, -v103
	v_fmac_f32_e32 v100, 0x3377d1cf, v92
	v_fmac_f32_e32 v101, 0x3377d1cf, v93
	v_fmac_f32_e32 v102, 0x3377d1cf, v94
	v_fmac_f32_e32 v103, 0x3377d1cf, v95
	v_fmac_f32_e32 v100, 0x3f317217, v92
	v_fmac_f32_e32 v101, 0x3f317217, v93
	v_fmac_f32_e32 v102, 0x3f317217, v94
	v_fmac_f32_e32 v103, 0x3f317217, v95
	v_cmp_lt_f32_e64 vcc, |v92|, s34
	v_cndmask_b32_e32 v92, v92, v100, vcc
	v_cmp_lt_f32_e64 vcc, |v93|, s34
	v_cndmask_b32_e32 v93, v93, v101, vcc
	v_cmp_lt_f32_e64 vcc, |v94|, s34
	v_cndmask_b32_e32 v94, v94, v102, vcc
	v_cmp_lt_f32_e64 vcc, |v95|, s34
	v_cndmask_b32_e32 v95, v95, v103, vcc
	v_cndmask_b32_e64 v100, 0, v213, s[22:23]
	v_cndmask_b32_e64 v101, 0, v213, s[24:25]
	v_cndmask_b32_e64 v102, 0, v213, s[26:27]
	v_cndmask_b32_e64 v103, 0, v213, s[28:29]
	v_sub_f32_e32 v92, v92, v100
	v_sub_f32_e32 v93, v93, v101
	v_sub_f32_e32 v94, v94, v102
	v_sub_f32_e32 v95, v95, v103
	v_add_f32_e32 v64, v64, v92
	v_add_f32_e32 v65, v65, v93
	v_add_f32_e32 v66, v66, v94
	v_add_f32_e32 v67, v67, v95
	v_mul_f32_e32 v92, 0xbfb8aa3b, v64
	v_mul_f32_e32 v93, 0xbfb8aa3b, v65
	v_mul_f32_e32 v94, 0xbfb8aa3b, v66
	v_mul_f32_e32 v95, 0xbfb8aa3b, v67
	v_mul_f32_e32 v100, 0x3fb8aa3b, v64
	v_mul_f32_e32 v101, 0x3fb8aa3b, v65
	v_mul_f32_e32 v102, 0x3fb8aa3b, v66
	v_mul_f32_e32 v103, 0x3fb8aa3b, v67
	v_exp_f32_e32 v92, v92
	v_exp_f32_e32 v93, v93
	v_exp_f32_e32 v94, v94
	v_exp_f32_e32 v95, v95
	v_exp_f32_e32 v100, v100
	v_exp_f32_e32 v101, v101
	v_exp_f32_e32 v102, v102
	v_exp_f32_e32 v103, v103
	v_sub_f32_e32 v96, 1.0, v96
	v_sub_f32_e32 v97, 1.0, v97
	v_sub_f32_e32 v98, 1.0, v98
	v_sub_f32_e32 v99, 1.0, v99
	v_mul_f32_e32 v96, v96, v92
	v_mul_f32_e32 v97, v97, v93
	v_mul_f32_e32 v98, v98, v94
	v_mul_f32_e32 v99, v99, v95
	v_lshlrev_b32_e32 v92, 16, v58
	v_and_b32_e32 v93, 0xffff0000, v58
	v_lshlrev_b32_e32 v94, 16, v59
	v_and_b32_e32 v95, 0xffff0000, v59
	v_mul_f32_e32 v92, v92, v100
	v_mul_f32_e32 v93, v93, v101
	v_mul_f32_e32 v94, v94, v102
	v_mul_f32_e32 v95, v95, v103
	v_mov_b32_e32 v116, v96
	v_mov_b32_e32 v132, v97
	v_mov_b32_e32 v166, v98
	v_mov_b32_e32 v182, v99
	v_cvt_pk_bf16_f32 v92, v92, v93
	v_cvt_pk_bf16_f32 v93, v94, v95
	v_cvt_pk_bf16_f32 v96, v96, v97
	v_cvt_pk_bf16_f32 v97, v98, v99
	global_store_dwordx2 v112, v[92:93], s[2:3]
	global_store_dwordx2 v114, v[96:97], s[2:3]
	s_sub_u32 s2, s2, 0x400
	s_subb_u32 s3, s3, 0
	v_lshlrev_b32_e32 v92, 16, v60
	v_and_b32_e32 v93, 0xffff0000, v60
	v_lshlrev_b32_e32 v94, 16, v61
	v_and_b32_e32 v95, 0xffff0000, v61
	v_mul_f32_e32 v92, 0xbfb8aa3b, v92
	v_mul_f32_e32 v93, 0xbfb8aa3b, v93
	v_mul_f32_e32 v94, 0xbfb8aa3b, v94
; DEV u16 f2bf(float f) { return (u16)(pack2(f, f) & 0xffffu); }
; DEV float bf2f(u16 h) { return __uint_as_float(((unsigned)h) << 16); }
; DEV float sigmoid_f(float x) { return __builtin_amdgcn_rcpf(1.f + __expf(-x)); }
; DEV void phase_p15(const Params& p, int g) {
;     ...
;     P15_LOAD(0, 0);
;     P15_LOAD(1, 1);
; #pragma unroll
;     for (int j8 = 0; j8 < 8; ++j8) {
;       const int st = j8 % 3;
;       if (j8 < 6) { P15_LOAD((j8 + 2) % 3, j8 + 2); }
; #pragma unroll
;       for (int cc = 0; cc < 2; ++cc) {
;         const int c = tid + 256 * cc;
;         unsigned kb[8];
; #pragma unroll
;         for (int e = 0; e < 8; ++e) {
;           const int jj = j8 * 8 + e;
;           const int j = dir ? 63 - jj : jj;
;           const size_t tok = (size_t)cidx * 64 + j;
;           const float f = lb[cc] + (1.f - lb[cc]) * sigmoid_f(bf2f(xr[st][cc][e]));
;           G[cc] += __logf(f);
;           const float eg = __expf(G[cc]), ig = __expf(-G[cc]);
;           Qp[tok * 512 + c] = f2bf(bf2f(qr[st][cc][e]) * eg);
;           const u16 kk = f2bf((1.f - f) * ig);
;           Kp[tok * 512 + c] = kk;
;           kb[e] = kk;
;         }
;         const int s0 = dir ? 56 - 8 * j8 : 8 * j8;
;         uint4 w;
;         w.x = dir ? (kb[7] | (kb[6] << 16)) : (kb[0] | (kb[1] << 16));
;         w.y = dir ? (kb[5] | (kb[4] << 16)) : (kb[2] | (kb[3] << 16));
;         w.z = dir ? (kb[3] | (kb[2] << 16)) : (kb[4] | (kb[5] << 16));
;         w.w = dir ? (kb[1] | (kb[0] << 16)) : (kb[6] | (kb[7] << 16));
;         *(uint4*)(KT + (((size_t)cidx * 2 + dir) * 512 + c) * 64 + s0) = w;
;       }
	v_mul_f32_e32 v95, 0xbfb8aa3b, v95
	v_exp_f32_e32 v92, v92
	v_exp_f32_e32 v93, v93
	v_exp_f32_e32 v94, v94
	v_exp_f32_e32 v95, v95
	v_add_f32_e32 v92, 1.0, v92
	v_add_f32_e32 v93, 1.0, v93
	v_add_f32_e32 v94, 1.0, v94
	v_add_f32_e32 v95, 1.0, v95
	v_rcp_f32_e32 v92, v92
	v_rcp_f32_e32 v93, v93
	v_rcp_f32_e32 v94, v94
	v_rcp_f32_e32 v95, v95
	v_fma_f32 v96, v72, v92, v68
	v_fma_f32 v97, v73, v93, v69
	v_fma_f32 v98, v74, v94, v70
	v_fma_f32 v99, v75, v95, v71
	v_cmp_gt_f32_e64 s[22:23], s30, v96
	v_cmp_gt_f32_e64 s[24:25], s30, v97
	v_cmp_gt_f32_e64 s[26:27], s30, v98
	v_cmp_gt_f32_e64 s[28:29], s30, v99
	v_cndmask_b32_e64 v92, 0, 32, s[22:23]
	v_cndmask_b32_e64 v93, 0, 32, s[24:25]
	v_cndmask_b32_e64 v94, 0, 32, s[26:27]
	v_cndmask_b32_e64 v95, 0, 32, s[28:29]
	v_ldexp_f32 v92, v96, v92
	v_ldexp_f32 v93, v97, v93
	v_ldexp_f32 v94, v98, v94
	v_ldexp_f32 v95, v99, v95
	v_log_f32_e32 v92, v92
	v_log_f32_e32 v93, v93
	v_log_f32_e32 v94, v94
	v_log_f32_e32 v95, v95
	v_mul_f32_e32 v100, 0x3f317217, v92
	v_mul_f32_e32 v101, 0x3f317217, v93
	v_mul_f32_e32 v102, 0x3f317217, v94
	v_mul_f32_e32 v103, 0x3f317217, v95
	v_fma_f32 v100, v92, s31, -v100
	v_fma_f32 v101, v93, s31, -v101
	v_fma_f32 v102, v94, s31, -v102
	v_fma_f32 v103, v95, s31, -v103
	v_fmac_f32_e32 v100, 0x3377d1cf, v92
	v_fmac_f32_e32 v101, 0x3377d1cf, v93
	v_fmac_f32_e32 v102, 0x3377d1cf, v94
	v_fmac_f32_e32 v103, 0x3377d1cf, v95
	v_fmac_f32_e32 v100, 0x3f317217, v92
	v_fmac_f32_e32 v101, 0x3f317217, v93
	v_fmac_f32_e32 v102, 0x3f317217, v94
	v_fmac_f32_e32 v103, 0x3f317217, v95
	v_cmp_lt_f32_e64 vcc, |v92|, s34
	v_cndmask_b32_e32 v92, v92, v100, vcc
	v_cmp_lt_f32_e64 vcc, |v93|, s34
	v_cndmask_b32_e32 v93, v93, v101, vcc
	v_cmp_lt_f32_e64 vcc, |v94|, s34
	v_cndmask_b32_e32 v94, v94, v102, vcc
	v_cmp_lt_f32_e64 vcc, |v95|, s34
	v_cndmask_b32_e32 v95, v95, v103, vcc
	v_cndmask_b32_e64 v100, 0, v213, s[22:23]
	v_cndmask_b32_e64 v101, 0, v213, s[24:25]
	v_cndmask_b32_e64 v102, 0, v213, s[26:27]
	v_cndmask_b32_e64 v103, 0, v213, s[28:29]
	v_sub_f32_e32 v92, v92, v100
	v_sub_f32_e32 v93, v93, v101
	v_sub_f32_e32 v94, v94, v102
	v_sub_f32_e32 v95, v95, v103
	v_add_f32_e32 v64, v64, v92
	v_add_f32_e32 v65, v65, v93
	v_add_f32_e32 v66, v66, v94
	v_add_f32_e32 v67, v67, v95
	v_mul_f32_e32 v92, 0xbfb8aa3b, v64
	v_mul_f32_e32 v93, 0xbfb8aa3b, v65
	v_mul_f32_e32 v94, 0xbfb8aa3b, v66
	v_mul_f32_e32 v95, 0xbfb8aa3b, v67
	v_mul_f32_e32 v100, 0x3fb8aa3b, v64
	v_mul_f32_e32 v101, 0x3fb8aa3b, v65
	v_mul_f32_e32 v102, 0x3fb8aa3b, v66
	v_mul_f32_e32 v103, 0x3fb8aa3b, v67
	v_exp_f32_e32 v92, v92
	v_exp_f32_e32 v93, v93
	v_exp_f32_e32 v94, v94
	v_exp_f32_e32 v95, v95
	v_exp_f32_e32 v100, v100
	v_exp_f32_e32 v101, v101
	v_exp_f32_e32 v102, v102
	v_exp_f32_e32 v103, v103
	v_sub_f32_e32 v96, 1.0, v96
	v_sub_f32_e32 v97, 1.0, v97
	v_sub_f32_e32 v98, 1.0, v98
	v_sub_f32_e32 v99, 1.0, v99
	v_mul_f32_e32 v96, v96, v92
	v_mul_f32_e32 v97, v97, v93
	v_mul_f32_e32 v98, v98, v94
	v_mul_f32_e32 v99, v99, v95
	v_lshlrev_b32_e32 v92, 16, v62
	v_and_b32_e32 v93, 0xffff0000, v62
	v_lshlrev_b32_e32 v94, 16, v63
	v_and_b32_e32 v95, 0xffff0000, v63
	v_mul_f32_e32 v92, v92, v100
	v_mul_f32_e32 v93, v93, v101
	v_mul_f32_e32 v94, v94, v102
	v_mul_f32_e32 v95, v95, v103
	v_cvt_pk_bf16_f32 v116, v96, v116
	v_cvt_pk_bf16_f32 v132, v97, v132
	v_cvt_pk_bf16_f32 v166, v98, v166
	v_cvt_pk_bf16_f32 v182, v99, v182
	v_cvt_pk_bf16_f32 v92, v92, v93
	v_cvt_pk_bf16_f32 v93, v94, v95
	v_cvt_pk_bf16_f32 v96, v96, v97
	v_cvt_pk_bf16_f32 v97, v98, v99
	global_store_dwordx2 v112, v[92:93], s[2:3]
	global_store_dwordx2 v114, v[96:97], s[2:3]
	s_sub_u32 s2, s2, 0x400
	s_subb_u32 s3, s3, 0
	s_cmp_eq_u32 s35, 1
	s_cbranch_scc1 .Lp15_d1_nl3
	global_load_dwordx2 v[32:33], v113, s[0:1]
	global_load_dwordx2 v[34:35], v112, s[0:1]
	s_sub_u32 s0, s0, 0x1400
	s_subb_u32 s1, s1, 0
	global_load_dwordx2 v[36:37], v113, s[0:1]
	global_load_dwordx2 v[38:39], v112, s[0:1]
	s_sub_u32 s0, s0, 0x1400
	s_subb_u32 s1, s1, 0
	global_load_dwordx2 v[40:41], v113, s[0:1]
	global_load_dwordx2 v[42:43], v112, s[0:1]
	s_sub_u32 s0, s0, 0x1400
	s_subb_u32 s1, s1, 0
	global_load_dwordx2 v[44:45], v113, s[0:1]
	global_load_dwordx2 v[46:47], v112, s[0:1]
	s_sub_u32 s0, s0, 0x1400
	s_subb_u32 s1, s1, 0
	global_load_dwordx2 v[48:49], v113, s[0:1]
	global_load_dwordx2 v[50:51], v112, s[0:1]
	s_sub_u32 s0, s0, 0x1400
	s_subb_u32 s1, s1, 0
	global_load_dwordx2 v[52:53], v113, s[0:1]
	global_load_dwordx2 v[54:55], v112, s[0:1]
	s_sub_u32 s0, s0, 0x1400
	s_subb_u32 s1, s1, 0
	global_load_dwordx2 v[56:57], v113, s[0:1]
	global_load_dwordx2 v[58:59], v112, s[0:1]
	s_sub_u32 s0, s0, 0x1400
	s_subb_u32 s1, s1, 0
	global_load_dwordx2 v[60:61], v113, s[0:1]
	global_load_dwordx2 v[62:63], v112, s[0:1]
	s_sub_u32 s0, s0, 0x1400
	s_subb_u32 s1, s1, 0
